# remaining back-to-back duplicate s_waitcnt (tails, short-K GEMMs, other phases) removed file-wide (49 sites)
# speedup vs baseline: 1.0020x; 1.0014x over previous
; #define LDA(dst, b, h) for (int m = 0; m < 4; ++m) for (int k = 0; k < 2; ++k) \
;     dst[m][k] = *reinterpret_cast<const bf16x8*>((char*)SA(b, h) + a_thr + (m * 2 + k) * 1024)
; #define LDB(dst, b, h) for (int n = 0; n < 2; ++n) for (int k = 0; k < 2; ++k) \
;     dst[n][k] = *reinterpret_cast<const bf16x8*>((char*)SB(b, h) + b_thr + (n * 2 + k) * 1024)
; #define MMA(ai, bj, At, Btf) do { __builtin_amdgcn_s_setprio(1); \
;     for (int m = 0; m < 4; ++m) for (int n = 0; n < 2; ++n) for (int k = 0; k < 2; ++k) \
;       acc[ai][bj][m][n] = __builtin_amdgcn_mfma_f32_16x16x32_bf16(Btf[n][k], At[m][k], acc[ai][bj][m][n], 0, 0, 0); \
;     __builtin_amdgcn_s_setprio(0); } while (0)
; #define WAIT_V(n) asm volatile("s_waitcnt vmcnt(" #n ")" ::: "memory")
; #define WAIT_L(n) asm volatile("s_waitcnt lgkmcnt(" #n ")" ::: "memory")
; #define BAR __builtin_amdgcn_s_barrier()
; #define SCHED __builtin_amdgcn_sched_barrier(0)
; template <bool OVL, bool PANEL = false, class Epi>
; __device__ __forceinline__ void gemm_phase(const bf16_t* __restrict__ A, long lda, const bf16_t* __restrict__ Bt, long ldb, int nM, int nN, int K,
;                                            const Epi& epi, bf16_t* shm, int w0) {
;     ...
;       LDB(B0, 0, 0); SCHED; LDA(At, 0, 0); STAGE(SA(1, 1), A, lda, aoff, brow + HALF, t + 1);
;       WAIT_L(8); BAR; WAIT_L(0); MMA(0, 0, At, B0); BAR; SCHED;
;       LDB(B1, 0, 1); STAGE(SB(0, 0), Bt, ldb, boff, bcol, t + 2);
;       BAR; WAIT_L(0); MMA(0, 1, At, B1); BAR;
;       LDA(At, 0, 1); STAGE(SA(0, 0), A, lda, aoff, brow, t + 2);
;       BAR; WAIT_L(0); MMA(1, 0, At, B0); BAR; SCHED;
;       STAGE(SB(0, 1), Bt, ldb, boff, bcol + HALF, t + 2);
;       WAIT_V(6); BAR; MMA(1, 1, At, B1); BAR;
.LBB0_125:
	ds_read_b128 v[138:141], v218
	ds_read_b128 v[142:145], v218 offset:1024
	ds_read_b128 v[146:149], v218 offset:2048
	ds_read_b128 v[150:153], v218 offset:3072
	s_add_u32 s8, s4, s6
	s_addc_u32 s9, s5, s7
	ds_read_b128 v[154:157], v213
	ds_read_b128 v[158:161], v213 offset:1024
	ds_read_b128 v[162:165], v213 offset:2048
	ds_read_b128 v[166:169], v213 offset:3072
	ds_read_b128 v[170:173], v213 offset:4096
	ds_read_b128 v[174:177], v213 offset:5120
	ds_read_b128 v[178:181], v213 offset:6144
	ds_read_b128 v[182:185], v213 offset:7168
	s_mov_b32 m0, s25
	s_add_u32 s98, s8, s14
	s_addc_u32 s99, s9, s15
	global_load_lds_dwordx4 v203, s[98:99]
	s_mov_b32 m0, s32
	s_add_u32 s98, s8, s16
	s_addc_u32 s99, s9, s17
	global_load_lds_dwordx4 v203, s[98:99]
	s_waitcnt lgkmcnt(8)
	s_waitcnt vmcnt(10)
	s_barrier
	s_waitcnt lgkmcnt(0)
	v_mfma_f32_16x16x32_bf16 v[126:129], v[138:141], v[154:157], v[126:129]
	v_mfma_f32_16x16x32_bf16 v[122:125], v[146:149], v[154:157], v[122:125]
	v_mfma_f32_16x16x32_bf16 v[118:121], v[138:141], v[162:165], v[118:121]
	v_mfma_f32_16x16x32_bf16 v[114:117], v[146:149], v[162:165], v[114:117]
	v_mfma_f32_16x16x32_bf16 v[110:113], v[138:141], v[170:173], v[110:113]
	v_mfma_f32_16x16x32_bf16 v[106:109], v[146:149], v[170:173], v[106:109]
	v_mfma_f32_16x16x32_bf16 v[102:105], v[138:141], v[178:181], v[102:105]
	v_mfma_f32_16x16x32_bf16 v[98:101], v[146:149], v[178:181], v[98:101]
	v_mfma_f32_16x16x32_bf16 v[126:129], v[142:145], v[158:161], v[126:129]
	v_mfma_f32_16x16x32_bf16 v[122:125], v[150:153], v[158:161], v[122:125]
	v_mfma_f32_16x16x32_bf16 v[118:121], v[142:145], v[166:169], v[118:121]
	v_mfma_f32_16x16x32_bf16 v[114:117], v[150:153], v[166:169], v[114:117]
	v_mfma_f32_16x16x32_bf16 v[110:113], v[142:145], v[174:177], v[110:113]
	v_mfma_f32_16x16x32_bf16 v[106:109], v[150:153], v[174:177], v[106:109]
	v_mfma_f32_16x16x32_bf16 v[102:105], v[142:145], v[182:185], v[102:105]
	v_mfma_f32_16x16x32_bf16 v[98:101], v[150:153], v[182:185], v[98:101]
	s_barrier
	s_add_u32 vcc_lo, s0, s6
	ds_read_b128 v[186:189], v219
	ds_read_b128 v[190:193], v219 offset:1024
	ds_read_b128 v[194:197], v219 offset:2048
	ds_read_b128 v[198:201], v219 offset:3072
	s_addc_u32 vcc_hi, s1, s7
	s_mov_b32 m0, s44
	s_add_u32 s98, vcc_lo, s34
	s_addc_u32 s99, vcc_hi, s35
	global_load_lds_dwordx4 v203, s[98:99]
	s_mov_b32 m0, s45
	s_add_u32 s98, vcc_lo, s18
	s_addc_u32 s99, vcc_hi, s19
	global_load_lds_dwordx4 v203, s[98:99]
	s_waitcnt vmcnt(10)
	s_barrier
	s_waitcnt lgkmcnt(0)
	v_mfma_f32_16x16x32_bf16 v[94:97], v[186:189], v[154:157], v[94:97]
	v_mfma_f32_16x16x32_bf16 v[90:93], v[194:197], v[154:157], v[90:93]
	v_mfma_f32_16x16x32_bf16 v[86:89], v[186:189], v[162:165], v[86:89]
	v_mfma_f32_16x16x32_bf16 v[82:85], v[194:197], v[162:165], v[82:85]
	v_mfma_f32_16x16x32_bf16 v[78:81], v[186:189], v[170:173], v[78:81]
	v_mfma_f32_16x16x32_bf16 v[74:77], v[194:197], v[170:173], v[74:77]
	v_mfma_f32_16x16x32_bf16 v[70:73], v[186:189], v[178:181], v[70:73]
	v_mfma_f32_16x16x32_bf16 v[66:69], v[194:197], v[178:181], v[66:69]
	v_mfma_f32_16x16x32_bf16 v[94:97], v[190:193], v[158:161], v[94:97]
	v_mfma_f32_16x16x32_bf16 v[90:93], v[198:201], v[158:161], v[90:93]
	v_mfma_f32_16x16x32_bf16 v[86:89], v[190:193], v[166:169], v[86:89]
	v_mfma_f32_16x16x32_bf16 v[82:85], v[198:201], v[166:169], v[82:85]
	v_mfma_f32_16x16x32_bf16 v[78:81], v[190:193], v[174:177], v[78:81]
	v_mfma_f32_16x16x32_bf16 v[74:77], v[198:201], v[174:177], v[74:77]
	v_mfma_f32_16x16x32_bf16 v[70:73], v[190:193], v[182:185], v[70:73]
	v_mfma_f32_16x16x32_bf16 v[66:69], v[198:201], v[182:185], v[66:69]
	s_barrier
	ds_read_b128 v[154:157], v213 offset:16384
	ds_read_b128 v[158:161], v213 offset:17408
	ds_read_b128 v[162:165], v213 offset:18432
	ds_read_b128 v[166:169], v213 offset:19456
	ds_read_b128 v[170:173], v213 offset:20480
	ds_read_b128 v[174:177], v213 offset:21504
	ds_read_b128 v[178:181], v213 offset:22528
	ds_read_b128 v[182:185], v213 offset:23552
	s_mov_b32 m0, s46
	s_add_u32 s98, s8, s34
	s_addc_u32 s99, s9, s35
	global_load_lds_dwordx4 v203, s[98:99]
	s_mov_b32 m0, s47
	s_add_u32 s98, s8, s18
	s_addc_u32 s99, s9, s19
	global_load_lds_dwordx4 v203, s[98:99]
	s_barrier
	s_waitcnt lgkmcnt(0)
	v_mfma_f32_16x16x32_bf16 v[62:65], v[138:141], v[154:157], v[62:65]
	v_mfma_f32_16x16x32_bf16 v[58:61], v[146:149], v[154:157], v[58:61]
	v_mfma_f32_16x16x32_bf16 v[54:57], v[138:141], v[162:165], v[54:57]
	v_mfma_f32_16x16x32_bf16 v[50:53], v[146:149], v[162:165], v[50:53]
	v_mfma_f32_16x16x32_bf16 v[46:49], v[138:141], v[170:173], v[46:49]
	v_mfma_f32_16x16x32_bf16 v[42:45], v[146:149], v[170:173], v[42:45]
	v_mfma_f32_16x16x32_bf16 v[38:41], v[138:141], v[178:181], v[38:41]
	v_mfma_f32_16x16x32_bf16 v[34:37], v[146:149], v[178:181], v[34:37]
	v_mfma_f32_16x16x32_bf16 v[62:65], v[142:145], v[158:161], v[62:65]
	v_mfma_f32_16x16x32_bf16 v[58:61], v[150:153], v[158:161], v[58:61]
	v_mfma_f32_16x16x32_bf16 v[54:57], v[142:145], v[166:169], v[54:57]
	v_mfma_f32_16x16x32_bf16 v[50:53], v[150:153], v[166:169], v[50:53]
	v_mfma_f32_16x16x32_bf16 v[46:49], v[142:145], v[174:177], v[46:49]
	v_mfma_f32_16x16x32_bf16 v[42:45], v[150:153], v[174:177], v[42:45]
	v_mfma_f32_16x16x32_bf16 v[38:41], v[142:145], v[182:185], v[38:41]
	v_mfma_f32_16x16x32_bf16 v[34:37], v[150:153], v[182:185], v[34:37]
	s_barrier
	s_mov_b32 m0, s48
	s_add_u32 s98, vcc_lo, s30
	s_addc_u32 s99, vcc_hi, s31
	global_load_lds_dwordx4 v203, s[98:99]
	s_mov_b32 m0, s49
	s_add_u32 s98, vcc_lo, s40
	s_addc_u32 s99, vcc_hi, s41
	global_load_lds_dwordx4 v203, s[98:99]
	s_waitcnt vmcnt(10)
	s_barrier
; #define LDA(dst, b, h) for (int m = 0; m < 4; ++m) for (int k = 0; k < 2; ++k) \
;     dst[m][k] = *reinterpret_cast<const bf16x8*>((char*)SA(b, h) + a_thr + (m * 2 + k) * 1024)
; #define LDB(dst, b, h) for (int n = 0; n < 2; ++n) for (int k = 0; k < 2; ++k) \
;     dst[n][k] = *reinterpret_cast<const bf16x8*>((char*)SB(b, h) + b_thr + (n * 2 + k) * 1024)
; #define MMA(ai, bj, At, Btf) do { __builtin_amdgcn_s_setprio(1); \
;     for (int m = 0; m < 4; ++m) for (int n = 0; n < 2; ++n) for (int k = 0; k < 2; ++k) \
;       acc[ai][bj][m][n] = __builtin_amdgcn_mfma_f32_16x16x32_bf16(Btf[n][k], At[m][k], acc[ai][bj][m][n], 0, 0, 0); \
;     __builtin_amdgcn_s_setprio(0); } while (0)
; #define WAIT_V(n) asm volatile("s_waitcnt vmcnt(" #n ")" ::: "memory")
; #define WAIT_L(n) asm volatile("s_waitcnt lgkmcnt(" #n ")" ::: "memory")
; #define BAR __builtin_amdgcn_s_barrier()
; #define SCHED __builtin_amdgcn_sched_barrier(0)
; template <bool OVL, bool PANEL = false, class Epi>
; __device__ __forceinline__ void gemm_phase(const bf16_t* __restrict__ A, long lda, const bf16_t* __restrict__ Bt, long ldb, int nM, int nN, int K,
;                                            const Epi& epi, bf16_t* shm, int w0) {
;     ...
;       WAIT_V(6); BAR; MMA(1, 1, At, B1); BAR;
;       LDB(B0, 1, 0); SCHED; LDA(At, 1, 0); STAGE(SA(0, 1), A, lda, aoff, brow + HALF, t + 2);
;       WAIT_L(8); BAR; WAIT_L(0); MMA(0, 0, At, B0); BAR; SCHED;
;       LDB(B1, 1, 1); STAGE(SB(1, 0), Bt, ldb, boff, bcol, t + 3);
;       BAR; WAIT_L(0); MMA(0, 1, At, B1); BAR;
	v_mfma_f32_16x16x32_bf16 v[30:33], v[186:189], v[154:157], v[30:33]
	v_mfma_f32_16x16x32_bf16 v[26:29], v[194:197], v[154:157], v[26:29]
	v_mfma_f32_16x16x32_bf16 v[22:25], v[186:189], v[162:165], v[22:25]
	v_mfma_f32_16x16x32_bf16 v[18:21], v[194:197], v[162:165], v[18:21]
	v_mfma_f32_16x16x32_bf16 v[14:17], v[186:189], v[170:173], v[14:17]
	v_mfma_f32_16x16x32_bf16 v[10:13], v[194:197], v[170:173], v[10:13]
	v_mfma_f32_16x16x32_bf16 v[6:9], v[186:189], v[178:181], v[6:9]
	v_mfma_f32_16x16x32_bf16 v[2:5], v[194:197], v[178:181], v[2:5]
	v_mfma_f32_16x16x32_bf16 v[30:33], v[190:193], v[158:161], v[30:33]
	v_mfma_f32_16x16x32_bf16 v[26:29], v[198:201], v[158:161], v[26:29]
	v_mfma_f32_16x16x32_bf16 v[22:25], v[190:193], v[166:169], v[22:25]
	v_mfma_f32_16x16x32_bf16 v[18:21], v[198:201], v[166:169], v[18:21]
	v_mfma_f32_16x16x32_bf16 v[14:17], v[190:193], v[174:177], v[14:17]
	v_mfma_f32_16x16x32_bf16 v[10:13], v[198:201], v[174:177], v[10:13]
	v_mfma_f32_16x16x32_bf16 v[6:9], v[190:193], v[182:185], v[6:9]
	v_mfma_f32_16x16x32_bf16 v[2:5], v[198:201], v[182:185], v[2:5]
	s_barrier
	ds_read_b128 v[138:141], v220
	ds_read_b128 v[142:145], v220 offset:1024
	ds_read_b128 v[146:149], v220 offset:2048
	ds_read_b128 v[150:153], v220 offset:3072
	ds_read_b128 v[154:157], v213 offset:32768
	ds_read_b128 v[158:161], v213 offset:33792
	ds_read_b128 v[162:165], v213 offset:34816
	ds_read_b128 v[166:169], v213 offset:35840
	ds_read_b128 v[170:173], v213 offset:36864
	ds_read_b128 v[174:177], v213 offset:37888
	ds_read_b128 v[178:181], v213 offset:38912
	ds_read_b128 v[182:185], v213 offset:39936
	s_mov_b32 m0, s50
	s_add_u32 s98, s8, s30
	s_addc_u32 s99, s9, s31
	global_load_lds_dwordx4 v203, s[98:99]
	s_mov_b32 m0, s51
	s_add_u32 s98, s8, s40
	s_addc_u32 s99, s9, s41
	global_load_lds_dwordx4 v203, s[98:99]
	s_waitcnt lgkmcnt(8)
	s_waitcnt vmcnt(10)
	s_barrier
	s_waitcnt lgkmcnt(0)
	v_mfma_f32_16x16x32_bf16 v[126:129], v[138:141], v[154:157], v[126:129]
	v_mfma_f32_16x16x32_bf16 v[122:125], v[146:149], v[154:157], v[122:125]
	v_mfma_f32_16x16x32_bf16 v[118:121], v[138:141], v[162:165], v[118:121]
	v_mfma_f32_16x16x32_bf16 v[114:117], v[146:149], v[162:165], v[114:117]
	v_mfma_f32_16x16x32_bf16 v[110:113], v[138:141], v[170:173], v[110:113]
	v_mfma_f32_16x16x32_bf16 v[106:109], v[146:149], v[170:173], v[106:109]
	v_mfma_f32_16x16x32_bf16 v[102:105], v[138:141], v[178:181], v[102:105]
	v_mfma_f32_16x16x32_bf16 v[98:101], v[146:149], v[178:181], v[98:101]
	v_mfma_f32_16x16x32_bf16 v[126:129], v[142:145], v[158:161], v[126:129]
	v_mfma_f32_16x16x32_bf16 v[122:125], v[150:153], v[158:161], v[122:125]
	v_mfma_f32_16x16x32_bf16 v[118:121], v[142:145], v[166:169], v[118:121]
	v_mfma_f32_16x16x32_bf16 v[114:117], v[150:153], v[166:169], v[114:117]
	v_mfma_f32_16x16x32_bf16 v[110:113], v[142:145], v[174:177], v[110:113]
	v_mfma_f32_16x16x32_bf16 v[106:109], v[150:153], v[174:177], v[106:109]
	v_mfma_f32_16x16x32_bf16 v[102:105], v[142:145], v[182:185], v[102:105]
	v_mfma_f32_16x16x32_bf16 v[98:101], v[150:153], v[182:185], v[98:101]
	s_barrier
	ds_read_b128 v[186:189], v221
	ds_read_b128 v[190:193], v221 offset:1024
	ds_read_b128 v[194:197], v221 offset:2048
	ds_read_b128 v[198:201], v221 offset:3072
	s_mov_b32 m0, s52
	s_add_u32 s98, vcc_lo, s94
	s_addc_u32 s99, vcc_hi, s95
	global_load_lds_dwordx4 v203, s[98:99]
	s_mov_b32 m0, s53
	s_add_u32 s98, vcc_lo, s42
	s_addc_u32 s99, vcc_hi, s43
	global_load_lds_dwordx4 v203, s[98:99]
	s_waitcnt vmcnt(10)
	s_barrier
	s_waitcnt lgkmcnt(0)
	v_mfma_f32_16x16x32_bf16 v[94:97], v[186:189], v[154:157], v[94:97]
	v_mfma_f32_16x16x32_bf16 v[90:93], v[194:197], v[154:157], v[90:93]
	v_mfma_f32_16x16x32_bf16 v[86:89], v[186:189], v[162:165], v[86:89]
	v_mfma_f32_16x16x32_bf16 v[82:85], v[194:197], v[162:165], v[82:85]
	v_mfma_f32_16x16x32_bf16 v[78:81], v[186:189], v[170:173], v[78:81]
	v_mfma_f32_16x16x32_bf16 v[74:77], v[194:197], v[170:173], v[74:77]
	v_mfma_f32_16x16x32_bf16 v[70:73], v[186:189], v[178:181], v[70:73]
	v_mfma_f32_16x16x32_bf16 v[66:69], v[194:197], v[178:181], v[66:69]
	v_mfma_f32_16x16x32_bf16 v[94:97], v[190:193], v[158:161], v[94:97]
	v_mfma_f32_16x16x32_bf16 v[90:93], v[198:201], v[158:161], v[90:93]
	v_mfma_f32_16x16x32_bf16 v[86:89], v[190:193], v[166:169], v[86:89]
	v_mfma_f32_16x16x32_bf16 v[82:85], v[198:201], v[166:169], v[82:85]
	v_mfma_f32_16x16x32_bf16 v[78:81], v[190:193], v[174:177], v[78:81]
	v_mfma_f32_16x16x32_bf16 v[74:77], v[198:201], v[174:177], v[74:77]
	v_mfma_f32_16x16x32_bf16 v[70:73], v[190:193], v[182:185], v[70:73]
	v_mfma_f32_16x16x32_bf16 v[66:69], v[198:201], v[182:185], v[66:69]
	s_barrier
; #define LDA(dst, b, h) for (int m = 0; m < 4; ++m) for (int k = 0; k < 2; ++k) \
;     dst[m][k] = *reinterpret_cast<const bf16x8*>((char*)SA(b, h) + a_thr + (m * 2 + k) * 1024)
; #define LDB(dst, b, h) for (int n = 0; n < 2; ++n) for (int k = 0; k < 2; ++k) \
;     dst[n][k] = *reinterpret_cast<const bf16x8*>((char*)SB(b, h) + b_thr + (n * 2 + k) * 1024)
; #define MMA(ai, bj, At, Btf) do { __builtin_amdgcn_s_setprio(1); \
;     for (int m = 0; m < 4; ++m) for (int n = 0; n < 2; ++n) for (int k = 0; k < 2; ++k) \
;       acc[ai][bj][m][n] = __builtin_amdgcn_mfma_f32_16x16x32_bf16(Btf[n][k], At[m][k], acc[ai][bj][m][n], 0, 0, 0); \
;     __builtin_amdgcn_s_setprio(0); } while (0)
; #define WAIT_V(n) asm volatile("s_waitcnt vmcnt(" #n ")" ::: "memory")
; #define WAIT_L(n) asm volatile("s_waitcnt lgkmcnt(" #n ")" ::: "memory")
; #define BAR __builtin_amdgcn_s_barrier()
; #define SCHED __builtin_amdgcn_sched_barrier(0)
; template <bool OVL, bool PANEL = false, class Epi>
; __device__ __forceinline__ void gemm_phase(const bf16_t* __restrict__ A, long lda, const bf16_t* __restrict__ Bt, long ldb, int nM, int nN, int K,
;                                            const Epi& epi, bf16_t* shm, int w0) {
;     ...
;       LDB(B1, 1, 1); STAGE(SB(1, 0), Bt, ldb, boff, bcol, t + 3);
;       BAR; WAIT_L(0); MMA(0, 1, At, B1); BAR;
;       LDA(At, 1, 1); STAGE(SA(1, 0), A, lda, aoff, brow, t + 3);
;       BAR; WAIT_L(0); MMA(1, 0, At, B0); BAR; SCHED;
;       STAGE(SB(1, 1), Bt, ldb, boff, bcol + HALF, t + 3);
;       WAIT_V(6); BAR; MMA(1, 1, At, B1); BAR;
;     }
;     { LDB(B0, 0, 0); LDA(At, 0, 0); STAGE(SA(1, 1), A, lda, aoff, brow + HALF, nt - 1);
	ds_read_b128 v[154:157], v213 offset:49152
	ds_read_b128 v[158:161], v213 offset:50176
	ds_read_b128 v[162:165], v213 offset:51200
	ds_read_b128 v[166:169], v213 offset:52224
	ds_read_b128 v[170:173], v213 offset:53248
	ds_read_b128 v[174:177], v213 offset:54272
	ds_read_b128 v[178:181], v213 offset:55296
	ds_read_b128 v[182:185], v213 offset:56320
	s_mov_b32 m0, s54
	s_add_u32 s98, s8, s94
	s_addc_u32 s99, s9, s95
	global_load_lds_dwordx4 v203, s[98:99]
	s_mov_b32 m0, s55
	s_add_u32 s98, s8, s42
	s_addc_u32 s99, s9, s43
	global_load_lds_dwordx4 v203, s[98:99]
	s_barrier
	s_waitcnt lgkmcnt(0)
	v_mfma_f32_16x16x32_bf16 v[62:65], v[138:141], v[154:157], v[62:65]
	v_mfma_f32_16x16x32_bf16 v[58:61], v[146:149], v[154:157], v[58:61]
	v_mfma_f32_16x16x32_bf16 v[54:57], v[138:141], v[162:165], v[54:57]
	v_mfma_f32_16x16x32_bf16 v[50:53], v[146:149], v[162:165], v[50:53]
	v_mfma_f32_16x16x32_bf16 v[46:49], v[138:141], v[170:173], v[46:49]
	v_mfma_f32_16x16x32_bf16 v[42:45], v[146:149], v[170:173], v[42:45]
	v_mfma_f32_16x16x32_bf16 v[38:41], v[138:141], v[178:181], v[38:41]
	v_mfma_f32_16x16x32_bf16 v[34:37], v[146:149], v[178:181], v[34:37]
	v_mfma_f32_16x16x32_bf16 v[62:65], v[142:145], v[158:161], v[62:65]
	v_mfma_f32_16x16x32_bf16 v[58:61], v[150:153], v[158:161], v[58:61]
	v_mfma_f32_16x16x32_bf16 v[54:57], v[142:145], v[166:169], v[54:57]
	v_mfma_f32_16x16x32_bf16 v[50:53], v[150:153], v[166:169], v[50:53]
	v_mfma_f32_16x16x32_bf16 v[46:49], v[142:145], v[174:177], v[46:49]
	v_mfma_f32_16x16x32_bf16 v[42:45], v[150:153], v[174:177], v[42:45]
	v_mfma_f32_16x16x32_bf16 v[38:41], v[142:145], v[182:185], v[38:41]
	v_mfma_f32_16x16x32_bf16 v[34:37], v[150:153], v[182:185], v[34:37]
	s_barrier
	s_mov_b64 s[8:9], 0xb0180
	s_mov_b64 s[8:9], 0x108180
	s_mov_b32 m0, s60
	s_add_u32 s98, vcc_lo, 0xb0180
	s_addc_u32 s99, vcc_hi, 0
	global_load_lds_dwordx4 v203, s[98:99]
	s_mov_b32 m0, s61
	s_add_u32 s98, vcc_lo, 0x108180
	s_addc_u32 s99, vcc_hi, 0
	global_load_lds_dwordx4 v203, s[98:99]
	s_add_i32 s2, s2, 2
	s_add_u32 s6, s6, 0x100
	s_addc_u32 s7, s7, 0
	s_cmp_gt_u32 s2, 39
	s_waitcnt vmcnt(10)
	s_barrier
	v_mfma_f32_16x16x32_bf16 v[30:33], v[186:189], v[154:157], v[30:33]
	v_mfma_f32_16x16x32_bf16 v[26:29], v[194:197], v[154:157], v[26:29]
	v_mfma_f32_16x16x32_bf16 v[22:25], v[186:189], v[162:165], v[22:25]
	v_mfma_f32_16x16x32_bf16 v[18:21], v[194:197], v[162:165], v[18:21]
	v_mfma_f32_16x16x32_bf16 v[14:17], v[186:189], v[170:173], v[14:17]
	v_mfma_f32_16x16x32_bf16 v[10:13], v[194:197], v[170:173], v[10:13]
	v_mfma_f32_16x16x32_bf16 v[6:9], v[186:189], v[178:181], v[6:9]
	v_mfma_f32_16x16x32_bf16 v[2:5], v[194:197], v[178:181], v[2:5]
	v_mfma_f32_16x16x32_bf16 v[30:33], v[190:193], v[158:161], v[30:33]
	v_mfma_f32_16x16x32_bf16 v[26:29], v[198:201], v[158:161], v[26:29]
	v_mfma_f32_16x16x32_bf16 v[22:25], v[190:193], v[166:169], v[22:25]
	v_mfma_f32_16x16x32_bf16 v[18:21], v[198:201], v[166:169], v[18:21]
	v_mfma_f32_16x16x32_bf16 v[14:17], v[190:193], v[174:177], v[14:17]
	v_mfma_f32_16x16x32_bf16 v[10:13], v[198:201], v[174:177], v[10:13]
	v_mfma_f32_16x16x32_bf16 v[6:9], v[190:193], v[182:185], v[6:9]
	v_mfma_f32_16x16x32_bf16 v[2:5], v[198:201], v[182:185], v[2:5]
	s_barrier
	s_cbranch_scc0 .LBB0_125
	s_waitcnt vmcnt(6)
	s_or_b32 s0, s28, 0x80
	s_mul_hi_i32 s1, s0, 0x1600
	s_mulk_i32 s0, 0x1600
	v_readlane_b32 s2, v250, 49
	v_add_u32_e32 v227, 16, v212
	s_add_u32 s0, s2, s0
	v_readlane_b32 s2, v250, 50
	v_add_u32_e32 v0, 0x10000, v227
	s_addc_u32 s1, s2, s1
	v_readfirstlane_b32 s2, v136
	ds_read_b128 v[130:133], v0
	ds_read_b128 v[138:141], v0 offset:1024
	ds_read_b128 v[142:145], v0 offset:2048
	ds_read_b128 v[146:149], v0 offset:3072
	ds_read_b128 v[150:153], v213
	ds_read_b128 v[154:157], v213 offset:1024
	ds_read_b128 v[158:161], v213 offset:2048
	ds_read_b128 v[162:165], v213 offset:3072
	ds_read_b128 v[166:169], v213 offset:4096
	ds_read_b128 v[170:173], v213 offset:5120
	ds_read_b128 v[174:177], v213 offset:6144
	ds_read_b128 v[178:181], v213 offset:7168
	v_mov_b32_e32 v0, v203
	s_mov_b32 m0, s2
	s_nop 0
	v_lshl_add_u64 v[134:135], s[0:1], 0, v[0:1]
	global_load_lds_dwordx4 v0, s[0:1]
	v_readfirstlane_b32 s0, v137
	v_lshl_add_u64 v[134:135], v[134:135], 0, s[26:27]
	s_mov_b32 m0, s0
	s_nop 0
	global_load_lds_dwordx4 v[134:135], off
	s_barrier
	s_waitcnt lgkmcnt(0)

; #define MMA(ai, bj, At, Btf) do { __builtin_amdgcn_s_setprio(1); \
;     for (int m = 0; m < 4; ++m) for (int n = 0; n < 2; ++n) for (int k = 0; k < 2; ++k) \
;       acc[ai][bj][m][n] = __builtin_amdgcn_mfma_f32_16x16x32_bf16(Btf[n][k], At[m][k], acc[ai][bj][m][n], 0, 0, 0); \
;     __builtin_amdgcn_s_setprio(0); } while (0)
; #define WAIT_L(n) asm volatile("s_waitcnt lgkmcnt(" #n ")" ::: "memory")
; #define BAR __builtin_amdgcn_s_barrier()
; template <bool OVL, bool PANEL = false, class Epi>
; __device__ __forceinline__ void gemm_phase(const bf16_t* __restrict__ A, long lda, const bf16_t* __restrict__ Bt, long ldb, int nM, int nN, int K,
;                                            const Epi& epi, bf16_t* shm, int w0) {
;     ...
;       BAR; WAIT_L(0); MMA(0, 0, At, B0); BAR;
	v_mfma_f32_16x16x32_bf16 v[126:129], v[130:133], v[150:153], v[126:129]
	v_mfma_f32_16x16x32_bf16 v[122:125], v[142:145], v[150:153], v[122:125]
	v_mfma_f32_16x16x32_bf16 v[118:121], v[130:133], v[158:161], v[118:121]
	v_mfma_f32_16x16x32_bf16 v[114:117], v[142:145], v[158:161], v[114:117]
	v_mfma_f32_16x16x32_bf16 v[110:113], v[130:133], v[166:169], v[110:113]
	v_mfma_f32_16x16x32_bf16 v[106:109], v[142:145], v[166:169], v[106:109]
	v_mfma_f32_16x16x32_bf16 v[102:105], v[130:133], v[174:177], v[102:105]
	v_mfma_f32_16x16x32_bf16 v[98:101], v[142:145], v[174:177], v[98:101]
	v_mfma_f32_16x16x32_bf16 v[126:129], v[138:141], v[154:157], v[126:129]
	v_mfma_f32_16x16x32_bf16 v[122:125], v[146:149], v[154:157], v[122:125]
	v_mfma_f32_16x16x32_bf16 v[118:121], v[138:141], v[162:165], v[118:121]
	v_mfma_f32_16x16x32_bf16 v[114:117], v[146:149], v[162:165], v[114:117]
	v_mfma_f32_16x16x32_bf16 v[110:113], v[138:141], v[170:173], v[110:113]
	v_mfma_f32_16x16x32_bf16 v[106:109], v[146:149], v[170:173], v[106:109]
	v_mfma_f32_16x16x32_bf16 v[102:105], v[138:141], v[178:181], v[102:105]
	v_mfma_f32_16x16x32_bf16 v[98:101], v[146:149], v[178:181], v[98:101]

; #define LDB(dst, b, h) for (int n = 0; n < 2; ++n) for (int k = 0; k < 2; ++k) \
;     dst[n][k] = *reinterpret_cast<const bf16x8*>((char*)SB(b, h) + b_thr + (n * 2 + k) * 1024)
; #define MMA(ai, bj, At, Btf) do { __builtin_amdgcn_s_setprio(1); \
;     for (int m = 0; m < 4; ++m) for (int n = 0; n < 2; ++n) for (int k = 0; k < 2; ++k) \
;       acc[ai][bj][m][n] = __builtin_amdgcn_mfma_f32_16x16x32_bf16(Btf[n][k], At[m][k], acc[ai][bj][m][n], 0, 0, 0); \
;     __builtin_amdgcn_s_setprio(0); } while (0)
; #define WAIT_L(n) asm volatile("s_waitcnt lgkmcnt(" #n ")" ::: "memory")
; #define BAR __builtin_amdgcn_s_barrier()
; template <bool OVL, bool PANEL = false, class Epi>
; __device__ __forceinline__ void gemm_phase(const bf16_t* __restrict__ A, long lda, const bf16_t* __restrict__ Bt, long ldb, int nM, int nN, int K,
;                                            const Epi& epi, bf16_t* shm, int w0) {
;     ...
;       LDB(B1, 0, 1); BAR; WAIT_L(0); MMA(0, 1, At, B1); BAR;
	v_add_u32_e32 v0, 0x14000, v227
	s_barrier
	ds_read_b128 v[134:137], v0
	ds_read_b128 v[182:185], v0 offset:1024
	ds_read_b128 v[186:189], v0 offset:2048
	ds_read_b128 v[190:193], v0 offset:3072
	s_barrier
	s_waitcnt lgkmcnt(0)

; #define LDB(dst, b, h) for (int n = 0; n < 2; ++n) for (int k = 0; k < 2; ++k) \
;     dst[n][k] = *reinterpret_cast<const bf16x8*>((char*)SB(b, h) + b_thr + (n * 2 + k) * 1024)
; #define MMA(ai, bj, At, Btf) do { __builtin_amdgcn_s_setprio(1); \
;     for (int m = 0; m < 4; ++m) for (int n = 0; n < 2; ++n) for (int k = 0; k < 2; ++k) \
;       acc[ai][bj][m][n] = __builtin_amdgcn_mfma_f32_16x16x32_bf16(Btf[n][k], At[m][k], acc[ai][bj][m][n], 0, 0, 0); \
;     __builtin_amdgcn_s_setprio(0); } while (0)
; #define WAIT_L(n) asm volatile("s_waitcnt lgkmcnt(" #n ")" ::: "memory")
; #define BAR __builtin_amdgcn_s_barrier()
; template <bool OVL, bool PANEL = false, class Epi>
; __device__ __forceinline__ void gemm_phase(const bf16_t* __restrict__ A, long lda, const bf16_t* __restrict__ Bt, long ldb, int nM, int nN, int K,
;                                            const Epi& epi, bf16_t* shm, int w0) {
;     ...
;       LDB(B1, 0, 1); BAR; WAIT_L(0); MMA(0, 1, At, B1); BAR;
	v_mfma_f32_16x16x32_bf16 v[94:97], v[134:137], v[150:153], v[94:97]
	v_mfma_f32_16x16x32_bf16 v[90:93], v[186:189], v[150:153], v[90:93]
	v_mfma_f32_16x16x32_bf16 v[86:89], v[134:137], v[158:161], v[86:89]
	v_mfma_f32_16x16x32_bf16 v[82:85], v[186:189], v[158:161], v[82:85]
	v_mfma_f32_16x16x32_bf16 v[78:81], v[134:137], v[166:169], v[78:81]
	v_mfma_f32_16x16x32_bf16 v[66:69], v[186:189], v[174:177], v[66:69]
	v_mfma_f32_16x16x32_bf16 v[94:97], v[182:185], v[154:157], v[94:97]
	v_mfma_f32_16x16x32_bf16 v[90:93], v[190:193], v[154:157], v[90:93]
	v_mfma_f32_16x16x32_bf16 v[86:89], v[182:185], v[162:165], v[86:89]
	v_mfma_f32_16x16x32_bf16 v[82:85], v[190:193], v[162:165], v[82:85]
	v_mfma_f32_16x16x32_bf16 v[78:81], v[182:185], v[170:173], v[78:81]
	v_mfma_f32_16x16x32_bf16 v[74:77], v[186:189], v[166:169], v[74:77]
	v_mfma_f32_16x16x32_bf16 v[70:73], v[134:137], v[174:177], v[70:73]
	v_mfma_f32_16x16x32_bf16 v[66:69], v[190:193], v[178:181], v[66:69]
	v_mfma_f32_16x16x32_bf16 v[150:153], v[190:193], v[170:173], v[74:77]
	v_mfma_f32_16x16x32_bf16 v[154:157], v[182:185], v[178:181], v[70:73]

; #define LDA(dst, b, h) for (int m = 0; m < 4; ++m) for (int k = 0; k < 2; ++k) \
;     dst[m][k] = *reinterpret_cast<const bf16x8*>((char*)SA(b, h) + a_thr + (m * 2 + k) * 1024)
; #define MMA(ai, bj, At, Btf) do { __builtin_amdgcn_s_setprio(1); \
;     for (int m = 0; m < 4; ++m) for (int n = 0; n < 2; ++n) for (int k = 0; k < 2; ++k) \
;       acc[ai][bj][m][n] = __builtin_amdgcn_mfma_f32_16x16x32_bf16(Btf[n][k], At[m][k], acc[ai][bj][m][n], 0, 0, 0); \
;     __builtin_amdgcn_s_setprio(0); } while (0)
; #define WAIT_V(n) asm volatile("s_waitcnt vmcnt(" #n ")" ::: "memory")
; #define WAIT_L(n) asm volatile("s_waitcnt lgkmcnt(" #n ")" ::: "memory")
; #define BAR __builtin_amdgcn_s_barrier()
; template <bool OVL, bool PANEL = false, class Epi>
; __device__ __forceinline__ void gemm_phase(const bf16_t* __restrict__ A, long lda, const bf16_t* __restrict__ Bt, long ldb, int nM, int nN, int K,
;                                            const Epi& epi, bf16_t* shm, int w0) {
;     ...
;       LDA(At, 0, 1); WAIT_V(4); BAR; WAIT_L(0); MMA(1, 0, At, B0); MMA(1, 1, At, B1); BAR; }
	s_barrier
	s_nop 2
	ds_read_b128 v[70:73], v213 offset:16384
	ds_read_b128 v[74:77], v213 offset:17408
	ds_read_b128 v[158:161], v213 offset:18432
	ds_read_b128 v[162:165], v213 offset:19456
	ds_read_b128 v[166:169], v213 offset:20480
	ds_read_b128 v[170:173], v213 offset:21504
	ds_read_b128 v[174:177], v213 offset:22528
	ds_read_b128 v[178:181], v213 offset:23552
	s_waitcnt vmcnt(4)
	s_barrier
	s_waitcnt lgkmcnt(0)

; #define LDA(dst, b, h) for (int m = 0; m < 4; ++m) for (int k = 0; k < 2; ++k) \
;     dst[m][k] = *reinterpret_cast<const bf16x8*>((char*)SA(b, h) + a_thr + (m * 2 + k) * 1024)
; #define MMA(ai, bj, At, Btf) do { __builtin_amdgcn_s_setprio(1); \
;     for (int m = 0; m < 4; ++m) for (int n = 0; n < 2; ++n) for (int k = 0; k < 2; ++k) \
;       acc[ai][bj][m][n] = __builtin_amdgcn_mfma_f32_16x16x32_bf16(Btf[n][k], At[m][k], acc[ai][bj][m][n], 0, 0, 0); \
;     __builtin_amdgcn_s_setprio(0); } while (0)
; #define WAIT_V(n) asm volatile("s_waitcnt vmcnt(" #n ")" ::: "memory")
; #define WAIT_L(n) asm volatile("s_waitcnt lgkmcnt(" #n ")" ::: "memory")
; #define BAR __builtin_amdgcn_s_barrier()
; template <bool OVL, bool PANEL = false, class Epi>
; __device__ __forceinline__ void gemm_phase(const bf16_t* __restrict__ A, long lda, const bf16_t* __restrict__ Bt, long ldb, int nM, int nN, int K,
;                                            const Epi& epi, bf16_t* shm, int w0) {
;     ...
;       LDA(At, 0, 1); WAIT_V(4); BAR; WAIT_L(0); MMA(1, 0, At, B0); MMA(1, 1, At, B1); BAR; }
	v_mfma_f32_16x16x32_bf16 v[58:61], v[142:145], v[70:73], v[58:61]
	v_mfma_f32_16x16x32_bf16 v[54:57], v[130:133], v[158:161], v[54:57]
	v_mfma_f32_16x16x32_bf16 v[62:65], v[130:133], v[70:73], v[62:65]
	v_mfma_f32_16x16x32_bf16 v[58:61], v[146:149], v[74:77], v[58:61]
	v_mfma_f32_16x16x32_bf16 v[54:57], v[138:141], v[162:165], v[54:57]
	v_mfma_f32_16x16x32_bf16 v[50:53], v[142:145], v[158:161], v[50:53]
	v_mfma_f32_16x16x32_bf16 v[46:49], v[130:133], v[166:169], v[46:49]
	v_mfma_f32_16x16x32_bf16 v[42:45], v[142:145], v[166:169], v[42:45]
	v_mfma_f32_16x16x32_bf16 v[38:41], v[130:133], v[174:177], v[38:41]
	v_mfma_f32_16x16x32_bf16 v[34:37], v[142:145], v[174:177], v[34:37]
	v_mfma_f32_16x16x32_bf16 v[194:197], v[138:141], v[74:77], v[62:65]
	v_mfma_f32_16x16x32_bf16 v[198:201], v[146:149], v[162:165], v[50:53]
	v_mfma_f32_16x16x32_bf16 v[214:217], v[138:141], v[170:173], v[46:49]
	v_mfma_f32_16x16x32_bf16 v[218:221], v[146:149], v[170:173], v[42:45]
	v_mfma_f32_16x16x32_bf16 v[130:133], v[138:141], v[178:181], v[38:41]
	v_mfma_f32_16x16x32_bf16 v[138:141], v[146:149], v[178:181], v[34:37]


; #define LDA(dst, b, h) for (int m = 0; m < 4; ++m) for (int k = 0; k < 2; ++k) \
;     dst[m][k] = *reinterpret_cast<const bf16x8*>((char*)SA(b, h) + a_thr + (m * 2 + k) * 1024)
; #define MMA(ai, bj, At, Btf) do { __builtin_amdgcn_s_setprio(1); \
;     for (int m = 0; m < 4; ++m) for (int n = 0; n < 2; ++n) for (int k = 0; k < 2; ++k) \
;       acc[ai][bj][m][n] = __builtin_amdgcn_mfma_f32_16x16x32_bf16(Btf[n][k], At[m][k], acc[ai][bj][m][n], 0, 0, 0); \
;     __builtin_amdgcn_s_setprio(0); } while (0)
; #define WAIT_V(n) asm volatile("s_waitcnt vmcnt(" #n ")" ::: "memory")
; #define WAIT_L(n) asm volatile("s_waitcnt lgkmcnt(" #n ")" ::: "memory")
; #define BAR __builtin_amdgcn_s_barrier()
; template <bool OVL, bool PANEL = false, class Epi>
; __device__ __forceinline__ void gemm_phase(const bf16_t* __restrict__ A, long lda, const bf16_t* __restrict__ Bt, long ldb, int nM, int nN, int K,
;                                            const Epi& epi, bf16_t* shm, int w0) {
;     ...
;       LDA(At, 0, 1); WAIT_V(4); BAR; WAIT_L(0); MMA(1, 0, At, B0); MMA(1, 1, At, B1); BAR; }
	v_mfma_f32_16x16x32_bf16 v[30:33], v[134:137], v[70:73], v[30:33]
	v_mfma_f32_16x16x32_bf16 v[26:29], v[186:189], v[70:73], v[26:29]
	v_mfma_f32_16x16x32_bf16 v[22:25], v[134:137], v[158:161], v[22:25]
	v_mfma_f32_16x16x32_bf16 v[18:21], v[186:189], v[158:161], v[18:21]
	v_mfma_f32_16x16x32_bf16 v[14:17], v[134:137], v[166:169], v[14:17]
	v_mfma_f32_16x16x32_bf16 v[10:13], v[186:189], v[166:169], v[10:13]
	v_mfma_f32_16x16x32_bf16 v[6:9], v[134:137], v[174:177], v[6:9]
	v_mfma_f32_16x16x32_bf16 v[2:5], v[186:189], v[174:177], v[2:5]
	v_mfma_f32_16x16x32_bf16 v[142:145], v[182:185], v[74:77], v[30:33]
	v_mfma_f32_16x16x32_bf16 v[146:149], v[190:193], v[74:77], v[26:29]
	v_mfma_f32_16x16x32_bf16 v[222:225], v[182:185], v[162:165], v[22:25]
	v_mfma_f32_16x16x32_bf16 v[158:161], v[190:193], v[162:165], v[18:21]
	v_mfma_f32_16x16x32_bf16 v[162:165], v[182:185], v[170:173], v[14:17]
	v_mfma_f32_16x16x32_bf16 v[166:169], v[190:193], v[170:173], v[10:13]
	v_mfma_f32_16x16x32_bf16 v[134:137], v[182:185], v[178:181], v[6:9]
	v_mfma_f32_16x16x32_bf16 v[170:173], v[190:193], v[178:181], v[2:5]

; #define LDA(dst, b, h) for (int m = 0; m < 4; ++m) for (int k = 0; k < 2; ++k) \
;     dst[m][k] = *reinterpret_cast<const bf16x8*>((char*)SA(b, h) + a_thr + (m * 2 + k) * 1024)
; #define LDB(dst, b, h) for (int n = 0; n < 2; ++n) for (int k = 0; k < 2; ++k) \
;     dst[n][k] = *reinterpret_cast<const bf16x8*>((char*)SB(b, h) + b_thr + (n * 2 + k) * 1024)
; #define MMA(ai, bj, At, Btf) do { __builtin_amdgcn_s_setprio(1); \
;     for (int m = 0; m < 4; ++m) for (int n = 0; n < 2; ++n) for (int k = 0; k < 2; ++k) \
;       acc[ai][bj][m][n] = __builtin_amdgcn_mfma_f32_16x16x32_bf16(Btf[n][k], At[m][k], acc[ai][bj][m][n], 0, 0, 0); \
;     __builtin_amdgcn_s_setprio(0); } while (0)
; #define WAIT_V(n) asm volatile("s_waitcnt vmcnt(" #n ")" ::: "memory")
; #define WAIT_L(n) asm volatile("s_waitcnt lgkmcnt(" #n ")" ::: "memory")
; #define BAR __builtin_amdgcn_s_barrier()
; template <bool OVL, bool PANEL = false, class Epi>
; __device__ __forceinline__ void gemm_phase(const bf16_t* __restrict__ A, long lda, const bf16_t* __restrict__ Bt, long ldb, int nM, int nN, int K,
;                                            const Epi& epi, bf16_t* shm, int w0) {
;     ...
;     { LDB(B0, 1, 0); LDA(At, 1, 0); WAIT_V(2); BAR; WAIT_L(0); MMA(0, 0, At, B0); BAR;
	v_add_u32_e32 v0, 0x18000, v227
	s_barrier
	ds_read_b128 v[34:37], v0
	ds_read_b128 v[174:177], v0 offset:1024
	ds_read_b128 v[178:181], v0 offset:2048
	ds_read_b128 v[182:185], v0 offset:3072
	ds_read_b128 v[18:21], v213 offset:32768
	ds_read_b128 v[22:25], v213 offset:33792
	ds_read_b128 v[26:29], v213 offset:34816
	ds_read_b128 v[50:53], v213 offset:35840
	ds_read_b128 v[186:189], v213 offset:36864
	ds_read_b128 v[190:193], v213 offset:37888
	ds_read_b128 v[228:231], v213 offset:38912
	ds_read_b128 v[232:235], v213 offset:39936
	s_waitcnt vmcnt(2)
	s_barrier
	s_waitcnt lgkmcnt(0)

; #define LDA(dst, b, h) for (int m = 0; m < 4; ++m) for (int k = 0; k < 2; ++k) \
;     dst[m][k] = *reinterpret_cast<const bf16x8*>((char*)SA(b, h) + a_thr + (m * 2 + k) * 1024)
; #define LDB(dst, b, h) for (int n = 0; n < 2; ++n) for (int k = 0; k < 2; ++k) \
;     dst[n][k] = *reinterpret_cast<const bf16x8*>((char*)SB(b, h) + b_thr + (n * 2 + k) * 1024)
; #define MMA(ai, bj, At, Btf) do { __builtin_amdgcn_s_setprio(1); \
;     for (int m = 0; m < 4; ++m) for (int n = 0; n < 2; ++n) for (int k = 0; k < 2; ++k) \
;       acc[ai][bj][m][n] = __builtin_amdgcn_mfma_f32_16x16x32_bf16(Btf[n][k], At[m][k], acc[ai][bj][m][n], 0, 0, 0); \
;     __builtin_amdgcn_s_setprio(0); } while (0)
; #define WAIT_V(n) asm volatile("s_waitcnt vmcnt(" #n ")" ::: "memory")
; #define WAIT_L(n) asm volatile("s_waitcnt lgkmcnt(" #n ")" ::: "memory")
; #define BAR __builtin_amdgcn_s_barrier()
; template <bool OVL, bool PANEL = false, class Epi>
; __device__ __forceinline__ void gemm_phase(const bf16_t* __restrict__ A, long lda, const bf16_t* __restrict__ Bt, long ldb, int nM, int nN, int K,
;                                            const Epi& epi, bf16_t* shm, int w0) {
;     ...
;     { LDB(B0, 1, 0); LDA(At, 1, 0); WAIT_V(2); BAR; WAIT_L(0); MMA(0, 0, At, B0); BAR;
	v_mfma_f32_16x16x32_bf16 v[6:9], v[178:181], v[18:21], v[122:125]
	v_mfma_f32_16x16x32_bf16 v[10:13], v[178:181], v[26:29], v[114:117]
	v_mfma_f32_16x16x32_bf16 v[14:17], v[178:181], v[186:189], v[106:109]
	v_mfma_f32_16x16x32_bf16 v[2:5], v[34:37], v[18:21], v[126:129]
	v_mfma_f32_16x16x32_bf16 v[30:33], v[182:185], v[22:25], v[6:9]
	v_mfma_f32_16x16x32_bf16 v[6:9], v[34:37], v[26:29], v[118:121]
	v_mfma_f32_16x16x32_bf16 v[38:41], v[182:185], v[50:53], v[10:13]
	v_mfma_f32_16x16x32_bf16 v[10:13], v[34:37], v[186:189], v[110:113]
	v_mfma_f32_16x16x32_bf16 v[42:45], v[182:185], v[190:193], v[14:17]
	v_mfma_f32_16x16x32_bf16 v[14:17], v[34:37], v[228:231], v[102:105]
	v_mfma_f32_16x16x32_bf16 v[46:49], v[178:181], v[228:231], v[98:101]
	v_mfma_f32_16x16x32_bf16 v[2:5], v[174:177], v[22:25], v[2:5]
	v_mfma_f32_16x16x32_bf16 v[6:9], v[174:177], v[50:53], v[6:9]
	v_mfma_f32_16x16x32_bf16 v[10:13], v[174:177], v[190:193], v[10:13]
	v_mfma_f32_16x16x32_bf16 v[14:17], v[174:177], v[232:235], v[14:17]
	v_mfma_f32_16x16x32_bf16 v[46:49], v[182:185], v[232:235], v[46:49]

; #define LDB(dst, b, h) for (int n = 0; n < 2; ++n) for (int k = 0; k < 2; ++k) \
;     dst[n][k] = *reinterpret_cast<const bf16x8*>((char*)SB(b, h) + b_thr + (n * 2 + k) * 1024)
; #define MMA(ai, bj, At, Btf) do { __builtin_amdgcn_s_setprio(1); \
;     for (int m = 0; m < 4; ++m) for (int n = 0; n < 2; ++n) for (int k = 0; k < 2; ++k) \
;       acc[ai][bj][m][n] = __builtin_amdgcn_mfma_f32_16x16x32_bf16(Btf[n][k], At[m][k], acc[ai][bj][m][n], 0, 0, 0); \
;     __builtin_amdgcn_s_setprio(0); } while (0)
; #define WAIT_V(n) asm volatile("s_waitcnt vmcnt(" #n ")" ::: "memory")
; #define WAIT_L(n) asm volatile("s_waitcnt lgkmcnt(" #n ")" ::: "memory")
; #define BAR __builtin_amdgcn_s_barrier()
; template <bool OVL, bool PANEL = false, class Epi>
; __device__ __forceinline__ void gemm_phase(const bf16_t* __restrict__ A, long lda, const bf16_t* __restrict__ Bt, long ldb, int nM, int nN, int K,
;                                            const Epi& epi, bf16_t* shm, int w0) {
;     ...
;       LDB(B1, 1, 1); WAIT_V(0); BAR; WAIT_L(0); MMA(0, 1, At, B1); BAR;
	v_add_u32_e32 v0, 0x1c000, v227
	s_barrier
	ds_read_b128 v[102:105], v0
	ds_read_b128 v[236:239], v0 offset:1024
	ds_read_b128 v[240:243], v0 offset:2048
	ds_read_b128 v[244:247], v0 offset:3072
	s_waitcnt vmcnt(0)
	s_barrier
	s_waitcnt lgkmcnt(0)

; #define LDB(dst, b, h) for (int n = 0; n < 2; ++n) for (int k = 0; k < 2; ++k) \
;     dst[n][k] = *reinterpret_cast<const bf16x8*>((char*)SB(b, h) + b_thr + (n * 2 + k) * 1024)
; #define MMA(ai, bj, At, Btf) do { __builtin_amdgcn_s_setprio(1); \
;     for (int m = 0; m < 4; ++m) for (int n = 0; n < 2; ++n) for (int k = 0; k < 2; ++k) \
;       acc[ai][bj][m][n] = __builtin_amdgcn_mfma_f32_16x16x32_bf16(Btf[n][k], At[m][k], acc[ai][bj][m][n], 0, 0, 0); \
;     __builtin_amdgcn_s_setprio(0); } while (0)
; #define WAIT_V(n) asm volatile("s_waitcnt vmcnt(" #n ")" ::: "memory")
; #define WAIT_L(n) asm volatile("s_waitcnt lgkmcnt(" #n ")" ::: "memory")
; #define BAR __builtin_amdgcn_s_barrier()
; template <bool OVL, bool PANEL = false, class Epi>
; __device__ __forceinline__ void gemm_phase(const bf16_t* __restrict__ A, long lda, const bf16_t* __restrict__ Bt, long ldb, int nM, int nN, int K,
;                                            const Epi& epi, bf16_t* shm, int w0) {
;     ...
;       LDB(B1, 1, 1); WAIT_V(0); BAR; WAIT_L(0); MMA(0, 1, At, B1); BAR;
	v_mfma_f32_16x16x32_bf16 v[62:65], v[102:105], v[18:21], v[94:97]
	v_mfma_f32_16x16x32_bf16 v[18:21], v[240:243], v[18:21], v[90:93]
	v_mfma_f32_16x16x32_bf16 v[98:101], v[244:247], v[22:25], v[18:21]
	v_mfma_f32_16x16x32_bf16 v[18:21], v[102:105], v[26:29], v[86:89]
	v_mfma_f32_16x16x32_bf16 v[70:73], v[236:239], v[50:53], v[18:21]
	v_mfma_f32_16x16x32_bf16 v[18:21], v[240:243], v[26:29], v[82:85]
	v_mfma_f32_16x16x32_bf16 v[106:109], v[244:247], v[50:53], v[18:21]
	v_mfma_f32_16x16x32_bf16 v[18:21], v[102:105], v[186:189], v[78:81]
	v_mfma_f32_16x16x32_bf16 v[74:77], v[236:239], v[190:193], v[18:21]
	v_mfma_f32_16x16x32_bf16 v[18:21], v[240:243], v[186:189], v[150:153]
	v_mfma_f32_16x16x32_bf16 v[110:113], v[244:247], v[190:193], v[18:21]
	v_mfma_f32_16x16x32_bf16 v[18:21], v[102:105], v[228:231], v[154:157]
	v_mfma_f32_16x16x32_bf16 v[78:81], v[236:239], v[232:235], v[18:21]
	v_mfma_f32_16x16x32_bf16 v[18:21], v[240:243], v[228:231], v[66:69]
	v_mfma_f32_16x16x32_bf16 v[62:65], v[236:239], v[22:25], v[62:65]
	v_mfma_f32_16x16x32_bf16 v[114:117], v[244:247], v[232:235], v[18:21]

; #define LDA(dst, b, h) for (int m = 0; m < 4; ++m) for (int k = 0; k < 2; ++k) \
;     dst[m][k] = *reinterpret_cast<const bf16x8*>((char*)SA(b, h) + a_thr + (m * 2 + k) * 1024)
; #define MMA(ai, bj, At, Btf) do { __builtin_amdgcn_s_setprio(1); \
;     for (int m = 0; m < 4; ++m) for (int n = 0; n < 2; ++n) for (int k = 0; k < 2; ++k) \
;       acc[ai][bj][m][n] = __builtin_amdgcn_mfma_f32_16x16x32_bf16(Btf[n][k], At[m][k], acc[ai][bj][m][n], 0, 0, 0); \
;     __builtin_amdgcn_s_setprio(0); } while (0)
; #define WAIT_L(n) asm volatile("s_waitcnt lgkmcnt(" #n ")" ::: "memory")
; #define BAR __builtin_amdgcn_s_barrier()
; template <bool OVL, bool PANEL = false, class Epi>
; __device__ __forceinline__ void gemm_phase(const bf16_t* __restrict__ A, long lda, const bf16_t* __restrict__ Bt, long ldb, int nM, int nN, int K,
;                                            const Epi& epi, bf16_t* shm, int w0) {
;     ...
;       LDA(At, 1, 1); BAR; WAIT_L(0); MMA(1, 0, At, B0); MMA(1, 1, At, B1); BAR; }
	s_barrier
	ds_read_b128 v[86:89], v213 offset:49152
	ds_read_b128 v[90:93], v213 offset:50176
	ds_read_b128 v[94:97], v213 offset:51200
	ds_read_b128 v[118:121], v213 offset:52224
	ds_read_b128 v[150:153], v213 offset:53248
	ds_read_b128 v[154:157], v213 offset:54272
	ds_read_b128 v[186:189], v213 offset:55296
	ds_read_b128 v[190:193], v213 offset:56320
	s_barrier
	s_waitcnt lgkmcnt(0)

; #define LDA(dst, b, h) for (int m = 0; m < 4; ++m) for (int k = 0; k < 2; ++k) \
;     dst[m][k] = *reinterpret_cast<const bf16x8*>((char*)SA(b, h) + a_thr + (m * 2 + k) * 1024)
; #define MMA(ai, bj, At, Btf) do { __builtin_amdgcn_s_setprio(1); \
;     for (int m = 0; m < 4; ++m) for (int n = 0; n < 2; ++n) for (int k = 0; k < 2; ++k) \
;       acc[ai][bj][m][n] = __builtin_amdgcn_mfma_f32_16x16x32_bf16(Btf[n][k], At[m][k], acc[ai][bj][m][n], 0, 0, 0); \
;     __builtin_amdgcn_s_setprio(0); } while (0)
; #define WAIT_L(n) asm volatile("s_waitcnt lgkmcnt(" #n ")" ::: "memory")
; #define BAR __builtin_amdgcn_s_barrier()
; template <bool OVL, bool PANEL = false, class Epi>
; __device__ __forceinline__ void gemm_phase(const bf16_t* __restrict__ A, long lda, const bf16_t* __restrict__ Bt, long ldb, int nM, int nN, int K,
;                                            const Epi& epi, bf16_t* shm, int w0) {
;     ...
;       LDA(At, 1, 1); BAR; WAIT_L(0); MMA(1, 0, At, B0); MMA(1, 1, At, B1); BAR; }
	v_mfma_f32_16x16x32_bf16 v[22:25], v[178:181], v[86:89], v[58:61]
	v_mfma_f32_16x16x32_bf16 v[26:29], v[178:181], v[94:97], v[198:201]
	v_mfma_f32_16x16x32_bf16 v[18:21], v[34:37], v[86:89], v[194:197]
	v_mfma_f32_16x16x32_bf16 v[50:53], v[182:185], v[90:93], v[22:25]
	v_mfma_f32_16x16x32_bf16 v[22:25], v[34:37], v[94:97], v[54:57]
	v_mfma_f32_16x16x32_bf16 v[54:57], v[182:185], v[118:121], v[26:29]
	v_mfma_f32_16x16x32_bf16 v[26:29], v[34:37], v[150:153], v[214:217]
	v_mfma_f32_16x16x32_bf16 v[58:61], v[178:181], v[150:153], v[218:221]
	v_mfma_f32_16x16x32_bf16 v[34:37], v[34:37], v[186:189], v[130:133]
	v_mfma_f32_16x16x32_bf16 v[66:69], v[178:181], v[186:189], v[138:141]
	v_mfma_f32_16x16x32_bf16 v[18:21], v[174:177], v[90:93], v[18:21]
	v_mfma_f32_16x16x32_bf16 v[22:25], v[174:177], v[118:121], v[22:25]
	v_mfma_f32_16x16x32_bf16 v[26:29], v[174:177], v[154:157], v[26:29]
	v_mfma_f32_16x16x32_bf16 v[58:61], v[182:185], v[154:157], v[58:61]
	v_mfma_f32_16x16x32_bf16 v[34:37], v[174:177], v[190:193], v[34:37]
	v_mfma_f32_16x16x32_bf16 v[66:69], v[182:185], v[190:193], v[66:69]


; #define LDA(dst, b, h) for (int m = 0; m < 4; ++m) for (int k = 0; k < 2; ++k) \
;     dst[m][k] = *reinterpret_cast<const bf16x8*>((char*)SA(b, h) + a_thr + (m * 2 + k) * 1024)
; #define MMA(ai, bj, At, Btf) do { __builtin_amdgcn_s_setprio(1); \
;     for (int m = 0; m < 4; ++m) for (int n = 0; n < 2; ++n) for (int k = 0; k < 2; ++k) \
;       acc[ai][bj][m][n] = __builtin_amdgcn_mfma_f32_16x16x32_bf16(Btf[n][k], At[m][k], acc[ai][bj][m][n], 0, 0, 0); \
;     __builtin_amdgcn_s_setprio(0); } while (0)
; #define WAIT_L(n) asm volatile("s_waitcnt lgkmcnt(" #n ")" ::: "memory")
; #define BAR __builtin_amdgcn_s_barrier()
; template <bool OVL, bool PANEL = false, class Epi>
; __device__ __forceinline__ void gemm_phase(const bf16_t* __restrict__ A, long lda, const bf16_t* __restrict__ Bt, long ldb, int nM, int nN, int K,
;                                            const Epi& epi, bf16_t* shm, int w0) {
;     ...
;       LDA(At, 1, 1); BAR; WAIT_L(0); MMA(1, 0, At, B0); MMA(1, 1, At, B1); BAR; }
	v_mfma_f32_16x16x32_bf16 v[82:85], v[102:105], v[86:89], v[142:145]
	v_mfma_f32_16x16x32_bf16 v[86:89], v[240:243], v[86:89], v[146:149]
	v_mfma_f32_16x16x32_bf16 v[82:85], v[236:239], v[90:93], v[82:85]
	v_mfma_f32_16x16x32_bf16 v[122:125], v[244:247], v[90:93], v[86:89]
	v_mfma_f32_16x16x32_bf16 v[86:89], v[102:105], v[94:97], v[222:225]
	v_mfma_f32_16x16x32_bf16 v[90:93], v[240:243], v[94:97], v[158:161]
	v_mfma_f32_16x16x32_bf16 v[94:97], v[240:243], v[150:153], v[166:169]
	v_mfma_f32_16x16x32_bf16 v[86:89], v[236:239], v[118:121], v[86:89]
	v_mfma_f32_16x16x32_bf16 v[126:129], v[244:247], v[118:121], v[90:93]
	v_mfma_f32_16x16x32_bf16 v[118:121], v[244:247], v[154:157], v[94:97]
	v_mfma_f32_16x16x32_bf16 v[94:97], v[102:105], v[186:189], v[134:137]
	v_mfma_f32_16x16x32_bf16 v[90:93], v[102:105], v[150:153], v[162:165]
	v_mfma_f32_16x16x32_bf16 v[102:105], v[236:239], v[190:193], v[94:97]
	v_mfma_f32_16x16x32_bf16 v[94:97], v[240:243], v[186:189], v[170:173]
	v_mfma_f32_16x16x32_bf16 v[90:93], v[236:239], v[154:157], v[90:93]
	v_mfma_f32_16x16x32_bf16 v[94:97], v[244:247], v[190:193], v[94:97]

; #define LDA(dst, b, h) for (int m = 0; m < 4; ++m) for (int k = 0; k < 2; ++k) \
;     dst[m][k] = *reinterpret_cast<const bf16x8*>((char*)SA(b, h) + a_thr + (m * 2 + k) * 1024)
; #define MMA(ai, bj, At, Btf) do { __builtin_amdgcn_s_setprio(1); \
;     for (int m = 0; m < 4; ++m) for (int n = 0; n < 2; ++n) for (int k = 0; k < 2; ++k) \
;       acc[ai][bj][m][n] = __builtin_amdgcn_mfma_f32_16x16x32_bf16(Btf[n][k], At[m][k], acc[ai][bj][m][n], 0, 0, 0); \
;     __builtin_amdgcn_s_setprio(0); } while (0)
; #define WAIT_L(n) asm volatile("s_waitcnt lgkmcnt(" #n ")" ::: "memory")
; #define BAR __builtin_amdgcn_s_barrier()
; template <bool OVL, bool PANEL = false, class Epi>
; __device__ __forceinline__ void gemm_phase(const bf16_t* __restrict__ A, long lda, const bf16_t* __restrict__ Bt, long ldb, int nM, int nN, int K,
;                                            const Epi& epi, bf16_t* shm, int w0) {
;     ...
;       LDA(At, 1, 1); BAR; WAIT_L(0); MMA(1, 0, At, B0); MMA(1, 1, At, B1); BAR; }
;     if (wr == 0) BAR;
	s_barrier
	s_and_saveexec_b64 s[0:1], s[58:59]
	s_cbranch_execz .LBB0_128
	s_barrier

; #define LDA(dst, b, h) for (int m = 0; m < 4; ++m) for (int k = 0; k < 2; ++k) \
;     dst[m][k] = *reinterpret_cast<const bf16x8*>((char*)SA(b, h) + a_thr + (m * 2 + k) * 1024)
; #define LDB(dst, b, h) for (int n = 0; n < 2; ++n) for (int k = 0; k < 2; ++k) \
;     dst[n][k] = *reinterpret_cast<const bf16x8*>((char*)SB(b, h) + b_thr + (n * 2 + k) * 1024)
; #define MMA(ai, bj, At, Btf) do { __builtin_amdgcn_s_setprio(1); \
;     for (int m = 0; m < 4; ++m) for (int n = 0; n < 2; ++n) for (int k = 0; k < 2; ++k) \
;       acc[ai][bj][m][n] = __builtin_amdgcn_mfma_f32_16x16x32_bf16(Btf[n][k], At[m][k], acc[ai][bj][m][n], 0, 0, 0); \
;     __builtin_amdgcn_s_setprio(0); } while (0)
; #define WAIT_V(n) asm volatile("s_waitcnt vmcnt(" #n ")" ::: "memory")
; #define WAIT_L(n) asm volatile("s_waitcnt lgkmcnt(" #n ")" ::: "memory")
; #define BAR __builtin_amdgcn_s_barrier()
; #define SCHED __builtin_amdgcn_sched_barrier(0)
; template <bool OVL, bool PANEL = false, class Epi>
; __device__ __forceinline__ void gemm_phase(const bf16_t* __restrict__ A, long lda, const bf16_t* __restrict__ Bt, long ldb, int nM, int nN, int K,
;                                            const Epi& epi, bf16_t* shm, int w0) {
;     ...
;       LDB(B0, 0, 0); SCHED; LDA(At, 0, 0); STAGE(SA(1, 1), A, lda, aoff, brow + HALF, t + 1);
;       WAIT_L(8); BAR; WAIT_L(0); MMA(0, 0, At, B0); BAR; SCHED;
;       LDB(B1, 0, 1); STAGE(SB(0, 0), Bt, ldb, boff, bcol, t + 2);
;       BAR; WAIT_L(0); MMA(0, 1, At, B1); BAR;
;       LDA(At, 0, 1); STAGE(SA(0, 0), A, lda, aoff, brow, t + 2);
;       BAR; WAIT_L(0); MMA(1, 0, At, B0); BAR; SCHED;
;       STAGE(SB(0, 1), Bt, ldb, boff, bcol + HALF, t + 2);
;       WAIT_V(6); BAR; MMA(1, 1, At, B1); BAR;
.LBB0_386:
	ds_read_b128 v[150:153], v218
	ds_read_b128 v[154:157], v218 offset:1024
	ds_read_b128 v[158:161], v218 offset:2048
	ds_read_b128 v[162:165], v218 offset:3072
	s_add_u32 s42, s10, vcc_lo
	s_addc_u32 s43, s11, vcc_hi
	ds_read_b128 v[166:169], v141
	ds_read_b128 v[170:173], v141 offset:1024
	ds_read_b128 v[174:177], v141 offset:2048
	ds_read_b128 v[178:181], v141 offset:3072
	ds_read_b128 v[182:185], v141 offset:4096
	ds_read_b128 v[186:189], v141 offset:5120
	ds_read_b128 v[190:193], v141 offset:6144
	ds_read_b128 v[194:197], v141 offset:7168
	s_mov_b32 m0, s16
	s_add_u32 s98, s42, s28
	s_addc_u32 s99, s43, s29
	global_load_lds_dwordx4 v131, s[98:99]
	s_mov_b32 m0, s32
	s_add_u32 s98, s42, s36
	s_addc_u32 s99, s43, s37
	global_load_lds_dwordx4 v131, s[98:99]
	s_waitcnt lgkmcnt(8)
	s_waitcnt vmcnt(10)
	s_barrier
	s_waitcnt lgkmcnt(0)
	v_mfma_f32_16x16x32_bf16 v[126:129], v[150:153], v[166:169], v[126:129]
	v_mfma_f32_16x16x32_bf16 v[122:125], v[158:161], v[166:169], v[122:125]
	v_mfma_f32_16x16x32_bf16 v[118:121], v[150:153], v[174:177], v[118:121]
	v_mfma_f32_16x16x32_bf16 v[114:117], v[158:161], v[174:177], v[114:117]
	v_mfma_f32_16x16x32_bf16 v[110:113], v[150:153], v[182:185], v[110:113]
	v_mfma_f32_16x16x32_bf16 v[106:109], v[158:161], v[182:185], v[106:109]
	v_mfma_f32_16x16x32_bf16 v[102:105], v[150:153], v[190:193], v[102:105]
	v_mfma_f32_16x16x32_bf16 v[98:101], v[158:161], v[190:193], v[98:101]
	v_mfma_f32_16x16x32_bf16 v[126:129], v[154:157], v[170:173], v[126:129]
	v_mfma_f32_16x16x32_bf16 v[122:125], v[162:165], v[170:173], v[122:125]
	v_mfma_f32_16x16x32_bf16 v[118:121], v[154:157], v[178:181], v[118:121]
	v_mfma_f32_16x16x32_bf16 v[114:117], v[162:165], v[178:181], v[114:117]
	v_mfma_f32_16x16x32_bf16 v[110:113], v[154:157], v[186:189], v[110:113]
	v_mfma_f32_16x16x32_bf16 v[106:109], v[162:165], v[186:189], v[106:109]
	v_mfma_f32_16x16x32_bf16 v[102:105], v[154:157], v[194:197], v[102:105]
	v_mfma_f32_16x16x32_bf16 v[98:101], v[162:165], v[194:197], v[98:101]
	s_barrier
	s_add_u32 s66, s8, vcc_lo
	ds_read_b128 v[198:201], v219
	ds_read_b128 v[202:205], v219 offset:1024
	ds_read_b128 v[206:209], v219 offset:2048
	ds_read_b128 v[210:213], v219 offset:3072
	s_addc_u32 s67, s9, vcc_hi
	s_mov_b32 m0, s46
	s_add_u32 s98, s66, s34
	s_addc_u32 s99, s67, s35
	global_load_lds_dwordx4 v131, s[98:99]
	s_mov_b32 m0, s47
	s_add_u32 s98, s66, s64
	s_addc_u32 s99, s67, s65
	global_load_lds_dwordx4 v131, s[98:99]
	s_waitcnt vmcnt(10)
	s_barrier
	s_waitcnt lgkmcnt(0)
	v_mfma_f32_16x16x32_bf16 v[94:97], v[198:201], v[166:169], v[94:97]
	v_mfma_f32_16x16x32_bf16 v[90:93], v[206:209], v[166:169], v[90:93]
	v_mfma_f32_16x16x32_bf16 v[86:89], v[198:201], v[174:177], v[86:89]
	v_mfma_f32_16x16x32_bf16 v[82:85], v[206:209], v[174:177], v[82:85]
	v_mfma_f32_16x16x32_bf16 v[78:81], v[198:201], v[182:185], v[78:81]
	v_mfma_f32_16x16x32_bf16 v[74:77], v[206:209], v[182:185], v[74:77]
	v_mfma_f32_16x16x32_bf16 v[70:73], v[198:201], v[190:193], v[70:73]
	v_mfma_f32_16x16x32_bf16 v[66:69], v[206:209], v[190:193], v[66:69]
	v_mfma_f32_16x16x32_bf16 v[94:97], v[202:205], v[170:173], v[94:97]
	v_mfma_f32_16x16x32_bf16 v[90:93], v[210:213], v[170:173], v[90:93]
	v_mfma_f32_16x16x32_bf16 v[86:89], v[202:205], v[178:181], v[86:89]
	v_mfma_f32_16x16x32_bf16 v[82:85], v[210:213], v[178:181], v[82:85]
	v_mfma_f32_16x16x32_bf16 v[78:81], v[202:205], v[186:189], v[78:81]
	v_mfma_f32_16x16x32_bf16 v[74:77], v[210:213], v[186:189], v[74:77]
	v_mfma_f32_16x16x32_bf16 v[70:73], v[202:205], v[194:197], v[70:73]
	v_mfma_f32_16x16x32_bf16 v[66:69], v[210:213], v[194:197], v[66:69]
	s_barrier
	ds_read_b128 v[166:169], v141 offset:16384
	ds_read_b128 v[170:173], v141 offset:17408
	ds_read_b128 v[174:177], v141 offset:18432
	ds_read_b128 v[178:181], v141 offset:19456
	ds_read_b128 v[182:185], v141 offset:20480
	ds_read_b128 v[186:189], v141 offset:21504
	ds_read_b128 v[190:193], v141 offset:22528
	ds_read_b128 v[194:197], v141 offset:23552
	s_mov_b32 m0, s48
	s_add_u32 s98, s42, s34
	s_addc_u32 s99, s43, s35
	global_load_lds_dwordx4 v131, s[98:99]
	s_mov_b32 m0, s49
	s_add_u32 s98, s42, s64
	s_addc_u32 s99, s43, s65
	global_load_lds_dwordx4 v131, s[98:99]
	s_barrier
	s_waitcnt lgkmcnt(0)
	v_mfma_f32_16x16x32_bf16 v[62:65], v[150:153], v[166:169], v[62:65]
	v_mfma_f32_16x16x32_bf16 v[58:61], v[158:161], v[166:169], v[58:61]
	v_mfma_f32_16x16x32_bf16 v[54:57], v[150:153], v[174:177], v[54:57]
	v_mfma_f32_16x16x32_bf16 v[50:53], v[158:161], v[174:177], v[50:53]
	v_mfma_f32_16x16x32_bf16 v[46:49], v[150:153], v[182:185], v[46:49]
	v_mfma_f32_16x16x32_bf16 v[42:45], v[158:161], v[182:185], v[42:45]
	v_mfma_f32_16x16x32_bf16 v[38:41], v[150:153], v[190:193], v[38:41]
	v_mfma_f32_16x16x32_bf16 v[34:37], v[158:161], v[190:193], v[34:37]
	v_mfma_f32_16x16x32_bf16 v[62:65], v[154:157], v[170:173], v[62:65]
	v_mfma_f32_16x16x32_bf16 v[58:61], v[162:165], v[170:173], v[58:61]
	v_mfma_f32_16x16x32_bf16 v[54:57], v[154:157], v[178:181], v[54:57]
	v_mfma_f32_16x16x32_bf16 v[50:53], v[162:165], v[178:181], v[50:53]
	v_mfma_f32_16x16x32_bf16 v[46:49], v[154:157], v[186:189], v[46:49]
	v_mfma_f32_16x16x32_bf16 v[42:45], v[162:165], v[186:189], v[42:45]
	v_mfma_f32_16x16x32_bf16 v[38:41], v[154:157], v[194:197], v[38:41]
	v_mfma_f32_16x16x32_bf16 v[34:37], v[162:165], v[194:197], v[34:37]
	s_barrier
	s_mov_b32 m0, s50
	s_add_u32 s98, s66, s68
	s_addc_u32 s99, s67, s69
	global_load_lds_dwordx4 v131, s[98:99]
	s_mov_b32 m0, s51
	s_add_u32 s98, s66, s70
	s_addc_u32 s99, s67, s71
	global_load_lds_dwordx4 v131, s[98:99]
	s_waitcnt vmcnt(10)
	s_barrier
; #define LDA(dst, b, h) for (int m = 0; m < 4; ++m) for (int k = 0; k < 2; ++k) \
;     dst[m][k] = *reinterpret_cast<const bf16x8*>((char*)SA(b, h) + a_thr + (m * 2 + k) * 1024)
; #define LDB(dst, b, h) for (int n = 0; n < 2; ++n) for (int k = 0; k < 2; ++k) \
;     dst[n][k] = *reinterpret_cast<const bf16x8*>((char*)SB(b, h) + b_thr + (n * 2 + k) * 1024)
; #define MMA(ai, bj, At, Btf) do { __builtin_amdgcn_s_setprio(1); \
;     for (int m = 0; m < 4; ++m) for (int n = 0; n < 2; ++n) for (int k = 0; k < 2; ++k) \
;       acc[ai][bj][m][n] = __builtin_amdgcn_mfma_f32_16x16x32_bf16(Btf[n][k], At[m][k], acc[ai][bj][m][n], 0, 0, 0); \
;     __builtin_amdgcn_s_setprio(0); } while (0)
; #define WAIT_V(n) asm volatile("s_waitcnt vmcnt(" #n ")" ::: "memory")
; #define WAIT_L(n) asm volatile("s_waitcnt lgkmcnt(" #n ")" ::: "memory")
; #define BAR __builtin_amdgcn_s_barrier()
; #define SCHED __builtin_amdgcn_sched_barrier(0)
; template <bool OVL, bool PANEL = false, class Epi>
; __device__ __forceinline__ void gemm_phase(const bf16_t* __restrict__ A, long lda, const bf16_t* __restrict__ Bt, long ldb, int nM, int nN, int K,
;                                            const Epi& epi, bf16_t* shm, int w0) {
;     ...
;       WAIT_V(6); BAR; MMA(1, 1, At, B1); BAR;
;       LDB(B0, 1, 0); SCHED; LDA(At, 1, 0); STAGE(SA(0, 1), A, lda, aoff, brow + HALF, t + 2);
;       WAIT_L(8); BAR; WAIT_L(0); MMA(0, 0, At, B0); BAR; SCHED;
;       LDB(B1, 1, 1); STAGE(SB(1, 0), Bt, ldb, boff, bcol, t + 3);
;       BAR; WAIT_L(0); MMA(0, 1, At, B1); BAR;
	v_mfma_f32_16x16x32_bf16 v[30:33], v[198:201], v[166:169], v[30:33]
	v_mfma_f32_16x16x32_bf16 v[26:29], v[206:209], v[166:169], v[26:29]
	v_mfma_f32_16x16x32_bf16 v[22:25], v[198:201], v[174:177], v[22:25]
	v_mfma_f32_16x16x32_bf16 v[18:21], v[206:209], v[174:177], v[18:21]
	v_mfma_f32_16x16x32_bf16 v[14:17], v[198:201], v[182:185], v[14:17]
	v_mfma_f32_16x16x32_bf16 v[10:13], v[206:209], v[182:185], v[10:13]
	v_mfma_f32_16x16x32_bf16 v[6:9], v[198:201], v[190:193], v[6:9]
	v_mfma_f32_16x16x32_bf16 v[2:5], v[206:209], v[190:193], v[2:5]
	v_mfma_f32_16x16x32_bf16 v[30:33], v[202:205], v[170:173], v[30:33]
	v_mfma_f32_16x16x32_bf16 v[26:29], v[210:213], v[170:173], v[26:29]
	v_mfma_f32_16x16x32_bf16 v[22:25], v[202:205], v[178:181], v[22:25]
	v_mfma_f32_16x16x32_bf16 v[18:21], v[210:213], v[178:181], v[18:21]
	v_mfma_f32_16x16x32_bf16 v[14:17], v[202:205], v[186:189], v[14:17]
	v_mfma_f32_16x16x32_bf16 v[10:13], v[210:213], v[186:189], v[10:13]
	v_mfma_f32_16x16x32_bf16 v[6:9], v[202:205], v[194:197], v[6:9]
	v_mfma_f32_16x16x32_bf16 v[2:5], v[210:213], v[194:197], v[2:5]
	s_barrier
	ds_read_b128 v[150:153], v220
	ds_read_b128 v[154:157], v220 offset:1024
	ds_read_b128 v[158:161], v220 offset:2048
	ds_read_b128 v[162:165], v220 offset:3072
	ds_read_b128 v[166:169], v141 offset:32768
	ds_read_b128 v[170:173], v141 offset:33792
	ds_read_b128 v[174:177], v141 offset:34816
	ds_read_b128 v[178:181], v141 offset:35840
	ds_read_b128 v[182:185], v141 offset:36864
	ds_read_b128 v[186:189], v141 offset:37888
	ds_read_b128 v[190:193], v141 offset:38912
	ds_read_b128 v[194:197], v141 offset:39936
	s_mov_b32 m0, s52
	s_add_u32 s98, s42, s68
	s_addc_u32 s99, s43, s69
	global_load_lds_dwordx4 v131, s[98:99]
	s_mov_b32 m0, s53
	s_add_u32 s98, s42, s70
	s_addc_u32 s99, s43, s71
	global_load_lds_dwordx4 v131, s[98:99]
	s_waitcnt lgkmcnt(8)
	s_waitcnt vmcnt(10)
	s_barrier
	s_waitcnt lgkmcnt(0)
	v_mfma_f32_16x16x32_bf16 v[126:129], v[150:153], v[166:169], v[126:129]
	v_mfma_f32_16x16x32_bf16 v[122:125], v[158:161], v[166:169], v[122:125]
	v_mfma_f32_16x16x32_bf16 v[118:121], v[150:153], v[174:177], v[118:121]
	v_mfma_f32_16x16x32_bf16 v[114:117], v[158:161], v[174:177], v[114:117]
	v_mfma_f32_16x16x32_bf16 v[110:113], v[150:153], v[182:185], v[110:113]
	v_mfma_f32_16x16x32_bf16 v[106:109], v[158:161], v[182:185], v[106:109]
	v_mfma_f32_16x16x32_bf16 v[102:105], v[150:153], v[190:193], v[102:105]
	v_mfma_f32_16x16x32_bf16 v[98:101], v[158:161], v[190:193], v[98:101]
	v_mfma_f32_16x16x32_bf16 v[126:129], v[154:157], v[170:173], v[126:129]
	v_mfma_f32_16x16x32_bf16 v[122:125], v[162:165], v[170:173], v[122:125]
	v_mfma_f32_16x16x32_bf16 v[118:121], v[154:157], v[178:181], v[118:121]
	v_mfma_f32_16x16x32_bf16 v[114:117], v[162:165], v[178:181], v[114:117]
	v_mfma_f32_16x16x32_bf16 v[110:113], v[154:157], v[186:189], v[110:113]
	v_mfma_f32_16x16x32_bf16 v[106:109], v[162:165], v[186:189], v[106:109]
	v_mfma_f32_16x16x32_bf16 v[102:105], v[154:157], v[194:197], v[102:105]
	v_mfma_f32_16x16x32_bf16 v[98:101], v[162:165], v[194:197], v[98:101]
	s_barrier
	ds_read_b128 v[198:201], v221
	ds_read_b128 v[202:205], v221 offset:1024
	ds_read_b128 v[206:209], v221 offset:2048
	ds_read_b128 v[210:213], v221 offset:3072
	s_mov_b32 m0, s54
	s_add_u32 s98, s66, s94
	s_addc_u32 s99, s67, s95
	global_load_lds_dwordx4 v131, s[98:99]
	s_mov_b32 m0, s55
	s_add_u32 s98, s66, s72
	s_addc_u32 s99, s67, s73
	global_load_lds_dwordx4 v131, s[98:99]
	s_waitcnt vmcnt(10)
	s_barrier
	s_waitcnt lgkmcnt(0)
	v_mfma_f32_16x16x32_bf16 v[94:97], v[198:201], v[166:169], v[94:97]
	v_mfma_f32_16x16x32_bf16 v[90:93], v[206:209], v[166:169], v[90:93]
	v_mfma_f32_16x16x32_bf16 v[86:89], v[198:201], v[174:177], v[86:89]
	v_mfma_f32_16x16x32_bf16 v[82:85], v[206:209], v[174:177], v[82:85]
	v_mfma_f32_16x16x32_bf16 v[78:81], v[198:201], v[182:185], v[78:81]
	v_mfma_f32_16x16x32_bf16 v[74:77], v[206:209], v[182:185], v[74:77]
	v_mfma_f32_16x16x32_bf16 v[70:73], v[198:201], v[190:193], v[70:73]
	v_mfma_f32_16x16x32_bf16 v[66:69], v[206:209], v[190:193], v[66:69]
	v_mfma_f32_16x16x32_bf16 v[94:97], v[202:205], v[170:173], v[94:97]
	v_mfma_f32_16x16x32_bf16 v[90:93], v[210:213], v[170:173], v[90:93]
	v_mfma_f32_16x16x32_bf16 v[86:89], v[202:205], v[178:181], v[86:89]
	v_mfma_f32_16x16x32_bf16 v[82:85], v[210:213], v[178:181], v[82:85]
	v_mfma_f32_16x16x32_bf16 v[78:81], v[202:205], v[186:189], v[78:81]
	v_mfma_f32_16x16x32_bf16 v[74:77], v[210:213], v[186:189], v[74:77]
	v_mfma_f32_16x16x32_bf16 v[70:73], v[202:205], v[194:197], v[70:73]
	v_mfma_f32_16x16x32_bf16 v[66:69], v[210:213], v[194:197], v[66:69]
	s_barrier
; #define LDA(dst, b, h) for (int m = 0; m < 4; ++m) for (int k = 0; k < 2; ++k) \
;     dst[m][k] = *reinterpret_cast<const bf16x8*>((char*)SA(b, h) + a_thr + (m * 2 + k) * 1024)
; #define LDB(dst, b, h) for (int n = 0; n < 2; ++n) for (int k = 0; k < 2; ++k) \
;     dst[n][k] = *reinterpret_cast<const bf16x8*>((char*)SB(b, h) + b_thr + (n * 2 + k) * 1024)
; #define MMA(ai, bj, At, Btf) do { __builtin_amdgcn_s_setprio(1); \
;     for (int m = 0; m < 4; ++m) for (int n = 0; n < 2; ++n) for (int k = 0; k < 2; ++k) \
;       acc[ai][bj][m][n] = __builtin_amdgcn_mfma_f32_16x16x32_bf16(Btf[n][k], At[m][k], acc[ai][bj][m][n], 0, 0, 0); \
;     __builtin_amdgcn_s_setprio(0); } while (0)
; #define WAIT_V(n) asm volatile("s_waitcnt vmcnt(" #n ")" ::: "memory")
; #define WAIT_L(n) asm volatile("s_waitcnt lgkmcnt(" #n ")" ::: "memory")
; #define BAR __builtin_amdgcn_s_barrier()
; #define SCHED __builtin_amdgcn_sched_barrier(0)
; template <bool OVL, bool PANEL = false, class Epi>
; __device__ __forceinline__ void gemm_phase(const bf16_t* __restrict__ A, long lda, const bf16_t* __restrict__ Bt, long ldb, int nM, int nN, int K,
;                                            const Epi& epi, bf16_t* shm, int w0) {
;     ...
;       LDA(At, 1, 1); STAGE(SA(1, 0), A, lda, aoff, brow, t + 3);
;       BAR; WAIT_L(0); MMA(1, 0, At, B0); BAR; SCHED;
;       STAGE(SB(1, 1), Bt, ldb, boff, bcol + HALF, t + 3);
;       WAIT_V(6); BAR; MMA(1, 1, At, B1); BAR;
;     }
;     { LDB(B0, 0, 0); LDA(At, 0, 0); STAGE(SA(1, 1), A, lda, aoff, brow + HALF, nt - 1);
	ds_read_b128 v[166:169], v141 offset:49152
	ds_read_b128 v[170:173], v141 offset:50176
	ds_read_b128 v[174:177], v141 offset:51200
	ds_read_b128 v[178:181], v141 offset:52224
	ds_read_b128 v[182:185], v141 offset:53248
	ds_read_b128 v[186:189], v141 offset:54272
	ds_read_b128 v[190:193], v141 offset:55296
	ds_read_b128 v[194:197], v141 offset:56320
	s_mov_b32 m0, s56
	s_add_u32 s98, s42, s94
	s_addc_u32 s99, s43, s95
	global_load_lds_dwordx4 v131, s[98:99]
	s_mov_b32 m0, s57
	s_add_u32 s98, s42, s72
	s_addc_u32 s99, s43, s73
	global_load_lds_dwordx4 v131, s[98:99]
	s_barrier
	s_waitcnt lgkmcnt(0)
	v_mfma_f32_16x16x32_bf16 v[62:65], v[150:153], v[166:169], v[62:65]
	v_mfma_f32_16x16x32_bf16 v[58:61], v[158:161], v[166:169], v[58:61]
	v_mfma_f32_16x16x32_bf16 v[54:57], v[150:153], v[174:177], v[54:57]
	v_mfma_f32_16x16x32_bf16 v[50:53], v[158:161], v[174:177], v[50:53]
	v_mfma_f32_16x16x32_bf16 v[46:49], v[150:153], v[182:185], v[46:49]
	v_mfma_f32_16x16x32_bf16 v[42:45], v[158:161], v[182:185], v[42:45]
	v_mfma_f32_16x16x32_bf16 v[38:41], v[150:153], v[190:193], v[38:41]
	v_mfma_f32_16x16x32_bf16 v[34:37], v[158:161], v[190:193], v[34:37]
	v_mfma_f32_16x16x32_bf16 v[62:65], v[154:157], v[170:173], v[62:65]
	v_mfma_f32_16x16x32_bf16 v[58:61], v[162:165], v[170:173], v[58:61]
	v_mfma_f32_16x16x32_bf16 v[54:57], v[154:157], v[178:181], v[54:57]
	v_mfma_f32_16x16x32_bf16 v[50:53], v[162:165], v[178:181], v[50:53]
	v_mfma_f32_16x16x32_bf16 v[46:49], v[154:157], v[186:189], v[46:49]
	v_mfma_f32_16x16x32_bf16 v[42:45], v[162:165], v[186:189], v[42:45]
	v_mfma_f32_16x16x32_bf16 v[38:41], v[154:157], v[194:197], v[38:41]
	v_mfma_f32_16x16x32_bf16 v[34:37], v[162:165], v[194:197], v[34:37]
	s_barrier
	s_mov_b32 m0, s58
	s_add_u32 s98, s66, s30
	s_addc_u32 s99, s67, s31
	global_load_lds_dwordx4 v131, s[98:99]
	s_mov_b32 m0, s59
	s_add_u32 s98, s66, s44
	s_addc_u32 s99, s67, s45
	global_load_lds_dwordx4 v131, s[98:99]
	s_add_i32 s18, s18, 2
	s_add_u32 vcc_lo, vcc_lo, 0x100
	s_addc_u32 vcc_hi, vcc_hi, 0
	s_cmp_lt_u32 s18, 12
	s_waitcnt vmcnt(10)
	s_barrier
	v_mfma_f32_16x16x32_bf16 v[30:33], v[198:201], v[166:169], v[30:33]
	v_mfma_f32_16x16x32_bf16 v[26:29], v[206:209], v[166:169], v[26:29]
	v_mfma_f32_16x16x32_bf16 v[22:25], v[198:201], v[174:177], v[22:25]
	v_mfma_f32_16x16x32_bf16 v[18:21], v[206:209], v[174:177], v[18:21]
	v_mfma_f32_16x16x32_bf16 v[14:17], v[198:201], v[182:185], v[14:17]
	v_mfma_f32_16x16x32_bf16 v[10:13], v[206:209], v[182:185], v[10:13]
	v_mfma_f32_16x16x32_bf16 v[6:9], v[198:201], v[190:193], v[6:9]
	v_mfma_f32_16x16x32_bf16 v[2:5], v[206:209], v[190:193], v[2:5]
	v_mfma_f32_16x16x32_bf16 v[30:33], v[202:205], v[170:173], v[30:33]
	v_mfma_f32_16x16x32_bf16 v[26:29], v[210:213], v[170:173], v[26:29]
	v_mfma_f32_16x16x32_bf16 v[22:25], v[202:205], v[178:181], v[22:25]
	v_mfma_f32_16x16x32_bf16 v[18:21], v[210:213], v[178:181], v[18:21]
	v_mfma_f32_16x16x32_bf16 v[14:17], v[202:205], v[186:189], v[14:17]
	v_mfma_f32_16x16x32_bf16 v[10:13], v[210:213], v[186:189], v[10:13]
	v_mfma_f32_16x16x32_bf16 v[6:9], v[202:205], v[194:197], v[6:9]
	v_mfma_f32_16x16x32_bf16 v[2:5], v[210:213], v[194:197], v[2:5]
	s_barrier
	s_cbranch_scc1 .LBB0_386
	s_waitcnt vmcnt(6)
	s_or_b32 s8, s2, 0x80
	s_mov_b32 s9, s3
	v_readlane_b32 s44, v252, 20
	s_lshl_b64 s[8:9], s[8:9], 11
	v_readlane_b32 s50, v252, 26
	v_add_u32_e32 v214, 16, v140
	v_readlane_b32 s51, v252, 27
	s_add_u32 s8, s50, s8
	v_add_u32_e32 v0, 0x10000, v214
	s_addc_u32 s9, s51, s9
	ds_read_b128 v[142:145], v0
	ds_read_b128 v[150:153], v0 offset:1024
	ds_read_b128 v[154:157], v0 offset:2048
	ds_read_b128 v[158:161], v0 offset:3072
	ds_read_b128 v[162:165], v141
	ds_read_b128 v[166:169], v141 offset:1024
	ds_read_b128 v[170:173], v141 offset:2048
	ds_read_b128 v[174:177], v141 offset:3072
	ds_read_b128 v[178:181], v141 offset:4096
	ds_read_b128 v[182:185], v141 offset:5120
	ds_read_b128 v[186:189], v141 offset:6144
	ds_read_b128 v[190:193], v141 offset:7168
	v_mov_b32_e32 v0, v131
	v_readlane_b32 s45, v252, 21
	v_lshl_add_u64 v[146:147], s[8:9], 0, v[0:1]
	s_mov_b64 s[8:9], 0x780
	v_lshl_add_u64 v[194:195], v[146:147], 0, s[8:9]
	v_readfirstlane_b32 s8, v148
	s_mov_b32 m0, s8
	s_mov_b64 s[8:9], 0x20780
	v_lshl_add_u64 v[146:147], v[146:147], 0, s[8:9]
	v_readfirstlane_b32 s8, v149
	global_load_lds_dwordx4 v[194:195], off
	s_mov_b32 m0, s8
	v_readlane_b32 s46, v252, 22
	global_load_lds_dwordx4 v[146:147], off
	s_barrier
	s_waitcnt lgkmcnt(0)
	v_readlane_b32 s47, v252, 23
	v_readlane_b32 s48, v252, 24
	v_readlane_b32 s49, v252, 25
	v_readlane_b32 s52, v252, 28
	v_readlane_b32 s53, v252, 29
	v_readlane_b32 s54, v252, 30
	v_readlane_b32 s55, v252, 31
	v_readlane_b32 s56, v252, 32
	v_readlane_b32 s57, v252, 33
	v_readlane_b32 s58, v252, 34
	v_readlane_b32 s59, v252, 35

; #define MMA(ai, bj, At, Btf) do { __builtin_amdgcn_s_setprio(1); \
;     for (int m = 0; m < 4; ++m) for (int n = 0; n < 2; ++n) for (int k = 0; k < 2; ++k) \
;       acc[ai][bj][m][n] = __builtin_amdgcn_mfma_f32_16x16x32_bf16(Btf[n][k], At[m][k], acc[ai][bj][m][n], 0, 0, 0); \
;     __builtin_amdgcn_s_setprio(0); } while (0)
; #define WAIT_L(n) asm volatile("s_waitcnt lgkmcnt(" #n ")" ::: "memory")
; #define BAR __builtin_amdgcn_s_barrier()
; template <bool OVL, bool PANEL = false, class Epi>
; __device__ __forceinline__ void gemm_phase(const bf16_t* __restrict__ A, long lda, const bf16_t* __restrict__ Bt, long ldb, int nM, int nN, int K,
;                                            const Epi& epi, bf16_t* shm, int w0) {
;     ...
;       BAR; WAIT_L(0); MMA(0, 0, At, B0); BAR;
	s_waitcnt lgkmcnt(0)
	v_mfma_f32_16x16x32_bf16 v[126:129], v[142:145], v[162:165], v[126:129]
	v_mfma_f32_16x16x32_bf16 v[122:125], v[154:157], v[162:165], v[122:125]
	v_mfma_f32_16x16x32_bf16 v[118:121], v[142:145], v[170:173], v[118:121]
	v_mfma_f32_16x16x32_bf16 v[114:117], v[154:157], v[170:173], v[114:117]
	v_mfma_f32_16x16x32_bf16 v[110:113], v[142:145], v[178:181], v[110:113]
	v_mfma_f32_16x16x32_bf16 v[106:109], v[154:157], v[178:181], v[106:109]
	v_mfma_f32_16x16x32_bf16 v[98:101], v[154:157], v[186:189], v[98:101]
	v_mfma_f32_16x16x32_bf16 v[126:129], v[150:153], v[166:169], v[126:129]
	v_mfma_f32_16x16x32_bf16 v[122:125], v[158:161], v[166:169], v[122:125]
	v_mfma_f32_16x16x32_bf16 v[118:121], v[150:153], v[174:177], v[118:121]
	v_mfma_f32_16x16x32_bf16 v[114:117], v[158:161], v[174:177], v[114:117]
	v_mfma_f32_16x16x32_bf16 v[110:113], v[150:153], v[182:185], v[110:113]
	v_mfma_f32_16x16x32_bf16 v[106:109], v[158:161], v[182:185], v[106:109]
	v_mfma_f32_16x16x32_bf16 v[102:105], v[142:145], v[186:189], v[102:105]
	v_mfma_f32_16x16x32_bf16 v[98:101], v[158:161], v[190:193], v[98:101]
	v_mfma_f32_16x16x32_bf16 v[146:149], v[150:153], v[190:193], v[102:105]

; #define LDB(dst, b, h) for (int n = 0; n < 2; ++n) for (int k = 0; k < 2; ++k) \
;     dst[n][k] = *reinterpret_cast<const bf16x8*>((char*)SB(b, h) + b_thr + (n * 2 + k) * 1024)
; #define MMA(ai, bj, At, Btf) do { __builtin_amdgcn_s_setprio(1); \
;     for (int m = 0; m < 4; ++m) for (int n = 0; n < 2; ++n) for (int k = 0; k < 2; ++k) \
;       acc[ai][bj][m][n] = __builtin_amdgcn_mfma_f32_16x16x32_bf16(Btf[n][k], At[m][k], acc[ai][bj][m][n], 0, 0, 0); \
;     __builtin_amdgcn_s_setprio(0); } while (0)
; #define WAIT_L(n) asm volatile("s_waitcnt lgkmcnt(" #n ")" ::: "memory")
; #define BAR __builtin_amdgcn_s_barrier()
; template <bool OVL, bool PANEL = false, class Epi>
; __device__ __forceinline__ void gemm_phase(const bf16_t* __restrict__ A, long lda, const bf16_t* __restrict__ Bt, long ldb, int nM, int nN, int K,
;                                            const Epi& epi, bf16_t* shm, int w0) {
;     ...
;       LDB(B1, 0, 1); BAR; WAIT_L(0); MMA(0, 1, At, B1); BAR;
	v_add_u32_e32 v0, 0x14000, v214
	s_barrier
	s_nop 2
	ds_read_b128 v[102:105], v0
	ds_read_b128 v[194:197], v0 offset:1024
	ds_read_b128 v[198:201], v0 offset:2048
	ds_read_b128 v[202:205], v0 offset:3072
	s_barrier
	s_waitcnt lgkmcnt(0)

; #define LDB(dst, b, h) for (int n = 0; n < 2; ++n) for (int k = 0; k < 2; ++k) \
;     dst[n][k] = *reinterpret_cast<const bf16x8*>((char*)SB(b, h) + b_thr + (n * 2 + k) * 1024)
; #define MMA(ai, bj, At, Btf) do { __builtin_amdgcn_s_setprio(1); \
;     for (int m = 0; m < 4; ++m) for (int n = 0; n < 2; ++n) for (int k = 0; k < 2; ++k) \
;       acc[ai][bj][m][n] = __builtin_amdgcn_mfma_f32_16x16x32_bf16(Btf[n][k], At[m][k], acc[ai][bj][m][n], 0, 0, 0); \
;     __builtin_amdgcn_s_setprio(0); } while (0)
; #define WAIT_L(n) asm volatile("s_waitcnt lgkmcnt(" #n ")" ::: "memory")
; #define BAR __builtin_amdgcn_s_barrier()
; template <bool OVL, bool PANEL = false, class Epi>
; __device__ __forceinline__ void gemm_phase(const bf16_t* __restrict__ A, long lda, const bf16_t* __restrict__ Bt, long ldb, int nM, int nN, int K,
;                                            const Epi& epi, bf16_t* shm, int w0) {
;     ...
;       LDB(B1, 0, 1); BAR; WAIT_L(0); MMA(0, 1, At, B1); BAR;
	v_mfma_f32_16x16x32_bf16 v[94:97], v[102:105], v[162:165], v[94:97]
	v_mfma_f32_16x16x32_bf16 v[86:89], v[102:105], v[170:173], v[86:89]
	v_mfma_f32_16x16x32_bf16 v[78:81], v[102:105], v[178:181], v[78:81]
	v_mfma_f32_16x16x32_bf16 v[74:77], v[198:201], v[178:181], v[74:77]
	v_mfma_f32_16x16x32_bf16 v[94:97], v[194:197], v[166:169], v[94:97]
	v_mfma_f32_16x16x32_bf16 v[90:93], v[198:201], v[162:165], v[90:93]
	v_mfma_f32_16x16x32_bf16 v[86:89], v[194:197], v[174:177], v[86:89]
	v_mfma_f32_16x16x32_bf16 v[82:85], v[198:201], v[170:173], v[82:85]
	v_mfma_f32_16x16x32_bf16 v[78:81], v[194:197], v[182:185], v[78:81]
	v_mfma_f32_16x16x32_bf16 v[74:77], v[202:205], v[182:185], v[74:77]
	v_mfma_f32_16x16x32_bf16 v[70:73], v[102:105], v[186:189], v[70:73]
	v_mfma_f32_16x16x32_bf16 v[66:69], v[198:201], v[186:189], v[66:69]
	v_mfma_f32_16x16x32_bf16 v[162:165], v[202:205], v[166:169], v[90:93]
	v_mfma_f32_16x16x32_bf16 v[166:169], v[202:205], v[174:177], v[82:85]
	v_mfma_f32_16x16x32_bf16 v[170:173], v[194:197], v[190:193], v[70:73]
	v_mfma_f32_16x16x32_bf16 v[174:177], v[202:205], v[190:193], v[66:69]

; #define LDA(dst, b, h) for (int m = 0; m < 4; ++m) for (int k = 0; k < 2; ++k) \
;     dst[m][k] = *reinterpret_cast<const bf16x8*>((char*)SA(b, h) + a_thr + (m * 2 + k) * 1024)
; #define MMA(ai, bj, At, Btf) do { __builtin_amdgcn_s_setprio(1); \
;     for (int m = 0; m < 4; ++m) for (int n = 0; n < 2; ++n) for (int k = 0; k < 2; ++k) \
;       acc[ai][bj][m][n] = __builtin_amdgcn_mfma_f32_16x16x32_bf16(Btf[n][k], At[m][k], acc[ai][bj][m][n], 0, 0, 0); \
;     __builtin_amdgcn_s_setprio(0); } while (0)
; #define WAIT_V(n) asm volatile("s_waitcnt vmcnt(" #n ")" ::: "memory")
; #define WAIT_L(n) asm volatile("s_waitcnt lgkmcnt(" #n ")" ::: "memory")
; #define BAR __builtin_amdgcn_s_barrier()
; template <bool OVL, bool PANEL = false, class Epi>
; __device__ __forceinline__ void gemm_phase(const bf16_t* __restrict__ A, long lda, const bf16_t* __restrict__ Bt, long ldb, int nM, int nN, int K,
;                                            const Epi& epi, bf16_t* shm, int w0) {
;     ...
;       LDA(At, 0, 1); WAIT_V(4); BAR; WAIT_L(0); MMA(1, 0, At, B0); MMA(1, 1, At, B1); BAR; }
	s_barrier
	s_nop 1
	ds_read_b128 v[66:69], v141 offset:16384
	ds_read_b128 v[70:73], v141 offset:17408
	ds_read_b128 v[82:85], v141 offset:18432
	ds_read_b128 v[90:93], v141 offset:19456
	ds_read_b128 v[178:181], v141 offset:20480
	ds_read_b128 v[182:185], v141 offset:21504
	ds_read_b128 v[186:189], v141 offset:22528
	ds_read_b128 v[190:193], v141 offset:23552
	s_waitcnt vmcnt(4)
	s_barrier
	s_waitcnt lgkmcnt(0)

; #define LDA(dst, b, h) for (int m = 0; m < 4; ++m) for (int k = 0; k < 2; ++k) \
;     dst[m][k] = *reinterpret_cast<const bf16x8*>((char*)SA(b, h) + a_thr + (m * 2 + k) * 1024)
; #define MMA(ai, bj, At, Btf) do { __builtin_amdgcn_s_setprio(1); \
;     for (int m = 0; m < 4; ++m) for (int n = 0; n < 2; ++n) for (int k = 0; k < 2; ++k) \
;       acc[ai][bj][m][n] = __builtin_amdgcn_mfma_f32_16x16x32_bf16(Btf[n][k], At[m][k], acc[ai][bj][m][n], 0, 0, 0); \
;     __builtin_amdgcn_s_setprio(0); } while (0)
; #define WAIT_V(n) asm volatile("s_waitcnt vmcnt(" #n ")" ::: "memory")
; #define WAIT_L(n) asm volatile("s_waitcnt lgkmcnt(" #n ")" ::: "memory")
; #define BAR __builtin_amdgcn_s_barrier()
; template <bool OVL, bool PANEL = false, class Epi>
; __device__ __forceinline__ void gemm_phase(const bf16_t* __restrict__ A, long lda, const bf16_t* __restrict__ Bt, long ldb, int nM, int nN, int K,
;                                            const Epi& epi, bf16_t* shm, int w0) {
;     ...
;       LDA(At, 0, 1); WAIT_V(4); BAR; WAIT_L(0); MMA(1, 0, At, B0); MMA(1, 1, At, B1); BAR; }
	v_mfma_f32_16x16x32_bf16 v[62:65], v[142:145], v[66:69], v[62:65]
	v_mfma_f32_16x16x32_bf16 v[54:57], v[142:145], v[82:85], v[54:57]
	v_mfma_f32_16x16x32_bf16 v[46:49], v[142:145], v[178:181], v[46:49]
	v_mfma_f32_16x16x32_bf16 v[42:45], v[154:157], v[178:181], v[42:45]
	v_mfma_f32_16x16x32_bf16 v[38:41], v[142:145], v[186:189], v[38:41]
	v_mfma_f32_16x16x32_bf16 v[34:37], v[154:157], v[186:189], v[34:37]
	v_mfma_f32_16x16x32_bf16 v[62:65], v[150:153], v[70:73], v[62:65]
	v_mfma_f32_16x16x32_bf16 v[58:61], v[154:157], v[66:69], v[58:61]
	v_mfma_f32_16x16x32_bf16 v[54:57], v[150:153], v[90:93], v[54:57]
	v_mfma_f32_16x16x32_bf16 v[50:53], v[154:157], v[82:85], v[50:53]
	v_mfma_f32_16x16x32_bf16 v[46:49], v[150:153], v[182:185], v[46:49]
	v_mfma_f32_16x16x32_bf16 v[42:45], v[158:161], v[182:185], v[42:45]
	v_mfma_f32_16x16x32_bf16 v[38:41], v[150:153], v[190:193], v[38:41]
	v_mfma_f32_16x16x32_bf16 v[34:37], v[158:161], v[190:193], v[34:37]
	v_mfma_f32_16x16x32_bf16 v[206:209], v[158:161], v[70:73], v[58:61]
	v_mfma_f32_16x16x32_bf16 v[210:213], v[158:161], v[90:93], v[50:53]


; #define LDA(dst, b, h) for (int m = 0; m < 4; ++m) for (int k = 0; k < 2; ++k) \
;     dst[m][k] = *reinterpret_cast<const bf16x8*>((char*)SA(b, h) + a_thr + (m * 2 + k) * 1024)
; #define MMA(ai, bj, At, Btf) do { __builtin_amdgcn_s_setprio(1); \
;     for (int m = 0; m < 4; ++m) for (int n = 0; n < 2; ++n) for (int k = 0; k < 2; ++k) \
;       acc[ai][bj][m][n] = __builtin_amdgcn_mfma_f32_16x16x32_bf16(Btf[n][k], At[m][k], acc[ai][bj][m][n], 0, 0, 0); \
;     __builtin_amdgcn_s_setprio(0); } while (0)
; #define WAIT_V(n) asm volatile("s_waitcnt vmcnt(" #n ")" ::: "memory")
; #define WAIT_L(n) asm volatile("s_waitcnt lgkmcnt(" #n ")" ::: "memory")
; #define BAR __builtin_amdgcn_s_barrier()
; template <bool OVL, bool PANEL = false, class Epi>
; __device__ __forceinline__ void gemm_phase(const bf16_t* __restrict__ A, long lda, const bf16_t* __restrict__ Bt, long ldb, int nM, int nN, int K,
;                                            const Epi& epi, bf16_t* shm, int w0) {
;     ...
;       LDA(At, 0, 1); WAIT_V(4); BAR; WAIT_L(0); MMA(1, 0, At, B0); MMA(1, 1, At, B1); BAR; }
	v_mfma_f32_16x16x32_bf16 v[30:33], v[102:105], v[66:69], v[30:33]
	v_mfma_f32_16x16x32_bf16 v[26:29], v[198:201], v[66:69], v[26:29]
	v_mfma_f32_16x16x32_bf16 v[22:25], v[102:105], v[82:85], v[22:25]
	v_mfma_f32_16x16x32_bf16 v[18:21], v[198:201], v[82:85], v[18:21]
	v_mfma_f32_16x16x32_bf16 v[14:17], v[102:105], v[178:181], v[14:17]
	v_mfma_f32_16x16x32_bf16 v[10:13], v[198:201], v[178:181], v[10:13]
	v_mfma_f32_16x16x32_bf16 v[6:9], v[102:105], v[186:189], v[6:9]
	v_mfma_f32_16x16x32_bf16 v[2:5], v[198:201], v[186:189], v[2:5]
	v_mfma_f32_16x16x32_bf16 v[30:33], v[194:197], v[70:73], v[30:33]
	v_mfma_f32_16x16x32_bf16 v[26:29], v[202:205], v[70:73], v[26:29]
	v_mfma_f32_16x16x32_bf16 v[22:25], v[194:197], v[90:93], v[22:25]
	v_mfma_f32_16x16x32_bf16 v[18:21], v[202:205], v[90:93], v[18:21]
	v_mfma_f32_16x16x32_bf16 v[14:17], v[194:197], v[182:185], v[14:17]
	v_mfma_f32_16x16x32_bf16 v[10:13], v[202:205], v[182:185], v[10:13]
	v_mfma_f32_16x16x32_bf16 v[6:9], v[194:197], v[190:193], v[6:9]
	v_mfma_f32_16x16x32_bf16 v[2:5], v[202:205], v[190:193], v[2:5]

; #define LDA(dst, b, h) for (int m = 0; m < 4; ++m) for (int k = 0; k < 2; ++k) \
;     dst[m][k] = *reinterpret_cast<const bf16x8*>((char*)SA(b, h) + a_thr + (m * 2 + k) * 1024)
; #define LDB(dst, b, h) for (int n = 0; n < 2; ++n) for (int k = 0; k < 2; ++k) \
;     dst[n][k] = *reinterpret_cast<const bf16x8*>((char*)SB(b, h) + b_thr + (n * 2 + k) * 1024)
; #define MMA(ai, bj, At, Btf) do { __builtin_amdgcn_s_setprio(1); \
;     for (int m = 0; m < 4; ++m) for (int n = 0; n < 2; ++n) for (int k = 0; k < 2; ++k) \
;       acc[ai][bj][m][n] = __builtin_amdgcn_mfma_f32_16x16x32_bf16(Btf[n][k], At[m][k], acc[ai][bj][m][n], 0, 0, 0); \
;     __builtin_amdgcn_s_setprio(0); } while (0)
; #define WAIT_V(n) asm volatile("s_waitcnt vmcnt(" #n ")" ::: "memory")
; #define WAIT_L(n) asm volatile("s_waitcnt lgkmcnt(" #n ")" ::: "memory")
; #define BAR __builtin_amdgcn_s_barrier()
; template <bool OVL, bool PANEL = false, class Epi>
; __device__ __forceinline__ void gemm_phase(const bf16_t* __restrict__ A, long lda, const bf16_t* __restrict__ Bt, long ldb, int nM, int nN, int K,
;                                            const Epi& epi, bf16_t* shm, int w0) {
;     ...
;     { LDB(B0, 1, 0); LDA(At, 1, 0); WAIT_V(2); BAR; WAIT_L(0); MMA(0, 0, At, B0); BAR;
	v_add_u32_e32 v0, 0x18000, v214
	s_barrier
	ds_read_b128 v[142:145], v0
	ds_read_b128 v[150:153], v0 offset:1024
	ds_read_b128 v[154:157], v0 offset:2048
	ds_read_b128 v[158:161], v0 offset:3072
	ds_read_b128 v[50:53], v141 offset:32768
	ds_read_b128 v[58:61], v141 offset:33792
	ds_read_b128 v[66:69], v141 offset:34816
	ds_read_b128 v[70:73], v141 offset:35840
	ds_read_b128 v[178:181], v141 offset:36864
	ds_read_b128 v[182:185], v141 offset:37888
	ds_read_b128 v[186:189], v141 offset:38912
	ds_read_b128 v[190:193], v141 offset:39936
	s_waitcnt vmcnt(2)
	s_barrier
	s_waitcnt lgkmcnt(0)

; #define LDA(dst, b, h) for (int m = 0; m < 4; ++m) for (int k = 0; k < 2; ++k) \
;     dst[m][k] = *reinterpret_cast<const bf16x8*>((char*)SA(b, h) + a_thr + (m * 2 + k) * 1024)
; #define LDB(dst, b, h) for (int n = 0; n < 2; ++n) for (int k = 0; k < 2; ++k) \
;     dst[n][k] = *reinterpret_cast<const bf16x8*>((char*)SB(b, h) + b_thr + (n * 2 + k) * 1024)
; #define MMA(ai, bj, At, Btf) do { __builtin_amdgcn_s_setprio(1); \
;     for (int m = 0; m < 4; ++m) for (int n = 0; n < 2; ++n) for (int k = 0; k < 2; ++k) \
;       acc[ai][bj][m][n] = __builtin_amdgcn_mfma_f32_16x16x32_bf16(Btf[n][k], At[m][k], acc[ai][bj][m][n], 0, 0, 0); \
;     __builtin_amdgcn_s_setprio(0); } while (0)
; #define WAIT_V(n) asm volatile("s_waitcnt vmcnt(" #n ")" ::: "memory")
; #define WAIT_L(n) asm volatile("s_waitcnt lgkmcnt(" #n ")" ::: "memory")
; #define BAR __builtin_amdgcn_s_barrier()
; template <bool OVL, bool PANEL = false, class Epi>
; __device__ __forceinline__ void gemm_phase(const bf16_t* __restrict__ A, long lda, const bf16_t* __restrict__ Bt, long ldb, int nM, int nN, int K,
;                                            const Epi& epi, bf16_t* shm, int w0) {
;     ...
;     { LDB(B0, 1, 0); LDA(At, 1, 0); WAIT_V(2); BAR; WAIT_L(0); MMA(0, 0, At, B0); BAR;
	v_mfma_f32_16x16x32_bf16 v[82:85], v[142:145], v[50:53], v[126:129]
	v_mfma_f32_16x16x32_bf16 v[126:129], v[150:153], v[58:61], v[82:85]
	v_mfma_f32_16x16x32_bf16 v[82:85], v[154:157], v[50:53], v[122:125]
	v_mfma_f32_16x16x32_bf16 v[122:125], v[158:161], v[58:61], v[82:85]
	v_mfma_f32_16x16x32_bf16 v[82:85], v[142:145], v[66:69], v[118:121]
	v_mfma_f32_16x16x32_bf16 v[118:121], v[150:153], v[70:73], v[82:85]
	v_mfma_f32_16x16x32_bf16 v[82:85], v[154:157], v[66:69], v[114:117]
	v_mfma_f32_16x16x32_bf16 v[114:117], v[158:161], v[70:73], v[82:85]
	v_mfma_f32_16x16x32_bf16 v[82:85], v[142:145], v[178:181], v[110:113]
	v_mfma_f32_16x16x32_bf16 v[110:113], v[150:153], v[182:185], v[82:85]
	v_mfma_f32_16x16x32_bf16 v[82:85], v[154:157], v[178:181], v[106:109]
	v_mfma_f32_16x16x32_bf16 v[102:105], v[158:161], v[182:185], v[82:85]
	v_mfma_f32_16x16x32_bf16 v[82:85], v[142:145], v[186:189], v[146:149]
	v_mfma_f32_16x16x32_bf16 v[90:93], v[150:153], v[190:193], v[82:85]
	v_mfma_f32_16x16x32_bf16 v[82:85], v[154:157], v[186:189], v[98:101]
	v_mfma_f32_16x16x32_bf16 v[82:85], v[158:161], v[190:193], v[82:85]

; #define LDB(dst, b, h) for (int n = 0; n < 2; ++n) for (int k = 0; k < 2; ++k) \
;     dst[n][k] = *reinterpret_cast<const bf16x8*>((char*)SB(b, h) + b_thr + (n * 2 + k) * 1024)
; #define MMA(ai, bj, At, Btf) do { __builtin_amdgcn_s_setprio(1); \
;     for (int m = 0; m < 4; ++m) for (int n = 0; n < 2; ++n) for (int k = 0; k < 2; ++k) \
;       acc[ai][bj][m][n] = __builtin_amdgcn_mfma_f32_16x16x32_bf16(Btf[n][k], At[m][k], acc[ai][bj][m][n], 0, 0, 0); \
;     __builtin_amdgcn_s_setprio(0); } while (0)
; #define WAIT_V(n) asm volatile("s_waitcnt vmcnt(" #n ")" ::: "memory")
; #define WAIT_L(n) asm volatile("s_waitcnt lgkmcnt(" #n ")" ::: "memory")
; #define BAR __builtin_amdgcn_s_barrier()
; template <bool OVL, bool PANEL = false, class Epi>
; __device__ __forceinline__ void gemm_phase(const bf16_t* __restrict__ A, long lda, const bf16_t* __restrict__ Bt, long ldb, int nM, int nN, int K,
;                                            const Epi& epi, bf16_t* shm, int w0) {
;     ...
;       LDB(B1, 1, 1); WAIT_V(0); BAR; WAIT_L(0); MMA(0, 1, At, B1); BAR;
	v_add_u32_e32 v0, 0x1c000, v214
	s_barrier
	ds_read_b128 v[146:149], v0
	ds_read_b128 v[194:197], v0 offset:1024
	ds_read_b128 v[198:201], v0 offset:2048
	ds_read_b128 v[202:205], v0 offset:3072
	s_waitcnt vmcnt(0)
	s_barrier
	s_waitcnt lgkmcnt(0)

; #define LDB(dst, b, h) for (int n = 0; n < 2; ++n) for (int k = 0; k < 2; ++k) \
;     dst[n][k] = *reinterpret_cast<const bf16x8*>((char*)SB(b, h) + b_thr + (n * 2 + k) * 1024)
; #define MMA(ai, bj, At, Btf) do { __builtin_amdgcn_s_setprio(1); \
;     for (int m = 0; m < 4; ++m) for (int n = 0; n < 2; ++n) for (int k = 0; k < 2; ++k) \
;       acc[ai][bj][m][n] = __builtin_amdgcn_mfma_f32_16x16x32_bf16(Btf[n][k], At[m][k], acc[ai][bj][m][n], 0, 0, 0); \
;     __builtin_amdgcn_s_setprio(0); } while (0)
; #define WAIT_V(n) asm volatile("s_waitcnt vmcnt(" #n ")" ::: "memory")
; #define WAIT_L(n) asm volatile("s_waitcnt lgkmcnt(" #n ")" ::: "memory")
; #define BAR __builtin_amdgcn_s_barrier()
; template <bool OVL, bool PANEL = false, class Epi>
; __device__ __forceinline__ void gemm_phase(const bf16_t* __restrict__ A, long lda, const bf16_t* __restrict__ Bt, long ldb, int nM, int nN, int K,
;                                            const Epi& epi, bf16_t* shm, int w0) {
;     ...
;       LDB(B1, 1, 1); WAIT_V(0); BAR; WAIT_L(0); MMA(0, 1, At, B1); BAR;
	v_mfma_f32_16x16x32_bf16 v[94:97], v[146:149], v[50:53], v[94:97]
	v_mfma_f32_16x16x32_bf16 v[50:53], v[198:201], v[50:53], v[162:165]
	v_mfma_f32_16x16x32_bf16 v[98:101], v[202:205], v[58:61], v[50:53]
	v_mfma_f32_16x16x32_bf16 v[50:53], v[146:149], v[66:69], v[86:89]
	v_mfma_f32_16x16x32_bf16 v[106:109], v[194:197], v[58:61], v[94:97]
	v_mfma_f32_16x16x32_bf16 v[94:97], v[194:197], v[70:73], v[50:53]
	v_mfma_f32_16x16x32_bf16 v[50:53], v[198:201], v[66:69], v[166:169]
	v_mfma_f32_16x16x32_bf16 v[86:89], v[202:205], v[70:73], v[50:53]
	v_mfma_f32_16x16x32_bf16 v[50:53], v[146:149], v[178:181], v[78:81]
	v_mfma_f32_16x16x32_bf16 v[70:73], v[194:197], v[182:185], v[50:53]
	v_mfma_f32_16x16x32_bf16 v[50:53], v[198:201], v[178:181], v[74:77]
	v_mfma_f32_16x16x32_bf16 v[66:69], v[202:205], v[182:185], v[50:53]
	v_mfma_f32_16x16x32_bf16 v[50:53], v[146:149], v[186:189], v[170:173]
	v_mfma_f32_16x16x32_bf16 v[58:61], v[194:197], v[190:193], v[50:53]
	v_mfma_f32_16x16x32_bf16 v[50:53], v[198:201], v[186:189], v[174:177]
	v_mfma_f32_16x16x32_bf16 v[50:53], v[202:205], v[190:193], v[50:53]

; #define LDA(dst, b, h) for (int m = 0; m < 4; ++m) for (int k = 0; k < 2; ++k) \
;     dst[m][k] = *reinterpret_cast<const bf16x8*>((char*)SA(b, h) + a_thr + (m * 2 + k) * 1024)
; #define MMA(ai, bj, At, Btf) do { __builtin_amdgcn_s_setprio(1); \
;     for (int m = 0; m < 4; ++m) for (int n = 0; n < 2; ++n) for (int k = 0; k < 2; ++k) \
;       acc[ai][bj][m][n] = __builtin_amdgcn_mfma_f32_16x16x32_bf16(Btf[n][k], At[m][k], acc[ai][bj][m][n], 0, 0, 0); \
;     __builtin_amdgcn_s_setprio(0); } while (0)
; #define WAIT_L(n) asm volatile("s_waitcnt lgkmcnt(" #n ")" ::: "memory")
; #define BAR __builtin_amdgcn_s_barrier()
; template <bool OVL, bool PANEL = false, class Epi>
; __device__ __forceinline__ void gemm_phase(const bf16_t* __restrict__ A, long lda, const bf16_t* __restrict__ Bt, long ldb, int nM, int nN, int K,
;                                            const Epi& epi, bf16_t* shm, int w0) {
;     ...
;       LDA(At, 1, 1); BAR; WAIT_L(0); MMA(1, 0, At, B0); MMA(1, 1, At, B1); BAR; }
	s_barrier
	ds_read_b128 v[162:165], v141 offset:49152
	ds_read_b128 v[166:169], v141 offset:50176
	ds_read_b128 v[170:173], v141 offset:51200
	ds_read_b128 v[174:177], v141 offset:52224
	ds_read_b128 v[178:181], v141 offset:53248
	ds_read_b128 v[182:185], v141 offset:54272
	ds_read_b128 v[186:189], v141 offset:55296
	ds_read_b128 v[190:193], v141 offset:56320
	s_barrier
	s_waitcnt lgkmcnt(0)

; #define LDA(dst, b, h) for (int m = 0; m < 4; ++m) for (int k = 0; k < 2; ++k) \
;     dst[m][k] = *reinterpret_cast<const bf16x8*>((char*)SA(b, h) + a_thr + (m * 2 + k) * 1024)
; #define MMA(ai, bj, At, Btf) do { __builtin_amdgcn_s_setprio(1); \
;     for (int m = 0; m < 4; ++m) for (int n = 0; n < 2; ++n) for (int k = 0; k < 2; ++k) \
;       acc[ai][bj][m][n] = __builtin_amdgcn_mfma_f32_16x16x32_bf16(Btf[n][k], At[m][k], acc[ai][bj][m][n], 0, 0, 0); \
;     __builtin_amdgcn_s_setprio(0); } while (0)
; #define WAIT_L(n) asm volatile("s_waitcnt lgkmcnt(" #n ")" ::: "memory")
; #define BAR __builtin_amdgcn_s_barrier()
; template <bool OVL, bool PANEL = false, class Epi>
; __device__ __forceinline__ void gemm_phase(const bf16_t* __restrict__ A, long lda, const bf16_t* __restrict__ Bt, long ldb, int nM, int nN, int K,
;                                            const Epi& epi, bf16_t* shm, int w0) {
;     ...
;       LDA(At, 1, 1); BAR; WAIT_L(0); MMA(1, 0, At, B0); MMA(1, 1, At, B1); BAR; }
	v_mfma_f32_16x16x32_bf16 v[62:65], v[142:145], v[162:165], v[62:65]
	v_mfma_f32_16x16x32_bf16 v[78:81], v[150:153], v[166:169], v[62:65]
	v_mfma_f32_16x16x32_bf16 v[62:65], v[154:157], v[162:165], v[206:209]
	v_mfma_f32_16x16x32_bf16 v[54:57], v[142:145], v[170:173], v[54:57]
	v_mfma_f32_16x16x32_bf16 v[74:77], v[158:161], v[166:169], v[62:65]
	v_mfma_f32_16x16x32_bf16 v[62:65], v[150:153], v[174:177], v[54:57]
	v_mfma_f32_16x16x32_bf16 v[54:57], v[154:157], v[170:173], v[210:213]
	v_mfma_f32_16x16x32_bf16 v[46:49], v[142:145], v[178:181], v[46:49]
	v_mfma_f32_16x16x32_bf16 v[42:45], v[154:157], v[178:181], v[42:45]
	v_mfma_f32_16x16x32_bf16 v[38:41], v[142:145], v[186:189], v[38:41]
	v_mfma_f32_16x16x32_bf16 v[34:37], v[154:157], v[186:189], v[34:37]
	v_mfma_f32_16x16x32_bf16 v[54:57], v[158:161], v[174:177], v[54:57]
	v_mfma_f32_16x16x32_bf16 v[46:49], v[150:153], v[182:185], v[46:49]
	v_mfma_f32_16x16x32_bf16 v[42:45], v[158:161], v[182:185], v[42:45]
	v_mfma_f32_16x16x32_bf16 v[38:41], v[150:153], v[190:193], v[38:41]
	v_mfma_f32_16x16x32_bf16 v[34:37], v[158:161], v[190:193], v[34:37]


; #define LDA(dst, b, h) for (int m = 0; m < 4; ++m) for (int k = 0; k < 2; ++k) \
;     dst[m][k] = *reinterpret_cast<const bf16x8*>((char*)SA(b, h) + a_thr + (m * 2 + k) * 1024)
; #define MMA(ai, bj, At, Btf) do { __builtin_amdgcn_s_setprio(1); \
;     for (int m = 0; m < 4; ++m) for (int n = 0; n < 2; ++n) for (int k = 0; k < 2; ++k) \
;       acc[ai][bj][m][n] = __builtin_amdgcn_mfma_f32_16x16x32_bf16(Btf[n][k], At[m][k], acc[ai][bj][m][n], 0, 0, 0); \
;     __builtin_amdgcn_s_setprio(0); } while (0)
; #define WAIT_L(n) asm volatile("s_waitcnt lgkmcnt(" #n ")" ::: "memory")
; #define BAR __builtin_amdgcn_s_barrier()
; template <bool OVL, bool PANEL = false, class Epi>
; __device__ __forceinline__ void gemm_phase(const bf16_t* __restrict__ A, long lda, const bf16_t* __restrict__ Bt, long ldb, int nM, int nN, int K,
;                                            const Epi& epi, bf16_t* shm, int w0) {
;     ...
;       LDA(At, 1, 1); BAR; WAIT_L(0); MMA(1, 0, At, B0); MMA(1, 1, At, B1); BAR; }
	v_mfma_f32_16x16x32_bf16 v[30:33], v[146:149], v[162:165], v[30:33]
	v_mfma_f32_16x16x32_bf16 v[26:29], v[198:201], v[162:165], v[26:29]
	v_mfma_f32_16x16x32_bf16 v[22:25], v[146:149], v[170:173], v[22:25]
	v_mfma_f32_16x16x32_bf16 v[18:21], v[198:201], v[170:173], v[18:21]
	v_mfma_f32_16x16x32_bf16 v[14:17], v[146:149], v[178:181], v[14:17]
	v_mfma_f32_16x16x32_bf16 v[10:13], v[198:201], v[178:181], v[10:13]
	v_mfma_f32_16x16x32_bf16 v[6:9], v[146:149], v[186:189], v[6:9]
	v_mfma_f32_16x16x32_bf16 v[2:5], v[198:201], v[186:189], v[2:5]
	v_mfma_f32_16x16x32_bf16 v[30:33], v[194:197], v[166:169], v[30:33]
	v_mfma_f32_16x16x32_bf16 v[26:29], v[202:205], v[166:169], v[26:29]
	v_mfma_f32_16x16x32_bf16 v[22:25], v[194:197], v[174:177], v[22:25]
	v_mfma_f32_16x16x32_bf16 v[18:21], v[202:205], v[174:177], v[18:21]
	v_mfma_f32_16x16x32_bf16 v[14:17], v[194:197], v[182:185], v[14:17]
	v_mfma_f32_16x16x32_bf16 v[10:13], v[202:205], v[182:185], v[10:13]
	v_mfma_f32_16x16x32_bf16 v[6:9], v[194:197], v[190:193], v[6:9]
	v_mfma_f32_16x16x32_bf16 v[2:5], v[202:205], v[190:193], v[2:5]

; #define LDA(dst, b, h) for (int m = 0; m < 4; ++m) for (int k = 0; k < 2; ++k) \
;     dst[m][k] = *reinterpret_cast<const bf16x8*>((char*)SA(b, h) + a_thr + (m * 2 + k) * 1024)
; #define MMA(ai, bj, At, Btf) do { __builtin_amdgcn_s_setprio(1); \
;     for (int m = 0; m < 4; ++m) for (int n = 0; n < 2; ++n) for (int k = 0; k < 2; ++k) \
;       acc[ai][bj][m][n] = __builtin_amdgcn_mfma_f32_16x16x32_bf16(Btf[n][k], At[m][k], acc[ai][bj][m][n], 0, 0, 0); \
;     __builtin_amdgcn_s_setprio(0); } while (0)
; #define WAIT_L(n) asm volatile("s_waitcnt lgkmcnt(" #n ")" ::: "memory")
; #define BAR __builtin_amdgcn_s_barrier()
; template <bool OVL, bool PANEL = false, class Epi>
; __device__ __forceinline__ void gemm_phase(const bf16_t* __restrict__ A, long lda, const bf16_t* __restrict__ Bt, long ldb, int nM, int nN, int K,
;                                            const Epi& epi, bf16_t* shm, int w0) {
;     ...
;       LDA(At, 1, 1); BAR; WAIT_L(0); MMA(1, 0, At, B0); MMA(1, 1, At, B1); BAR; }
;     if (wr == 0) BAR;
	s_barrier
	s_and_saveexec_b64 s[8:9], s[78:79]
	s_cbranch_execz .LBB0_389
	s_barrier

; #define LDA(dst, b, h) for (int m = 0; m < 4; ++m) for (int k = 0; k < 2; ++k) \
;     dst[m][k] = *reinterpret_cast<const bf16x8*>((char*)SA(b, h) + a_thr + (m * 2 + k) * 1024)
; #define LDB(dst, b, h) for (int n = 0; n < 2; ++n) for (int k = 0; k < 2; ++k) \
;     dst[n][k] = *reinterpret_cast<const bf16x8*>((char*)SB(b, h) + b_thr + (n * 2 + k) * 1024)
; #define MMA(ai, bj, At, Btf) do { __builtin_amdgcn_s_setprio(1); \
;     for (int m = 0; m < 4; ++m) for (int n = 0; n < 2; ++n) for (int k = 0; k < 2; ++k) \
;       acc[ai][bj][m][n] = __builtin_amdgcn_mfma_f32_16x16x32_bf16(Btf[n][k], At[m][k], acc[ai][bj][m][n], 0, 0, 0); \
;     __builtin_amdgcn_s_setprio(0); } while (0)
; #define WAIT_V(n) asm volatile("s_waitcnt vmcnt(" #n ")" ::: "memory")
; #define WAIT_L(n) asm volatile("s_waitcnt lgkmcnt(" #n ")" ::: "memory")
; #define BAR __builtin_amdgcn_s_barrier()
; #define SCHED __builtin_amdgcn_sched_barrier(0)
; template <bool OVL, bool PANEL = false, class Epi>
; __device__ __forceinline__ void gemm_phase(const bf16_t* __restrict__ A, long lda, const bf16_t* __restrict__ Bt, long ldb, int nM, int nN, int K,
;                                            const Epi& epi, bf16_t* shm, int w0) {
;     ...
;       LDB(B0, 0, 0); SCHED; LDA(At, 0, 0); STAGE(SA(1, 1), A, lda, aoff, brow + HALF, t + 1);
;       WAIT_L(8); BAR; WAIT_L(0); MMA(0, 0, At, B0); BAR; SCHED;
;       LDB(B1, 0, 1); STAGE(SB(0, 0), Bt, ldb, boff, bcol, t + 2);
;       BAR; WAIT_L(0); MMA(0, 1, At, B1); BAR;
;       LDA(At, 0, 1); STAGE(SA(0, 0), A, lda, aoff, brow, t + 2);
;       BAR; WAIT_L(0); MMA(1, 0, At, B0); BAR; SCHED;
;       STAGE(SB(0, 1), Bt, ldb, boff, bcol + HALF, t + 2);
;       WAIT_V(6); BAR; MMA(1, 1, At, B1); BAR;
.LBB0_410:
	ds_read_b128 v[152:155], v220
	ds_read_b128 v[156:159], v220 offset:1024
	ds_read_b128 v[160:163], v220 offset:2048
	ds_read_b128 v[164:167], v220 offset:3072
	s_add_u32 s12, s8, s10
	s_addc_u32 s13, s9, s11
	ds_read_b128 v[168:171], v143
	ds_read_b128 v[172:175], v143 offset:1024
	ds_read_b128 v[176:179], v143 offset:2048
	ds_read_b128 v[180:183], v143 offset:3072
	ds_read_b128 v[184:187], v143 offset:4096
	ds_read_b128 v[188:191], v143 offset:5120
	ds_read_b128 v[192:195], v143 offset:6144
	ds_read_b128 v[196:199], v143 offset:7168
	s_mov_b32 m0, s16
	s_add_u32 s98, s12, s24
	s_addc_u32 s99, s13, s25
	global_load_lds_dwordx4 v131, s[98:99]
	s_mov_b32 m0, s23
	s_add_u32 s98, s12, s36
	s_addc_u32 s99, s13, s37
	global_load_lds_dwordx4 v131, s[98:99]
	s_waitcnt lgkmcnt(8)
	s_waitcnt vmcnt(10)
	s_barrier
	s_waitcnt lgkmcnt(0)
	v_mfma_f32_16x16x32_bf16 v[126:129], v[152:155], v[168:171], v[126:129]
	v_mfma_f32_16x16x32_bf16 v[122:125], v[160:163], v[168:171], v[122:125]
	v_mfma_f32_16x16x32_bf16 v[118:121], v[152:155], v[176:179], v[118:121]
	v_mfma_f32_16x16x32_bf16 v[114:117], v[160:163], v[176:179], v[114:117]
	v_mfma_f32_16x16x32_bf16 v[110:113], v[152:155], v[184:187], v[110:113]
	v_mfma_f32_16x16x32_bf16 v[106:109], v[160:163], v[184:187], v[106:109]
	v_mfma_f32_16x16x32_bf16 v[102:105], v[152:155], v[192:195], v[102:105]
	v_mfma_f32_16x16x32_bf16 v[98:101], v[160:163], v[192:195], v[98:101]
	v_mfma_f32_16x16x32_bf16 v[126:129], v[156:159], v[172:175], v[126:129]
	v_mfma_f32_16x16x32_bf16 v[122:125], v[164:167], v[172:175], v[122:125]
	v_mfma_f32_16x16x32_bf16 v[118:121], v[156:159], v[180:183], v[118:121]
	v_mfma_f32_16x16x32_bf16 v[114:117], v[164:167], v[180:183], v[114:117]
	v_mfma_f32_16x16x32_bf16 v[110:113], v[156:159], v[188:191], v[110:113]
	v_mfma_f32_16x16x32_bf16 v[106:109], v[164:167], v[188:191], v[106:109]
	v_mfma_f32_16x16x32_bf16 v[102:105], v[156:159], v[196:199], v[102:105]
	v_mfma_f32_16x16x32_bf16 v[98:101], v[164:167], v[196:199], v[98:101]
	s_barrier
	s_add_u32 s14, s0, s10
	ds_read_b128 v[200:203], v221
	ds_read_b128 v[204:207], v221 offset:1024
	ds_read_b128 v[208:211], v221 offset:2048
	ds_read_b128 v[212:215], v221 offset:3072
	s_addc_u32 s15, s1, s11
	s_mov_b32 m0, s30
	s_add_u32 s98, s14, s34
	s_addc_u32 s99, s15, s35
	global_load_lds_dwordx4 v131, s[98:99]
	s_mov_b32 m0, s31
	s_add_u32 s98, s14, s64
	s_addc_u32 s99, s15, s65
	global_load_lds_dwordx4 v131, s[98:99]
	s_waitcnt vmcnt(10)
	s_barrier
	s_waitcnt lgkmcnt(0)
	v_mfma_f32_16x16x32_bf16 v[94:97], v[200:203], v[168:171], v[94:97]
	v_mfma_f32_16x16x32_bf16 v[90:93], v[208:211], v[168:171], v[90:93]
	v_mfma_f32_16x16x32_bf16 v[86:89], v[200:203], v[176:179], v[86:89]
	v_mfma_f32_16x16x32_bf16 v[82:85], v[208:211], v[176:179], v[82:85]
	v_mfma_f32_16x16x32_bf16 v[78:81], v[200:203], v[184:187], v[78:81]
	v_mfma_f32_16x16x32_bf16 v[74:77], v[208:211], v[184:187], v[74:77]
	v_mfma_f32_16x16x32_bf16 v[70:73], v[200:203], v[192:195], v[70:73]
	v_mfma_f32_16x16x32_bf16 v[66:69], v[208:211], v[192:195], v[66:69]
	v_mfma_f32_16x16x32_bf16 v[94:97], v[204:207], v[172:175], v[94:97]
	v_mfma_f32_16x16x32_bf16 v[90:93], v[212:215], v[172:175], v[90:93]
	v_mfma_f32_16x16x32_bf16 v[86:89], v[204:207], v[180:183], v[86:89]
	v_mfma_f32_16x16x32_bf16 v[82:85], v[212:215], v[180:183], v[82:85]
	v_mfma_f32_16x16x32_bf16 v[78:81], v[204:207], v[188:191], v[78:81]
	v_mfma_f32_16x16x32_bf16 v[74:77], v[212:215], v[188:191], v[74:77]
	v_mfma_f32_16x16x32_bf16 v[70:73], v[204:207], v[196:199], v[70:73]
	v_mfma_f32_16x16x32_bf16 v[66:69], v[212:215], v[196:199], v[66:69]
	s_barrier
	ds_read_b128 v[168:171], v143 offset:16384
	ds_read_b128 v[172:175], v143 offset:17408
	ds_read_b128 v[176:179], v143 offset:18432
	ds_read_b128 v[180:183], v143 offset:19456
	ds_read_b128 v[184:187], v143 offset:20480
	ds_read_b128 v[188:191], v143 offset:21504
	ds_read_b128 v[192:195], v143 offset:22528
	ds_read_b128 v[196:199], v143 offset:23552
	s_mov_b32 m0, s32
	s_add_u32 s98, s12, s34
	s_addc_u32 s99, s13, s35
	global_load_lds_dwordx4 v131, s[98:99]
	s_mov_b32 m0, s40
	s_add_u32 s98, s12, s64
	s_addc_u32 s99, s13, s65
	global_load_lds_dwordx4 v131, s[98:99]
	s_barrier
	s_waitcnt lgkmcnt(0)
	v_mfma_f32_16x16x32_bf16 v[62:65], v[152:155], v[168:171], v[62:65]
	v_mfma_f32_16x16x32_bf16 v[58:61], v[160:163], v[168:171], v[58:61]
	v_mfma_f32_16x16x32_bf16 v[54:57], v[152:155], v[176:179], v[54:57]
	v_mfma_f32_16x16x32_bf16 v[50:53], v[160:163], v[176:179], v[50:53]
	v_mfma_f32_16x16x32_bf16 v[46:49], v[152:155], v[184:187], v[46:49]
	v_mfma_f32_16x16x32_bf16 v[42:45], v[160:163], v[184:187], v[42:45]
	v_mfma_f32_16x16x32_bf16 v[38:41], v[152:155], v[192:195], v[38:41]
	v_mfma_f32_16x16x32_bf16 v[34:37], v[160:163], v[192:195], v[34:37]
	v_mfma_f32_16x16x32_bf16 v[62:65], v[156:159], v[172:175], v[62:65]
	v_mfma_f32_16x16x32_bf16 v[58:61], v[164:167], v[172:175], v[58:61]
	v_mfma_f32_16x16x32_bf16 v[54:57], v[156:159], v[180:183], v[54:57]
	v_mfma_f32_16x16x32_bf16 v[50:53], v[164:167], v[180:183], v[50:53]
	v_mfma_f32_16x16x32_bf16 v[46:49], v[156:159], v[188:191], v[46:49]
	v_mfma_f32_16x16x32_bf16 v[42:45], v[164:167], v[188:191], v[42:45]
	v_mfma_f32_16x16x32_bf16 v[38:41], v[156:159], v[196:199], v[38:41]
	v_mfma_f32_16x16x32_bf16 v[34:37], v[164:167], v[196:199], v[34:37]
	s_barrier
	s_mov_b32 m0, s41
	s_add_u32 s98, s14, s68
	s_addc_u32 s99, s15, s69
	global_load_lds_dwordx4 v131, s[98:99]
	s_mov_b32 m0, s42
	s_add_u32 s98, s14, s70
	s_addc_u32 s99, s15, s71
	global_load_lds_dwordx4 v131, s[98:99]
	s_waitcnt vmcnt(10)
	s_barrier
; #define LDA(dst, b, h) for (int m = 0; m < 4; ++m) for (int k = 0; k < 2; ++k) \
;     dst[m][k] = *reinterpret_cast<const bf16x8*>((char*)SA(b, h) + a_thr + (m * 2 + k) * 1024)
; #define LDB(dst, b, h) for (int n = 0; n < 2; ++n) for (int k = 0; k < 2; ++k) \
;     dst[n][k] = *reinterpret_cast<const bf16x8*>((char*)SB(b, h) + b_thr + (n * 2 + k) * 1024)
; #define MMA(ai, bj, At, Btf) do { __builtin_amdgcn_s_setprio(1); \
;     for (int m = 0; m < 4; ++m) for (int n = 0; n < 2; ++n) for (int k = 0; k < 2; ++k) \
;       acc[ai][bj][m][n] = __builtin_amdgcn_mfma_f32_16x16x32_bf16(Btf[n][k], At[m][k], acc[ai][bj][m][n], 0, 0, 0); \
;     __builtin_amdgcn_s_setprio(0); } while (0)
; #define WAIT_V(n) asm volatile("s_waitcnt vmcnt(" #n ")" ::: "memory")
; #define WAIT_L(n) asm volatile("s_waitcnt lgkmcnt(" #n ")" ::: "memory")
; #define BAR __builtin_amdgcn_s_barrier()
; #define SCHED __builtin_amdgcn_sched_barrier(0)
; template <bool OVL, bool PANEL = false, class Epi>
; __device__ __forceinline__ void gemm_phase(const bf16_t* __restrict__ A, long lda, const bf16_t* __restrict__ Bt, long ldb, int nM, int nN, int K,
;                                            const Epi& epi, bf16_t* shm, int w0) {
;     ...
;       WAIT_V(6); BAR; MMA(1, 1, At, B1); BAR;
;       LDB(B0, 1, 0); SCHED; LDA(At, 1, 0); STAGE(SA(0, 1), A, lda, aoff, brow + HALF, t + 2);
;       WAIT_L(8); BAR; WAIT_L(0); MMA(0, 0, At, B0); BAR; SCHED;
;       LDB(B1, 1, 1); STAGE(SB(1, 0), Bt, ldb, boff, bcol, t + 3);
;       BAR; WAIT_L(0); MMA(0, 1, At, B1); BAR;
	v_mfma_f32_16x16x32_bf16 v[30:33], v[200:203], v[168:171], v[30:33]
	v_mfma_f32_16x16x32_bf16 v[26:29], v[208:211], v[168:171], v[26:29]
	v_mfma_f32_16x16x32_bf16 v[22:25], v[200:203], v[176:179], v[22:25]
	v_mfma_f32_16x16x32_bf16 v[18:21], v[208:211], v[176:179], v[18:21]
	v_mfma_f32_16x16x32_bf16 v[14:17], v[200:203], v[184:187], v[14:17]
	v_mfma_f32_16x16x32_bf16 v[10:13], v[208:211], v[184:187], v[10:13]
	v_mfma_f32_16x16x32_bf16 v[6:9], v[200:203], v[192:195], v[6:9]
	v_mfma_f32_16x16x32_bf16 v[2:5], v[208:211], v[192:195], v[2:5]
	v_mfma_f32_16x16x32_bf16 v[30:33], v[204:207], v[172:175], v[30:33]
	v_mfma_f32_16x16x32_bf16 v[26:29], v[212:215], v[172:175], v[26:29]
	v_mfma_f32_16x16x32_bf16 v[22:25], v[204:207], v[180:183], v[22:25]
	v_mfma_f32_16x16x32_bf16 v[18:21], v[212:215], v[180:183], v[18:21]
	v_mfma_f32_16x16x32_bf16 v[14:17], v[204:207], v[188:191], v[14:17]
	v_mfma_f32_16x16x32_bf16 v[10:13], v[212:215], v[188:191], v[10:13]
	v_mfma_f32_16x16x32_bf16 v[6:9], v[204:207], v[196:199], v[6:9]
	v_mfma_f32_16x16x32_bf16 v[2:5], v[212:215], v[196:199], v[2:5]
	s_barrier
	ds_read_b128 v[152:155], v222
	ds_read_b128 v[156:159], v222 offset:1024
	ds_read_b128 v[160:163], v222 offset:2048
	ds_read_b128 v[164:167], v222 offset:3072
	ds_read_b128 v[168:171], v143 offset:32768
	ds_read_b128 v[172:175], v143 offset:33792
	ds_read_b128 v[176:179], v143 offset:34816
	ds_read_b128 v[180:183], v143 offset:35840
	ds_read_b128 v[184:187], v143 offset:36864
	ds_read_b128 v[188:191], v143 offset:37888
	ds_read_b128 v[192:195], v143 offset:38912
	ds_read_b128 v[196:199], v143 offset:39936
	s_mov_b32 m0, s43
	s_add_u32 s98, s12, s68
	s_addc_u32 s99, s13, s69
	global_load_lds_dwordx4 v131, s[98:99]
	s_mov_b32 m0, s44
	s_add_u32 s98, s12, s70
	s_addc_u32 s99, s13, s71
	global_load_lds_dwordx4 v131, s[98:99]
	s_waitcnt lgkmcnt(8)
	s_waitcnt vmcnt(10)
	s_barrier
	s_waitcnt lgkmcnt(0)
	v_mfma_f32_16x16x32_bf16 v[126:129], v[152:155], v[168:171], v[126:129]
	v_mfma_f32_16x16x32_bf16 v[122:125], v[160:163], v[168:171], v[122:125]
	v_mfma_f32_16x16x32_bf16 v[118:121], v[152:155], v[176:179], v[118:121]
	v_mfma_f32_16x16x32_bf16 v[114:117], v[160:163], v[176:179], v[114:117]
	v_mfma_f32_16x16x32_bf16 v[110:113], v[152:155], v[184:187], v[110:113]
	v_mfma_f32_16x16x32_bf16 v[106:109], v[160:163], v[184:187], v[106:109]
	v_mfma_f32_16x16x32_bf16 v[102:105], v[152:155], v[192:195], v[102:105]
	v_mfma_f32_16x16x32_bf16 v[98:101], v[160:163], v[192:195], v[98:101]
	v_mfma_f32_16x16x32_bf16 v[126:129], v[156:159], v[172:175], v[126:129]
	v_mfma_f32_16x16x32_bf16 v[122:125], v[164:167], v[172:175], v[122:125]
	v_mfma_f32_16x16x32_bf16 v[118:121], v[156:159], v[180:183], v[118:121]
	v_mfma_f32_16x16x32_bf16 v[114:117], v[164:167], v[180:183], v[114:117]
	v_mfma_f32_16x16x32_bf16 v[110:113], v[156:159], v[188:191], v[110:113]
	v_mfma_f32_16x16x32_bf16 v[106:109], v[164:167], v[188:191], v[106:109]
	v_mfma_f32_16x16x32_bf16 v[102:105], v[156:159], v[196:199], v[102:105]
	v_mfma_f32_16x16x32_bf16 v[98:101], v[164:167], v[196:199], v[98:101]
	s_barrier
	ds_read_b128 v[200:203], v223
	ds_read_b128 v[204:207], v223 offset:1024
	ds_read_b128 v[208:211], v223 offset:2048
	ds_read_b128 v[212:215], v223 offset:3072
	s_mov_b32 m0, s45
	s_add_u32 s98, s14, s94
	s_addc_u32 s99, s15, s95
	global_load_lds_dwordx4 v131, s[98:99]
	s_mov_b32 m0, s46
	s_add_u32 s98, s14, s72
	s_addc_u32 s99, s15, s73
	global_load_lds_dwordx4 v131, s[98:99]
	s_waitcnt vmcnt(10)
	s_barrier
	s_waitcnt lgkmcnt(0)
	v_mfma_f32_16x16x32_bf16 v[94:97], v[200:203], v[168:171], v[94:97]
	v_mfma_f32_16x16x32_bf16 v[90:93], v[208:211], v[168:171], v[90:93]
	v_mfma_f32_16x16x32_bf16 v[86:89], v[200:203], v[176:179], v[86:89]
	v_mfma_f32_16x16x32_bf16 v[82:85], v[208:211], v[176:179], v[82:85]
	v_mfma_f32_16x16x32_bf16 v[78:81], v[200:203], v[184:187], v[78:81]
	v_mfma_f32_16x16x32_bf16 v[74:77], v[208:211], v[184:187], v[74:77]
	v_mfma_f32_16x16x32_bf16 v[70:73], v[200:203], v[192:195], v[70:73]
	v_mfma_f32_16x16x32_bf16 v[66:69], v[208:211], v[192:195], v[66:69]
	v_mfma_f32_16x16x32_bf16 v[94:97], v[204:207], v[172:175], v[94:97]
	v_mfma_f32_16x16x32_bf16 v[90:93], v[212:215], v[172:175], v[90:93]
	v_mfma_f32_16x16x32_bf16 v[86:89], v[204:207], v[180:183], v[86:89]
	v_mfma_f32_16x16x32_bf16 v[82:85], v[212:215], v[180:183], v[82:85]
	v_mfma_f32_16x16x32_bf16 v[78:81], v[204:207], v[188:191], v[78:81]
	v_mfma_f32_16x16x32_bf16 v[74:77], v[212:215], v[188:191], v[74:77]
	v_mfma_f32_16x16x32_bf16 v[70:73], v[204:207], v[196:199], v[70:73]
	v_mfma_f32_16x16x32_bf16 v[66:69], v[212:215], v[196:199], v[66:69]
	s_barrier
; #define LDA(dst, b, h) for (int m = 0; m < 4; ++m) for (int k = 0; k < 2; ++k) \
;     dst[m][k] = *reinterpret_cast<const bf16x8*>((char*)SA(b, h) + a_thr + (m * 2 + k) * 1024)
; #define LDB(dst, b, h) for (int n = 0; n < 2; ++n) for (int k = 0; k < 2; ++k) \
;     dst[n][k] = *reinterpret_cast<const bf16x8*>((char*)SB(b, h) + b_thr + (n * 2 + k) * 1024)
; #define MMA(ai, bj, At, Btf) do { __builtin_amdgcn_s_setprio(1); \
;     for (int m = 0; m < 4; ++m) for (int n = 0; n < 2; ++n) for (int k = 0; k < 2; ++k) \
;       acc[ai][bj][m][n] = __builtin_amdgcn_mfma_f32_16x16x32_bf16(Btf[n][k], At[m][k], acc[ai][bj][m][n], 0, 0, 0); \
;     __builtin_amdgcn_s_setprio(0); } while (0)
; #define WAIT_V(n) asm volatile("s_waitcnt vmcnt(" #n ")" ::: "memory")
; #define WAIT_L(n) asm volatile("s_waitcnt lgkmcnt(" #n ")" ::: "memory")
; #define BAR __builtin_amdgcn_s_barrier()
; #define SCHED __builtin_amdgcn_sched_barrier(0)
; template <bool OVL, bool PANEL = false, class Epi>
; __device__ __forceinline__ void gemm_phase(const bf16_t* __restrict__ A, long lda, const bf16_t* __restrict__ Bt, long ldb, int nM, int nN, int K,
;                                            const Epi& epi, bf16_t* shm, int w0) {
;     ...
;       LDA(At, 1, 1); STAGE(SA(1, 0), A, lda, aoff, brow, t + 3);
;       BAR; WAIT_L(0); MMA(1, 0, At, B0); BAR; SCHED;
;       STAGE(SB(1, 1), Bt, ldb, boff, bcol + HALF, t + 3);
;       WAIT_V(6); BAR; MMA(1, 1, At, B1); BAR;
;     }
;     { LDB(B0, 0, 0); LDA(At, 0, 0); STAGE(SA(1, 1), A, lda, aoff, brow + HALF, nt - 1);
	ds_read_b128 v[168:171], v143 offset:49152
	ds_read_b128 v[172:175], v143 offset:50176
	ds_read_b128 v[176:179], v143 offset:51200
	ds_read_b128 v[180:183], v143 offset:52224
	ds_read_b128 v[184:187], v143 offset:53248
	ds_read_b128 v[188:191], v143 offset:54272
	ds_read_b128 v[192:195], v143 offset:55296
	ds_read_b128 v[196:199], v143 offset:56320
	s_mov_b32 m0, s47
	s_add_u32 s98, s12, s94
	s_addc_u32 s99, s13, s95
	global_load_lds_dwordx4 v131, s[98:99]
	s_mov_b32 m0, s48
	s_add_u32 s98, s12, s72
	s_addc_u32 s99, s13, s73
	global_load_lds_dwordx4 v131, s[98:99]
	s_barrier
	s_waitcnt lgkmcnt(0)
	v_mfma_f32_16x16x32_bf16 v[62:65], v[152:155], v[168:171], v[62:65]
	v_mfma_f32_16x16x32_bf16 v[58:61], v[160:163], v[168:171], v[58:61]
	v_mfma_f32_16x16x32_bf16 v[54:57], v[152:155], v[176:179], v[54:57]
	v_mfma_f32_16x16x32_bf16 v[50:53], v[160:163], v[176:179], v[50:53]
	v_mfma_f32_16x16x32_bf16 v[46:49], v[152:155], v[184:187], v[46:49]
	v_mfma_f32_16x16x32_bf16 v[42:45], v[160:163], v[184:187], v[42:45]
	v_mfma_f32_16x16x32_bf16 v[38:41], v[152:155], v[192:195], v[38:41]
	v_mfma_f32_16x16x32_bf16 v[34:37], v[160:163], v[192:195], v[34:37]
	v_mfma_f32_16x16x32_bf16 v[62:65], v[156:159], v[172:175], v[62:65]
	v_mfma_f32_16x16x32_bf16 v[58:61], v[164:167], v[172:175], v[58:61]
	v_mfma_f32_16x16x32_bf16 v[54:57], v[156:159], v[180:183], v[54:57]
	v_mfma_f32_16x16x32_bf16 v[50:53], v[164:167], v[180:183], v[50:53]
	v_mfma_f32_16x16x32_bf16 v[46:49], v[156:159], v[188:191], v[46:49]
	v_mfma_f32_16x16x32_bf16 v[42:45], v[164:167], v[188:191], v[42:45]
	v_mfma_f32_16x16x32_bf16 v[38:41], v[156:159], v[196:199], v[38:41]
	v_mfma_f32_16x16x32_bf16 v[34:37], v[164:167], v[196:199], v[34:37]
	s_barrier
	s_mov_b32 m0, s49
	s_add_u32 s98, s14, s26
	s_addc_u32 s99, s15, s27
	global_load_lds_dwordx4 v131, s[98:99]
	s_mov_b32 m0, s50
	s_add_u32 s98, s14, s28
	s_addc_u32 s99, s15, s29
	global_load_lds_dwordx4 v131, s[98:99]
	s_add_i32 s21, s21, 2
	s_add_u32 s10, s10, 0x100
	s_addc_u32 s11, s11, 0
	s_cmp_lt_u32 s21, 12
	s_waitcnt vmcnt(10)
	s_barrier
	v_mfma_f32_16x16x32_bf16 v[30:33], v[200:203], v[168:171], v[30:33]
	v_mfma_f32_16x16x32_bf16 v[26:29], v[208:211], v[168:171], v[26:29]
	v_mfma_f32_16x16x32_bf16 v[22:25], v[200:203], v[176:179], v[22:25]
	v_mfma_f32_16x16x32_bf16 v[18:21], v[208:211], v[176:179], v[18:21]
	v_mfma_f32_16x16x32_bf16 v[14:17], v[200:203], v[184:187], v[14:17]
	v_mfma_f32_16x16x32_bf16 v[10:13], v[208:211], v[184:187], v[10:13]
	v_mfma_f32_16x16x32_bf16 v[6:9], v[200:203], v[192:195], v[6:9]
	v_mfma_f32_16x16x32_bf16 v[2:5], v[208:211], v[192:195], v[2:5]
	v_mfma_f32_16x16x32_bf16 v[30:33], v[204:207], v[172:175], v[30:33]
	v_mfma_f32_16x16x32_bf16 v[26:29], v[212:215], v[172:175], v[26:29]
	v_mfma_f32_16x16x32_bf16 v[22:25], v[204:207], v[180:183], v[22:25]
	v_mfma_f32_16x16x32_bf16 v[18:21], v[212:215], v[180:183], v[18:21]
	v_mfma_f32_16x16x32_bf16 v[14:17], v[204:207], v[188:191], v[14:17]
	v_mfma_f32_16x16x32_bf16 v[10:13], v[212:215], v[188:191], v[10:13]
	v_mfma_f32_16x16x32_bf16 v[6:9], v[204:207], v[196:199], v[6:9]
	v_mfma_f32_16x16x32_bf16 v[2:5], v[212:215], v[196:199], v[2:5]
	s_barrier
	s_cbranch_scc1 .LBB0_410
	s_waitcnt vmcnt(6)
	v_add_u32_e32 v212, 16, v140
	v_add_u32_e32 v0, 0x10000, v212
	ds_read_b128 v[144:147], v0
	ds_read_b128 v[152:155], v0 offset:1024
	ds_read_b128 v[156:159], v0 offset:2048
	ds_read_b128 v[160:163], v0 offset:3072
	ds_read_b128 v[164:167], v143
	ds_read_b128 v[168:171], v143 offset:1024
	ds_read_b128 v[172:175], v143 offset:2048
	ds_read_b128 v[176:179], v143 offset:3072
	ds_read_b128 v[180:183], v143 offset:4096
	ds_read_b128 v[184:187], v143 offset:5120
	ds_read_b128 v[188:191], v143 offset:6144
	ds_read_b128 v[192:195], v143 offset:7168
	v_mov_b32_e32 v0, v131
	s_mov_b64 s[0:1], 0x40780
	v_lshl_add_u64 v[148:149], s[8:9], 0, v[0:1]
	v_lshl_add_u64 v[196:197], v[148:149], 0, s[0:1]
	v_readfirstlane_b32 s0, v150
	s_mov_b32 m0, s0
	s_mov_b64 s[0:1], 0x60780
	v_lshl_add_u64 v[148:149], v[148:149], 0, s[0:1]
	v_readfirstlane_b32 s0, v151
	global_load_lds_dwordx4 v[196:197], off
	s_mov_b32 m0, s0
	s_nop 0
	global_load_lds_dwordx4 v[148:149], off
	s_barrier
	s_waitcnt lgkmcnt(0)

; #define MMA(ai, bj, At, Btf) do { __builtin_amdgcn_s_setprio(1); \
;     for (int m = 0; m < 4; ++m) for (int n = 0; n < 2; ++n) for (int k = 0; k < 2; ++k) \
;       acc[ai][bj][m][n] = __builtin_amdgcn_mfma_f32_16x16x32_bf16(Btf[n][k], At[m][k], acc[ai][bj][m][n], 0, 0, 0); \
;     __builtin_amdgcn_s_setprio(0); } while (0)
; #define WAIT_L(n) asm volatile("s_waitcnt lgkmcnt(" #n ")" ::: "memory")
; #define BAR __builtin_amdgcn_s_barrier()
; template <bool OVL, bool PANEL = false, class Epi>
; __device__ __forceinline__ void gemm_phase(const bf16_t* __restrict__ A, long lda, const bf16_t* __restrict__ Bt, long ldb, int nM, int nN, int K,
;                                            const Epi& epi, bf16_t* shm, int w0) {
;     ...
;       BAR; WAIT_L(0); MMA(0, 0, At, B0); BAR;
	v_mfma_f32_16x16x32_bf16 v[126:129], v[144:147], v[164:167], v[126:129]
	v_mfma_f32_16x16x32_bf16 v[122:125], v[156:159], v[164:167], v[122:125]
	v_mfma_f32_16x16x32_bf16 v[118:121], v[144:147], v[172:175], v[118:121]
	v_mfma_f32_16x16x32_bf16 v[114:117], v[156:159], v[172:175], v[114:117]
	v_mfma_f32_16x16x32_bf16 v[110:113], v[144:147], v[180:183], v[110:113]
	v_mfma_f32_16x16x32_bf16 v[106:109], v[156:159], v[180:183], v[106:109]
	v_mfma_f32_16x16x32_bf16 v[102:105], v[144:147], v[188:191], v[102:105]
	v_mfma_f32_16x16x32_bf16 v[126:129], v[152:155], v[168:171], v[126:129]
	v_mfma_f32_16x16x32_bf16 v[122:125], v[160:163], v[168:171], v[122:125]
	v_mfma_f32_16x16x32_bf16 v[118:121], v[152:155], v[176:179], v[118:121]
	v_mfma_f32_16x16x32_bf16 v[114:117], v[160:163], v[176:179], v[114:117]
	v_mfma_f32_16x16x32_bf16 v[110:113], v[152:155], v[184:187], v[110:113]
	v_mfma_f32_16x16x32_bf16 v[106:109], v[160:163], v[184:187], v[106:109]
	v_mfma_f32_16x16x32_bf16 v[102:105], v[152:155], v[192:195], v[102:105]
	v_mfma_f32_16x16x32_bf16 v[98:101], v[156:159], v[188:191], v[98:101]
	v_mfma_f32_16x16x32_bf16 v[148:151], v[160:163], v[192:195], v[98:101]

; #define LDB(dst, b, h) for (int n = 0; n < 2; ++n) for (int k = 0; k < 2; ++k) \
;     dst[n][k] = *reinterpret_cast<const bf16x8*>((char*)SB(b, h) + b_thr + (n * 2 + k) * 1024)
; #define MMA(ai, bj, At, Btf) do { __builtin_amdgcn_s_setprio(1); \
;     for (int m = 0; m < 4; ++m) for (int n = 0; n < 2; ++n) for (int k = 0; k < 2; ++k) \
;       acc[ai][bj][m][n] = __builtin_amdgcn_mfma_f32_16x16x32_bf16(Btf[n][k], At[m][k], acc[ai][bj][m][n], 0, 0, 0); \
;     __builtin_amdgcn_s_setprio(0); } while (0)
; #define WAIT_L(n) asm volatile("s_waitcnt lgkmcnt(" #n ")" ::: "memory")
; #define BAR __builtin_amdgcn_s_barrier()
; template <bool OVL, bool PANEL = false, class Epi>
; __device__ __forceinline__ void gemm_phase(const bf16_t* __restrict__ A, long lda, const bf16_t* __restrict__ Bt, long ldb, int nM, int nN, int K,
;                                            const Epi& epi, bf16_t* shm, int w0) {
;     ...
;       LDB(B1, 0, 1); BAR; WAIT_L(0); MMA(0, 1, At, B1); BAR;
	v_add_u32_e32 v0, 0x14000, v212
	s_barrier
	s_nop 3
	ds_read_b128 v[98:101], v0
	ds_read_b128 v[196:199], v0 offset:1024
	ds_read_b128 v[200:203], v0 offset:2048
	ds_read_b128 v[204:207], v0 offset:3072
	s_barrier
	s_waitcnt lgkmcnt(0)

; #define LDB(dst, b, h) for (int n = 0; n < 2; ++n) for (int k = 0; k < 2; ++k) \
;     dst[n][k] = *reinterpret_cast<const bf16x8*>((char*)SB(b, h) + b_thr + (n * 2 + k) * 1024)
; #define MMA(ai, bj, At, Btf) do { __builtin_amdgcn_s_setprio(1); \
;     for (int m = 0; m < 4; ++m) for (int n = 0; n < 2; ++n) for (int k = 0; k < 2; ++k) \
;       acc[ai][bj][m][n] = __builtin_amdgcn_mfma_f32_16x16x32_bf16(Btf[n][k], At[m][k], acc[ai][bj][m][n], 0, 0, 0); \
;     __builtin_amdgcn_s_setprio(0); } while (0)
; #define WAIT_L(n) asm volatile("s_waitcnt lgkmcnt(" #n ")" ::: "memory")
; #define BAR __builtin_amdgcn_s_barrier()
; template <bool OVL, bool PANEL = false, class Epi>
; __device__ __forceinline__ void gemm_phase(const bf16_t* __restrict__ A, long lda, const bf16_t* __restrict__ Bt, long ldb, int nM, int nN, int K,
;                                            const Epi& epi, bf16_t* shm, int w0) {
;     ...
;       LDB(B1, 0, 1); BAR; WAIT_L(0); MMA(0, 1, At, B1); BAR;
	v_mfma_f32_16x16x32_bf16 v[94:97], v[98:101], v[164:167], v[94:97]
	v_mfma_f32_16x16x32_bf16 v[86:89], v[98:101], v[172:175], v[86:89]
	v_mfma_f32_16x16x32_bf16 v[82:85], v[200:203], v[172:175], v[82:85]
	v_mfma_f32_16x16x32_bf16 v[78:81], v[98:101], v[180:183], v[78:81]
	v_mfma_f32_16x16x32_bf16 v[74:77], v[200:203], v[180:183], v[74:77]
	v_mfma_f32_16x16x32_bf16 v[94:97], v[196:199], v[168:171], v[94:97]
	v_mfma_f32_16x16x32_bf16 v[90:93], v[200:203], v[164:167], v[90:93]
	v_mfma_f32_16x16x32_bf16 v[86:89], v[196:199], v[176:179], v[86:89]
	v_mfma_f32_16x16x32_bf16 v[82:85], v[204:207], v[176:179], v[82:85]
	v_mfma_f32_16x16x32_bf16 v[78:81], v[196:199], v[184:187], v[78:81]
	v_mfma_f32_16x16x32_bf16 v[74:77], v[204:207], v[184:187], v[74:77]
	v_mfma_f32_16x16x32_bf16 v[70:73], v[98:101], v[188:191], v[70:73]
	v_mfma_f32_16x16x32_bf16 v[66:69], v[200:203], v[188:191], v[66:69]
	v_mfma_f32_16x16x32_bf16 v[164:167], v[204:207], v[168:171], v[90:93]
	v_mfma_f32_16x16x32_bf16 v[168:171], v[196:199], v[192:195], v[70:73]
	v_mfma_f32_16x16x32_bf16 v[172:175], v[204:207], v[192:195], v[66:69]

; #define LDA(dst, b, h) for (int m = 0; m < 4; ++m) for (int k = 0; k < 2; ++k) \
;     dst[m][k] = *reinterpret_cast<const bf16x8*>((char*)SA(b, h) + a_thr + (m * 2 + k) * 1024)
; #define MMA(ai, bj, At, Btf) do { __builtin_amdgcn_s_setprio(1); \
;     for (int m = 0; m < 4; ++m) for (int n = 0; n < 2; ++n) for (int k = 0; k < 2; ++k) \
;       acc[ai][bj][m][n] = __builtin_amdgcn_mfma_f32_16x16x32_bf16(Btf[n][k], At[m][k], acc[ai][bj][m][n], 0, 0, 0); \
;     __builtin_amdgcn_s_setprio(0); } while (0)
; #define WAIT_V(n) asm volatile("s_waitcnt vmcnt(" #n ")" ::: "memory")
; #define WAIT_L(n) asm volatile("s_waitcnt lgkmcnt(" #n ")" ::: "memory")
; #define BAR __builtin_amdgcn_s_barrier()
; template <bool OVL, bool PANEL = false, class Epi>
; __device__ __forceinline__ void gemm_phase(const bf16_t* __restrict__ A, long lda, const bf16_t* __restrict__ Bt, long ldb, int nM, int nN, int K,
;                                            const Epi& epi, bf16_t* shm, int w0) {
;     ...
;       LDA(At, 0, 1); WAIT_V(4); BAR; WAIT_L(0); MMA(1, 0, At, B0); MMA(1, 1, At, B1); BAR; }
	s_barrier
	s_nop 2
	ds_read_b128 v[66:69], v143 offset:16384
	ds_read_b128 v[70:73], v143 offset:17408
	ds_read_b128 v[90:93], v143 offset:18432
	ds_read_b128 v[176:179], v143 offset:19456
	ds_read_b128 v[180:183], v143 offset:20480
	ds_read_b128 v[184:187], v143 offset:21504
	ds_read_b128 v[188:191], v143 offset:22528
	ds_read_b128 v[192:195], v143 offset:23552
	s_waitcnt vmcnt(4)
	s_barrier
	s_waitcnt lgkmcnt(0)

; #define LDA(dst, b, h) for (int m = 0; m < 4; ++m) for (int k = 0; k < 2; ++k) \
;     dst[m][k] = *reinterpret_cast<const bf16x8*>((char*)SA(b, h) + a_thr + (m * 2 + k) * 1024)
; #define MMA(ai, bj, At, Btf) do { __builtin_amdgcn_s_setprio(1); \
;     for (int m = 0; m < 4; ++m) for (int n = 0; n < 2; ++n) for (int k = 0; k < 2; ++k) \
;       acc[ai][bj][m][n] = __builtin_amdgcn_mfma_f32_16x16x32_bf16(Btf[n][k], At[m][k], acc[ai][bj][m][n], 0, 0, 0); \
;     __builtin_amdgcn_s_setprio(0); } while (0)
; #define WAIT_V(n) asm volatile("s_waitcnt vmcnt(" #n ")" ::: "memory")
; #define WAIT_L(n) asm volatile("s_waitcnt lgkmcnt(" #n ")" ::: "memory")
; #define BAR __builtin_amdgcn_s_barrier()
; template <bool OVL, bool PANEL = false, class Epi>
; __device__ __forceinline__ void gemm_phase(const bf16_t* __restrict__ A, long lda, const bf16_t* __restrict__ Bt, long ldb, int nM, int nN, int K,
;                                            const Epi& epi, bf16_t* shm, int w0) {
;     ...
;       LDA(At, 0, 1); WAIT_V(4); BAR; WAIT_L(0); MMA(1, 0, At, B0); MMA(1, 1, At, B1); BAR; }
	v_mfma_f32_16x16x32_bf16 v[62:65], v[144:147], v[66:69], v[62:65]
	v_mfma_f32_16x16x32_bf16 v[54:57], v[144:147], v[90:93], v[54:57]
	v_mfma_f32_16x16x32_bf16 v[50:53], v[156:159], v[90:93], v[50:53]
	v_mfma_f32_16x16x32_bf16 v[46:49], v[144:147], v[180:183], v[46:49]
	v_mfma_f32_16x16x32_bf16 v[42:45], v[156:159], v[180:183], v[42:45]
	v_mfma_f32_16x16x32_bf16 v[38:41], v[144:147], v[188:191], v[38:41]
	v_mfma_f32_16x16x32_bf16 v[34:37], v[156:159], v[188:191], v[34:37]
	v_mfma_f32_16x16x32_bf16 v[62:65], v[152:155], v[70:73], v[62:65]
	v_mfma_f32_16x16x32_bf16 v[58:61], v[156:159], v[66:69], v[58:61]
	v_mfma_f32_16x16x32_bf16 v[54:57], v[152:155], v[176:179], v[54:57]
	v_mfma_f32_16x16x32_bf16 v[50:53], v[160:163], v[176:179], v[50:53]
	v_mfma_f32_16x16x32_bf16 v[46:49], v[152:155], v[184:187], v[46:49]
	v_mfma_f32_16x16x32_bf16 v[42:45], v[160:163], v[184:187], v[42:45]
	v_mfma_f32_16x16x32_bf16 v[38:41], v[152:155], v[192:195], v[38:41]
	v_mfma_f32_16x16x32_bf16 v[34:37], v[160:163], v[192:195], v[34:37]
	v_mfma_f32_16x16x32_bf16 v[208:211], v[160:163], v[70:73], v[58:61]


; #define LDA(dst, b, h) for (int m = 0; m < 4; ++m) for (int k = 0; k < 2; ++k) \
;     dst[m][k] = *reinterpret_cast<const bf16x8*>((char*)SA(b, h) + a_thr + (m * 2 + k) * 1024)
; #define MMA(ai, bj, At, Btf) do { __builtin_amdgcn_s_setprio(1); \
;     for (int m = 0; m < 4; ++m) for (int n = 0; n < 2; ++n) for (int k = 0; k < 2; ++k) \
;       acc[ai][bj][m][n] = __builtin_amdgcn_mfma_f32_16x16x32_bf16(Btf[n][k], At[m][k], acc[ai][bj][m][n], 0, 0, 0); \
;     __builtin_amdgcn_s_setprio(0); } while (0)
; #define WAIT_V(n) asm volatile("s_waitcnt vmcnt(" #n ")" ::: "memory")
; #define WAIT_L(n) asm volatile("s_waitcnt lgkmcnt(" #n ")" ::: "memory")
; #define BAR __builtin_amdgcn_s_barrier()
; template <bool OVL, bool PANEL = false, class Epi>
; __device__ __forceinline__ void gemm_phase(const bf16_t* __restrict__ A, long lda, const bf16_t* __restrict__ Bt, long ldb, int nM, int nN, int K,
;                                            const Epi& epi, bf16_t* shm, int w0) {
;     ...
;       LDA(At, 0, 1); WAIT_V(4); BAR; WAIT_L(0); MMA(1, 0, At, B0); MMA(1, 1, At, B1); BAR; }
	v_mfma_f32_16x16x32_bf16 v[30:33], v[98:101], v[66:69], v[30:33]
	v_mfma_f32_16x16x32_bf16 v[26:29], v[200:203], v[66:69], v[26:29]
	v_mfma_f32_16x16x32_bf16 v[22:25], v[98:101], v[90:93], v[22:25]
	v_mfma_f32_16x16x32_bf16 v[18:21], v[200:203], v[90:93], v[18:21]
	v_mfma_f32_16x16x32_bf16 v[14:17], v[98:101], v[180:183], v[14:17]
	v_mfma_f32_16x16x32_bf16 v[10:13], v[200:203], v[180:183], v[10:13]
	v_mfma_f32_16x16x32_bf16 v[6:9], v[98:101], v[188:191], v[6:9]
	v_mfma_f32_16x16x32_bf16 v[2:5], v[200:203], v[188:191], v[2:5]
	v_mfma_f32_16x16x32_bf16 v[30:33], v[196:199], v[70:73], v[30:33]
	v_mfma_f32_16x16x32_bf16 v[26:29], v[204:207], v[70:73], v[26:29]
	v_mfma_f32_16x16x32_bf16 v[22:25], v[196:199], v[176:179], v[22:25]
	v_mfma_f32_16x16x32_bf16 v[18:21], v[204:207], v[176:179], v[18:21]
	v_mfma_f32_16x16x32_bf16 v[14:17], v[196:199], v[184:187], v[14:17]
	v_mfma_f32_16x16x32_bf16 v[10:13], v[204:207], v[184:187], v[10:13]
	v_mfma_f32_16x16x32_bf16 v[6:9], v[196:199], v[192:195], v[6:9]
	v_mfma_f32_16x16x32_bf16 v[2:5], v[204:207], v[192:195], v[2:5]

; #define LDA(dst, b, h) for (int m = 0; m < 4; ++m) for (int k = 0; k < 2; ++k) \
;     dst[m][k] = *reinterpret_cast<const bf16x8*>((char*)SA(b, h) + a_thr + (m * 2 + k) * 1024)
; #define LDB(dst, b, h) for (int n = 0; n < 2; ++n) for (int k = 0; k < 2; ++k) \
;     dst[n][k] = *reinterpret_cast<const bf16x8*>((char*)SB(b, h) + b_thr + (n * 2 + k) * 1024)
; #define MMA(ai, bj, At, Btf) do { __builtin_amdgcn_s_setprio(1); \
;     for (int m = 0; m < 4; ++m) for (int n = 0; n < 2; ++n) for (int k = 0; k < 2; ++k) \
;       acc[ai][bj][m][n] = __builtin_amdgcn_mfma_f32_16x16x32_bf16(Btf[n][k], At[m][k], acc[ai][bj][m][n], 0, 0, 0); \
;     __builtin_amdgcn_s_setprio(0); } while (0)
; #define WAIT_V(n) asm volatile("s_waitcnt vmcnt(" #n ")" ::: "memory")
; #define WAIT_L(n) asm volatile("s_waitcnt lgkmcnt(" #n ")" ::: "memory")
; #define BAR __builtin_amdgcn_s_barrier()
; template <bool OVL, bool PANEL = false, class Epi>
; __device__ __forceinline__ void gemm_phase(const bf16_t* __restrict__ A, long lda, const bf16_t* __restrict__ Bt, long ldb, int nM, int nN, int K,
;                                            const Epi& epi, bf16_t* shm, int w0) {
;     ...
;     { LDB(B0, 1, 0); LDA(At, 1, 0); WAIT_V(2); BAR; WAIT_L(0); MMA(0, 0, At, B0); BAR;
	v_add_u32_e32 v0, 0x18000, v212
	s_barrier
	ds_read_b128 v[144:147], v0
	ds_read_b128 v[152:155], v0 offset:1024
	ds_read_b128 v[156:159], v0 offset:2048
	ds_read_b128 v[160:163], v0 offset:3072
	ds_read_b128 v[58:61], v143 offset:32768
	ds_read_b128 v[66:69], v143 offset:33792
	ds_read_b128 v[70:73], v143 offset:34816
	ds_read_b128 v[176:179], v143 offset:35840
	ds_read_b128 v[180:183], v143 offset:36864
	ds_read_b128 v[184:187], v143 offset:37888
	ds_read_b128 v[188:191], v143 offset:38912
	ds_read_b128 v[192:195], v143 offset:39936
	s_waitcnt vmcnt(2)
	s_barrier
	s_waitcnt lgkmcnt(0)

; #define LDA(dst, b, h) for (int m = 0; m < 4; ++m) for (int k = 0; k < 2; ++k) \
;     dst[m][k] = *reinterpret_cast<const bf16x8*>((char*)SA(b, h) + a_thr + (m * 2 + k) * 1024)
; #define LDB(dst, b, h) for (int n = 0; n < 2; ++n) for (int k = 0; k < 2; ++k) \
;     dst[n][k] = *reinterpret_cast<const bf16x8*>((char*)SB(b, h) + b_thr + (n * 2 + k) * 1024)
; #define MMA(ai, bj, At, Btf) do { __builtin_amdgcn_s_setprio(1); \
;     for (int m = 0; m < 4; ++m) for (int n = 0; n < 2; ++n) for (int k = 0; k < 2; ++k) \
;       acc[ai][bj][m][n] = __builtin_amdgcn_mfma_f32_16x16x32_bf16(Btf[n][k], At[m][k], acc[ai][bj][m][n], 0, 0, 0); \
;     __builtin_amdgcn_s_setprio(0); } while (0)
; #define WAIT_V(n) asm volatile("s_waitcnt vmcnt(" #n ")" ::: "memory")
; #define WAIT_L(n) asm volatile("s_waitcnt lgkmcnt(" #n ")" ::: "memory")
; #define BAR __builtin_amdgcn_s_barrier()
; template <bool OVL, bool PANEL = false, class Epi>
; __device__ __forceinline__ void gemm_phase(const bf16_t* __restrict__ A, long lda, const bf16_t* __restrict__ Bt, long ldb, int nM, int nN, int K,
;                                            const Epi& epi, bf16_t* shm, int w0) {
;     ...
;     { LDB(B0, 1, 0); LDA(At, 1, 0); WAIT_V(2); BAR; WAIT_L(0); MMA(0, 0, At, B0); BAR;
	v_mfma_f32_16x16x32_bf16 v[90:93], v[144:147], v[58:61], v[126:129]
	v_mfma_f32_16x16x32_bf16 v[126:129], v[152:155], v[66:69], v[90:93]
	v_mfma_f32_16x16x32_bf16 v[90:93], v[156:159], v[58:61], v[122:125]
	v_mfma_f32_16x16x32_bf16 v[122:125], v[160:163], v[66:69], v[90:93]
	v_mfma_f32_16x16x32_bf16 v[90:93], v[144:147], v[70:73], v[118:121]
	v_mfma_f32_16x16x32_bf16 v[118:121], v[152:155], v[176:179], v[90:93]
	v_mfma_f32_16x16x32_bf16 v[90:93], v[156:159], v[70:73], v[114:117]
	v_mfma_f32_16x16x32_bf16 v[114:117], v[160:163], v[176:179], v[90:93]
	v_mfma_f32_16x16x32_bf16 v[90:93], v[144:147], v[180:183], v[110:113]
	v_mfma_f32_16x16x32_bf16 v[110:113], v[152:155], v[184:187], v[90:93]
	v_mfma_f32_16x16x32_bf16 v[90:93], v[156:159], v[180:183], v[106:109]
	v_mfma_f32_16x16x32_bf16 v[106:109], v[160:163], v[184:187], v[90:93]
	v_mfma_f32_16x16x32_bf16 v[90:93], v[144:147], v[188:191], v[102:105]
	v_mfma_f32_16x16x32_bf16 v[98:101], v[152:155], v[192:195], v[90:93]
	v_mfma_f32_16x16x32_bf16 v[90:93], v[156:159], v[188:191], v[148:151]
	v_mfma_f32_16x16x32_bf16 v[90:93], v[160:163], v[192:195], v[90:93]

; #define LDB(dst, b, h) for (int n = 0; n < 2; ++n) for (int k = 0; k < 2; ++k) \
;     dst[n][k] = *reinterpret_cast<const bf16x8*>((char*)SB(b, h) + b_thr + (n * 2 + k) * 1024)
; #define MMA(ai, bj, At, Btf) do { __builtin_amdgcn_s_setprio(1); \
;     for (int m = 0; m < 4; ++m) for (int n = 0; n < 2; ++n) for (int k = 0; k < 2; ++k) \
;       acc[ai][bj][m][n] = __builtin_amdgcn_mfma_f32_16x16x32_bf16(Btf[n][k], At[m][k], acc[ai][bj][m][n], 0, 0, 0); \
;     __builtin_amdgcn_s_setprio(0); } while (0)
; #define WAIT_V(n) asm volatile("s_waitcnt vmcnt(" #n ")" ::: "memory")
; #define WAIT_L(n) asm volatile("s_waitcnt lgkmcnt(" #n ")" ::: "memory")
; #define BAR __builtin_amdgcn_s_barrier()
; template <bool OVL, bool PANEL = false, class Epi>
; __device__ __forceinline__ void gemm_phase(const bf16_t* __restrict__ A, long lda, const bf16_t* __restrict__ Bt, long ldb, int nM, int nN, int K,
;                                            const Epi& epi, bf16_t* shm, int w0) {
;     ...
;       LDB(B1, 1, 1); WAIT_V(0); BAR; WAIT_L(0); MMA(0, 1, At, B1); BAR;
	v_add_u32_e32 v0, 0x1c000, v212
	s_barrier
	ds_read_b128 v[148:151], v0
	ds_read_b128 v[196:199], v0 offset:1024
	ds_read_b128 v[200:203], v0 offset:2048
	ds_read_b128 v[204:207], v0 offset:3072
	s_waitcnt vmcnt(0)
	s_barrier
	s_waitcnt lgkmcnt(0)

; #define LDB(dst, b, h) for (int n = 0; n < 2; ++n) for (int k = 0; k < 2; ++k) \
;     dst[n][k] = *reinterpret_cast<const bf16x8*>((char*)SB(b, h) + b_thr + (n * 2 + k) * 1024)
; #define MMA(ai, bj, At, Btf) do { __builtin_amdgcn_s_setprio(1); \
;     for (int m = 0; m < 4; ++m) for (int n = 0; n < 2; ++n) for (int k = 0; k < 2; ++k) \
;       acc[ai][bj][m][n] = __builtin_amdgcn_mfma_f32_16x16x32_bf16(Btf[n][k], At[m][k], acc[ai][bj][m][n], 0, 0, 0); \
;     __builtin_amdgcn_s_setprio(0); } while (0)
; #define WAIT_V(n) asm volatile("s_waitcnt vmcnt(" #n ")" ::: "memory")
; #define WAIT_L(n) asm volatile("s_waitcnt lgkmcnt(" #n ")" ::: "memory")
; #define BAR __builtin_amdgcn_s_barrier()
; template <bool OVL, bool PANEL = false, class Epi>
; __device__ __forceinline__ void gemm_phase(const bf16_t* __restrict__ A, long lda, const bf16_t* __restrict__ Bt, long ldb, int nM, int nN, int K,
;                                            const Epi& epi, bf16_t* shm, int w0) {
;     ...
;       LDB(B1, 1, 1); WAIT_V(0); BAR; WAIT_L(0); MMA(0, 1, At, B1); BAR;
	v_mfma_f32_16x16x32_bf16 v[94:97], v[148:151], v[58:61], v[94:97]
	v_mfma_f32_16x16x32_bf16 v[58:61], v[200:203], v[58:61], v[164:167]
	v_mfma_f32_16x16x32_bf16 v[102:105], v[196:199], v[66:69], v[94:97]
	v_mfma_f32_16x16x32_bf16 v[94:97], v[204:207], v[66:69], v[58:61]
	v_mfma_f32_16x16x32_bf16 v[58:61], v[148:151], v[70:73], v[86:89]
	v_mfma_f32_16x16x32_bf16 v[86:89], v[196:199], v[176:179], v[58:61]
	v_mfma_f32_16x16x32_bf16 v[58:61], v[200:203], v[70:73], v[82:85]
	v_mfma_f32_16x16x32_bf16 v[82:85], v[204:207], v[176:179], v[58:61]
	v_mfma_f32_16x16x32_bf16 v[58:61], v[148:151], v[180:183], v[78:81]
	v_mfma_f32_16x16x32_bf16 v[78:81], v[196:199], v[184:187], v[58:61]
	v_mfma_f32_16x16x32_bf16 v[58:61], v[200:203], v[180:183], v[74:77]
	v_mfma_f32_16x16x32_bf16 v[70:73], v[204:207], v[184:187], v[58:61]
	v_mfma_f32_16x16x32_bf16 v[58:61], v[148:151], v[188:191], v[168:171]
	v_mfma_f32_16x16x32_bf16 v[66:69], v[196:199], v[192:195], v[58:61]
	v_mfma_f32_16x16x32_bf16 v[58:61], v[200:203], v[188:191], v[172:175]
	v_mfma_f32_16x16x32_bf16 v[58:61], v[204:207], v[192:195], v[58:61]

; #define LDA(dst, b, h) for (int m = 0; m < 4; ++m) for (int k = 0; k < 2; ++k) \
;     dst[m][k] = *reinterpret_cast<const bf16x8*>((char*)SA(b, h) + a_thr + (m * 2 + k) * 1024)
; #define MMA(ai, bj, At, Btf) do { __builtin_amdgcn_s_setprio(1); \
;     for (int m = 0; m < 4; ++m) for (int n = 0; n < 2; ++n) for (int k = 0; k < 2; ++k) \
;       acc[ai][bj][m][n] = __builtin_amdgcn_mfma_f32_16x16x32_bf16(Btf[n][k], At[m][k], acc[ai][bj][m][n], 0, 0, 0); \
;     __builtin_amdgcn_s_setprio(0); } while (0)
; #define WAIT_L(n) asm volatile("s_waitcnt lgkmcnt(" #n ")" ::: "memory")
; #define BAR __builtin_amdgcn_s_barrier()
; template <bool OVL, bool PANEL = false, class Epi>
; __device__ __forceinline__ void gemm_phase(const bf16_t* __restrict__ A, long lda, const bf16_t* __restrict__ Bt, long ldb, int nM, int nN, int K,
;                                            const Epi& epi, bf16_t* shm, int w0) {
;     ...
;       LDA(At, 1, 1); BAR; WAIT_L(0); MMA(1, 0, At, B0); MMA(1, 1, At, B1); BAR; }
	s_barrier
	ds_read_b128 v[164:167], v143 offset:49152
	ds_read_b128 v[168:171], v143 offset:50176
	ds_read_b128 v[172:175], v143 offset:51200
	ds_read_b128 v[176:179], v143 offset:52224
	ds_read_b128 v[180:183], v143 offset:53248
	ds_read_b128 v[184:187], v143 offset:54272
	ds_read_b128 v[188:191], v143 offset:55296
	ds_read_b128 v[192:195], v143 offset:56320
	s_barrier
	s_waitcnt lgkmcnt(0)

; #define LDA(dst, b, h) for (int m = 0; m < 4; ++m) for (int k = 0; k < 2; ++k) \
;     dst[m][k] = *reinterpret_cast<const bf16x8*>((char*)SA(b, h) + a_thr + (m * 2 + k) * 1024)
; #define MMA(ai, bj, At, Btf) do { __builtin_amdgcn_s_setprio(1); \
;     for (int m = 0; m < 4; ++m) for (int n = 0; n < 2; ++n) for (int k = 0; k < 2; ++k) \
;       acc[ai][bj][m][n] = __builtin_amdgcn_mfma_f32_16x16x32_bf16(Btf[n][k], At[m][k], acc[ai][bj][m][n], 0, 0, 0); \
;     __builtin_amdgcn_s_setprio(0); } while (0)
; #define WAIT_L(n) asm volatile("s_waitcnt lgkmcnt(" #n ")" ::: "memory")
; #define BAR __builtin_amdgcn_s_barrier()
; template <bool OVL, bool PANEL = false, class Epi>
; __device__ __forceinline__ void gemm_phase(const bf16_t* __restrict__ A, long lda, const bf16_t* __restrict__ Bt, long ldb, int nM, int nN, int K,
;                                            const Epi& epi, bf16_t* shm, int w0) {
;     ...
;       LDA(At, 1, 1); BAR; WAIT_L(0); MMA(1, 0, At, B0); MMA(1, 1, At, B1); BAR; }
	v_mfma_f32_16x16x32_bf16 v[62:65], v[144:147], v[164:167], v[62:65]
	v_mfma_f32_16x16x32_bf16 v[74:77], v[152:155], v[168:171], v[62:65]
	v_mfma_f32_16x16x32_bf16 v[62:65], v[156:159], v[164:167], v[208:211]
	v_mfma_f32_16x16x32_bf16 v[54:57], v[144:147], v[172:175], v[54:57]
	v_mfma_f32_16x16x32_bf16 v[50:53], v[156:159], v[172:175], v[50:53]
	v_mfma_f32_16x16x32_bf16 v[46:49], v[144:147], v[180:183], v[46:49]
	v_mfma_f32_16x16x32_bf16 v[42:45], v[156:159], v[180:183], v[42:45]
	v_mfma_f32_16x16x32_bf16 v[38:41], v[144:147], v[188:191], v[38:41]
	v_mfma_f32_16x16x32_bf16 v[34:37], v[156:159], v[188:191], v[34:37]
	v_mfma_f32_16x16x32_bf16 v[62:65], v[160:163], v[168:171], v[62:65]
	v_mfma_f32_16x16x32_bf16 v[54:57], v[152:155], v[176:179], v[54:57]
	v_mfma_f32_16x16x32_bf16 v[50:53], v[160:163], v[176:179], v[50:53]
	v_mfma_f32_16x16x32_bf16 v[46:49], v[152:155], v[184:187], v[46:49]
	v_mfma_f32_16x16x32_bf16 v[42:45], v[160:163], v[184:187], v[42:45]
	v_mfma_f32_16x16x32_bf16 v[38:41], v[152:155], v[192:195], v[38:41]
	v_mfma_f32_16x16x32_bf16 v[34:37], v[160:163], v[192:195], v[34:37]


; #define LDA(dst, b, h) for (int m = 0; m < 4; ++m) for (int k = 0; k < 2; ++k) \
;     dst[m][k] = *reinterpret_cast<const bf16x8*>((char*)SA(b, h) + a_thr + (m * 2 + k) * 1024)
; #define MMA(ai, bj, At, Btf) do { __builtin_amdgcn_s_setprio(1); \
;     for (int m = 0; m < 4; ++m) for (int n = 0; n < 2; ++n) for (int k = 0; k < 2; ++k) \
;       acc[ai][bj][m][n] = __builtin_amdgcn_mfma_f32_16x16x32_bf16(Btf[n][k], At[m][k], acc[ai][bj][m][n], 0, 0, 0); \
;     __builtin_amdgcn_s_setprio(0); } while (0)
; #define WAIT_L(n) asm volatile("s_waitcnt lgkmcnt(" #n ")" ::: "memory")
; #define BAR __builtin_amdgcn_s_barrier()
; template <bool OVL, bool PANEL = false, class Epi>
; __device__ __forceinline__ void gemm_phase(const bf16_t* __restrict__ A, long lda, const bf16_t* __restrict__ Bt, long ldb, int nM, int nN, int K,
;                                            const Epi& epi, bf16_t* shm, int w0) {
;     ...
;       LDA(At, 1, 1); BAR; WAIT_L(0); MMA(1, 0, At, B0); MMA(1, 1, At, B1); BAR; }
	v_mfma_f32_16x16x32_bf16 v[30:33], v[148:151], v[164:167], v[30:33]
	v_mfma_f32_16x16x32_bf16 v[26:29], v[200:203], v[164:167], v[26:29]
	v_mfma_f32_16x16x32_bf16 v[22:25], v[148:151], v[172:175], v[22:25]
	v_mfma_f32_16x16x32_bf16 v[18:21], v[200:203], v[172:175], v[18:21]
	v_mfma_f32_16x16x32_bf16 v[14:17], v[148:151], v[180:183], v[14:17]
	v_mfma_f32_16x16x32_bf16 v[10:13], v[200:203], v[180:183], v[10:13]
	v_mfma_f32_16x16x32_bf16 v[6:9], v[148:151], v[188:191], v[6:9]
	v_mfma_f32_16x16x32_bf16 v[2:5], v[200:203], v[188:191], v[2:5]
	v_mfma_f32_16x16x32_bf16 v[30:33], v[196:199], v[168:171], v[30:33]
	v_mfma_f32_16x16x32_bf16 v[26:29], v[204:207], v[168:171], v[26:29]
	v_mfma_f32_16x16x32_bf16 v[22:25], v[196:199], v[176:179], v[22:25]
	v_mfma_f32_16x16x32_bf16 v[18:21], v[204:207], v[176:179], v[18:21]
	v_mfma_f32_16x16x32_bf16 v[14:17], v[196:199], v[184:187], v[14:17]
	v_mfma_f32_16x16x32_bf16 v[10:13], v[204:207], v[184:187], v[10:13]
	v_mfma_f32_16x16x32_bf16 v[6:9], v[196:199], v[192:195], v[6:9]
	v_mfma_f32_16x16x32_bf16 v[2:5], v[204:207], v[192:195], v[2:5]

; #define LDA(dst, b, h) for (int m = 0; m < 4; ++m) for (int k = 0; k < 2; ++k) \
;     dst[m][k] = *reinterpret_cast<const bf16x8*>((char*)SA(b, h) + a_thr + (m * 2 + k) * 1024)
; #define MMA(ai, bj, At, Btf) do { __builtin_amdgcn_s_setprio(1); \
;     for (int m = 0; m < 4; ++m) for (int n = 0; n < 2; ++n) for (int k = 0; k < 2; ++k) \
;       acc[ai][bj][m][n] = __builtin_amdgcn_mfma_f32_16x16x32_bf16(Btf[n][k], At[m][k], acc[ai][bj][m][n], 0, 0, 0); \
;     __builtin_amdgcn_s_setprio(0); } while (0)
; #define WAIT_L(n) asm volatile("s_waitcnt lgkmcnt(" #n ")" ::: "memory")
; #define BAR __builtin_amdgcn_s_barrier()
; template <bool OVL, bool PANEL = false, class Epi>
; __device__ __forceinline__ void gemm_phase(const bf16_t* __restrict__ A, long lda, const bf16_t* __restrict__ Bt, long ldb, int nM, int nN, int K,
;                                            const Epi& epi, bf16_t* shm, int w0) {
;     ...
;       LDA(At, 1, 1); BAR; WAIT_L(0); MMA(1, 0, At, B0); MMA(1, 1, At, B1); BAR; }
;     if (wr == 0) BAR;
	s_barrier
	s_and_saveexec_b64 s[0:1], s[6:7]
	s_cbranch_execz .LBB0_413
	s_barrier

; #define LDA(dst, b, h) for (int m = 0; m < 4; ++m) for (int k = 0; k < 2; ++k) \
;     dst[m][k] = *reinterpret_cast<const bf16x8*>((char*)SA(b, h) + a_thr + (m * 2 + k) * 1024)
; #define LDB(dst, b, h) for (int n = 0; n < 2; ++n) for (int k = 0; k < 2; ++k) \
;     dst[n][k] = *reinterpret_cast<const bf16x8*>((char*)SB(b, h) + b_thr + (n * 2 + k) * 1024)
; #define MMA(ai, bj, At, Btf) do { __builtin_amdgcn_s_setprio(1); \
;     for (int m = 0; m < 4; ++m) for (int n = 0; n < 2; ++n) for (int k = 0; k < 2; ++k) \
;       acc[ai][bj][m][n] = __builtin_amdgcn_mfma_f32_16x16x32_bf16(Btf[n][k], At[m][k], acc[ai][bj][m][n], 0, 0, 0); \
;     __builtin_amdgcn_s_setprio(0); } while (0)
; #define WAIT_V(n) asm volatile("s_waitcnt vmcnt(" #n ")" ::: "memory")
; #define WAIT_L(n) asm volatile("s_waitcnt lgkmcnt(" #n ")" ::: "memory")
; #define BAR __builtin_amdgcn_s_barrier()
; #define SCHED __builtin_amdgcn_sched_barrier(0)
; template <bool OVL, bool PANEL = false, class Epi>
; __device__ __forceinline__ void gemm_phase(const bf16_t* __restrict__ A, long lda, const bf16_t* __restrict__ Bt, long ldb, int nM, int nN, int K,
;                                            const Epi& epi, bf16_t* shm, int w0) {
;     ...
;       LDB(B0, 0, 0); SCHED; LDA(At, 0, 0); STAGE(SA(1, 1), A, lda, aoff, brow + HALF, t + 1);
;       WAIT_L(8); BAR; WAIT_L(0); MMA(0, 0, At, B0); BAR; SCHED;
;       LDB(B1, 0, 1); STAGE(SB(0, 0), Bt, ldb, boff, bcol, t + 2);
;       BAR; WAIT_L(0); MMA(0, 1, At, B1); BAR;
;       LDA(At, 0, 1); STAGE(SA(0, 0), A, lda, aoff, brow, t + 2);
;       BAR; WAIT_L(0); MMA(1, 0, At, B0); BAR; SCHED;
;       STAGE(SB(0, 1), Bt, ldb, boff, bcol + HALF, t + 2);
;       WAIT_V(6); BAR; MMA(1, 1, At, B1); BAR;
.LBB0_472:
	ds_read_b128 v[138:141], v206
	ds_read_b128 v[142:145], v206 offset:1024
	ds_read_b128 v[146:149], v206 offset:2048
	ds_read_b128 v[150:153], v206 offset:3072
	s_add_u32 vcc_lo, s8, s80
	s_addc_u32 vcc_hi, s9, s81
	ds_read_b128 v[154:157], v241
	ds_read_b128 v[158:161], v241 offset:1024
	ds_read_b128 v[162:165], v241 offset:2048
	ds_read_b128 v[166:169], v241 offset:3072
	ds_read_b128 v[170:173], v241 offset:4096
	ds_read_b128 v[174:177], v241 offset:5120
	ds_read_b128 v[178:181], v241 offset:6144
	ds_read_b128 v[182:185], v241 offset:7168
	s_mov_b32 m0, s16
	s_add_u32 s98, vcc_lo, s12
	s_addc_u32 s99, vcc_hi, s13
	global_load_lds_dwordx4 v221, s[98:99]
	s_mov_b32 m0, s32
	s_add_u32 s98, vcc_lo, s36
	s_addc_u32 s99, vcc_hi, s37
	global_load_lds_dwordx4 v221, s[98:99]
	s_waitcnt lgkmcnt(8)
	s_waitcnt vmcnt(10)
	s_barrier
	s_waitcnt lgkmcnt(0)
	v_mfma_f32_16x16x32_bf16 v[126:129], v[138:141], v[154:157], v[126:129]
	v_mfma_f32_16x16x32_bf16 v[122:125], v[146:149], v[154:157], v[122:125]
	v_mfma_f32_16x16x32_bf16 v[118:121], v[138:141], v[162:165], v[118:121]
	v_mfma_f32_16x16x32_bf16 v[114:117], v[146:149], v[162:165], v[114:117]
	v_mfma_f32_16x16x32_bf16 v[110:113], v[138:141], v[170:173], v[110:113]
	v_mfma_f32_16x16x32_bf16 v[106:109], v[146:149], v[170:173], v[106:109]
	v_mfma_f32_16x16x32_bf16 v[102:105], v[138:141], v[178:181], v[102:105]
	v_mfma_f32_16x16x32_bf16 v[98:101], v[146:149], v[178:181], v[98:101]
	v_mfma_f32_16x16x32_bf16 v[126:129], v[142:145], v[158:161], v[126:129]
	v_mfma_f32_16x16x32_bf16 v[122:125], v[150:153], v[158:161], v[122:125]
	v_mfma_f32_16x16x32_bf16 v[118:121], v[142:145], v[166:169], v[118:121]
	v_mfma_f32_16x16x32_bf16 v[114:117], v[150:153], v[166:169], v[114:117]
	v_mfma_f32_16x16x32_bf16 v[110:113], v[142:145], v[174:177], v[110:113]
	v_mfma_f32_16x16x32_bf16 v[106:109], v[150:153], v[174:177], v[106:109]
	v_mfma_f32_16x16x32_bf16 v[102:105], v[142:145], v[182:185], v[102:105]
	v_mfma_f32_16x16x32_bf16 v[98:101], v[150:153], v[182:185], v[98:101]
	s_barrier
	s_add_u32 s0, s6, s80
	ds_read_b128 v[186:189], v207
	ds_read_b128 v[190:193], v207 offset:1024
	ds_read_b128 v[194:197], v207 offset:2048
	ds_read_b128 v[198:201], v207 offset:3072
	s_addc_u32 s1, s7, s81
	s_mov_b32 m0, s44
	s_add_u32 s98, s0, s34
	s_addc_u32 s99, s1, s35
	global_load_lds_dwordx4 v221, s[98:99]
	s_mov_b32 m0, s45
	s_add_u32 s98, s0, s64
	s_addc_u32 s99, s1, s65
	global_load_lds_dwordx4 v221, s[98:99]
	s_waitcnt vmcnt(10)
	s_barrier
	s_waitcnt lgkmcnt(0)
	v_mfma_f32_16x16x32_bf16 v[94:97], v[186:189], v[154:157], v[94:97]
	v_mfma_f32_16x16x32_bf16 v[90:93], v[194:197], v[154:157], v[90:93]
	v_mfma_f32_16x16x32_bf16 v[86:89], v[186:189], v[162:165], v[86:89]
	v_mfma_f32_16x16x32_bf16 v[82:85], v[194:197], v[162:165], v[82:85]
	v_mfma_f32_16x16x32_bf16 v[78:81], v[186:189], v[170:173], v[78:81]
	v_mfma_f32_16x16x32_bf16 v[74:77], v[194:197], v[170:173], v[74:77]
	v_mfma_f32_16x16x32_bf16 v[70:73], v[186:189], v[178:181], v[70:73]
	v_mfma_f32_16x16x32_bf16 v[66:69], v[194:197], v[178:181], v[66:69]
	v_mfma_f32_16x16x32_bf16 v[94:97], v[190:193], v[158:161], v[94:97]
	v_mfma_f32_16x16x32_bf16 v[90:93], v[198:201], v[158:161], v[90:93]
	v_mfma_f32_16x16x32_bf16 v[86:89], v[190:193], v[166:169], v[86:89]
	v_mfma_f32_16x16x32_bf16 v[82:85], v[198:201], v[166:169], v[82:85]
	v_mfma_f32_16x16x32_bf16 v[78:81], v[190:193], v[174:177], v[78:81]
	v_mfma_f32_16x16x32_bf16 v[74:77], v[198:201], v[174:177], v[74:77]
	v_mfma_f32_16x16x32_bf16 v[70:73], v[190:193], v[182:185], v[70:73]
	v_mfma_f32_16x16x32_bf16 v[66:69], v[198:201], v[182:185], v[66:69]
	s_barrier
	ds_read_b128 v[154:157], v241 offset:16384
	ds_read_b128 v[158:161], v241 offset:17408
	ds_read_b128 v[162:165], v241 offset:18432
	ds_read_b128 v[166:169], v241 offset:19456
	ds_read_b128 v[170:173], v241 offset:20480
	ds_read_b128 v[174:177], v241 offset:21504
	ds_read_b128 v[178:181], v241 offset:22528
	ds_read_b128 v[182:185], v241 offset:23552
	s_mov_b32 m0, s46
	s_add_u32 s98, vcc_lo, s34
	s_addc_u32 s99, vcc_hi, s35
	global_load_lds_dwordx4 v221, s[98:99]
	s_mov_b32 m0, s47
	s_add_u32 s98, vcc_lo, s64
	s_addc_u32 s99, vcc_hi, s65
	global_load_lds_dwordx4 v221, s[98:99]
	s_barrier
	s_waitcnt lgkmcnt(0)
	v_mfma_f32_16x16x32_bf16 v[62:65], v[138:141], v[154:157], v[62:65]
	v_mfma_f32_16x16x32_bf16 v[58:61], v[146:149], v[154:157], v[58:61]
	v_mfma_f32_16x16x32_bf16 v[54:57], v[138:141], v[162:165], v[54:57]
	v_mfma_f32_16x16x32_bf16 v[50:53], v[146:149], v[162:165], v[50:53]
	v_mfma_f32_16x16x32_bf16 v[46:49], v[138:141], v[170:173], v[46:49]
	v_mfma_f32_16x16x32_bf16 v[42:45], v[146:149], v[170:173], v[42:45]
	v_mfma_f32_16x16x32_bf16 v[38:41], v[138:141], v[178:181], v[38:41]
	v_mfma_f32_16x16x32_bf16 v[34:37], v[146:149], v[178:181], v[34:37]
	v_mfma_f32_16x16x32_bf16 v[62:65], v[142:145], v[158:161], v[62:65]
	v_mfma_f32_16x16x32_bf16 v[58:61], v[150:153], v[158:161], v[58:61]
	v_mfma_f32_16x16x32_bf16 v[54:57], v[142:145], v[166:169], v[54:57]
	v_mfma_f32_16x16x32_bf16 v[50:53], v[150:153], v[166:169], v[50:53]
	v_mfma_f32_16x16x32_bf16 v[46:49], v[142:145], v[174:177], v[46:49]
	v_mfma_f32_16x16x32_bf16 v[42:45], v[150:153], v[174:177], v[42:45]
	v_mfma_f32_16x16x32_bf16 v[38:41], v[142:145], v[182:185], v[38:41]
	v_mfma_f32_16x16x32_bf16 v[34:37], v[150:153], v[182:185], v[34:37]
	s_barrier
	s_mov_b32 m0, s48
	s_add_u32 s98, s0, s68
	s_addc_u32 s99, s1, s69
	global_load_lds_dwordx4 v221, s[98:99]
	s_mov_b32 m0, s49
	s_add_u32 s98, s0, s70
	s_addc_u32 s99, s1, s71
	global_load_lds_dwordx4 v221, s[98:99]
	s_waitcnt vmcnt(10)
	s_barrier
; #define LDA(dst, b, h) for (int m = 0; m < 4; ++m) for (int k = 0; k < 2; ++k) \
;     dst[m][k] = *reinterpret_cast<const bf16x8*>((char*)SA(b, h) + a_thr + (m * 2 + k) * 1024)
; #define LDB(dst, b, h) for (int n = 0; n < 2; ++n) for (int k = 0; k < 2; ++k) \
;     dst[n][k] = *reinterpret_cast<const bf16x8*>((char*)SB(b, h) + b_thr + (n * 2 + k) * 1024)
; #define MMA(ai, bj, At, Btf) do { __builtin_amdgcn_s_setprio(1); \
;     for (int m = 0; m < 4; ++m) for (int n = 0; n < 2; ++n) for (int k = 0; k < 2; ++k) \
;       acc[ai][bj][m][n] = __builtin_amdgcn_mfma_f32_16x16x32_bf16(Btf[n][k], At[m][k], acc[ai][bj][m][n], 0, 0, 0); \
;     __builtin_amdgcn_s_setprio(0); } while (0)
; #define WAIT_V(n) asm volatile("s_waitcnt vmcnt(" #n ")" ::: "memory")
; #define WAIT_L(n) asm volatile("s_waitcnt lgkmcnt(" #n ")" ::: "memory")
; #define BAR __builtin_amdgcn_s_barrier()
; #define SCHED __builtin_amdgcn_sched_barrier(0)
; template <bool OVL, bool PANEL = false, class Epi>
; __device__ __forceinline__ void gemm_phase(const bf16_t* __restrict__ A, long lda, const bf16_t* __restrict__ Bt, long ldb, int nM, int nN, int K,
;                                            const Epi& epi, bf16_t* shm, int w0) {
;     ...
;       WAIT_V(6); BAR; MMA(1, 1, At, B1); BAR;
;       LDB(B0, 1, 0); SCHED; LDA(At, 1, 0); STAGE(SA(0, 1), A, lda, aoff, brow + HALF, t + 2);
;       WAIT_L(8); BAR; WAIT_L(0); MMA(0, 0, At, B0); BAR; SCHED;
;       LDB(B1, 1, 1); STAGE(SB(1, 0), Bt, ldb, boff, bcol, t + 3);
;       BAR; WAIT_L(0); MMA(0, 1, At, B1); BAR;
	v_mfma_f32_16x16x32_bf16 v[30:33], v[186:189], v[154:157], v[30:33]
	v_mfma_f32_16x16x32_bf16 v[26:29], v[194:197], v[154:157], v[26:29]
	v_mfma_f32_16x16x32_bf16 v[22:25], v[186:189], v[162:165], v[22:25]
	v_mfma_f32_16x16x32_bf16 v[18:21], v[194:197], v[162:165], v[18:21]
	v_mfma_f32_16x16x32_bf16 v[14:17], v[186:189], v[170:173], v[14:17]
	v_mfma_f32_16x16x32_bf16 v[10:13], v[194:197], v[170:173], v[10:13]
	v_mfma_f32_16x16x32_bf16 v[6:9], v[186:189], v[178:181], v[6:9]
	v_mfma_f32_16x16x32_bf16 v[2:5], v[194:197], v[178:181], v[2:5]
	v_mfma_f32_16x16x32_bf16 v[30:33], v[190:193], v[158:161], v[30:33]
	v_mfma_f32_16x16x32_bf16 v[26:29], v[198:201], v[158:161], v[26:29]
	v_mfma_f32_16x16x32_bf16 v[22:25], v[190:193], v[166:169], v[22:25]
	v_mfma_f32_16x16x32_bf16 v[18:21], v[198:201], v[166:169], v[18:21]
	v_mfma_f32_16x16x32_bf16 v[14:17], v[190:193], v[174:177], v[14:17]
	v_mfma_f32_16x16x32_bf16 v[10:13], v[198:201], v[174:177], v[10:13]
	v_mfma_f32_16x16x32_bf16 v[6:9], v[190:193], v[182:185], v[6:9]
	v_mfma_f32_16x16x32_bf16 v[2:5], v[198:201], v[182:185], v[2:5]
	s_barrier
	ds_read_b128 v[138:141], v208
	ds_read_b128 v[142:145], v208 offset:1024
	ds_read_b128 v[146:149], v208 offset:2048
	ds_read_b128 v[150:153], v208 offset:3072
	ds_read_b128 v[154:157], v241 offset:32768
	ds_read_b128 v[158:161], v241 offset:33792
	ds_read_b128 v[162:165], v241 offset:34816
	ds_read_b128 v[166:169], v241 offset:35840
	ds_read_b128 v[170:173], v241 offset:36864
	ds_read_b128 v[174:177], v241 offset:37888
	ds_read_b128 v[178:181], v241 offset:38912
	ds_read_b128 v[182:185], v241 offset:39936
	s_mov_b32 m0, s50
	s_add_u32 s98, vcc_lo, s68
	s_addc_u32 s99, vcc_hi, s69
	global_load_lds_dwordx4 v221, s[98:99]
	s_mov_b32 m0, s51
	s_add_u32 s98, vcc_lo, s70
	s_addc_u32 s99, vcc_hi, s71
	global_load_lds_dwordx4 v221, s[98:99]
	s_waitcnt lgkmcnt(8)
	s_waitcnt vmcnt(10)
	s_barrier
	s_waitcnt lgkmcnt(0)
	v_mfma_f32_16x16x32_bf16 v[126:129], v[138:141], v[154:157], v[126:129]
	v_mfma_f32_16x16x32_bf16 v[122:125], v[146:149], v[154:157], v[122:125]
	v_mfma_f32_16x16x32_bf16 v[118:121], v[138:141], v[162:165], v[118:121]
	v_mfma_f32_16x16x32_bf16 v[114:117], v[146:149], v[162:165], v[114:117]
	v_mfma_f32_16x16x32_bf16 v[110:113], v[138:141], v[170:173], v[110:113]
	v_mfma_f32_16x16x32_bf16 v[106:109], v[146:149], v[170:173], v[106:109]
	v_mfma_f32_16x16x32_bf16 v[102:105], v[138:141], v[178:181], v[102:105]
	v_mfma_f32_16x16x32_bf16 v[98:101], v[146:149], v[178:181], v[98:101]
	v_mfma_f32_16x16x32_bf16 v[126:129], v[142:145], v[158:161], v[126:129]
	v_mfma_f32_16x16x32_bf16 v[122:125], v[150:153], v[158:161], v[122:125]
	v_mfma_f32_16x16x32_bf16 v[118:121], v[142:145], v[166:169], v[118:121]
	v_mfma_f32_16x16x32_bf16 v[114:117], v[150:153], v[166:169], v[114:117]
	v_mfma_f32_16x16x32_bf16 v[110:113], v[142:145], v[174:177], v[110:113]
	v_mfma_f32_16x16x32_bf16 v[106:109], v[150:153], v[174:177], v[106:109]
	v_mfma_f32_16x16x32_bf16 v[102:105], v[142:145], v[182:185], v[102:105]
	v_mfma_f32_16x16x32_bf16 v[98:101], v[150:153], v[182:185], v[98:101]
	s_barrier
	ds_read_b128 v[186:189], v209
	ds_read_b128 v[190:193], v209 offset:1024
	ds_read_b128 v[194:197], v209 offset:2048
	ds_read_b128 v[198:201], v209 offset:3072
	s_mov_b32 m0, s52
	s_add_u32 s98, s0, s94
	s_addc_u32 s99, s1, s95
	global_load_lds_dwordx4 v221, s[98:99]
	s_mov_b32 m0, s53
	s_add_u32 s98, s0, s72
	s_addc_u32 s99, s1, s73
	global_load_lds_dwordx4 v221, s[98:99]
	s_waitcnt vmcnt(10)
	s_barrier
	s_waitcnt lgkmcnt(0)
	v_mfma_f32_16x16x32_bf16 v[94:97], v[186:189], v[154:157], v[94:97]
	v_mfma_f32_16x16x32_bf16 v[90:93], v[194:197], v[154:157], v[90:93]
	v_mfma_f32_16x16x32_bf16 v[86:89], v[186:189], v[162:165], v[86:89]
	v_mfma_f32_16x16x32_bf16 v[82:85], v[194:197], v[162:165], v[82:85]
	v_mfma_f32_16x16x32_bf16 v[78:81], v[186:189], v[170:173], v[78:81]
	v_mfma_f32_16x16x32_bf16 v[74:77], v[194:197], v[170:173], v[74:77]
	v_mfma_f32_16x16x32_bf16 v[70:73], v[186:189], v[178:181], v[70:73]
	v_mfma_f32_16x16x32_bf16 v[66:69], v[194:197], v[178:181], v[66:69]
	v_mfma_f32_16x16x32_bf16 v[94:97], v[190:193], v[158:161], v[94:97]
	v_mfma_f32_16x16x32_bf16 v[90:93], v[198:201], v[158:161], v[90:93]
	v_mfma_f32_16x16x32_bf16 v[86:89], v[190:193], v[166:169], v[86:89]
	v_mfma_f32_16x16x32_bf16 v[82:85], v[198:201], v[166:169], v[82:85]
	v_mfma_f32_16x16x32_bf16 v[78:81], v[190:193], v[174:177], v[78:81]
	v_mfma_f32_16x16x32_bf16 v[74:77], v[198:201], v[174:177], v[74:77]
	v_mfma_f32_16x16x32_bf16 v[70:73], v[190:193], v[182:185], v[70:73]
	v_mfma_f32_16x16x32_bf16 v[66:69], v[198:201], v[182:185], v[66:69]
	s_barrier
; #define LDA(dst, b, h) for (int m = 0; m < 4; ++m) for (int k = 0; k < 2; ++k) \
;     dst[m][k] = *reinterpret_cast<const bf16x8*>((char*)SA(b, h) + a_thr + (m * 2 + k) * 1024)
; #define LDB(dst, b, h) for (int n = 0; n < 2; ++n) for (int k = 0; k < 2; ++k) \
;     dst[n][k] = *reinterpret_cast<const bf16x8*>((char*)SB(b, h) + b_thr + (n * 2 + k) * 1024)
; #define MMA(ai, bj, At, Btf) do { __builtin_amdgcn_s_setprio(1); \
;     for (int m = 0; m < 4; ++m) for (int n = 0; n < 2; ++n) for (int k = 0; k < 2; ++k) \
;       acc[ai][bj][m][n] = __builtin_amdgcn_mfma_f32_16x16x32_bf16(Btf[n][k], At[m][k], acc[ai][bj][m][n], 0, 0, 0); \
;     __builtin_amdgcn_s_setprio(0); } while (0)
; #define WAIT_V(n) asm volatile("s_waitcnt vmcnt(" #n ")" ::: "memory")
; #define WAIT_L(n) asm volatile("s_waitcnt lgkmcnt(" #n ")" ::: "memory")
; #define BAR __builtin_amdgcn_s_barrier()
; #define SCHED __builtin_amdgcn_sched_barrier(0)
; template <bool OVL, bool PANEL = false, class Epi>
; __device__ __forceinline__ void gemm_phase(const bf16_t* __restrict__ A, long lda, const bf16_t* __restrict__ Bt, long ldb, int nM, int nN, int K,
;                                            const Epi& epi, bf16_t* shm, int w0) {
;     ...
;       LDA(At, 1, 1); STAGE(SA(1, 0), A, lda, aoff, brow, t + 3);
;       BAR; WAIT_L(0); MMA(1, 0, At, B0); BAR; SCHED;
;       STAGE(SB(1, 1), Bt, ldb, boff, bcol + HALF, t + 3);
;       WAIT_V(6); BAR; MMA(1, 1, At, B1); BAR;
;     }
;     { LDB(B0, 0, 0); LDA(At, 0, 0); STAGE(SA(1, 1), A, lda, aoff, brow + HALF, nt - 1);
	ds_read_b128 v[154:157], v241 offset:49152
	ds_read_b128 v[158:161], v241 offset:50176
	ds_read_b128 v[162:165], v241 offset:51200
	ds_read_b128 v[166:169], v241 offset:52224
	ds_read_b128 v[170:173], v241 offset:53248
	ds_read_b128 v[174:177], v241 offset:54272
	ds_read_b128 v[178:181], v241 offset:55296
	ds_read_b128 v[182:185], v241 offset:56320
	s_mov_b32 m0, s54
	s_add_u32 s98, vcc_lo, s94
	s_addc_u32 s99, vcc_hi, s95
	global_load_lds_dwordx4 v221, s[98:99]
	s_mov_b32 m0, s55
	s_add_u32 s98, vcc_lo, s72
	s_addc_u32 s99, vcc_hi, s73
	global_load_lds_dwordx4 v221, s[98:99]
	s_barrier
	s_waitcnt lgkmcnt(0)
	v_mfma_f32_16x16x32_bf16 v[62:65], v[138:141], v[154:157], v[62:65]
	v_mfma_f32_16x16x32_bf16 v[58:61], v[146:149], v[154:157], v[58:61]
	v_mfma_f32_16x16x32_bf16 v[54:57], v[138:141], v[162:165], v[54:57]
	v_mfma_f32_16x16x32_bf16 v[50:53], v[146:149], v[162:165], v[50:53]
	v_mfma_f32_16x16x32_bf16 v[46:49], v[138:141], v[170:173], v[46:49]
	v_mfma_f32_16x16x32_bf16 v[42:45], v[146:149], v[170:173], v[42:45]
	v_mfma_f32_16x16x32_bf16 v[38:41], v[138:141], v[178:181], v[38:41]
	v_mfma_f32_16x16x32_bf16 v[34:37], v[146:149], v[178:181], v[34:37]
	v_mfma_f32_16x16x32_bf16 v[62:65], v[142:145], v[158:161], v[62:65]
	v_mfma_f32_16x16x32_bf16 v[58:61], v[150:153], v[158:161], v[58:61]
	v_mfma_f32_16x16x32_bf16 v[54:57], v[142:145], v[166:169], v[54:57]
	v_mfma_f32_16x16x32_bf16 v[50:53], v[150:153], v[166:169], v[50:53]
	v_mfma_f32_16x16x32_bf16 v[46:49], v[142:145], v[174:177], v[46:49]
	v_mfma_f32_16x16x32_bf16 v[42:45], v[150:153], v[174:177], v[42:45]
	v_mfma_f32_16x16x32_bf16 v[38:41], v[142:145], v[182:185], v[38:41]
	v_mfma_f32_16x16x32_bf16 v[34:37], v[150:153], v[182:185], v[34:37]
	s_barrier
	s_mov_b32 m0, s56
	s_add_u32 s98, s0, s14
	s_addc_u32 s99, s1, s15
	global_load_lds_dwordx4 v221, s[98:99]
	s_mov_b32 m0, s57
	s_add_u32 s98, s0, s18
	s_addc_u32 s99, s1, s19
	global_load_lds_dwordx4 v221, s[98:99]
	s_add_i32 s2, s2, 2
	s_add_u32 s80, s80, 0x100
	s_addc_u32 s81, s81, 0
	s_cmp_gt_u32 s2, 11
	s_waitcnt vmcnt(10)
	s_barrier
	v_mfma_f32_16x16x32_bf16 v[30:33], v[186:189], v[154:157], v[30:33]
	v_mfma_f32_16x16x32_bf16 v[26:29], v[194:197], v[154:157], v[26:29]
	v_mfma_f32_16x16x32_bf16 v[22:25], v[186:189], v[162:165], v[22:25]
	v_mfma_f32_16x16x32_bf16 v[18:21], v[194:197], v[162:165], v[18:21]
	v_mfma_f32_16x16x32_bf16 v[14:17], v[186:189], v[170:173], v[14:17]
	v_mfma_f32_16x16x32_bf16 v[10:13], v[194:197], v[170:173], v[10:13]
	v_mfma_f32_16x16x32_bf16 v[6:9], v[186:189], v[178:181], v[6:9]
	v_mfma_f32_16x16x32_bf16 v[2:5], v[194:197], v[178:181], v[2:5]
	v_mfma_f32_16x16x32_bf16 v[30:33], v[190:193], v[158:161], v[30:33]
	v_mfma_f32_16x16x32_bf16 v[26:29], v[198:201], v[158:161], v[26:29]
	v_mfma_f32_16x16x32_bf16 v[22:25], v[190:193], v[166:169], v[22:25]
	v_mfma_f32_16x16x32_bf16 v[18:21], v[198:201], v[166:169], v[18:21]
	v_mfma_f32_16x16x32_bf16 v[14:17], v[190:193], v[174:177], v[14:17]
	v_mfma_f32_16x16x32_bf16 v[10:13], v[198:201], v[174:177], v[10:13]
	v_mfma_f32_16x16x32_bf16 v[6:9], v[190:193], v[182:185], v[6:9]
	v_mfma_f32_16x16x32_bf16 v[2:5], v[198:201], v[182:185], v[2:5]
	s_barrier
	s_cbranch_scc0 .LBB0_472
	s_waitcnt vmcnt(6)
	s_or_b32 s0, s82, 0x80
	s_ashr_i32 s1, s0, 31
	v_readlane_b32 s44, v252, 20
	s_lshl_b64 s[0:1], s[0:1], 11
	v_readlane_b32 s50, v252, 26
	v_add_u32_e32 v206, 16, v240
	v_readlane_b32 s51, v252, 27
	s_add_u32 s0, s50, s0
	v_add_u32_e32 v0, 0x10000, v206
	s_addc_u32 s1, s51, s1
	ds_read_b128 v[130:133], v0
	ds_read_b128 v[138:141], v0 offset:1024
	ds_read_b128 v[142:145], v0 offset:2048
	ds_read_b128 v[146:149], v0 offset:3072
	ds_read_b128 v[150:153], v241
	ds_read_b128 v[154:157], v241 offset:1024
	ds_read_b128 v[158:161], v241 offset:2048
	ds_read_b128 v[162:165], v241 offset:3072
	ds_read_b128 v[166:169], v241 offset:4096
	ds_read_b128 v[170:173], v241 offset:5120
	ds_read_b128 v[174:177], v241 offset:6144
	ds_read_b128 v[178:181], v241 offset:7168
	v_mov_b32_e32 v0, v221
	v_readlane_b32 s45, v252, 21
	v_lshl_add_u64 v[134:135], s[0:1], 0, v[0:1]
	s_mov_b64 s[0:1], 0x780
	v_lshl_add_u64 v[182:183], v[134:135], 0, s[0:1]
	v_readfirstlane_b32 s0, v136
	s_mov_b32 m0, s0
	s_mov_b64 s[0:1], 0x20780
	v_lshl_add_u64 v[134:135], v[134:135], 0, s[0:1]
	v_readfirstlane_b32 s0, v137
	global_load_lds_dwordx4 v[182:183], off
	s_mov_b32 m0, s0
	v_readlane_b32 s46, v252, 22
	global_load_lds_dwordx4 v[134:135], off
	s_barrier
	s_waitcnt lgkmcnt(0)
	v_readlane_b32 s47, v252, 23
	v_readlane_b32 s48, v252, 24
	v_readlane_b32 s49, v252, 25
	v_readlane_b32 s52, v252, 28
	v_readlane_b32 s53, v252, 29
	v_readlane_b32 s54, v252, 30
	v_readlane_b32 s55, v252, 31
	v_readlane_b32 s56, v252, 32
	v_readlane_b32 s57, v252, 33
	v_readlane_b32 s58, v252, 34
	v_readlane_b32 s59, v252, 35

; #define MMA(ai, bj, At, Btf) do { __builtin_amdgcn_s_setprio(1); \
;     for (int m = 0; m < 4; ++m) for (int n = 0; n < 2; ++n) for (int k = 0; k < 2; ++k) \
;       acc[ai][bj][m][n] = __builtin_amdgcn_mfma_f32_16x16x32_bf16(Btf[n][k], At[m][k], acc[ai][bj][m][n], 0, 0, 0); \
;     __builtin_amdgcn_s_setprio(0); } while (0)
; #define WAIT_L(n) asm volatile("s_waitcnt lgkmcnt(" #n ")" ::: "memory")
; #define BAR __builtin_amdgcn_s_barrier()
; template <bool OVL, bool PANEL = false, class Epi>
; __device__ __forceinline__ void gemm_phase(const bf16_t* __restrict__ A, long lda, const bf16_t* __restrict__ Bt, long ldb, int nM, int nN, int K,
;                                            const Epi& epi, bf16_t* shm, int w0) {
;     ...
;       BAR; WAIT_L(0); MMA(0, 0, At, B0); BAR;
	s_waitcnt lgkmcnt(0)
	v_mfma_f32_16x16x32_bf16 v[126:129], v[130:133], v[150:153], v[126:129]
	v_mfma_f32_16x16x32_bf16 v[122:125], v[142:145], v[150:153], v[122:125]
	v_mfma_f32_16x16x32_bf16 v[118:121], v[130:133], v[158:161], v[118:121]
	v_mfma_f32_16x16x32_bf16 v[114:117], v[142:145], v[158:161], v[114:117]
	v_mfma_f32_16x16x32_bf16 v[106:109], v[142:145], v[166:169], v[106:109]
	v_mfma_f32_16x16x32_bf16 v[102:105], v[130:133], v[174:177], v[102:105]
	v_mfma_f32_16x16x32_bf16 v[98:101], v[142:145], v[174:177], v[98:101]
	v_mfma_f32_16x16x32_bf16 v[126:129], v[138:141], v[154:157], v[126:129]
	v_mfma_f32_16x16x32_bf16 v[122:125], v[146:149], v[154:157], v[122:125]
	v_mfma_f32_16x16x32_bf16 v[118:121], v[138:141], v[162:165], v[118:121]
	v_mfma_f32_16x16x32_bf16 v[114:117], v[146:149], v[162:165], v[114:117]
	v_mfma_f32_16x16x32_bf16 v[110:113], v[130:133], v[166:169], v[110:113]
	v_mfma_f32_16x16x32_bf16 v[106:109], v[146:149], v[170:173], v[106:109]
	v_mfma_f32_16x16x32_bf16 v[102:105], v[138:141], v[178:181], v[102:105]
	v_mfma_f32_16x16x32_bf16 v[98:101], v[146:149], v[178:181], v[98:101]
	v_mfma_f32_16x16x32_bf16 v[134:137], v[138:141], v[170:173], v[110:113]

; #define LDB(dst, b, h) for (int n = 0; n < 2; ++n) for (int k = 0; k < 2; ++k) \
;     dst[n][k] = *reinterpret_cast<const bf16x8*>((char*)SB(b, h) + b_thr + (n * 2 + k) * 1024)
; #define MMA(ai, bj, At, Btf) do { __builtin_amdgcn_s_setprio(1); \
;     for (int m = 0; m < 4; ++m) for (int n = 0; n < 2; ++n) for (int k = 0; k < 2; ++k) \
;       acc[ai][bj][m][n] = __builtin_amdgcn_mfma_f32_16x16x32_bf16(Btf[n][k], At[m][k], acc[ai][bj][m][n], 0, 0, 0); \
;     __builtin_amdgcn_s_setprio(0); } while (0)
; #define WAIT_L(n) asm volatile("s_waitcnt lgkmcnt(" #n ")" ::: "memory")
; #define BAR __builtin_amdgcn_s_barrier()
; template <bool OVL, bool PANEL = false, class Epi>
; __device__ __forceinline__ void gemm_phase(const bf16_t* __restrict__ A, long lda, const bf16_t* __restrict__ Bt, long ldb, int nM, int nN, int K,
;                                            const Epi& epi, bf16_t* shm, int w0) {
;     ...
;       LDB(B1, 0, 1); BAR; WAIT_L(0); MMA(0, 1, At, B1); BAR;
	v_add_u32_e32 v0, 0x14000, v206
	s_barrier
	s_nop 0
	ds_read_b128 v[110:113], v0
	ds_read_b128 v[182:185], v0 offset:1024
	ds_read_b128 v[186:189], v0 offset:2048
	ds_read_b128 v[190:193], v0 offset:3072
	s_barrier
	s_waitcnt lgkmcnt(0)

; #define LDB(dst, b, h) for (int n = 0; n < 2; ++n) for (int k = 0; k < 2; ++k) \
;     dst[n][k] = *reinterpret_cast<const bf16x8*>((char*)SB(b, h) + b_thr + (n * 2 + k) * 1024)
; #define MMA(ai, bj, At, Btf) do { __builtin_amdgcn_s_setprio(1); \
;     for (int m = 0; m < 4; ++m) for (int n = 0; n < 2; ++n) for (int k = 0; k < 2; ++k) \
;       acc[ai][bj][m][n] = __builtin_amdgcn_mfma_f32_16x16x32_bf16(Btf[n][k], At[m][k], acc[ai][bj][m][n], 0, 0, 0); \
;     __builtin_amdgcn_s_setprio(0); } while (0)
; #define WAIT_L(n) asm volatile("s_waitcnt lgkmcnt(" #n ")" ::: "memory")
; #define BAR __builtin_amdgcn_s_barrier()
; template <bool OVL, bool PANEL = false, class Epi>
; __device__ __forceinline__ void gemm_phase(const bf16_t* __restrict__ A, long lda, const bf16_t* __restrict__ Bt, long ldb, int nM, int nN, int K,
;                                            const Epi& epi, bf16_t* shm, int w0) {
;     ...
;       LDB(B1, 0, 1); BAR; WAIT_L(0); MMA(0, 1, At, B1); BAR;
	v_mfma_f32_16x16x32_bf16 v[90:93], v[186:189], v[150:153], v[90:93]
	v_mfma_f32_16x16x32_bf16 v[74:77], v[186:189], v[166:169], v[74:77]
	v_mfma_f32_16x16x32_bf16 v[70:73], v[110:113], v[174:177], v[70:73]
	v_mfma_f32_16x16x32_bf16 v[66:69], v[186:189], v[174:177], v[66:69]
	v_mfma_f32_16x16x32_bf16 v[94:97], v[110:113], v[150:153], v[94:97]
	v_mfma_f32_16x16x32_bf16 v[90:93], v[190:193], v[154:157], v[90:93]
	v_mfma_f32_16x16x32_bf16 v[86:89], v[110:113], v[158:161], v[86:89]
	v_mfma_f32_16x16x32_bf16 v[82:85], v[186:189], v[158:161], v[82:85]
	v_mfma_f32_16x16x32_bf16 v[78:81], v[110:113], v[166:169], v[78:81]
	v_mfma_f32_16x16x32_bf16 v[74:77], v[190:193], v[170:173], v[74:77]
	v_mfma_f32_16x16x32_bf16 v[70:73], v[182:185], v[178:181], v[70:73]
	v_mfma_f32_16x16x32_bf16 v[66:69], v[190:193], v[178:181], v[66:69]
	v_mfma_f32_16x16x32_bf16 v[194:197], v[182:185], v[154:157], v[94:97]
	v_mfma_f32_16x16x32_bf16 v[150:153], v[182:185], v[162:165], v[86:89]
	v_mfma_f32_16x16x32_bf16 v[154:157], v[190:193], v[162:165], v[82:85]
	v_mfma_f32_16x16x32_bf16 v[158:161], v[182:185], v[170:173], v[78:81]

; #define LDA(dst, b, h) for (int m = 0; m < 4; ++m) for (int k = 0; k < 2; ++k) \
;     dst[m][k] = *reinterpret_cast<const bf16x8*>((char*)SA(b, h) + a_thr + (m * 2 + k) * 1024)
; #define MMA(ai, bj, At, Btf) do { __builtin_amdgcn_s_setprio(1); \
;     for (int m = 0; m < 4; ++m) for (int n = 0; n < 2; ++n) for (int k = 0; k < 2; ++k) \
;       acc[ai][bj][m][n] = __builtin_amdgcn_mfma_f32_16x16x32_bf16(Btf[n][k], At[m][k], acc[ai][bj][m][n], 0, 0, 0); \
;     __builtin_amdgcn_s_setprio(0); } while (0)
; #define WAIT_V(n) asm volatile("s_waitcnt vmcnt(" #n ")" ::: "memory")
; #define WAIT_L(n) asm volatile("s_waitcnt lgkmcnt(" #n ")" ::: "memory")
; #define BAR __builtin_amdgcn_s_barrier()
; template <bool OVL, bool PANEL = false, class Epi>
; __device__ __forceinline__ void gemm_phase(const bf16_t* __restrict__ A, long lda, const bf16_t* __restrict__ Bt, long ldb, int nM, int nN, int K,
;                                            const Epi& epi, bf16_t* shm, int w0) {
;     ...
;       LDA(At, 0, 1); WAIT_V(4); BAR; WAIT_L(0); MMA(1, 0, At, B0); MMA(1, 1, At, B1); BAR; }
	s_barrier
	s_nop 0
	ds_read_b128 v[78:81], v241 offset:16384
	ds_read_b128 v[82:85], v241 offset:17408
	ds_read_b128 v[86:89], v241 offset:18432
	ds_read_b128 v[94:97], v241 offset:19456
	ds_read_b128 v[162:165], v241 offset:20480
	ds_read_b128 v[166:169], v241 offset:21504
	ds_read_b128 v[170:173], v241 offset:22528
	ds_read_b128 v[174:177], v241 offset:23552
	s_waitcnt vmcnt(4)
	s_barrier
	s_waitcnt lgkmcnt(0)

; #define LDA(dst, b, h) for (int m = 0; m < 4; ++m) for (int k = 0; k < 2; ++k) \
;     dst[m][k] = *reinterpret_cast<const bf16x8*>((char*)SA(b, h) + a_thr + (m * 2 + k) * 1024)
; #define MMA(ai, bj, At, Btf) do { __builtin_amdgcn_s_setprio(1); \
;     for (int m = 0; m < 4; ++m) for (int n = 0; n < 2; ++n) for (int k = 0; k < 2; ++k) \
;       acc[ai][bj][m][n] = __builtin_amdgcn_mfma_f32_16x16x32_bf16(Btf[n][k], At[m][k], acc[ai][bj][m][n], 0, 0, 0); \
;     __builtin_amdgcn_s_setprio(0); } while (0)
; #define WAIT_V(n) asm volatile("s_waitcnt vmcnt(" #n ")" ::: "memory")
; #define WAIT_L(n) asm volatile("s_waitcnt lgkmcnt(" #n ")" ::: "memory")
; #define BAR __builtin_amdgcn_s_barrier()
; template <bool OVL, bool PANEL = false, class Epi>
; __device__ __forceinline__ void gemm_phase(const bf16_t* __restrict__ A, long lda, const bf16_t* __restrict__ Bt, long ldb, int nM, int nN, int K,
;                                            const Epi& epi, bf16_t* shm, int w0) {
;     ...
;       LDA(At, 0, 1); WAIT_V(4); BAR; WAIT_L(0); MMA(1, 0, At, B0); MMA(1, 1, At, B1); BAR; }
	v_mfma_f32_16x16x32_bf16 v[62:65], v[130:133], v[78:81], v[62:65]
	v_mfma_f32_16x16x32_bf16 v[58:61], v[142:145], v[78:81], v[58:61]
	v_mfma_f32_16x16x32_bf16 v[54:57], v[130:133], v[86:89], v[54:57]
	v_mfma_f32_16x16x32_bf16 v[50:53], v[142:145], v[86:89], v[50:53]
	v_mfma_f32_16x16x32_bf16 v[46:49], v[130:133], v[162:165], v[46:49]
	v_mfma_f32_16x16x32_bf16 v[42:45], v[142:145], v[162:165], v[42:45]
	v_mfma_f32_16x16x32_bf16 v[34:37], v[142:145], v[170:173], v[34:37]
	v_mfma_f32_16x16x32_bf16 v[62:65], v[138:141], v[82:85], v[62:65]
	v_mfma_f32_16x16x32_bf16 v[58:61], v[146:149], v[82:85], v[58:61]
	v_mfma_f32_16x16x32_bf16 v[54:57], v[138:141], v[94:97], v[54:57]
	v_mfma_f32_16x16x32_bf16 v[50:53], v[146:149], v[94:97], v[50:53]
	v_mfma_f32_16x16x32_bf16 v[46:49], v[138:141], v[166:169], v[46:49]
	v_mfma_f32_16x16x32_bf16 v[42:45], v[146:149], v[166:169], v[42:45]
	v_mfma_f32_16x16x32_bf16 v[38:41], v[130:133], v[170:173], v[38:41]
	v_mfma_f32_16x16x32_bf16 v[34:37], v[146:149], v[174:177], v[34:37]
	v_mfma_f32_16x16x32_bf16 v[130:133], v[138:141], v[174:177], v[38:41]


; #define LDA(dst, b, h) for (int m = 0; m < 4; ++m) for (int k = 0; k < 2; ++k) \
;     dst[m][k] = *reinterpret_cast<const bf16x8*>((char*)SA(b, h) + a_thr + (m * 2 + k) * 1024)
; #define MMA(ai, bj, At, Btf) do { __builtin_amdgcn_s_setprio(1); \
;     for (int m = 0; m < 4; ++m) for (int n = 0; n < 2; ++n) for (int k = 0; k < 2; ++k) \
;       acc[ai][bj][m][n] = __builtin_amdgcn_mfma_f32_16x16x32_bf16(Btf[n][k], At[m][k], acc[ai][bj][m][n], 0, 0, 0); \
;     __builtin_amdgcn_s_setprio(0); } while (0)
; #define WAIT_V(n) asm volatile("s_waitcnt vmcnt(" #n ")" ::: "memory")
; #define WAIT_L(n) asm volatile("s_waitcnt lgkmcnt(" #n ")" ::: "memory")
; #define BAR __builtin_amdgcn_s_barrier()
; template <bool OVL, bool PANEL = false, class Epi>
; __device__ __forceinline__ void gemm_phase(const bf16_t* __restrict__ A, long lda, const bf16_t* __restrict__ Bt, long ldb, int nM, int nN, int K,
;                                            const Epi& epi, bf16_t* shm, int w0) {
;     ...
;       LDA(At, 0, 1); WAIT_V(4); BAR; WAIT_L(0); MMA(1, 0, At, B0); MMA(1, 1, At, B1); BAR; }
	v_mfma_f32_16x16x32_bf16 v[30:33], v[110:113], v[78:81], v[30:33]
	v_mfma_f32_16x16x32_bf16 v[26:29], v[186:189], v[78:81], v[26:29]
	v_mfma_f32_16x16x32_bf16 v[22:25], v[110:113], v[86:89], v[22:25]
	v_mfma_f32_16x16x32_bf16 v[18:21], v[186:189], v[86:89], v[18:21]
	v_mfma_f32_16x16x32_bf16 v[14:17], v[110:113], v[162:165], v[14:17]
	v_mfma_f32_16x16x32_bf16 v[10:13], v[186:189], v[162:165], v[10:13]
	v_mfma_f32_16x16x32_bf16 v[6:9], v[110:113], v[170:173], v[6:9]
	v_mfma_f32_16x16x32_bf16 v[2:5], v[186:189], v[170:173], v[2:5]
	v_mfma_f32_16x16x32_bf16 v[138:141], v[182:185], v[82:85], v[30:33]
	v_mfma_f32_16x16x32_bf16 v[142:145], v[190:193], v[82:85], v[26:29]
	v_mfma_f32_16x16x32_bf16 v[146:149], v[182:185], v[94:97], v[22:25]
	v_mfma_f32_16x16x32_bf16 v[178:181], v[190:193], v[94:97], v[18:21]
	v_mfma_f32_16x16x32_bf16 v[198:201], v[182:185], v[166:169], v[14:17]
	v_mfma_f32_16x16x32_bf16 v[162:165], v[190:193], v[166:169], v[10:13]
	v_mfma_f32_16x16x32_bf16 v[166:169], v[182:185], v[174:177], v[6:9]
	v_mfma_f32_16x16x32_bf16 v[170:173], v[190:193], v[174:177], v[2:5]

; #define LDA(dst, b, h) for (int m = 0; m < 4; ++m) for (int k = 0; k < 2; ++k) \
;     dst[m][k] = *reinterpret_cast<const bf16x8*>((char*)SA(b, h) + a_thr + (m * 2 + k) * 1024)
; #define LDB(dst, b, h) for (int n = 0; n < 2; ++n) for (int k = 0; k < 2; ++k) \
;     dst[n][k] = *reinterpret_cast<const bf16x8*>((char*)SB(b, h) + b_thr + (n * 2 + k) * 1024)
; #define MMA(ai, bj, At, Btf) do { __builtin_amdgcn_s_setprio(1); \
;     for (int m = 0; m < 4; ++m) for (int n = 0; n < 2; ++n) for (int k = 0; k < 2; ++k) \
;       acc[ai][bj][m][n] = __builtin_amdgcn_mfma_f32_16x16x32_bf16(Btf[n][k], At[m][k], acc[ai][bj][m][n], 0, 0, 0); \
;     __builtin_amdgcn_s_setprio(0); } while (0)
; #define WAIT_V(n) asm volatile("s_waitcnt vmcnt(" #n ")" ::: "memory")
; #define WAIT_L(n) asm volatile("s_waitcnt lgkmcnt(" #n ")" ::: "memory")
; #define BAR __builtin_amdgcn_s_barrier()
; template <bool OVL, bool PANEL = false, class Epi>
; __device__ __forceinline__ void gemm_phase(const bf16_t* __restrict__ A, long lda, const bf16_t* __restrict__ Bt, long ldb, int nM, int nN, int K,
;                                            const Epi& epi, bf16_t* shm, int w0) {
;     ...
;     { LDB(B0, 1, 0); LDA(At, 1, 0); WAIT_V(2); BAR; WAIT_L(0); MMA(0, 0, At, B0); BAR;
	v_add_u32_e32 v0, 0x18000, v206
	s_barrier
	ds_read_b128 v[174:177], v0
	ds_read_b128 v[182:185], v0 offset:1024
	ds_read_b128 v[186:189], v0 offset:2048
	ds_read_b128 v[190:193], v0 offset:3072
	ds_read_b128 v[6:9], v241 offset:32768
	ds_read_b128 v[14:17], v241 offset:33792
	ds_read_b128 v[18:21], v241 offset:34816
	ds_read_b128 v[22:25], v241 offset:35840
	ds_read_b128 v[26:29], v241 offset:36864
	ds_read_b128 v[30:33], v241 offset:37888
	ds_read_b128 v[38:41], v241 offset:38912
	ds_read_b128 v[202:205], v241 offset:39936
	s_waitcnt vmcnt(2)
	s_barrier
	s_waitcnt lgkmcnt(0)

; #define LDA(dst, b, h) for (int m = 0; m < 4; ++m) for (int k = 0; k < 2; ++k) \
;     dst[m][k] = *reinterpret_cast<const bf16x8*>((char*)SA(b, h) + a_thr + (m * 2 + k) * 1024)
; #define LDB(dst, b, h) for (int n = 0; n < 2; ++n) for (int k = 0; k < 2; ++k) \
;     dst[n][k] = *reinterpret_cast<const bf16x8*>((char*)SB(b, h) + b_thr + (n * 2 + k) * 1024)
; #define MMA(ai, bj, At, Btf) do { __builtin_amdgcn_s_setprio(1); \
;     for (int m = 0; m < 4; ++m) for (int n = 0; n < 2; ++n) for (int k = 0; k < 2; ++k) \
;       acc[ai][bj][m][n] = __builtin_amdgcn_mfma_f32_16x16x32_bf16(Btf[n][k], At[m][k], acc[ai][bj][m][n], 0, 0, 0); \
;     __builtin_amdgcn_s_setprio(0); } while (0)
; #define WAIT_V(n) asm volatile("s_waitcnt vmcnt(" #n ")" ::: "memory")
; #define WAIT_L(n) asm volatile("s_waitcnt lgkmcnt(" #n ")" ::: "memory")
; #define BAR __builtin_amdgcn_s_barrier()
; template <bool OVL, bool PANEL = false, class Epi>
; __device__ __forceinline__ void gemm_phase(const bf16_t* __restrict__ A, long lda, const bf16_t* __restrict__ Bt, long ldb, int nM, int nN, int K,
;                                            const Epi& epi, bf16_t* shm, int w0) {
;     ...
;     { LDB(B0, 1, 0); LDA(At, 1, 0); WAIT_V(2); BAR; WAIT_L(0); MMA(0, 0, At, B0); BAR;
	v_mfma_f32_16x16x32_bf16 v[2:5], v[174:177], v[6:9], v[126:129]
	v_mfma_f32_16x16x32_bf16 v[126:129], v[182:185], v[14:17], v[2:5]
	v_mfma_f32_16x16x32_bf16 v[2:5], v[186:189], v[6:9], v[122:125]
	v_mfma_f32_16x16x32_bf16 v[82:85], v[190:193], v[14:17], v[2:5]
	v_mfma_f32_16x16x32_bf16 v[2:5], v[174:177], v[18:21], v[118:121]
	v_mfma_f32_16x16x32_bf16 v[110:113], v[182:185], v[22:25], v[2:5]
	v_mfma_f32_16x16x32_bf16 v[2:5], v[186:189], v[18:21], v[114:117]
	v_mfma_f32_16x16x32_bf16 v[86:89], v[190:193], v[22:25], v[2:5]
	v_mfma_f32_16x16x32_bf16 v[2:5], v[174:177], v[26:29], v[134:137]
	v_mfma_f32_16x16x32_bf16 v[94:97], v[182:185], v[30:33], v[2:5]
	v_mfma_f32_16x16x32_bf16 v[2:5], v[186:189], v[26:29], v[106:109]
	v_mfma_f32_16x16x32_bf16 v[78:81], v[190:193], v[30:33], v[2:5]
	v_mfma_f32_16x16x32_bf16 v[2:5], v[174:177], v[38:41], v[102:105]
	v_mfma_f32_16x16x32_bf16 v[10:13], v[186:189], v[38:41], v[98:101]
	v_mfma_f32_16x16x32_bf16 v[2:5], v[182:185], v[202:205], v[2:5]
	v_mfma_f32_16x16x32_bf16 v[10:13], v[190:193], v[202:205], v[10:13]

; #define LDB(dst, b, h) for (int n = 0; n < 2; ++n) for (int k = 0; k < 2; ++k) \
;     dst[n][k] = *reinterpret_cast<const bf16x8*>((char*)SB(b, h) + b_thr + (n * 2 + k) * 1024)
; #define MMA(ai, bj, At, Btf) do { __builtin_amdgcn_s_setprio(1); \
;     for (int m = 0; m < 4; ++m) for (int n = 0; n < 2; ++n) for (int k = 0; k < 2; ++k) \
;       acc[ai][bj][m][n] = __builtin_amdgcn_mfma_f32_16x16x32_bf16(Btf[n][k], At[m][k], acc[ai][bj][m][n], 0, 0, 0); \
;     __builtin_amdgcn_s_setprio(0); } while (0)
; #define WAIT_V(n) asm volatile("s_waitcnt vmcnt(" #n ")" ::: "memory")
; #define WAIT_L(n) asm volatile("s_waitcnt lgkmcnt(" #n ")" ::: "memory")
; #define BAR __builtin_amdgcn_s_barrier()
; template <bool OVL, bool PANEL = false, class Epi>
; __device__ __forceinline__ void gemm_phase(const bf16_t* __restrict__ A, long lda, const bf16_t* __restrict__ Bt, long ldb, int nM, int nN, int K,
;                                            const Epi& epi, bf16_t* shm, int w0) {
;     ...
;       LDB(B1, 1, 1); WAIT_V(0); BAR; WAIT_L(0); MMA(0, 1, At, B1); BAR;
	v_add_u32_e32 v0, 0x1c000, v206
	s_barrier
	ds_read_b128 v[122:125], v0
	ds_read_b128 v[134:137], v0 offset:1024
	ds_read_b128 v[206:209], v0 offset:2048
	ds_read_b128 v[210:213], v0 offset:3072
	s_waitcnt vmcnt(0)
	s_barrier
	s_waitcnt lgkmcnt(0)

; #define LDB(dst, b, h) for (int n = 0; n < 2; ++n) for (int k = 0; k < 2; ++k) \
;     dst[n][k] = *reinterpret_cast<const bf16x8*>((char*)SB(b, h) + b_thr + (n * 2 + k) * 1024)
; #define MMA(ai, bj, At, Btf) do { __builtin_amdgcn_s_setprio(1); \
;     for (int m = 0; m < 4; ++m) for (int n = 0; n < 2; ++n) for (int k = 0; k < 2; ++k) \
;       acc[ai][bj][m][n] = __builtin_amdgcn_mfma_f32_16x16x32_bf16(Btf[n][k], At[m][k], acc[ai][bj][m][n], 0, 0, 0); \
;     __builtin_amdgcn_s_setprio(0); } while (0)
; #define WAIT_V(n) asm volatile("s_waitcnt vmcnt(" #n ")" ::: "memory")
; #define WAIT_L(n) asm volatile("s_waitcnt lgkmcnt(" #n ")" ::: "memory")
; #define BAR __builtin_amdgcn_s_barrier()
; template <bool OVL, bool PANEL = false, class Epi>
; __device__ __forceinline__ void gemm_phase(const bf16_t* __restrict__ A, long lda, const bf16_t* __restrict__ Bt, long ldb, int nM, int nN, int K,
;                                            const Epi& epi, bf16_t* shm, int w0) {
;     ...
;       LDB(B1, 1, 1); WAIT_V(0); BAR; WAIT_L(0); MMA(0, 1, At, B1); BAR;
	v_mfma_f32_16x16x32_bf16 v[98:101], v[122:125], v[6:9], v[194:197]
	v_mfma_f32_16x16x32_bf16 v[6:9], v[206:209], v[6:9], v[90:93]
	v_mfma_f32_16x16x32_bf16 v[114:117], v[210:213], v[14:17], v[6:9]
	v_mfma_f32_16x16x32_bf16 v[6:9], v[122:125], v[18:21], v[150:153]
	v_mfma_f32_16x16x32_bf16 v[102:105], v[134:137], v[22:25], v[6:9]
	v_mfma_f32_16x16x32_bf16 v[6:9], v[206:209], v[18:21], v[154:157]
	v_mfma_f32_16x16x32_bf16 v[118:121], v[210:213], v[22:25], v[6:9]
	v_mfma_f32_16x16x32_bf16 v[6:9], v[122:125], v[26:29], v[158:161]
	v_mfma_f32_16x16x32_bf16 v[90:93], v[134:137], v[30:33], v[6:9]
	v_mfma_f32_16x16x32_bf16 v[6:9], v[206:209], v[26:29], v[74:77]
	v_mfma_f32_16x16x32_bf16 v[106:109], v[210:213], v[30:33], v[6:9]
	v_mfma_f32_16x16x32_bf16 v[6:9], v[122:125], v[38:41], v[70:73]
	v_mfma_f32_16x16x32_bf16 v[22:25], v[134:137], v[202:205], v[6:9]
	v_mfma_f32_16x16x32_bf16 v[6:9], v[206:209], v[38:41], v[66:69]
	v_mfma_f32_16x16x32_bf16 v[98:101], v[134:137], v[14:17], v[98:101]
	v_mfma_f32_16x16x32_bf16 v[38:41], v[210:213], v[202:205], v[6:9]

; #define LDA(dst, b, h) for (int m = 0; m < 4; ++m) for (int k = 0; k < 2; ++k) \
;     dst[m][k] = *reinterpret_cast<const bf16x8*>((char*)SA(b, h) + a_thr + (m * 2 + k) * 1024)
; #define MMA(ai, bj, At, Btf) do { __builtin_amdgcn_s_setprio(1); \
;     for (int m = 0; m < 4; ++m) for (int n = 0; n < 2; ++n) for (int k = 0; k < 2; ++k) \
;       acc[ai][bj][m][n] = __builtin_amdgcn_mfma_f32_16x16x32_bf16(Btf[n][k], At[m][k], acc[ai][bj][m][n], 0, 0, 0); \
;     __builtin_amdgcn_s_setprio(0); } while (0)
; #define WAIT_L(n) asm volatile("s_waitcnt lgkmcnt(" #n ")" ::: "memory")
; #define BAR __builtin_amdgcn_s_barrier()
; template <bool OVL, bool PANEL = false, class Epi>
; __device__ __forceinline__ void gemm_phase(const bf16_t* __restrict__ A, long lda, const bf16_t* __restrict__ Bt, long ldb, int nM, int nN, int K,
;                                            const Epi& epi, bf16_t* shm, int w0) {
;     ...
;       LDA(At, 1, 1); BAR; WAIT_L(0); MMA(1, 0, At, B0); MMA(1, 1, At, B1); BAR; }
	s_barrier
	ds_read_b128 v[70:73], v241 offset:49152
	ds_read_b128 v[74:77], v241 offset:50176
	ds_read_b128 v[150:153], v241 offset:51200
	ds_read_b128 v[154:157], v241 offset:52224
	ds_read_b128 v[158:161], v241 offset:53248
	ds_read_b128 v[194:197], v241 offset:54272
	ds_read_b128 v[202:205], v241 offset:55296
	ds_read_b128 v[214:217], v241 offset:56320
	s_barrier
	s_waitcnt lgkmcnt(0)

; #define LDA(dst, b, h) for (int m = 0; m < 4; ++m) for (int k = 0; k < 2; ++k) \
;     dst[m][k] = *reinterpret_cast<const bf16x8*>((char*)SA(b, h) + a_thr + (m * 2 + k) * 1024)
; #define MMA(ai, bj, At, Btf) do { __builtin_amdgcn_s_setprio(1); \
;     for (int m = 0; m < 4; ++m) for (int n = 0; n < 2; ++n) for (int k = 0; k < 2; ++k) \
;       acc[ai][bj][m][n] = __builtin_amdgcn_mfma_f32_16x16x32_bf16(Btf[n][k], At[m][k], acc[ai][bj][m][n], 0, 0, 0); \
;     __builtin_amdgcn_s_setprio(0); } while (0)
; #define WAIT_L(n) asm volatile("s_waitcnt lgkmcnt(" #n ")" ::: "memory")
; #define BAR __builtin_amdgcn_s_barrier()
; template <bool OVL, bool PANEL = false, class Epi>
; __device__ __forceinline__ void gemm_phase(const bf16_t* __restrict__ A, long lda, const bf16_t* __restrict__ Bt, long ldb, int nM, int nN, int K,
;                                            const Epi& epi, bf16_t* shm, int w0) {
;     ...
;       LDA(At, 1, 1); BAR; WAIT_L(0); MMA(1, 0, At, B0); MMA(1, 1, At, B1); BAR; }
	v_mfma_f32_16x16x32_bf16 v[14:17], v[186:189], v[70:73], v[58:61]
	v_mfma_f32_16x16x32_bf16 v[42:45], v[186:189], v[158:161], v[42:45]
	v_mfma_f32_16x16x32_bf16 v[6:9], v[174:177], v[70:73], v[62:65]
	v_mfma_f32_16x16x32_bf16 v[18:21], v[190:193], v[74:77], v[14:17]
	v_mfma_f32_16x16x32_bf16 v[14:17], v[174:177], v[150:153], v[54:57]
	v_mfma_f32_16x16x32_bf16 v[26:29], v[186:189], v[150:153], v[50:53]
	v_mfma_f32_16x16x32_bf16 v[30:33], v[174:177], v[158:161], v[46:49]
	v_mfma_f32_16x16x32_bf16 v[46:49], v[190:193], v[194:197], v[42:45]
	v_mfma_f32_16x16x32_bf16 v[42:45], v[174:177], v[202:205], v[130:133]
	v_mfma_f32_16x16x32_bf16 v[34:37], v[186:189], v[202:205], v[34:37]
	v_mfma_f32_16x16x32_bf16 v[6:9], v[182:185], v[74:77], v[6:9]
	v_mfma_f32_16x16x32_bf16 v[14:17], v[182:185], v[154:157], v[14:17]
	v_mfma_f32_16x16x32_bf16 v[26:29], v[190:193], v[154:157], v[26:29]
	v_mfma_f32_16x16x32_bf16 v[30:33], v[182:185], v[194:197], v[30:33]
	v_mfma_f32_16x16x32_bf16 v[54:57], v[182:185], v[214:217], v[42:45]
	v_mfma_f32_16x16x32_bf16 v[66:69], v[190:193], v[214:217], v[34:37]


; #define LDA(dst, b, h) for (int m = 0; m < 4; ++m) for (int k = 0; k < 2; ++k) \
;     dst[m][k] = *reinterpret_cast<const bf16x8*>((char*)SA(b, h) + a_thr + (m * 2 + k) * 1024)
; #define MMA(ai, bj, At, Btf) do { __builtin_amdgcn_s_setprio(1); \
;     for (int m = 0; m < 4; ++m) for (int n = 0; n < 2; ++n) for (int k = 0; k < 2; ++k) \
;       acc[ai][bj][m][n] = __builtin_amdgcn_mfma_f32_16x16x32_bf16(Btf[n][k], At[m][k], acc[ai][bj][m][n], 0, 0, 0); \
;     __builtin_amdgcn_s_setprio(0); } while (0)
; #define WAIT_L(n) asm volatile("s_waitcnt lgkmcnt(" #n ")" ::: "memory")
; #define BAR __builtin_amdgcn_s_barrier()
; template <bool OVL, bool PANEL = false, class Epi>
; __device__ __forceinline__ void gemm_phase(const bf16_t* __restrict__ A, long lda, const bf16_t* __restrict__ Bt, long ldb, int nM, int nN, int K,
;                                            const Epi& epi, bf16_t* shm, int w0) {
;     ...
;       LDA(At, 1, 1); BAR; WAIT_L(0); MMA(1, 0, At, B0); MMA(1, 1, At, B1); BAR; }
	v_mfma_f32_16x16x32_bf16 v[34:37], v[122:125], v[70:73], v[138:141]
	v_mfma_f32_16x16x32_bf16 v[42:45], v[206:209], v[70:73], v[142:145]
	v_mfma_f32_16x16x32_bf16 v[34:37], v[134:137], v[74:77], v[34:37]
	v_mfma_f32_16x16x32_bf16 v[50:53], v[210:213], v[74:77], v[42:45]
	v_mfma_f32_16x16x32_bf16 v[42:45], v[122:125], v[150:153], v[146:149]
	v_mfma_f32_16x16x32_bf16 v[58:61], v[206:209], v[150:153], v[178:181]
	v_mfma_f32_16x16x32_bf16 v[62:65], v[122:125], v[158:161], v[198:201]
	v_mfma_f32_16x16x32_bf16 v[70:73], v[206:209], v[158:161], v[162:165]
	v_mfma_f32_16x16x32_bf16 v[74:77], v[122:125], v[202:205], v[166:169]
	v_mfma_f32_16x16x32_bf16 v[122:125], v[206:209], v[202:205], v[170:173]
	v_mfma_f32_16x16x32_bf16 v[42:45], v[134:137], v[154:157], v[42:45]
	v_mfma_f32_16x16x32_bf16 v[58:61], v[210:213], v[154:157], v[58:61]
	v_mfma_f32_16x16x32_bf16 v[62:65], v[134:137], v[194:197], v[62:65]
	v_mfma_f32_16x16x32_bf16 v[70:73], v[210:213], v[194:197], v[70:73]
	v_mfma_f32_16x16x32_bf16 v[74:77], v[134:137], v[214:217], v[74:77]
	v_mfma_f32_16x16x32_bf16 v[122:125], v[210:213], v[214:217], v[122:125]

; #define LDA(dst, b, h) for (int m = 0; m < 4; ++m) for (int k = 0; k < 2; ++k) \
;     dst[m][k] = *reinterpret_cast<const bf16x8*>((char*)SA(b, h) + a_thr + (m * 2 + k) * 1024)
; #define MMA(ai, bj, At, Btf) do { __builtin_amdgcn_s_setprio(1); \
;     for (int m = 0; m < 4; ++m) for (int n = 0; n < 2; ++n) for (int k = 0; k < 2; ++k) \
;       acc[ai][bj][m][n] = __builtin_amdgcn_mfma_f32_16x16x32_bf16(Btf[n][k], At[m][k], acc[ai][bj][m][n], 0, 0, 0); \
;     __builtin_amdgcn_s_setprio(0); } while (0)
; #define WAIT_L(n) asm volatile("s_waitcnt lgkmcnt(" #n ")" ::: "memory")
; #define BAR __builtin_amdgcn_s_barrier()
; template <bool OVL, bool PANEL = false, class Epi>
; __device__ __forceinline__ void gemm_phase(const bf16_t* __restrict__ A, long lda, const bf16_t* __restrict__ Bt, long ldb, int nM, int nN, int K,
;                                            const Epi& epi, bf16_t* shm, int w0) {
;     ...
;       LDA(At, 1, 1); BAR; WAIT_L(0); MMA(1, 0, At, B0); MMA(1, 1, At, B1); BAR; }
;     if (wr == 0) BAR;
	s_barrier
	s_and_saveexec_b64 s[0:1], s[90:91]
	s_cbranch_execz .LBB0_475
	s_barrier

; #define LDA(dst, b, h) for (int m = 0; m < 4; ++m) for (int k = 0; k < 2; ++k) \
;     dst[m][k] = *reinterpret_cast<const bf16x8*>((char*)SA(b, h) + a_thr + (m * 2 + k) * 1024)
; #define LDB(dst, b, h) for (int n = 0; n < 2; ++n) for (int k = 0; k < 2; ++k) \
;     dst[n][k] = *reinterpret_cast<const bf16x8*>((char*)SB(b, h) + b_thr + (n * 2 + k) * 1024)
; #define WAIT_V(n) asm volatile("s_waitcnt vmcnt(" #n ")" ::: "memory")
; #define BAR __builtin_amdgcn_s_barrier()
; #define SCHED __builtin_amdgcn_sched_barrier(0)
; template <bool OVL, bool PANEL = false, class Epi>
; __device__ __forceinline__ void gemm_phase(const bf16_t* __restrict__ A, long lda, const bf16_t* __restrict__ Bt, long ldb, int nM, int nN, int K,
;                                            const Epi& epi, bf16_t* shm, int w0) {
;     ...
;     if (wr == 1) BAR;
;     WAIT_V(4); BAR;
;     STAGE(SB(1, 0), Bt, ldb, boff, bcol, 1); STAGE(SA(1, 0), A, lda, aoff, brow, 1); STAGE(SB(1, 1), Bt, ldb, boff, bcol + HALF, 1);
;     WAIT_V(6); BAR;
;     for (int t = 0; t < nt - 2; t += 2) {
;       LDB(B0, 0, 0); SCHED; LDA(At, 0, 0); STAGE(SA(1, 1), A, lda, aoff, brow + HALF, t + 1);
;     ...
;     { LDB(B0, 0, 0); LDA(At, 0, 0); STAGE(SA(1, 1), A, lda, aoff, brow + HALF, nt - 1);
.LBB0_685:
	s_or_b64 exec, exec, s[8:9]
	s_lshl_b32 s12, s21, 8
	s_ashr_i32 s13, s12, 31
	v_readlane_b32 s76, v252, 3
	s_lshl_b32 s23, s22, 8
	s_lshl_b64 s[8:9], s[12:13], 9
	v_readlane_b32 s84, v252, 11
	v_readlane_b32 s85, v252, 12
	s_add_u32 s40, s84, s8
	v_mov_b32_e32 v0, v136
	s_waitcnt vmcnt(4)
	s_barrier
	s_addc_u32 s41, s85, s9
	s_mov_b64 s[24:25], 0x80
	v_lshl_add_u64 v[2:3], s[40:41], 0, v[0:1]
	v_add_u32_e32 v0, s96, v134
	v_readlane_b32 s44, v252, 20
	v_readfirstlane_b32 s42, v0
	v_add_u32_e32 v0, 0x2000, v0
	v_lshl_add_u64 v[4:5], v[2:3], 0, s[24:25]
	s_mov_b32 m0, s42
	s_mov_b64 s[26:27], 0x8080
	v_readfirstlane_b32 s31, v0
	s_mul_i32 s8, s22, 0xf8000
	v_readlane_b32 s52, v252, 28
	global_load_lds_dwordx4 v[4:5], off
	v_lshl_add_u64 v[2:3], v[2:3], 0, s[26:27]
	s_mov_b32 m0, s31
	s_mul_hi_u32 s9, s23, 0xf80
	v_readlane_b32 s53, v252, 29
	s_add_u32 s14, s52, s8
	v_mov_b32_e32 v0, v135
	global_load_lds_dwordx4 v[2:3], off
	s_addc_u32 s15, s53, s9
	v_readlane_b32 s45, v252, 21
	v_lshl_add_u64 v[2:3], s[14:15], 0, v[0:1]
	v_add_u32_e32 v0, 0x8000, v139
	s_or_b32 s8, s12, 0x80
	v_readlane_b32 s46, v252, 22
	v_readlane_b32 s47, v252, 23
	s_mov_b64 s[44:45], 0xcc0
	v_readfirstlane_b32 s30, v0
	v_add_u32_e32 v0, 0xa000, v139
	s_ashr_i32 s9, s8, 31
	v_lshl_add_u64 v[4:5], v[2:3], 0, s[44:45]
	s_mov_b32 m0, s30
	s_mov_b64 s[46:47], 0x3ecc0
	v_readfirstlane_b32 s28, v0
	s_lshl_b64 s[8:9], s[8:9], 9
	global_load_lds_dwordx4 v[4:5], off
	v_lshl_add_u64 v[2:3], v[2:3], 0, s[46:47]
	s_mov_b32 m0, s28
	s_add_u32 s10, s84, s8
	v_mov_b32_e32 v0, v136
	global_load_lds_dwordx4 v[2:3], off
	s_addc_u32 s11, s85, s9
	v_add_u32_e32 v144, s20, v149
	v_lshl_add_u64 v[2:3], s[10:11], 0, v[0:1]
	v_add_u32_e32 v0, s75, v134
	v_lshl_add_u64 v[4:5], v[2:3], 0, s[24:25]
	v_readfirstlane_b32 s25, v0
	v_add_u32_e32 v0, 0x2000, v0
	s_mov_b32 m0, s25
	v_readfirstlane_b32 s24, v0
	global_load_lds_dwordx4 v[4:5], off
	v_lshl_add_u64 v[2:3], v[2:3], 0, s[26:27]
	s_mov_b32 m0, s24
	s_or_b32 s8, s23, 0x80
	global_load_lds_dwordx4 v[2:3], off
	s_waitcnt vmcnt(6)
	s_barrier
	ds_read_b128 v[2:5], v144
	ds_read_b128 v[6:9], v144 offset:1024
	s_waitcnt vmcnt(0)
	ds_read_b128 v[10:13], v144 offset:2048
	s_waitcnt lgkmcnt(0)
	ds_read_b128 v[14:17], v144 offset:3072
	s_mul_hi_u32 s9, s8, 0xf80
	s_mulk_i32 s8, 0xf80
	s_add_u32 s8, s52, s8
	s_addc_u32 s9, s53, s9
	v_readlane_b32 s77, v252, 4
	v_readlane_b32 s78, v252, 5
	v_readlane_b32 s79, v252, 6
	v_readlane_b32 s80, v252, 7
	v_readlane_b32 s81, v252, 8
	v_readlane_b32 s82, v252, 9
	v_readlane_b32 s83, v252, 10
	v_readlane_b32 s86, v252, 13
	v_readlane_b32 s87, v252, 14
	v_readlane_b32 s88, v252, 15
	v_readlane_b32 s89, v252, 16
	v_readlane_b32 s90, v252, 17
	v_readlane_b32 s91, v252, 18
	v_readlane_b32 s48, v252, 24
	v_readlane_b32 s49, v252, 25
	v_readlane_b32 s50, v252, 26
	v_readlane_b32 s51, v252, 27
	v_readlane_b32 s54, v252, 30
	v_readlane_b32 s55, v252, 31
	v_readlane_b32 s56, v252, 32
	v_readlane_b32 s57, v252, 33
	v_readlane_b32 s58, v252, 34
	v_readlane_b32 s59, v252, 35
	v_mov_b32_e32 v0, v135
	ds_read_b128 v[18:21], v148
	ds_read_b128 v[22:25], v148 offset:1024
	ds_read_b128 v[26:29], v148 offset:2048
	ds_read_b128 v[30:33], v148 offset:3072
	ds_read_b128 v[34:37], v148 offset:4096
	ds_read_b128 v[38:41], v148 offset:5120
	ds_read_b128 v[42:45], v148 offset:6144
	ds_read_b128 v[46:49], v148 offset:7168
	s_nop 0
	v_lshl_add_u64 v[50:51], s[8:9], 0, v[0:1]
	v_add_u32_e32 v0, 0xc000, v139
	v_lshl_add_u64 v[52:53], v[50:51], 0, s[44:45]
	v_readfirstlane_b32 s29, v0
	v_add_u32_e32 v0, 0xe000, v139
	s_mov_b32 m0, s29
	v_readfirstlane_b32 s13, v0
	global_load_lds_dwordx4 v[52:53], off
	v_lshl_add_u64 v[50:51], v[50:51], 0, s[46:47]
	s_mov_b32 m0, s13
	s_nop 0
	global_load_lds_dwordx4 v[50:51], off
	s_waitcnt lgkmcnt(8)
	s_barrier
	s_waitcnt lgkmcnt(0)

; #define MMA(ai, bj, At, Btf) do { __builtin_amdgcn_s_setprio(1); \
;     for (int m = 0; m < 4; ++m) for (int n = 0; n < 2; ++n) for (int k = 0; k < 2; ++k) \
;       acc[ai][bj][m][n] = __builtin_amdgcn_mfma_f32_16x16x32_bf16(Btf[n][k], At[m][k], acc[ai][bj][m][n], 0, 0, 0); \
;     __builtin_amdgcn_s_setprio(0); } while (0)
; #define WAIT_L(n) asm volatile("s_waitcnt lgkmcnt(" #n ")" ::: "memory")
; #define BAR __builtin_amdgcn_s_barrier()
; #define SCHED __builtin_amdgcn_sched_barrier(0)
; template <bool OVL, bool PANEL = false, class Epi>
; __device__ __forceinline__ void gemm_phase(const bf16_t* __restrict__ A, long lda, const bf16_t* __restrict__ Bt, long ldb, int nM, int nN, int K,
;                                            const Epi& epi, bf16_t* shm, int w0) {
;     ...
;       WAIT_L(8); BAR; WAIT_L(0); MMA(0, 0, At, B0); BAR; SCHED;
	v_mfma_f32_16x16x32_bf16 v[50:53], v[2:5], v[18:21], 0
	v_mfma_f32_16x16x32_bf16 v[54:57], v[10:13], v[18:21], 0
	v_mfma_f32_16x16x32_bf16 v[58:61], v[2:5], v[26:29], 0
	v_mfma_f32_16x16x32_bf16 v[62:65], v[10:13], v[26:29], 0
	v_mfma_f32_16x16x32_bf16 v[66:69], v[2:5], v[34:37], 0
	v_mfma_f32_16x16x32_bf16 v[70:73], v[10:13], v[34:37], 0
	v_mfma_f32_16x16x32_bf16 v[74:77], v[2:5], v[42:45], 0
	v_mfma_f32_16x16x32_bf16 v[78:81], v[10:13], v[42:45], 0
	v_mfma_f32_16x16x32_bf16 v[50:53], v[6:9], v[22:25], v[50:53]
	v_mfma_f32_16x16x32_bf16 v[54:57], v[14:17], v[22:25], v[54:57]
	v_mfma_f32_16x16x32_bf16 v[58:61], v[6:9], v[30:33], v[58:61]
	v_mfma_f32_16x16x32_bf16 v[62:65], v[14:17], v[30:33], v[62:65]
	v_mfma_f32_16x16x32_bf16 v[66:69], v[6:9], v[38:41], v[66:69]
	v_mfma_f32_16x16x32_bf16 v[70:73], v[14:17], v[38:41], v[70:73]
	v_mfma_f32_16x16x32_bf16 v[74:77], v[6:9], v[46:49], v[74:77]
	v_mfma_f32_16x16x32_bf16 v[78:81], v[14:17], v[46:49], v[78:81]

; #define LDB(dst, b, h) for (int n = 0; n < 2; ++n) for (int k = 0; k < 2; ++k) \
;     dst[n][k] = *reinterpret_cast<const bf16x8*>((char*)SB(b, h) + b_thr + (n * 2 + k) * 1024)
; #define MMA(ai, bj, At, Btf) do { __builtin_amdgcn_s_setprio(1); \
;     for (int m = 0; m < 4; ++m) for (int n = 0; n < 2; ++n) for (int k = 0; k < 2; ++k) \
;       acc[ai][bj][m][n] = __builtin_amdgcn_mfma_f32_16x16x32_bf16(Btf[n][k], At[m][k], acc[ai][bj][m][n], 0, 0, 0); \
;     __builtin_amdgcn_s_setprio(0); } while (0)
; #define WAIT_L(n) asm volatile("s_waitcnt lgkmcnt(" #n ")" ::: "memory")
; #define BAR __builtin_amdgcn_s_barrier()
; template <bool OVL, bool PANEL = false, class Epi>
; __device__ __forceinline__ void gemm_phase(const bf16_t* __restrict__ A, long lda, const bf16_t* __restrict__ Bt, long ldb, int nM, int nN, int K,
;                                            const Epi& epi, bf16_t* shm, int w0) {
;     ...
;       LDB(B1, 0, 1); STAGE(SB(0, 0), Bt, ldb, boff, bcol, t + 2);
;       BAR; WAIT_L(0); MMA(0, 1, At, B1); BAR;
	s_barrier
	v_add_u32_e32 v145, s33, v149
	v_mov_b32_e32 v0, v136
	ds_read_b128 v[82:85], v145
	ds_read_b128 v[86:89], v145 offset:1024
	ds_read_b128 v[90:93], v145 offset:2048
	ds_read_b128 v[94:97], v145 offset:3072
	v_readfirstlane_b32 s43, v137
	v_lshl_add_u64 v[98:99], s[40:41], 0, v[0:1]
	v_add_u32_e32 v0, 0x2000, v137
	v_lshl_add_u64 v[100:101], v[98:99], 0, s[34:35]
	s_mov_b32 m0, s43
	s_mov_b64 s[26:27], 0x8100
	v_readfirstlane_b32 s43, v0
	global_load_lds_dwordx4 v[100:101], off
	v_lshl_add_u64 v[98:99], v[98:99], 0, s[26:27]
	s_mov_b32 m0, s43
	s_nop 0
	global_load_lds_dwordx4 v[98:99], off
	s_barrier
	s_waitcnt lgkmcnt(0)

; #define MMA(ai, bj, At, Btf) do { __builtin_amdgcn_s_setprio(1); \
;     for (int m = 0; m < 4; ++m) for (int n = 0; n < 2; ++n) for (int k = 0; k < 2; ++k) \
;       acc[ai][bj][m][n] = __builtin_amdgcn_mfma_f32_16x16x32_bf16(Btf[n][k], At[m][k], acc[ai][bj][m][n], 0, 0, 0); \
;     __builtin_amdgcn_s_setprio(0); } while (0)
; #define WAIT_L(n) asm volatile("s_waitcnt lgkmcnt(" #n ")" ::: "memory")
; #define BAR __builtin_amdgcn_s_barrier()
; template <bool OVL, bool PANEL = false, class Epi>
; __device__ __forceinline__ void gemm_phase(const bf16_t* __restrict__ A, long lda, const bf16_t* __restrict__ Bt, long ldb, int nM, int nN, int K,
;                                            const Epi& epi, bf16_t* shm, int w0) {
;     ...
;       BAR; WAIT_L(0); MMA(0, 1, At, B1); BAR;
	v_mfma_f32_16x16x32_bf16 v[98:101], v[82:85], v[18:21], 0
	v_mfma_f32_16x16x32_bf16 v[18:21], v[90:93], v[18:21], 0
	v_mfma_f32_16x16x32_bf16 v[98:101], v[86:89], v[22:25], v[98:101]
	v_mfma_f32_16x16x32_bf16 v[18:21], v[94:97], v[22:25], v[18:21]
	v_mfma_f32_16x16x32_bf16 v[22:25], v[82:85], v[26:29], 0
	v_mfma_f32_16x16x32_bf16 v[26:29], v[90:93], v[26:29], 0
	v_mfma_f32_16x16x32_bf16 v[22:25], v[86:89], v[30:33], v[22:25]
	v_mfma_f32_16x16x32_bf16 v[26:29], v[94:97], v[30:33], v[26:29]
	v_mfma_f32_16x16x32_bf16 v[30:33], v[82:85], v[34:37], 0
	v_mfma_f32_16x16x32_bf16 v[34:37], v[90:93], v[34:37], 0
	v_mfma_f32_16x16x32_bf16 v[30:33], v[86:89], v[38:41], v[30:33]
	v_mfma_f32_16x16x32_bf16 v[34:37], v[94:97], v[38:41], v[34:37]
	v_mfma_f32_16x16x32_bf16 v[38:41], v[82:85], v[42:45], 0
	v_mfma_f32_16x16x32_bf16 v[42:45], v[90:93], v[42:45], 0
	v_mfma_f32_16x16x32_bf16 v[38:41], v[86:89], v[46:49], v[38:41]
	v_mfma_f32_16x16x32_bf16 v[42:45], v[94:97], v[46:49], v[42:45]

; #define LDA(dst, b, h) for (int m = 0; m < 4; ++m) for (int k = 0; k < 2; ++k) \
;     dst[m][k] = *reinterpret_cast<const bf16x8*>((char*)SA(b, h) + a_thr + (m * 2 + k) * 1024)
; #define MMA(ai, bj, At, Btf) do { __builtin_amdgcn_s_setprio(1); \
;     for (int m = 0; m < 4; ++m) for (int n = 0; n < 2; ++n) for (int k = 0; k < 2; ++k) \
;       acc[ai][bj][m][n] = __builtin_amdgcn_mfma_f32_16x16x32_bf16(Btf[n][k], At[m][k], acc[ai][bj][m][n], 0, 0, 0); \
;     __builtin_amdgcn_s_setprio(0); } while (0)
; #define WAIT_L(n) asm volatile("s_waitcnt lgkmcnt(" #n ")" ::: "memory")
; #define BAR __builtin_amdgcn_s_barrier()
; #define SCHED __builtin_amdgcn_sched_barrier(0)
; template <bool OVL, bool PANEL = false, class Epi>
; __device__ __forceinline__ void gemm_phase(const bf16_t* __restrict__ A, long lda, const bf16_t* __restrict__ Bt, long ldb, int nM, int nN, int K,
;                                            const Epi& epi, bf16_t* shm, int w0) {
;     ...
;       LDA(At, 0, 1); STAGE(SA(0, 0), A, lda, aoff, brow, t + 2);
;       BAR; WAIT_L(0); MMA(1, 0, At, B0); BAR; SCHED;
	v_mov_b32_e32 v0, v135
	s_barrier
	ds_read_b128 v[46:49], v148 offset:16384
	ds_read_b128 v[102:105], v148 offset:17408
	ds_read_b128 v[106:109], v148 offset:18432
	ds_read_b128 v[110:113], v148 offset:19456
	ds_read_b128 v[114:117], v148 offset:20480
	ds_read_b128 v[118:121], v148 offset:21504
	ds_read_b128 v[122:125], v148 offset:22528
	ds_read_b128 v[126:129], v148 offset:23552
	s_mov_b64 s[44:45], 0xd40
	v_lshl_add_u64 v[130:131], s[14:15], 0, v[0:1]
	v_readfirstlane_b32 s43, v139
	v_add_u32_e32 v0, 0x2000, v139
	v_lshl_add_u64 v[132:133], v[130:131], 0, s[44:45]
	s_mov_b32 m0, s43
	s_mov_b64 s[46:47], 0x3ed40
	v_readfirstlane_b32 s43, v0
	global_load_lds_dwordx4 v[132:133], off
	v_lshl_add_u64 v[130:131], v[130:131], 0, s[46:47]
	s_mov_b32 m0, s43
	s_nop 0
	global_load_lds_dwordx4 v[130:131], off
	s_barrier
	s_waitcnt lgkmcnt(0)

; #define MMA(ai, bj, At, Btf) do { __builtin_amdgcn_s_setprio(1); \
;     for (int m = 0; m < 4; ++m) for (int n = 0; n < 2; ++n) for (int k = 0; k < 2; ++k) \
;       acc[ai][bj][m][n] = __builtin_amdgcn_mfma_f32_16x16x32_bf16(Btf[n][k], At[m][k], acc[ai][bj][m][n], 0, 0, 0); \
;     __builtin_amdgcn_s_setprio(0); } while (0)
; #define WAIT_L(n) asm volatile("s_waitcnt lgkmcnt(" #n ")" ::: "memory")
; #define BAR __builtin_amdgcn_s_barrier()
; #define SCHED __builtin_amdgcn_sched_barrier(0)
; template <bool OVL, bool PANEL = false, class Epi>
; __device__ __forceinline__ void gemm_phase(const bf16_t* __restrict__ A, long lda, const bf16_t* __restrict__ Bt, long ldb, int nM, int nN, int K,
;                                            const Epi& epi, bf16_t* shm, int w0) {
;     ...
;       BAR; WAIT_L(0); MMA(1, 0, At, B0); BAR; SCHED;
	v_mfma_f32_16x16x32_bf16 v[130:133], v[2:5], v[46:49], 0
	v_mfma_f32_16x16x32_bf16 v[154:157], v[2:5], v[106:109], 0
	v_mfma_f32_16x16x32_bf16 v[162:165], v[2:5], v[114:117], 0
	v_mfma_f32_16x16x32_bf16 v[2:5], v[2:5], v[122:125], 0
	v_mfma_f32_16x16x32_bf16 v[130:133], v[6:9], v[102:105], v[130:133]
	v_mfma_f32_16x16x32_bf16 v[154:157], v[6:9], v[110:113], v[154:157]
	v_mfma_f32_16x16x32_bf16 v[162:165], v[6:9], v[118:121], v[162:165]
	v_mfma_f32_16x16x32_bf16 v[2:5], v[6:9], v[126:129], v[2:5]
	v_mfma_f32_16x16x32_bf16 v[6:9], v[10:13], v[122:125], 0
	v_mfma_f32_16x16x32_bf16 v[150:153], v[10:13], v[46:49], 0
	v_mfma_f32_16x16x32_bf16 v[158:161], v[10:13], v[106:109], 0
	v_mfma_f32_16x16x32_bf16 v[166:169], v[10:13], v[114:117], 0
	v_mfma_f32_16x16x32_bf16 v[6:9], v[14:17], v[126:129], v[6:9]
	v_mfma_f32_16x16x32_bf16 v[150:153], v[14:17], v[102:105], v[150:153]
	v_mfma_f32_16x16x32_bf16 v[158:161], v[14:17], v[110:113], v[158:161]
	v_mfma_f32_16x16x32_bf16 v[166:169], v[14:17], v[118:121], v[166:169]

; #define MMA(ai, bj, At, Btf) do { __builtin_amdgcn_s_setprio(1); \
;     for (int m = 0; m < 4; ++m) for (int n = 0; n < 2; ++n) for (int k = 0; k < 2; ++k) \
;       acc[ai][bj][m][n] = __builtin_amdgcn_mfma_f32_16x16x32_bf16(Btf[n][k], At[m][k], acc[ai][bj][m][n], 0, 0, 0); \
;     __builtin_amdgcn_s_setprio(0); } while (0)
; #define WAIT_V(n) asm volatile("s_waitcnt vmcnt(" #n ")" ::: "memory")
; #define BAR __builtin_amdgcn_s_barrier()
; template <bool OVL, bool PANEL = false, class Epi>
; __device__ __forceinline__ void gemm_phase(const bf16_t* __restrict__ A, long lda, const bf16_t* __restrict__ Bt, long ldb, int nM, int nN, int K,
;                                            const Epi& epi, bf16_t* shm, int w0) {
;     ...
;       STAGE(SB(0, 1), Bt, ldb, boff, bcol + HALF, t + 2);
;       WAIT_V(6); BAR; MMA(1, 1, At, B1); BAR;
	s_barrier
	v_mov_b32_e32 v0, v136
	v_readfirstlane_b32 s43, v227
	v_lshl_add_u64 v[10:11], s[10:11], 0, v[0:1]
	v_add_u32_e32 v0, 0x2000, v227
	v_lshl_add_u64 v[12:13], v[10:11], 0, s[34:35]
	s_mov_b32 m0, s43
	v_readfirstlane_b32 s43, v0
	global_load_lds_dwordx4 v[12:13], off
	v_lshl_add_u64 v[10:11], v[10:11], 0, s[26:27]
	s_mov_b32 m0, s43
	s_nop 0
	global_load_lds_dwordx4 v[10:11], off
	s_waitcnt vmcnt(6)
	s_barrier

; #define MMA(ai, bj, At, Btf) do { __builtin_amdgcn_s_setprio(1); \
;     for (int m = 0; m < 4; ++m) for (int n = 0; n < 2; ++n) for (int k = 0; k < 2; ++k) \
;       acc[ai][bj][m][n] = __builtin_amdgcn_mfma_f32_16x16x32_bf16(Btf[n][k], At[m][k], acc[ai][bj][m][n], 0, 0, 0); \
;     __builtin_amdgcn_s_setprio(0); } while (0)
; #define WAIT_V(n) asm volatile("s_waitcnt vmcnt(" #n ")" ::: "memory")
; #define BAR __builtin_amdgcn_s_barrier()
; template <bool OVL, bool PANEL = false, class Epi>
; __device__ __forceinline__ void gemm_phase(const bf16_t* __restrict__ A, long lda, const bf16_t* __restrict__ Bt, long ldb, int nM, int nN, int K,
;                                            const Epi& epi, bf16_t* shm, int w0) {
;     ...
;       WAIT_V(6); BAR; MMA(1, 1, At, B1); BAR;
	v_mfma_f32_16x16x32_bf16 v[10:13], v[82:85], v[46:49], 0
	v_mfma_f32_16x16x32_bf16 v[14:17], v[90:93], v[46:49], 0
	v_mfma_f32_16x16x32_bf16 v[10:13], v[86:89], v[102:105], v[10:13]
	v_mfma_f32_16x16x32_bf16 v[14:17], v[94:97], v[102:105], v[14:17]
	v_mfma_f32_16x16x32_bf16 v[46:49], v[82:85], v[106:109], 0
	v_mfma_f32_16x16x32_bf16 v[102:105], v[90:93], v[106:109], 0
	v_mfma_f32_16x16x32_bf16 v[106:109], v[82:85], v[114:117], 0
	v_mfma_f32_16x16x32_bf16 v[82:85], v[82:85], v[122:125], 0
	v_mfma_f32_16x16x32_bf16 v[46:49], v[86:89], v[110:113], v[46:49]
	v_mfma_f32_16x16x32_bf16 v[102:105], v[94:97], v[110:113], v[102:105]
	v_mfma_f32_16x16x32_bf16 v[106:109], v[86:89], v[118:121], v[106:109]
	v_mfma_f32_16x16x32_bf16 v[110:113], v[90:93], v[114:117], 0
	v_mfma_f32_16x16x32_bf16 v[82:85], v[86:89], v[126:129], v[82:85]
	v_mfma_f32_16x16x32_bf16 v[86:89], v[90:93], v[122:125], 0
	v_mfma_f32_16x16x32_bf16 v[110:113], v[94:97], v[118:121], v[110:113]
	v_mfma_f32_16x16x32_bf16 v[86:89], v[94:97], v[126:129], v[86:89]

; #define LDA(dst, b, h) for (int m = 0; m < 4; ++m) for (int k = 0; k < 2; ++k) \
;     dst[m][k] = *reinterpret_cast<const bf16x8*>((char*)SA(b, h) + a_thr + (m * 2 + k) * 1024)
; #define LDB(dst, b, h) for (int n = 0; n < 2; ++n) for (int k = 0; k < 2; ++k) \
;     dst[n][k] = *reinterpret_cast<const bf16x8*>((char*)SB(b, h) + b_thr + (n * 2 + k) * 1024)
; #define MMA(ai, bj, At, Btf) do { __builtin_amdgcn_s_setprio(1); \
;     for (int m = 0; m < 4; ++m) for (int n = 0; n < 2; ++n) for (int k = 0; k < 2; ++k) \
;       acc[ai][bj][m][n] = __builtin_amdgcn_mfma_f32_16x16x32_bf16(Btf[n][k], At[m][k], acc[ai][bj][m][n], 0, 0, 0); \
;     __builtin_amdgcn_s_setprio(0); } while (0)
; #define WAIT_L(n) asm volatile("s_waitcnt lgkmcnt(" #n ")" ::: "memory")
; #define BAR __builtin_amdgcn_s_barrier()
; #define SCHED __builtin_amdgcn_sched_barrier(0)
; template <bool OVL, bool PANEL = false, class Epi>
; __device__ __forceinline__ void gemm_phase(const bf16_t* __restrict__ A, long lda, const bf16_t* __restrict__ Bt, long ldb, int nM, int nN, int K,
;                                            const Epi& epi, bf16_t* shm, int w0) {
;     ...
;       LDB(B0, 1, 0); SCHED; LDA(At, 1, 0); STAGE(SA(0, 1), A, lda, aoff, brow + HALF, t + 2);
;       WAIT_L(8); BAR; WAIT_L(0); MMA(0, 0, At, B0); BAR; SCHED;
	v_add_u32_e32 v146, s96, v149
	s_barrier
	ds_read_b128 v[90:93], v146
	ds_read_b128 v[94:97], v146 offset:1024
	ds_read_b128 v[114:117], v146 offset:2048
	ds_read_b128 v[118:121], v146 offset:3072
	v_mov_b32_e32 v0, v135
	ds_read_b128 v[122:125], v148 offset:32768
	ds_read_b128 v[126:129], v148 offset:33792
	ds_read_b128 v[170:173], v148 offset:34816
	ds_read_b128 v[174:177], v148 offset:35840
	ds_read_b128 v[178:181], v148 offset:36864
	ds_read_b128 v[182:185], v148 offset:37888
	ds_read_b128 v[186:189], v148 offset:38912
	ds_read_b128 v[190:193], v148 offset:39936
	s_nop 0
	v_lshl_add_u64 v[140:141], s[8:9], 0, v[0:1]
	v_add_u32_e32 v0, 0x4000, v139
	v_lshl_add_u64 v[142:143], v[140:141], 0, s[44:45]
	v_readfirstlane_b32 s43, v0
	s_mov_b32 m0, s43
	v_readfirstlane_b32 s43, v138
	global_load_lds_dwordx4 v[142:143], off
	v_lshl_add_u64 v[140:141], v[140:141], 0, s[46:47]
	s_mov_b32 m0, s43
	s_nop 0
	global_load_lds_dwordx4 v[140:141], off
	s_waitcnt lgkmcnt(8)
	s_barrier
	s_waitcnt lgkmcnt(0)

; #define MMA(ai, bj, At, Btf) do { __builtin_amdgcn_s_setprio(1); \
;     for (int m = 0; m < 4; ++m) for (int n = 0; n < 2; ++n) for (int k = 0; k < 2; ++k) \
;       acc[ai][bj][m][n] = __builtin_amdgcn_mfma_f32_16x16x32_bf16(Btf[n][k], At[m][k], acc[ai][bj][m][n], 0, 0, 0); \
;     __builtin_amdgcn_s_setprio(0); } while (0)
; #define WAIT_L(n) asm volatile("s_waitcnt lgkmcnt(" #n ")" ::: "memory")
; #define BAR __builtin_amdgcn_s_barrier()
; #define SCHED __builtin_amdgcn_sched_barrier(0)
; template <bool OVL, bool PANEL = false, class Epi>
; __device__ __forceinline__ void gemm_phase(const bf16_t* __restrict__ A, long lda, const bf16_t* __restrict__ Bt, long ldb, int nM, int nN, int K,
;                                            const Epi& epi, bf16_t* shm, int w0) {
;     ...
;       WAIT_L(8); BAR; WAIT_L(0); MMA(0, 0, At, B0); BAR; SCHED;
	v_mfma_f32_16x16x32_bf16 v[50:53], v[90:93], v[122:125], v[50:53]
	v_mfma_f32_16x16x32_bf16 v[54:57], v[114:117], v[122:125], v[54:57]
	v_mfma_f32_16x16x32_bf16 v[58:61], v[90:93], v[170:173], v[58:61]
	v_mfma_f32_16x16x32_bf16 v[62:65], v[114:117], v[170:173], v[62:65]
	v_mfma_f32_16x16x32_bf16 v[66:69], v[90:93], v[178:181], v[66:69]
	v_mfma_f32_16x16x32_bf16 v[70:73], v[114:117], v[178:181], v[70:73]
	v_mfma_f32_16x16x32_bf16 v[74:77], v[90:93], v[186:189], v[74:77]
	v_mfma_f32_16x16x32_bf16 v[78:81], v[114:117], v[186:189], v[78:81]
	v_mfma_f32_16x16x32_bf16 v[50:53], v[94:97], v[126:129], v[50:53]
	v_mfma_f32_16x16x32_bf16 v[54:57], v[118:121], v[126:129], v[54:57]
	v_mfma_f32_16x16x32_bf16 v[58:61], v[94:97], v[174:177], v[58:61]
	v_mfma_f32_16x16x32_bf16 v[62:65], v[118:121], v[174:177], v[62:65]
	v_mfma_f32_16x16x32_bf16 v[66:69], v[94:97], v[182:185], v[66:69]
	v_mfma_f32_16x16x32_bf16 v[70:73], v[118:121], v[182:185], v[70:73]
	v_mfma_f32_16x16x32_bf16 v[74:77], v[94:97], v[190:193], v[74:77]
	v_mfma_f32_16x16x32_bf16 v[78:81], v[118:121], v[190:193], v[78:81]

; #define LDB(dst, b, h) for (int n = 0; n < 2; ++n) for (int k = 0; k < 2; ++k) \
;     dst[n][k] = *reinterpret_cast<const bf16x8*>((char*)SB(b, h) + b_thr + (n * 2 + k) * 1024)
; #define MMA(ai, bj, At, Btf) do { __builtin_amdgcn_s_setprio(1); \
;     for (int m = 0; m < 4; ++m) for (int n = 0; n < 2; ++n) for (int k = 0; k < 2; ++k) \
;       acc[ai][bj][m][n] = __builtin_amdgcn_mfma_f32_16x16x32_bf16(Btf[n][k], At[m][k], acc[ai][bj][m][n], 0, 0, 0); \
;     __builtin_amdgcn_s_setprio(0); } while (0)
; #define WAIT_L(n) asm volatile("s_waitcnt lgkmcnt(" #n ")" ::: "memory")
; #define BAR __builtin_amdgcn_s_barrier()
; template <bool OVL, bool PANEL = false, class Epi>
; __device__ __forceinline__ void gemm_phase(const bf16_t* __restrict__ A, long lda, const bf16_t* __restrict__ Bt, long ldb, int nM, int nN, int K,
;                                            const Epi& epi, bf16_t* shm, int w0) {
;     ...
;       LDB(B1, 1, 1); STAGE(SB(1, 0), Bt, ldb, boff, bcol, t + 3);
;       BAR; WAIT_L(0); MMA(0, 1, At, B1); BAR;
	s_barrier
	v_add_u32_e32 v147, s75, v149
	v_mov_b32_e32 v0, v136
	ds_read_b128 v[194:197], v147
	ds_read_b128 v[198:201], v147 offset:1024
	ds_read_b128 v[202:205], v147 offset:2048
	ds_read_b128 v[206:209], v147 offset:3072
	s_mov_b32 m0, s42
	v_lshl_add_u64 v[140:141], s[40:41], 0, v[0:1]
	v_lshl_add_u64 v[142:143], v[140:141], 0, s[94:95]
	s_mov_b64 s[26:27], 0x8180
	global_load_lds_dwordx4 v[142:143], off
	v_lshl_add_u64 v[140:141], v[140:141], 0, s[26:27]
	s_mov_b32 m0, s31
	s_nop 0
	global_load_lds_dwordx4 v[140:141], off
	s_barrier
	s_waitcnt lgkmcnt(0)

; #define MMA(ai, bj, At, Btf) do { __builtin_amdgcn_s_setprio(1); \
;     for (int m = 0; m < 4; ++m) for (int n = 0; n < 2; ++n) for (int k = 0; k < 2; ++k) \
;       acc[ai][bj][m][n] = __builtin_amdgcn_mfma_f32_16x16x32_bf16(Btf[n][k], At[m][k], acc[ai][bj][m][n], 0, 0, 0); \
;     __builtin_amdgcn_s_setprio(0); } while (0)
; #define WAIT_L(n) asm volatile("s_waitcnt lgkmcnt(" #n ")" ::: "memory")
; #define BAR __builtin_amdgcn_s_barrier()
; template <bool OVL, bool PANEL = false, class Epi>
; __device__ __forceinline__ void gemm_phase(const bf16_t* __restrict__ A, long lda, const bf16_t* __restrict__ Bt, long ldb, int nM, int nN, int K,
;                                            const Epi& epi, bf16_t* shm, int w0) {
;     ...
;       BAR; WAIT_L(0); MMA(0, 1, At, B1); BAR;
	v_mfma_f32_16x16x32_bf16 v[98:101], v[194:197], v[122:125], v[98:101]
	v_mfma_f32_16x16x32_bf16 v[18:21], v[202:205], v[122:125], v[18:21]
	v_mfma_f32_16x16x32_bf16 v[22:25], v[194:197], v[170:173], v[22:25]
	v_mfma_f32_16x16x32_bf16 v[26:29], v[202:205], v[170:173], v[26:29]
	v_mfma_f32_16x16x32_bf16 v[30:33], v[194:197], v[178:181], v[30:33]
	v_mfma_f32_16x16x32_bf16 v[34:37], v[202:205], v[178:181], v[34:37]
	v_mfma_f32_16x16x32_bf16 v[38:41], v[194:197], v[186:189], v[38:41]
	v_mfma_f32_16x16x32_bf16 v[42:45], v[202:205], v[186:189], v[42:45]
	v_mfma_f32_16x16x32_bf16 v[98:101], v[198:201], v[126:129], v[98:101]
	v_mfma_f32_16x16x32_bf16 v[18:21], v[206:209], v[126:129], v[18:21]
	v_mfma_f32_16x16x32_bf16 v[22:25], v[198:201], v[174:177], v[22:25]
	v_mfma_f32_16x16x32_bf16 v[26:29], v[206:209], v[174:177], v[26:29]
	v_mfma_f32_16x16x32_bf16 v[30:33], v[198:201], v[182:185], v[30:33]
	v_mfma_f32_16x16x32_bf16 v[34:37], v[206:209], v[182:185], v[34:37]
	v_mfma_f32_16x16x32_bf16 v[38:41], v[198:201], v[190:193], v[38:41]
	v_mfma_f32_16x16x32_bf16 v[42:45], v[206:209], v[190:193], v[42:45]

; #define LDA(dst, b, h) for (int m = 0; m < 4; ++m) for (int k = 0; k < 2; ++k) \
;     dst[m][k] = *reinterpret_cast<const bf16x8*>((char*)SA(b, h) + a_thr + (m * 2 + k) * 1024)
; #define MMA(ai, bj, At, Btf) do { __builtin_amdgcn_s_setprio(1); \
;     for (int m = 0; m < 4; ++m) for (int n = 0; n < 2; ++n) for (int k = 0; k < 2; ++k) \
;       acc[ai][bj][m][n] = __builtin_amdgcn_mfma_f32_16x16x32_bf16(Btf[n][k], At[m][k], acc[ai][bj][m][n], 0, 0, 0); \
;     __builtin_amdgcn_s_setprio(0); } while (0)
; #define WAIT_L(n) asm volatile("s_waitcnt lgkmcnt(" #n ")" ::: "memory")
; #define BAR __builtin_amdgcn_s_barrier()
; #define SCHED __builtin_amdgcn_sched_barrier(0)
; template <bool OVL, bool PANEL = false, class Epi>
; __device__ __forceinline__ void gemm_phase(const bf16_t* __restrict__ A, long lda, const bf16_t* __restrict__ Bt, long ldb, int nM, int nN, int K,
;                                            const Epi& epi, bf16_t* shm, int w0) {
;     ...
;       LDA(At, 1, 1); STAGE(SA(1, 0), A, lda, aoff, brow, t + 3);
;       BAR; WAIT_L(0); MMA(1, 0, At, B0); BAR; SCHED;
	v_mov_b32_e32 v0, v135
	s_barrier
	ds_read_b128 v[122:125], v148 offset:49152
	ds_read_b128 v[126:129], v148 offset:50176
	ds_read_b128 v[170:173], v148 offset:51200
	ds_read_b128 v[174:177], v148 offset:52224
	ds_read_b128 v[178:181], v148 offset:53248
	ds_read_b128 v[182:185], v148 offset:54272
	ds_read_b128 v[186:189], v148 offset:55296
	ds_read_b128 v[190:193], v148 offset:56320
	s_mov_b32 m0, s30
	v_lshl_add_u64 v[140:141], s[14:15], 0, v[0:1]
	s_mov_b64 s[14:15], 0xdc0
	v_lshl_add_u64 v[142:143], v[140:141], 0, s[14:15]
	s_mov_b64 s[30:31], 0x3edc0
	global_load_lds_dwordx4 v[142:143], off
	v_lshl_add_u64 v[140:141], v[140:141], 0, s[30:31]
	s_mov_b32 m0, s28
	s_nop 0
	global_load_lds_dwordx4 v[140:141], off
	s_barrier
	s_waitcnt lgkmcnt(0)

; #define MMA(ai, bj, At, Btf) do { __builtin_amdgcn_s_setprio(1); \
;     for (int m = 0; m < 4; ++m) for (int n = 0; n < 2; ++n) for (int k = 0; k < 2; ++k) \
;       acc[ai][bj][m][n] = __builtin_amdgcn_mfma_f32_16x16x32_bf16(Btf[n][k], At[m][k], acc[ai][bj][m][n], 0, 0, 0); \
;     __builtin_amdgcn_s_setprio(0); } while (0)
; #define WAIT_L(n) asm volatile("s_waitcnt lgkmcnt(" #n ")" ::: "memory")
; #define BAR __builtin_amdgcn_s_barrier()
; #define SCHED __builtin_amdgcn_sched_barrier(0)
; template <bool OVL, bool PANEL = false, class Epi>
; __device__ __forceinline__ void gemm_phase(const bf16_t* __restrict__ A, long lda, const bf16_t* __restrict__ Bt, long ldb, int nM, int nN, int K,
;                                            const Epi& epi, bf16_t* shm, int w0) {
;     ...
;       BAR; WAIT_L(0); MMA(1, 0, At, B0); BAR; SCHED;
	v_mfma_f32_16x16x32_bf16 v[2:5], v[90:93], v[186:189], v[2:5]
	v_mfma_f32_16x16x32_bf16 v[6:9], v[114:117], v[186:189], v[6:9]
	v_mfma_f32_16x16x32_bf16 v[130:133], v[90:93], v[122:125], v[130:133]
	v_mfma_f32_16x16x32_bf16 v[150:153], v[114:117], v[122:125], v[150:153]
	v_mfma_f32_16x16x32_bf16 v[154:157], v[90:93], v[170:173], v[154:157]
	v_mfma_f32_16x16x32_bf16 v[158:161], v[114:117], v[170:173], v[158:161]
	v_mfma_f32_16x16x32_bf16 v[162:165], v[90:93], v[178:181], v[162:165]
	v_mfma_f32_16x16x32_bf16 v[166:169], v[114:117], v[178:181], v[166:169]
	v_mfma_f32_16x16x32_bf16 v[2:5], v[94:97], v[190:193], v[2:5]
	v_mfma_f32_16x16x32_bf16 v[6:9], v[118:121], v[190:193], v[6:9]
	v_mfma_f32_16x16x32_bf16 v[130:133], v[94:97], v[126:129], v[130:133]
	v_mfma_f32_16x16x32_bf16 v[150:153], v[118:121], v[126:129], v[150:153]
	v_mfma_f32_16x16x32_bf16 v[154:157], v[94:97], v[174:177], v[154:157]
	v_mfma_f32_16x16x32_bf16 v[158:161], v[118:121], v[174:177], v[158:161]
	v_mfma_f32_16x16x32_bf16 v[162:165], v[94:97], v[182:185], v[162:165]
	v_mfma_f32_16x16x32_bf16 v[166:169], v[118:121], v[182:185], v[166:169]

; #define MMA(ai, bj, At, Btf) do { __builtin_amdgcn_s_setprio(1); \
;     for (int m = 0; m < 4; ++m) for (int n = 0; n < 2; ++n) for (int k = 0; k < 2; ++k) \
;       acc[ai][bj][m][n] = __builtin_amdgcn_mfma_f32_16x16x32_bf16(Btf[n][k], At[m][k], acc[ai][bj][m][n], 0, 0, 0); \
;     __builtin_amdgcn_s_setprio(0); } while (0)
; #define WAIT_V(n) asm volatile("s_waitcnt vmcnt(" #n ")" ::: "memory")
; #define BAR __builtin_amdgcn_s_barrier()
; template <bool OVL, bool PANEL = false, class Epi>
; __device__ __forceinline__ void gemm_phase(const bf16_t* __restrict__ A, long lda, const bf16_t* __restrict__ Bt, long ldb, int nM, int nN, int K,
;                                            const Epi& epi, bf16_t* shm, int w0) {
;     ...
;       STAGE(SB(1, 1), Bt, ldb, boff, bcol + HALF, t + 3);
;       WAIT_V(6); BAR; MMA(1, 1, At, B1); BAR;
	s_barrier
	v_mov_b32_e32 v0, v136
	s_mov_b32 m0, s25
	v_lshl_add_u64 v[90:91], s[10:11], 0, v[0:1]
	v_lshl_add_u64 v[92:93], v[90:91], 0, s[94:95]
	global_load_lds_dwordx4 v[92:93], off
	v_lshl_add_u64 v[90:91], v[90:91], 0, s[26:27]
	s_mov_b32 m0, s24
	s_nop 0
	global_load_lds_dwordx4 v[90:91], off
	s_waitcnt vmcnt(6)
	s_barrier

; #define MMA(ai, bj, At, Btf) do { __builtin_amdgcn_s_setprio(1); \
;     for (int m = 0; m < 4; ++m) for (int n = 0; n < 2; ++n) for (int k = 0; k < 2; ++k) \
;       acc[ai][bj][m][n] = __builtin_amdgcn_mfma_f32_16x16x32_bf16(Btf[n][k], At[m][k], acc[ai][bj][m][n], 0, 0, 0); \
;     __builtin_amdgcn_s_setprio(0); } while (0)
; #define WAIT_V(n) asm volatile("s_waitcnt vmcnt(" #n ")" ::: "memory")
; #define BAR __builtin_amdgcn_s_barrier()
; template <bool OVL, bool PANEL = false, class Epi>
; __device__ __forceinline__ void gemm_phase(const bf16_t* __restrict__ A, long lda, const bf16_t* __restrict__ Bt, long ldb, int nM, int nN, int K,
;                                            const Epi& epi, bf16_t* shm, int w0) {
;     ...
;       WAIT_V(6); BAR; MMA(1, 1, At, B1); BAR;
	v_mfma_f32_16x16x32_bf16 v[10:13], v[194:197], v[122:125], v[10:13]
	v_mfma_f32_16x16x32_bf16 v[14:17], v[202:205], v[122:125], v[14:17]
	v_mfma_f32_16x16x32_bf16 v[46:49], v[194:197], v[170:173], v[46:49]
	v_mfma_f32_16x16x32_bf16 v[90:93], v[202:205], v[170:173], v[102:105]
	v_mfma_f32_16x16x32_bf16 v[94:97], v[194:197], v[178:181], v[106:109]
	v_mfma_f32_16x16x32_bf16 v[102:105], v[202:205], v[178:181], v[110:113]
	v_mfma_f32_16x16x32_bf16 v[82:85], v[194:197], v[186:189], v[82:85]
	v_mfma_f32_16x16x32_bf16 v[86:89], v[202:205], v[186:189], v[86:89]
	v_mfma_f32_16x16x32_bf16 v[10:13], v[198:201], v[126:129], v[10:13]
	v_mfma_f32_16x16x32_bf16 v[14:17], v[206:209], v[126:129], v[14:17]
	v_mfma_f32_16x16x32_bf16 v[46:49], v[198:201], v[174:177], v[46:49]
	v_mfma_f32_16x16x32_bf16 v[90:93], v[206:209], v[174:177], v[90:93]
	v_mfma_f32_16x16x32_bf16 v[94:97], v[198:201], v[182:185], v[94:97]
	v_mfma_f32_16x16x32_bf16 v[102:105], v[206:209], v[182:185], v[102:105]
	v_mfma_f32_16x16x32_bf16 v[82:85], v[198:201], v[190:193], v[82:85]
	v_mfma_f32_16x16x32_bf16 v[86:89], v[206:209], v[190:193], v[86:89]

; #define LDA(dst, b, h) for (int m = 0; m < 4; ++m) for (int k = 0; k < 2; ++k) \
;     dst[m][k] = *reinterpret_cast<const bf16x8*>((char*)SA(b, h) + a_thr + (m * 2 + k) * 1024)
; #define LDB(dst, b, h) for (int n = 0; n < 2; ++n) for (int k = 0; k < 2; ++k) \
;     dst[n][k] = *reinterpret_cast<const bf16x8*>((char*)SB(b, h) + b_thr + (n * 2 + k) * 1024)
; #define MMA(ai, bj, At, Btf) do { __builtin_amdgcn_s_setprio(1); \
;     for (int m = 0; m < 4; ++m) for (int n = 0; n < 2; ++n) for (int k = 0; k < 2; ++k) \
;       acc[ai][bj][m][n] = __builtin_amdgcn_mfma_f32_16x16x32_bf16(Btf[n][k], At[m][k], acc[ai][bj][m][n], 0, 0, 0); \
;     __builtin_amdgcn_s_setprio(0); } while (0)
; #define WAIT_L(n) asm volatile("s_waitcnt lgkmcnt(" #n ")" ::: "memory")
; #define BAR __builtin_amdgcn_s_barrier()
; template <bool OVL, bool PANEL = false, class Epi>
; __device__ __forceinline__ void gemm_phase(const bf16_t* __restrict__ A, long lda, const bf16_t* __restrict__ Bt, long ldb, int nM, int nN, int K,
;                                            const Epi& epi, bf16_t* shm, int w0) {
;     ...
;     { LDB(B0, 0, 0); LDA(At, 0, 0); STAGE(SA(1, 1), A, lda, aoff, brow + HALF, nt - 1);
;       BAR; WAIT_L(0); MMA(0, 0, At, B0); BAR;
	v_mov_b32_e32 v0, v135
	s_barrier
	ds_read_b128 v[106:109], v144
	ds_read_b128 v[110:113], v144 offset:1024
	ds_read_b128 v[114:117], v144 offset:2048
	ds_read_b128 v[118:121], v144 offset:3072
	ds_read_b128 v[122:125], v148
	ds_read_b128 v[126:129], v148 offset:1024
	ds_read_b128 v[170:173], v148 offset:2048
	ds_read_b128 v[174:177], v148 offset:3072
	ds_read_b128 v[178:181], v148 offset:4096
	ds_read_b128 v[182:185], v148 offset:5120
	ds_read_b128 v[186:189], v148 offset:6144
	ds_read_b128 v[190:193], v148 offset:7168
	s_mov_b32 m0, s29
	v_lshl_add_u64 v[140:141], s[8:9], 0, v[0:1]
	v_lshl_add_u64 v[142:143], v[140:141], 0, s[14:15]
	global_load_lds_dwordx4 v[142:143], off
	v_lshl_add_u64 v[140:141], v[140:141], 0, s[30:31]
	s_mov_b32 m0, s13
	s_nop 0
	global_load_lds_dwordx4 v[140:141], off
	s_barrier
	s_waitcnt lgkmcnt(0)

; #define MMA(ai, bj, At, Btf) do { __builtin_amdgcn_s_setprio(1); \
;     for (int m = 0; m < 4; ++m) for (int n = 0; n < 2; ++n) for (int k = 0; k < 2; ++k) \
;       acc[ai][bj][m][n] = __builtin_amdgcn_mfma_f32_16x16x32_bf16(Btf[n][k], At[m][k], acc[ai][bj][m][n], 0, 0, 0); \
;     __builtin_amdgcn_s_setprio(0); } while (0)
; #define WAIT_L(n) asm volatile("s_waitcnt lgkmcnt(" #n ")" ::: "memory")
; #define BAR __builtin_amdgcn_s_barrier()
; template <bool OVL, bool PANEL = false, class Epi>
; __device__ __forceinline__ void gemm_phase(const bf16_t* __restrict__ A, long lda, const bf16_t* __restrict__ Bt, long ldb, int nM, int nN, int K,
;                                            const Epi& epi, bf16_t* shm, int w0) {
;     ...
;       BAR; WAIT_L(0); MMA(0, 0, At, B0); BAR;
	v_mfma_f32_16x16x32_bf16 v[50:53], v[106:109], v[122:125], v[50:53]
	v_mfma_f32_16x16x32_bf16 v[54:57], v[114:117], v[122:125], v[54:57]
	v_mfma_f32_16x16x32_bf16 v[58:61], v[106:109], v[170:173], v[58:61]
	v_mfma_f32_16x16x32_bf16 v[62:65], v[114:117], v[170:173], v[62:65]
	v_mfma_f32_16x16x32_bf16 v[66:69], v[106:109], v[178:181], v[66:69]
	v_mfma_f32_16x16x32_bf16 v[70:73], v[114:117], v[178:181], v[70:73]
	v_mfma_f32_16x16x32_bf16 v[74:77], v[106:109], v[186:189], v[74:77]
	v_mfma_f32_16x16x32_bf16 v[78:81], v[114:117], v[186:189], v[78:81]
	v_mfma_f32_16x16x32_bf16 v[50:53], v[110:113], v[126:129], v[50:53]
	v_mfma_f32_16x16x32_bf16 v[54:57], v[118:121], v[126:129], v[54:57]
	v_mfma_f32_16x16x32_bf16 v[58:61], v[110:113], v[174:177], v[58:61]
	v_mfma_f32_16x16x32_bf16 v[62:65], v[118:121], v[174:177], v[62:65]
	v_mfma_f32_16x16x32_bf16 v[66:69], v[110:113], v[182:185], v[66:69]
	v_mfma_f32_16x16x32_bf16 v[70:73], v[118:121], v[182:185], v[70:73]
	v_mfma_f32_16x16x32_bf16 v[74:77], v[110:113], v[190:193], v[74:77]
	v_mfma_f32_16x16x32_bf16 v[78:81], v[118:121], v[190:193], v[78:81]

; #define LDB(dst, b, h) for (int n = 0; n < 2; ++n) for (int k = 0; k < 2; ++k) \
;     dst[n][k] = *reinterpret_cast<const bf16x8*>((char*)SB(b, h) + b_thr + (n * 2 + k) * 1024)
; #define MMA(ai, bj, At, Btf) do { __builtin_amdgcn_s_setprio(1); \
;     for (int m = 0; m < 4; ++m) for (int n = 0; n < 2; ++n) for (int k = 0; k < 2; ++k) \
;       acc[ai][bj][m][n] = __builtin_amdgcn_mfma_f32_16x16x32_bf16(Btf[n][k], At[m][k], acc[ai][bj][m][n], 0, 0, 0); \
;     __builtin_amdgcn_s_setprio(0); } while (0)
; #define WAIT_L(n) asm volatile("s_waitcnt lgkmcnt(" #n ")" ::: "memory")
; #define BAR __builtin_amdgcn_s_barrier()
; template <bool OVL, bool PANEL = false, class Epi>
; __device__ __forceinline__ void gemm_phase(const bf16_t* __restrict__ A, long lda, const bf16_t* __restrict__ Bt, long ldb, int nM, int nN, int K,
;                                            const Epi& epi, bf16_t* shm, int w0) {
;     ...
;       LDB(B1, 0, 1); BAR; WAIT_L(0); MMA(0, 1, At, B1); BAR;
	s_barrier
	ds_read_b128 v[194:197], v145
	ds_read_b128 v[198:201], v145 offset:1024
	ds_read_b128 v[202:205], v145 offset:2048
	ds_read_b128 v[206:209], v145 offset:3072
	s_barrier
	s_waitcnt lgkmcnt(0)

; #define LDB(dst, b, h) for (int n = 0; n < 2; ++n) for (int k = 0; k < 2; ++k) \
;     dst[n][k] = *reinterpret_cast<const bf16x8*>((char*)SB(b, h) + b_thr + (n * 2 + k) * 1024)
; #define MMA(ai, bj, At, Btf) do { __builtin_amdgcn_s_setprio(1); \
;     for (int m = 0; m < 4; ++m) for (int n = 0; n < 2; ++n) for (int k = 0; k < 2; ++k) \
;       acc[ai][bj][m][n] = __builtin_amdgcn_mfma_f32_16x16x32_bf16(Btf[n][k], At[m][k], acc[ai][bj][m][n], 0, 0, 0); \
;     __builtin_amdgcn_s_setprio(0); } while (0)
; #define WAIT_L(n) asm volatile("s_waitcnt lgkmcnt(" #n ")" ::: "memory")
; #define BAR __builtin_amdgcn_s_barrier()
; template <bool OVL, bool PANEL = false, class Epi>
; __device__ __forceinline__ void gemm_phase(const bf16_t* __restrict__ A, long lda, const bf16_t* __restrict__ Bt, long ldb, int nM, int nN, int K,
;                                            const Epi& epi, bf16_t* shm, int w0) {
;     ...
;       LDB(B1, 0, 1); BAR; WAIT_L(0); MMA(0, 1, At, B1); BAR;
	v_mfma_f32_16x16x32_bf16 v[18:21], v[202:205], v[122:125], v[18:21]
	v_mfma_f32_16x16x32_bf16 v[22:25], v[194:197], v[170:173], v[22:25]
	v_mfma_f32_16x16x32_bf16 v[26:29], v[202:205], v[170:173], v[26:29]
	v_mfma_f32_16x16x32_bf16 v[30:33], v[194:197], v[178:181], v[30:33]
	v_mfma_f32_16x16x32_bf16 v[34:37], v[202:205], v[178:181], v[34:37]
	v_mfma_f32_16x16x32_bf16 v[38:41], v[194:197], v[186:189], v[38:41]
	v_mfma_f32_16x16x32_bf16 v[42:45], v[202:205], v[186:189], v[42:45]
	v_mfma_f32_16x16x32_bf16 v[98:101], v[194:197], v[122:125], v[98:101]
	v_mfma_f32_16x16x32_bf16 v[18:21], v[206:209], v[126:129], v[18:21]
	v_mfma_f32_16x16x32_bf16 v[22:25], v[198:201], v[174:177], v[22:25]
	v_mfma_f32_16x16x32_bf16 v[26:29], v[206:209], v[174:177], v[26:29]
	v_mfma_f32_16x16x32_bf16 v[30:33], v[198:201], v[182:185], v[30:33]
	v_mfma_f32_16x16x32_bf16 v[34:37], v[206:209], v[182:185], v[34:37]
	v_mfma_f32_16x16x32_bf16 v[38:41], v[198:201], v[190:193], v[38:41]
	v_mfma_f32_16x16x32_bf16 v[42:45], v[206:209], v[190:193], v[42:45]
	v_mfma_f32_16x16x32_bf16 v[210:213], v[198:201], v[126:129], v[98:101]

; #define LDA(dst, b, h) for (int m = 0; m < 4; ++m) for (int k = 0; k < 2; ++k) \
;     dst[m][k] = *reinterpret_cast<const bf16x8*>((char*)SA(b, h) + a_thr + (m * 2 + k) * 1024)
; #define MMA(ai, bj, At, Btf) do { __builtin_amdgcn_s_setprio(1); \
;     for (int m = 0; m < 4; ++m) for (int n = 0; n < 2; ++n) for (int k = 0; k < 2; ++k) \
;       acc[ai][bj][m][n] = __builtin_amdgcn_mfma_f32_16x16x32_bf16(Btf[n][k], At[m][k], acc[ai][bj][m][n], 0, 0, 0); \
;     __builtin_amdgcn_s_setprio(0); } while (0)
; #define WAIT_V(n) asm volatile("s_waitcnt vmcnt(" #n ")" ::: "memory")
; #define WAIT_L(n) asm volatile("s_waitcnt lgkmcnt(" #n ")" ::: "memory")
; #define BAR __builtin_amdgcn_s_barrier()
; template <bool OVL, bool PANEL = false, class Epi>
; __device__ __forceinline__ void gemm_phase(const bf16_t* __restrict__ A, long lda, const bf16_t* __restrict__ Bt, long ldb, int nM, int nN, int K,
;                                            const Epi& epi, bf16_t* shm, int w0) {
;     ...
;       LDA(At, 0, 1); WAIT_V(4); BAR; WAIT_L(0); MMA(1, 0, At, B0); MMA(1, 1, At, B1); BAR; }
	s_barrier
	s_nop 0
	ds_read_b128 v[98:101], v148 offset:16384
	ds_read_b128 v[122:125], v148 offset:17408
	ds_read_b128 v[126:129], v148 offset:18432
	ds_read_b128 v[170:173], v148 offset:19456
	ds_read_b128 v[174:177], v148 offset:20480
	ds_read_b128 v[178:181], v148 offset:21504
	ds_read_b128 v[182:185], v148 offset:22528
	ds_read_b128 v[186:189], v148 offset:23552
	s_waitcnt vmcnt(4)
	s_barrier
	s_waitcnt lgkmcnt(0)

; #define LDA(dst, b, h) for (int m = 0; m < 4; ++m) for (int k = 0; k < 2; ++k) \
;     dst[m][k] = *reinterpret_cast<const bf16x8*>((char*)SA(b, h) + a_thr + (m * 2 + k) * 1024)
; #define MMA(ai, bj, At, Btf) do { __builtin_amdgcn_s_setprio(1); \
;     for (int m = 0; m < 4; ++m) for (int n = 0; n < 2; ++n) for (int k = 0; k < 2; ++k) \
;       acc[ai][bj][m][n] = __builtin_amdgcn_mfma_f32_16x16x32_bf16(Btf[n][k], At[m][k], acc[ai][bj][m][n], 0, 0, 0); \
;     __builtin_amdgcn_s_setprio(0); } while (0)
; #define WAIT_V(n) asm volatile("s_waitcnt vmcnt(" #n ")" ::: "memory")
; #define WAIT_L(n) asm volatile("s_waitcnt lgkmcnt(" #n ")" ::: "memory")
; #define BAR __builtin_amdgcn_s_barrier()
; template <bool OVL, bool PANEL = false, class Epi>
; __device__ __forceinline__ void gemm_phase(const bf16_t* __restrict__ A, long lda, const bf16_t* __restrict__ Bt, long ldb, int nM, int nN, int K,
;                                            const Epi& epi, bf16_t* shm, int w0) {
;     ...
;       LDA(At, 0, 1); WAIT_V(4); BAR; WAIT_L(0); MMA(1, 0, At, B0); MMA(1, 1, At, B1); BAR; }
	v_mfma_f32_16x16x32_bf16 v[2:5], v[106:109], v[182:185], v[2:5]
	v_mfma_f32_16x16x32_bf16 v[6:9], v[114:117], v[182:185], v[6:9]
	v_mfma_f32_16x16x32_bf16 v[130:133], v[106:109], v[98:101], v[130:133]
	v_mfma_f32_16x16x32_bf16 v[150:153], v[114:117], v[98:101], v[150:153]
	v_mfma_f32_16x16x32_bf16 v[154:157], v[106:109], v[126:129], v[154:157]
	v_mfma_f32_16x16x32_bf16 v[158:161], v[114:117], v[126:129], v[158:161]
	v_mfma_f32_16x16x32_bf16 v[162:165], v[106:109], v[174:177], v[162:165]
	v_mfma_f32_16x16x32_bf16 v[166:169], v[114:117], v[174:177], v[166:169]
	v_mfma_f32_16x16x32_bf16 v[2:5], v[110:113], v[186:189], v[2:5]
	v_mfma_f32_16x16x32_bf16 v[6:9], v[118:121], v[186:189], v[6:9]
	v_mfma_f32_16x16x32_bf16 v[130:133], v[110:113], v[122:125], v[130:133]
	v_mfma_f32_16x16x32_bf16 v[150:153], v[118:121], v[122:125], v[150:153]
	v_mfma_f32_16x16x32_bf16 v[154:157], v[110:113], v[170:173], v[154:157]
	v_mfma_f32_16x16x32_bf16 v[158:161], v[118:121], v[170:173], v[158:161]
	v_mfma_f32_16x16x32_bf16 v[162:165], v[110:113], v[178:181], v[162:165]
	v_mfma_f32_16x16x32_bf16 v[166:169], v[118:121], v[178:181], v[166:169]


; #define LDA(dst, b, h) for (int m = 0; m < 4; ++m) for (int k = 0; k < 2; ++k) \
;     dst[m][k] = *reinterpret_cast<const bf16x8*>((char*)SA(b, h) + a_thr + (m * 2 + k) * 1024)
; #define MMA(ai, bj, At, Btf) do { __builtin_amdgcn_s_setprio(1); \
;     for (int m = 0; m < 4; ++m) for (int n = 0; n < 2; ++n) for (int k = 0; k < 2; ++k) \
;       acc[ai][bj][m][n] = __builtin_amdgcn_mfma_f32_16x16x32_bf16(Btf[n][k], At[m][k], acc[ai][bj][m][n], 0, 0, 0); \
;     __builtin_amdgcn_s_setprio(0); } while (0)
; #define WAIT_V(n) asm volatile("s_waitcnt vmcnt(" #n ")" ::: "memory")
; #define WAIT_L(n) asm volatile("s_waitcnt lgkmcnt(" #n ")" ::: "memory")
; #define BAR __builtin_amdgcn_s_barrier()
; template <bool OVL, bool PANEL = false, class Epi>
; __device__ __forceinline__ void gemm_phase(const bf16_t* __restrict__ A, long lda, const bf16_t* __restrict__ Bt, long ldb, int nM, int nN, int K,
;                                            const Epi& epi, bf16_t* shm, int w0) {
;     ...
;       LDA(At, 0, 1); WAIT_V(4); BAR; WAIT_L(0); MMA(1, 0, At, B0); MMA(1, 1, At, B1); BAR; }
	v_mfma_f32_16x16x32_bf16 v[46:49], v[194:197], v[126:129], v[46:49]
	v_mfma_f32_16x16x32_bf16 v[190:193], v[198:201], v[170:173], v[46:49]
	v_mfma_f32_16x16x32_bf16 v[46:49], v[202:205], v[126:129], v[90:93]
	v_mfma_f32_16x16x32_bf16 v[170:173], v[206:209], v[170:173], v[46:49]
	v_mfma_f32_16x16x32_bf16 v[46:49], v[194:197], v[174:177], v[94:97]
	v_mfma_f32_16x16x32_bf16 v[214:217], v[198:201], v[178:181], v[46:49]
	v_mfma_f32_16x16x32_bf16 v[46:49], v[202:205], v[174:177], v[102:105]
	v_mfma_f32_16x16x32_bf16 v[10:13], v[194:197], v[98:101], v[10:13]
	v_mfma_f32_16x16x32_bf16 v[14:17], v[202:205], v[98:101], v[14:17]
	v_mfma_f32_16x16x32_bf16 v[174:177], v[206:209], v[178:181], v[46:49]
	v_mfma_f32_16x16x32_bf16 v[46:49], v[194:197], v[182:185], v[82:85]
	v_mfma_f32_16x16x32_bf16 v[10:13], v[198:201], v[122:125], v[10:13]
	v_mfma_f32_16x16x32_bf16 v[14:17], v[206:209], v[122:125], v[14:17]
	v_mfma_f32_16x16x32_bf16 v[178:181], v[198:201], v[186:189], v[46:49]
	v_mfma_f32_16x16x32_bf16 v[46:49], v[202:205], v[182:185], v[86:89]
	v_mfma_f32_16x16x32_bf16 v[182:185], v[206:209], v[186:189], v[46:49]

; #define LDA(dst, b, h) for (int m = 0; m < 4; ++m) for (int k = 0; k < 2; ++k) \
;     dst[m][k] = *reinterpret_cast<const bf16x8*>((char*)SA(b, h) + a_thr + (m * 2 + k) * 1024)
; #define LDB(dst, b, h) for (int n = 0; n < 2; ++n) for (int k = 0; k < 2; ++k) \
;     dst[n][k] = *reinterpret_cast<const bf16x8*>((char*)SB(b, h) + b_thr + (n * 2 + k) * 1024)
; #define MMA(ai, bj, At, Btf) do { __builtin_amdgcn_s_setprio(1); \
;     for (int m = 0; m < 4; ++m) for (int n = 0; n < 2; ++n) for (int k = 0; k < 2; ++k) \
;       acc[ai][bj][m][n] = __builtin_amdgcn_mfma_f32_16x16x32_bf16(Btf[n][k], At[m][k], acc[ai][bj][m][n], 0, 0, 0); \
;     __builtin_amdgcn_s_setprio(0); } while (0)
; #define WAIT_V(n) asm volatile("s_waitcnt vmcnt(" #n ")" ::: "memory")
; #define WAIT_L(n) asm volatile("s_waitcnt lgkmcnt(" #n ")" ::: "memory")
; #define BAR __builtin_amdgcn_s_barrier()
; template <bool OVL, bool PANEL = false, class Epi>
; __device__ __forceinline__ void gemm_phase(const bf16_t* __restrict__ A, long lda, const bf16_t* __restrict__ Bt, long ldb, int nM, int nN, int K,
;                                            const Epi& epi, bf16_t* shm, int w0) {
;     ...
;     { LDB(B0, 1, 0); LDA(At, 1, 0); WAIT_V(2); BAR; WAIT_L(0); MMA(0, 0, At, B0); BAR;
	s_barrier
	ds_read_b128 v[186:189], v146
	ds_read_b128 v[194:197], v146 offset:1024
	ds_read_b128 v[198:201], v146 offset:2048
	ds_read_b128 v[202:205], v146 offset:3072
	s_nop 0
	ds_read_b128 v[46:49], v148 offset:32768
	ds_read_b128 v[82:85], v148 offset:33792
	ds_read_b128 v[206:209], v148 offset:34816
	ds_read_b128 v[218:221], v148 offset:35840
	ds_read_b128 v[222:225], v148 offset:36864
	ds_read_b128 v[228:231], v148 offset:37888
	ds_read_b128 v[232:235], v148 offset:38912
	ds_read_b128 v[236:239], v148 offset:39936
	s_waitcnt vmcnt(2)
	s_barrier
	s_waitcnt lgkmcnt(0)

; #define LDA(dst, b, h) for (int m = 0; m < 4; ++m) for (int k = 0; k < 2; ++k) \
;     dst[m][k] = *reinterpret_cast<const bf16x8*>((char*)SA(b, h) + a_thr + (m * 2 + k) * 1024)
; #define LDB(dst, b, h) for (int n = 0; n < 2; ++n) for (int k = 0; k < 2; ++k) \
;     dst[n][k] = *reinterpret_cast<const bf16x8*>((char*)SB(b, h) + b_thr + (n * 2 + k) * 1024)
; #define MMA(ai, bj, At, Btf) do { __builtin_amdgcn_s_setprio(1); \
;     for (int m = 0; m < 4; ++m) for (int n = 0; n < 2; ++n) for (int k = 0; k < 2; ++k) \
;       acc[ai][bj][m][n] = __builtin_amdgcn_mfma_f32_16x16x32_bf16(Btf[n][k], At[m][k], acc[ai][bj][m][n], 0, 0, 0); \
;     __builtin_amdgcn_s_setprio(0); } while (0)
; #define WAIT_V(n) asm volatile("s_waitcnt vmcnt(" #n ")" ::: "memory")
; #define WAIT_L(n) asm volatile("s_waitcnt lgkmcnt(" #n ")" ::: "memory")
; #define BAR __builtin_amdgcn_s_barrier()
; template <bool OVL, bool PANEL = false, class Epi>
; __device__ __forceinline__ void gemm_phase(const bf16_t* __restrict__ A, long lda, const bf16_t* __restrict__ Bt, long ldb, int nM, int nN, int K,
;                                            const Epi& epi, bf16_t* shm, int w0) {
;     ...
;     { LDB(B0, 1, 0); LDA(At, 1, 0); WAIT_V(2); BAR; WAIT_L(0); MMA(0, 0, At, B0); BAR;
	v_mfma_f32_16x16x32_bf16 v[50:53], v[186:189], v[46:49], v[50:53]
	v_mfma_f32_16x16x32_bf16 v[126:129], v[194:197], v[82:85], v[50:53]
	v_mfma_f32_16x16x32_bf16 v[50:53], v[198:201], v[46:49], v[54:57]
	v_mfma_f32_16x16x32_bf16 v[122:125], v[202:205], v[82:85], v[50:53]
	v_mfma_f32_16x16x32_bf16 v[50:53], v[186:189], v[206:209], v[58:61]
	v_mfma_f32_16x16x32_bf16 v[118:121], v[194:197], v[218:221], v[50:53]
	v_mfma_f32_16x16x32_bf16 v[50:53], v[198:201], v[206:209], v[62:65]
	v_mfma_f32_16x16x32_bf16 v[114:117], v[202:205], v[218:221], v[50:53]
	v_mfma_f32_16x16x32_bf16 v[50:53], v[186:189], v[222:225], v[66:69]
	v_mfma_f32_16x16x32_bf16 v[110:113], v[194:197], v[228:231], v[50:53]
	v_mfma_f32_16x16x32_bf16 v[50:53], v[198:201], v[222:225], v[70:73]
	v_mfma_f32_16x16x32_bf16 v[106:109], v[202:205], v[228:231], v[50:53]
	v_mfma_f32_16x16x32_bf16 v[50:53], v[186:189], v[232:235], v[74:77]
	v_mfma_f32_16x16x32_bf16 v[102:105], v[194:197], v[236:239], v[50:53]
	v_mfma_f32_16x16x32_bf16 v[50:53], v[198:201], v[232:235], v[78:81]
	v_mfma_f32_16x16x32_bf16 v[98:101], v[202:205], v[236:239], v[50:53]

; #define LDB(dst, b, h) for (int n = 0; n < 2; ++n) for (int k = 0; k < 2; ++k) \
;     dst[n][k] = *reinterpret_cast<const bf16x8*>((char*)SB(b, h) + b_thr + (n * 2 + k) * 1024)
; #define MMA(ai, bj, At, Btf) do { __builtin_amdgcn_s_setprio(1); \
;     for (int m = 0; m < 4; ++m) for (int n = 0; n < 2; ++n) for (int k = 0; k < 2; ++k) \
;       acc[ai][bj][m][n] = __builtin_amdgcn_mfma_f32_16x16x32_bf16(Btf[n][k], At[m][k], acc[ai][bj][m][n], 0, 0, 0); \
;     __builtin_amdgcn_s_setprio(0); } while (0)
; #define WAIT_V(n) asm volatile("s_waitcnt vmcnt(" #n ")" ::: "memory")
; #define WAIT_L(n) asm volatile("s_waitcnt lgkmcnt(" #n ")" ::: "memory")
; #define BAR __builtin_amdgcn_s_barrier()
; template <bool OVL, bool PANEL = false, class Epi>
; __device__ __forceinline__ void gemm_phase(const bf16_t* __restrict__ A, long lda, const bf16_t* __restrict__ Bt, long ldb, int nM, int nN, int K,
;                                            const Epi& epi, bf16_t* shm, int w0) {
;     ...
;       LDB(B1, 1, 1); WAIT_V(0); BAR; WAIT_L(0); MMA(0, 1, At, B1); BAR;
	s_barrier
	ds_read_b128 v[240:243], v147
	ds_read_b128 v[244:247], v147 offset:1024
	ds_read_b128 v[140:143], v147 offset:2048
	ds_read_b128 v[144:147], v147 offset:3072
	s_waitcnt vmcnt(0)
	s_barrier
	s_waitcnt lgkmcnt(0)

; #define LDB(dst, b, h) for (int n = 0; n < 2; ++n) for (int k = 0; k < 2; ++k) \
;     dst[n][k] = *reinterpret_cast<const bf16x8*>((char*)SB(b, h) + b_thr + (n * 2 + k) * 1024)
; #define MMA(ai, bj, At, Btf) do { __builtin_amdgcn_s_setprio(1); \
;     for (int m = 0; m < 4; ++m) for (int n = 0; n < 2; ++n) for (int k = 0; k < 2; ++k) \
;       acc[ai][bj][m][n] = __builtin_amdgcn_mfma_f32_16x16x32_bf16(Btf[n][k], At[m][k], acc[ai][bj][m][n], 0, 0, 0); \
;     __builtin_amdgcn_s_setprio(0); } while (0)
; #define WAIT_V(n) asm volatile("s_waitcnt vmcnt(" #n ")" ::: "memory")
; #define WAIT_L(n) asm volatile("s_waitcnt lgkmcnt(" #n ")" ::: "memory")
; #define BAR __builtin_amdgcn_s_barrier()
; template <bool OVL, bool PANEL = false, class Epi>
; __device__ __forceinline__ void gemm_phase(const bf16_t* __restrict__ A, long lda, const bf16_t* __restrict__ Bt, long ldb, int nM, int nN, int K,
;                                            const Epi& epi, bf16_t* shm, int w0) {
;     ...
;       LDB(B1, 1, 1); WAIT_V(0); BAR; WAIT_L(0); MMA(0, 1, At, B1); BAR;
	v_mfma_f32_16x16x32_bf16 v[18:21], v[140:143], v[46:49], v[18:21]
	v_mfma_f32_16x16x32_bf16 v[90:93], v[144:147], v[82:85], v[18:21]
	v_mfma_f32_16x16x32_bf16 v[18:21], v[240:243], v[206:209], v[22:25]
	v_mfma_f32_16x16x32_bf16 v[50:53], v[240:243], v[46:49], v[210:213]
	v_mfma_f32_16x16x32_bf16 v[86:89], v[244:247], v[218:221], v[18:21]
	v_mfma_f32_16x16x32_bf16 v[18:21], v[140:143], v[206:209], v[26:29]
	v_mfma_f32_16x16x32_bf16 v[94:97], v[244:247], v[82:85], v[50:53]
	v_mfma_f32_16x16x32_bf16 v[82:85], v[144:147], v[218:221], v[18:21]
	v_mfma_f32_16x16x32_bf16 v[18:21], v[240:243], v[222:225], v[30:33]
	v_mfma_f32_16x16x32_bf16 v[78:81], v[244:247], v[228:231], v[18:21]
	v_mfma_f32_16x16x32_bf16 v[18:21], v[140:143], v[222:225], v[34:37]
	v_mfma_f32_16x16x32_bf16 v[74:77], v[144:147], v[228:231], v[18:21]
	v_mfma_f32_16x16x32_bf16 v[18:21], v[240:243], v[232:235], v[38:41]
	v_mfma_f32_16x16x32_bf16 v[70:73], v[244:247], v[236:239], v[18:21]
	v_mfma_f32_16x16x32_bf16 v[18:21], v[140:143], v[232:235], v[42:45]
	v_mfma_f32_16x16x32_bf16 v[66:69], v[144:147], v[236:239], v[18:21]

; #define LDA(dst, b, h) for (int m = 0; m < 4; ++m) for (int k = 0; k < 2; ++k) \
;     dst[m][k] = *reinterpret_cast<const bf16x8*>((char*)SA(b, h) + a_thr + (m * 2 + k) * 1024)
; #define MMA(ai, bj, At, Btf) do { __builtin_amdgcn_s_setprio(1); \
;     for (int m = 0; m < 4; ++m) for (int n = 0; n < 2; ++n) for (int k = 0; k < 2; ++k) \
;       acc[ai][bj][m][n] = __builtin_amdgcn_mfma_f32_16x16x32_bf16(Btf[n][k], At[m][k], acc[ai][bj][m][n], 0, 0, 0); \
;     __builtin_amdgcn_s_setprio(0); } while (0)
; #define WAIT_L(n) asm volatile("s_waitcnt lgkmcnt(" #n ")" ::: "memory")
; #define BAR __builtin_amdgcn_s_barrier()
; template <bool OVL, bool PANEL = false, class Epi>
; __device__ __forceinline__ void gemm_phase(const bf16_t* __restrict__ A, long lda, const bf16_t* __restrict__ Bt, long ldb, int nM, int nN, int K,
;                                            const Epi& epi, bf16_t* shm, int w0) {
;     ...
;       LDA(At, 1, 1); BAR; WAIT_L(0); MMA(1, 0, At, B0); MMA(1, 1, At, B1); BAR; }
	s_barrier
	s_nop 4
	ds_read_b128 v[18:21], v148 offset:49152
	ds_read_b128 v[22:25], v148 offset:50176
	ds_read_b128 v[206:209], v148 offset:51200
	ds_read_b128 v[210:213], v148 offset:52224
	ds_read_b128 v[218:221], v148 offset:53248
	ds_read_b128 v[222:225], v148 offset:54272
	ds_read_b128 v[228:231], v148 offset:55296
	ds_read_b128 v[232:235], v148 offset:56320
	s_barrier
	s_waitcnt lgkmcnt(0)

; #define LDA(dst, b, h) for (int m = 0; m < 4; ++m) for (int k = 0; k < 2; ++k) \
;     dst[m][k] = *reinterpret_cast<const bf16x8*>((char*)SA(b, h) + a_thr + (m * 2 + k) * 1024)
; #define MMA(ai, bj, At, Btf) do { __builtin_amdgcn_s_setprio(1); \
;     for (int m = 0; m < 4; ++m) for (int n = 0; n < 2; ++n) for (int k = 0; k < 2; ++k) \
;       acc[ai][bj][m][n] = __builtin_amdgcn_mfma_f32_16x16x32_bf16(Btf[n][k], At[m][k], acc[ai][bj][m][n], 0, 0, 0); \
;     __builtin_amdgcn_s_setprio(0); } while (0)
; #define WAIT_L(n) asm volatile("s_waitcnt lgkmcnt(" #n ")" ::: "memory")
; #define BAR __builtin_amdgcn_s_barrier()
; template <bool OVL, bool PANEL = false, class Epi>
; __device__ __forceinline__ void gemm_phase(const bf16_t* __restrict__ A, long lda, const bf16_t* __restrict__ Bt, long ldb, int nM, int nN, int K,
;                                            const Epi& epi, bf16_t* shm, int w0) {
;     ...
;       LDA(At, 1, 1); BAR; WAIT_L(0); MMA(1, 0, At, B0); MMA(1, 1, At, B1); BAR; }
	v_mfma_f32_16x16x32_bf16 v[26:29], v[186:189], v[18:21], v[130:133]
	v_mfma_f32_16x16x32_bf16 v[62:65], v[194:197], v[22:25], v[26:29]
	v_mfma_f32_16x16x32_bf16 v[26:29], v[198:201], v[18:21], v[150:153]
	v_mfma_f32_16x16x32_bf16 v[58:61], v[202:205], v[22:25], v[26:29]
	v_mfma_f32_16x16x32_bf16 v[26:29], v[186:189], v[206:209], v[154:157]
	v_mfma_f32_16x16x32_bf16 v[54:57], v[194:197], v[210:213], v[26:29]
	v_mfma_f32_16x16x32_bf16 v[26:29], v[198:201], v[206:209], v[158:161]
	v_mfma_f32_16x16x32_bf16 v[50:53], v[202:205], v[210:213], v[26:29]
	v_mfma_f32_16x16x32_bf16 v[26:29], v[186:189], v[218:221], v[162:165]
	v_mfma_f32_16x16x32_bf16 v[2:5], v[186:189], v[228:231], v[2:5]
	v_mfma_f32_16x16x32_bf16 v[46:49], v[194:197], v[222:225], v[26:29]
	v_mfma_f32_16x16x32_bf16 v[26:29], v[198:201], v[218:221], v[166:169]
	v_mfma_f32_16x16x32_bf16 v[38:41], v[194:197], v[232:235], v[2:5]
	v_mfma_f32_16x16x32_bf16 v[2:5], v[198:201], v[228:231], v[6:9]
	v_mfma_f32_16x16x32_bf16 v[42:45], v[202:205], v[222:225], v[26:29]
	v_mfma_f32_16x16x32_bf16 v[34:37], v[202:205], v[232:235], v[2:5]


; #define LDA(dst, b, h) for (int m = 0; m < 4; ++m) for (int k = 0; k < 2; ++k) \
;     dst[m][k] = *reinterpret_cast<const bf16x8*>((char*)SA(b, h) + a_thr + (m * 2 + k) * 1024)
; #define MMA(ai, bj, At, Btf) do { __builtin_amdgcn_s_setprio(1); \
;     for (int m = 0; m < 4; ++m) for (int n = 0; n < 2; ++n) for (int k = 0; k < 2; ++k) \
;       acc[ai][bj][m][n] = __builtin_amdgcn_mfma_f32_16x16x32_bf16(Btf[n][k], At[m][k], acc[ai][bj][m][n], 0, 0, 0); \
;     __builtin_amdgcn_s_setprio(0); } while (0)
; #define WAIT_L(n) asm volatile("s_waitcnt lgkmcnt(" #n ")" ::: "memory")
; #define BAR __builtin_amdgcn_s_barrier()
; template <bool OVL, bool PANEL = false, class Epi>
; __device__ __forceinline__ void gemm_phase(const bf16_t* __restrict__ A, long lda, const bf16_t* __restrict__ Bt, long ldb, int nM, int nN, int K,
;                                            const Epi& epi, bf16_t* shm, int w0) {
;     ...
;       LDA(At, 1, 1); BAR; WAIT_L(0); MMA(1, 0, At, B0); MMA(1, 1, At, B1); BAR; }
	v_mfma_f32_16x16x32_bf16 v[2:5], v[240:243], v[18:21], v[10:13]
	v_mfma_f32_16x16x32_bf16 v[30:33], v[244:247], v[22:25], v[2:5]
	v_mfma_f32_16x16x32_bf16 v[2:5], v[140:143], v[18:21], v[14:17]
	v_mfma_f32_16x16x32_bf16 v[26:29], v[144:147], v[22:25], v[2:5]
	v_mfma_f32_16x16x32_bf16 v[2:5], v[240:243], v[206:209], v[190:193]
	v_mfma_f32_16x16x32_bf16 v[22:25], v[244:247], v[210:213], v[2:5]
	v_mfma_f32_16x16x32_bf16 v[2:5], v[140:143], v[206:209], v[170:173]
	v_mfma_f32_16x16x32_bf16 v[18:21], v[144:147], v[210:213], v[2:5]
	v_mfma_f32_16x16x32_bf16 v[2:5], v[240:243], v[218:221], v[214:217]
	v_mfma_f32_16x16x32_bf16 v[14:17], v[244:247], v[222:225], v[2:5]
	v_mfma_f32_16x16x32_bf16 v[2:5], v[140:143], v[218:221], v[174:177]
	v_mfma_f32_16x16x32_bf16 v[10:13], v[144:147], v[222:225], v[2:5]
	v_mfma_f32_16x16x32_bf16 v[2:5], v[240:243], v[228:231], v[178:181]
	v_mfma_f32_16x16x32_bf16 v[6:9], v[244:247], v[232:235], v[2:5]
	v_mfma_f32_16x16x32_bf16 v[2:5], v[140:143], v[228:231], v[182:185]
	v_mfma_f32_16x16x32_bf16 v[2:5], v[144:147], v[232:235], v[2:5]

; #define LDA(dst, b, h) for (int m = 0; m < 4; ++m) for (int k = 0; k < 2; ++k) \
;     dst[m][k] = *reinterpret_cast<const bf16x8*>((char*)SA(b, h) + a_thr + (m * 2 + k) * 1024)
; #define MMA(ai, bj, At, Btf) do { __builtin_amdgcn_s_setprio(1); \
;     for (int m = 0; m < 4; ++m) for (int n = 0; n < 2; ++n) for (int k = 0; k < 2; ++k) \
;       acc[ai][bj][m][n] = __builtin_amdgcn_mfma_f32_16x16x32_bf16(Btf[n][k], At[m][k], acc[ai][bj][m][n], 0, 0, 0); \
;     __builtin_amdgcn_s_setprio(0); } while (0)
; #define WAIT_L(n) asm volatile("s_waitcnt lgkmcnt(" #n ")" ::: "memory")
; #define BAR __builtin_amdgcn_s_barrier()
; template <bool OVL, bool PANEL = false, class Epi>
; __device__ __forceinline__ void gemm_phase(const bf16_t* __restrict__ A, long lda, const bf16_t* __restrict__ Bt, long ldb, int nM, int nN, int K,
;                                            const Epi& epi, bf16_t* shm, int w0) {
;     ...
;       LDA(At, 1, 1); BAR; WAIT_L(0); MMA(1, 0, At, B0); MMA(1, 1, At, B1); BAR; }
;     if (wr == 0) BAR;
	s_barrier
	s_and_saveexec_b64 s[8:9], s[6:7]
	s_cbranch_execz .LBB0_687
	s_barrier

; #define LDA(dst, b, h) for (int m = 0; m < 4; ++m) for (int k = 0; k < 2; ++k) \
;     dst[m][k] = *reinterpret_cast<const bf16x8*>((char*)SA(b, h) + a_thr + (m * 2 + k) * 1024)
; #define LDB(dst, b, h) for (int n = 0; n < 2; ++n) for (int k = 0; k < 2; ++k) \
;     dst[n][k] = *reinterpret_cast<const bf16x8*>((char*)SB(b, h) + b_thr + (n * 2 + k) * 1024)
; #define MMA(ai, bj, At, Btf) do { __builtin_amdgcn_s_setprio(1); \
;     for (int m = 0; m < 4; ++m) for (int n = 0; n < 2; ++n) for (int k = 0; k < 2; ++k) \
;       acc[ai][bj][m][n] = __builtin_amdgcn_mfma_f32_16x16x32_bf16(Btf[n][k], At[m][k], acc[ai][bj][m][n], 0, 0, 0); \
;     __builtin_amdgcn_s_setprio(0); } while (0)
; #define WAIT_V(n) asm volatile("s_waitcnt vmcnt(" #n ")" ::: "memory")
; #define WAIT_L(n) asm volatile("s_waitcnt lgkmcnt(" #n ")" ::: "memory")
; #define BAR __builtin_amdgcn_s_barrier()
; template <bool OVL, bool PANEL = false, class Epi>
; __device__ __forceinline__ void gemm_phase(const bf16_t* __restrict__ A, long lda, const bf16_t* __restrict__ Bt, long ldb, int nM, int nN, int K,
;                                            const Epi& epi, bf16_t* shm, int w0) {
;     ...
;     if (wr == 1) BAR;
;     WAIT_V(4); BAR;
;     STAGE(SB(1, 0), Bt, ldb, boff, bcol, 1); STAGE(SA(1, 0), A, lda, aoff, brow, 1); STAGE(SB(1, 1), Bt, ldb, boff, bcol + HALF, 1);
;     WAIT_V(6); BAR;
;     ...
;     { LDB(B0, 0, 0); LDA(At, 0, 0); STAGE(SA(1, 1), A, lda, aoff, brow + HALF, nt - 1);
;       BAR; WAIT_L(0); MMA(0, 0, At, B0); BAR;
.LBB0_696:
	s_or_b64 exec, exec, s[8:9]
	v_readlane_b32 s16, v252, 3
	s_lshl_b32 s14, s2, 8
	s_lshl_b32 s8, s13, 17
	v_readlane_b32 s26, v252, 13
	v_readlane_b32 s27, v252, 14
	s_add_u32 s8, s26, s8
	v_mov_b32_e32 v0, v134
	s_waitcnt vmcnt(4)
	s_barrier
	s_addc_u32 s9, s27, 0
	s_mov_b64 s[10:11], 0x80
	v_lshl_add_u64 v[2:3], s[8:9], 0, v[0:1]
	v_add_u32_e32 v0, s96, v227
	v_lshl_add_u64 v[4:5], v[2:3], 0, s[10:11]
	v_readfirstlane_b32 s10, v0
	v_readlane_b32 s17, v252, 4
	v_readlane_b32 s18, v252, 5
	v_readlane_b32 s19, v252, 6
	v_readlane_b32 s20, v252, 7
	v_readlane_b32 s21, v252, 8
	v_readlane_b32 s22, v252, 9
	v_readlane_b32 s23, v252, 10
	v_readlane_b32 s24, v252, 11
	v_readlane_b32 s25, v252, 12
	v_readlane_b32 s28, v252, 15
	v_readlane_b32 s29, v252, 16
	v_readlane_b32 s30, v252, 17
	v_readlane_b32 s31, v252, 18
	s_mov_b32 m0, s10
	s_mov_b64 s[10:11], 0x8080
	v_add_u32_e32 v0, 0x2000, v0
	v_lshl_add_u64 v[2:3], v[2:3], 0, s[10:11]
	v_readfirstlane_b32 s10, v0
	v_readlane_b32 s16, v252, 20
	global_load_lds_dwordx4 v[4:5], off
	s_mov_b32 m0, s10
	s_mul_i32 s10, s2, 0xf8000
	v_readlane_b32 s24, v252, 28
	s_mul_hi_u32 s11, s14, 0xf80
	v_readlane_b32 s25, v252, 29
	s_add_u32 s10, s24, s10
	v_mov_b32_e32 v0, v249
	global_load_lds_dwordx4 v[2:3], off
	s_addc_u32 s11, s25, s11
	v_readlane_b32 s17, v252, 21
	v_lshl_add_u64 v[2:3], s[10:11], 0, v[0:1]
	v_add_u32_e32 v0, 0x8000, v137
	v_readlane_b32 s18, v252, 22
	v_readlane_b32 s19, v252, 23
	s_mov_b64 s[16:17], 0xec0
	v_readfirstlane_b32 s10, v0
	v_add_u32_e32 v0, 0xa000, v137
	v_lshl_add_u64 v[4:5], v[2:3], 0, s[16:17]
	s_mov_b32 m0, s10
	s_mov_b64 s[18:19], 0x3eec0
	v_readfirstlane_b32 s10, v0
	global_load_lds_dwordx4 v[4:5], off
	v_lshl_add_u64 v[2:3], v[2:3], 0, s[18:19]
	s_mov_b32 m0, s10
	v_mov_b32_e32 v0, v134
	global_load_lds_dwordx4 v[2:3], off
	v_add_u32_e32 v82, 16, v143
	v_lshl_add_u64 v[2:3], s[8:9], 0, v[0:1]
	s_mov_b64 s[8:9], 0x10080
	v_add_u32_e32 v0, s75, v227
	v_lshl_add_u64 v[4:5], v[2:3], 0, s[8:9]
	v_readfirstlane_b32 s8, v0
	s_mov_b32 m0, s8
	s_mov_b64 s[8:9], 0x18080
	v_add_u32_e32 v0, 0x2000, v0
	v_lshl_add_u64 v[2:3], v[2:3], 0, s[8:9]
	v_readfirstlane_b32 s8, v0
	global_load_lds_dwordx4 v[4:5], off
	s_mov_b32 m0, s8
	s_or_b32 s8, s14, 0x80
	global_load_lds_dwordx4 v[2:3], off
	v_add_u32_e32 v0, 0x10000, v82
	s_mul_hi_u32 s9, s8, 0xf80
	s_mulk_i32 s8, 0xf80
	s_waitcnt vmcnt(6)
	s_barrier
	ds_read_b128 v[2:5], v0
	ds_read_b128 v[6:9], v0 offset:1024
	s_waitcnt vmcnt(0)
	ds_read_b128 v[10:13], v0 offset:2048
	ds_read_b128 v[14:17], v0 offset:3072
	ds_read_b128 v[18:21], v144
	ds_read_b128 v[22:25], v144 offset:1024
	ds_read_b128 v[26:29], v144 offset:2048
	ds_read_b128 v[30:33], v144 offset:3072
	ds_read_b128 v[34:37], v144 offset:4096
	ds_read_b128 v[38:41], v144 offset:5120
	ds_read_b128 v[42:45], v144 offset:6144
	ds_read_b128 v[46:49], v144 offset:7168
	s_add_u32 s8, s24, s8
	v_mov_b32_e32 v0, v249
	s_addc_u32 s9, s25, s9
	v_readlane_b32 s20, v252, 24
	v_lshl_add_u64 v[50:51], s[8:9], 0, v[0:1]
	v_add_u32_e32 v0, 0xc000, v137
	v_lshl_add_u64 v[52:53], v[50:51], 0, s[16:17]
	v_readfirstlane_b32 s8, v0
	v_add_u32_e32 v0, 0xe000, v137
	s_mov_b32 m0, s8
	v_readfirstlane_b32 s8, v0
	global_load_lds_dwordx4 v[52:53], off
	v_lshl_add_u64 v[50:51], v[50:51], 0, s[18:19]
	s_mov_b32 m0, s8
	v_readlane_b32 s21, v252, 25
	global_load_lds_dwordx4 v[50:51], off
	s_barrier
	s_waitcnt lgkmcnt(0)
	v_readlane_b32 s22, v252, 26
	v_readlane_b32 s23, v252, 27
	v_readlane_b32 s26, v252, 30
	v_readlane_b32 s27, v252, 31
	v_readlane_b32 s28, v252, 32
	v_readlane_b32 s29, v252, 33
	v_readlane_b32 s30, v252, 34
	v_readlane_b32 s31, v252, 35

; #define MMA(ai, bj, At, Btf) do { __builtin_amdgcn_s_setprio(1); \
;     for (int m = 0; m < 4; ++m) for (int n = 0; n < 2; ++n) for (int k = 0; k < 2; ++k) \
;       acc[ai][bj][m][n] = __builtin_amdgcn_mfma_f32_16x16x32_bf16(Btf[n][k], At[m][k], acc[ai][bj][m][n], 0, 0, 0); \
;     __builtin_amdgcn_s_setprio(0); } while (0)
; #define WAIT_L(n) asm volatile("s_waitcnt lgkmcnt(" #n ")" ::: "memory")
; #define BAR __builtin_amdgcn_s_barrier()
; template <bool OVL, bool PANEL = false, class Epi>
; __device__ __forceinline__ void gemm_phase(const bf16_t* __restrict__ A, long lda, const bf16_t* __restrict__ Bt, long ldb, int nM, int nN, int K,
;                                            const Epi& epi, bf16_t* shm, int w0) {
;     ...
;       BAR; WAIT_L(0); MMA(0, 0, At, B0); BAR;
	s_waitcnt lgkmcnt(0)
	v_mfma_f32_16x16x32_bf16 v[50:53], v[2:5], v[18:21], 0
	v_mfma_f32_16x16x32_bf16 v[54:57], v[10:13], v[18:21], 0
	v_mfma_f32_16x16x32_bf16 v[58:61], v[2:5], v[26:29], 0
	v_mfma_f32_16x16x32_bf16 v[62:65], v[10:13], v[26:29], 0
	v_mfma_f32_16x16x32_bf16 v[66:69], v[2:5], v[34:37], 0
	v_mfma_f32_16x16x32_bf16 v[70:73], v[10:13], v[34:37], 0
	v_mfma_f32_16x16x32_bf16 v[74:77], v[2:5], v[42:45], 0
	v_mfma_f32_16x16x32_bf16 v[78:81], v[10:13], v[42:45], 0
	v_mfma_f32_16x16x32_bf16 v[50:53], v[6:9], v[22:25], v[50:53]
	v_mfma_f32_16x16x32_bf16 v[54:57], v[14:17], v[22:25], v[54:57]
	v_mfma_f32_16x16x32_bf16 v[58:61], v[6:9], v[30:33], v[58:61]
	v_mfma_f32_16x16x32_bf16 v[62:65], v[14:17], v[30:33], v[62:65]
	v_mfma_f32_16x16x32_bf16 v[66:69], v[6:9], v[38:41], v[66:69]
	v_mfma_f32_16x16x32_bf16 v[70:73], v[14:17], v[38:41], v[70:73]
	v_mfma_f32_16x16x32_bf16 v[74:77], v[6:9], v[46:49], v[74:77]
	v_mfma_f32_16x16x32_bf16 v[78:81], v[14:17], v[46:49], v[78:81]

; #define LDB(dst, b, h) for (int n = 0; n < 2; ++n) for (int k = 0; k < 2; ++k) \
;     dst[n][k] = *reinterpret_cast<const bf16x8*>((char*)SB(b, h) + b_thr + (n * 2 + k) * 1024)
; #define MMA(ai, bj, At, Btf) do { __builtin_amdgcn_s_setprio(1); \
;     for (int m = 0; m < 4; ++m) for (int n = 0; n < 2; ++n) for (int k = 0; k < 2; ++k) \
;       acc[ai][bj][m][n] = __builtin_amdgcn_mfma_f32_16x16x32_bf16(Btf[n][k], At[m][k], acc[ai][bj][m][n], 0, 0, 0); \
;     __builtin_amdgcn_s_setprio(0); } while (0)
; #define WAIT_L(n) asm volatile("s_waitcnt lgkmcnt(" #n ")" ::: "memory")
; #define BAR __builtin_amdgcn_s_barrier()
; template <bool OVL, bool PANEL = false, class Epi>
; __device__ __forceinline__ void gemm_phase(const bf16_t* __restrict__ A, long lda, const bf16_t* __restrict__ Bt, long ldb, int nM, int nN, int K,
;                                            const Epi& epi, bf16_t* shm, int w0) {
;     ...
;       LDB(B1, 0, 1); BAR; WAIT_L(0); MMA(0, 1, At, B1); BAR;
	v_add_u32_e32 v0, 0x14000, v82
	s_barrier
	ds_read_b128 v[82:85], v0
	ds_read_b128 v[86:89], v0 offset:1024
	ds_read_b128 v[90:93], v0 offset:2048
	ds_read_b128 v[94:97], v0 offset:3072
	s_barrier
	s_waitcnt lgkmcnt(0)

; #define LDB(dst, b, h) for (int n = 0; n < 2; ++n) for (int k = 0; k < 2; ++k) \
;     dst[n][k] = *reinterpret_cast<const bf16x8*>((char*)SB(b, h) + b_thr + (n * 2 + k) * 1024)
; #define MMA(ai, bj, At, Btf) do { __builtin_amdgcn_s_setprio(1); \
;     for (int m = 0; m < 4; ++m) for (int n = 0; n < 2; ++n) for (int k = 0; k < 2; ++k) \
;       acc[ai][bj][m][n] = __builtin_amdgcn_mfma_f32_16x16x32_bf16(Btf[n][k], At[m][k], acc[ai][bj][m][n], 0, 0, 0); \
;     __builtin_amdgcn_s_setprio(0); } while (0)
; #define WAIT_L(n) asm volatile("s_waitcnt lgkmcnt(" #n ")" ::: "memory")
; #define BAR __builtin_amdgcn_s_barrier()
; template <bool OVL, bool PANEL = false, class Epi>
; __device__ __forceinline__ void gemm_phase(const bf16_t* __restrict__ A, long lda, const bf16_t* __restrict__ Bt, long ldb, int nM, int nN, int K,
;                                            const Epi& epi, bf16_t* shm, int w0) {
;     ...
;       LDB(B1, 0, 1); BAR; WAIT_L(0); MMA(0, 1, At, B1); BAR;
	v_mfma_f32_16x16x32_bf16 v[98:101], v[82:85], v[18:21], 0
	v_mfma_f32_16x16x32_bf16 v[18:21], v[90:93], v[18:21], 0
	v_mfma_f32_16x16x32_bf16 v[146:149], v[86:89], v[22:25], v[98:101]
	v_mfma_f32_16x16x32_bf16 v[18:21], v[94:97], v[22:25], v[18:21]
	v_mfma_f32_16x16x32_bf16 v[22:25], v[82:85], v[26:29], 0
	v_mfma_f32_16x16x32_bf16 v[26:29], v[90:93], v[26:29], 0
	v_mfma_f32_16x16x32_bf16 v[22:25], v[86:89], v[30:33], v[22:25]
	v_mfma_f32_16x16x32_bf16 v[26:29], v[94:97], v[30:33], v[26:29]
	v_mfma_f32_16x16x32_bf16 v[30:33], v[82:85], v[34:37], 0
	v_mfma_f32_16x16x32_bf16 v[34:37], v[90:93], v[34:37], 0
	v_mfma_f32_16x16x32_bf16 v[30:33], v[86:89], v[38:41], v[30:33]
	v_mfma_f32_16x16x32_bf16 v[34:37], v[94:97], v[38:41], v[34:37]
	v_mfma_f32_16x16x32_bf16 v[38:41], v[82:85], v[42:45], 0
	v_mfma_f32_16x16x32_bf16 v[42:45], v[90:93], v[42:45], 0
	v_mfma_f32_16x16x32_bf16 v[38:41], v[86:89], v[46:49], v[38:41]
	v_mfma_f32_16x16x32_bf16 v[42:45], v[94:97], v[46:49], v[42:45]

; #define LDA(dst, b, h) for (int m = 0; m < 4; ++m) for (int k = 0; k < 2; ++k) \
;     dst[m][k] = *reinterpret_cast<const bf16x8*>((char*)SA(b, h) + a_thr + (m * 2 + k) * 1024)
; #define MMA(ai, bj, At, Btf) do { __builtin_amdgcn_s_setprio(1); \
;     for (int m = 0; m < 4; ++m) for (int n = 0; n < 2; ++n) for (int k = 0; k < 2; ++k) \
;       acc[ai][bj][m][n] = __builtin_amdgcn_mfma_f32_16x16x32_bf16(Btf[n][k], At[m][k], acc[ai][bj][m][n], 0, 0, 0); \
;     __builtin_amdgcn_s_setprio(0); } while (0)
; #define WAIT_V(n) asm volatile("s_waitcnt vmcnt(" #n ")" ::: "memory")
; #define WAIT_L(n) asm volatile("s_waitcnt lgkmcnt(" #n ")" ::: "memory")
; #define BAR __builtin_amdgcn_s_barrier()
; template <bool OVL, bool PANEL = false, class Epi>
; __device__ __forceinline__ void gemm_phase(const bf16_t* __restrict__ A, long lda, const bf16_t* __restrict__ Bt, long ldb, int nM, int nN, int K,
;                                            const Epi& epi, bf16_t* shm, int w0) {
;     ...
;       LDA(At, 0, 1); WAIT_V(4); BAR; WAIT_L(0); MMA(1, 0, At, B0); MMA(1, 1, At, B1); BAR; }
	s_barrier
	ds_read_b128 v[46:49], v144 offset:16384
	ds_read_b128 v[98:101], v144 offset:17408
	ds_read_b128 v[102:105], v144 offset:18432
	ds_read_b128 v[106:109], v144 offset:19456
	ds_read_b128 v[110:113], v144 offset:20480
	ds_read_b128 v[114:117], v144 offset:21504
	ds_read_b128 v[118:121], v144 offset:22528
	ds_read_b128 v[122:125], v144 offset:23552
	s_waitcnt vmcnt(4)
	s_barrier
	s_waitcnt lgkmcnt(0)

; #define LDA(dst, b, h) for (int m = 0; m < 4; ++m) for (int k = 0; k < 2; ++k) \
;     dst[m][k] = *reinterpret_cast<const bf16x8*>((char*)SA(b, h) + a_thr + (m * 2 + k) * 1024)
; #define MMA(ai, bj, At, Btf) do { __builtin_amdgcn_s_setprio(1); \
;     for (int m = 0; m < 4; ++m) for (int n = 0; n < 2; ++n) for (int k = 0; k < 2; ++k) \
;       acc[ai][bj][m][n] = __builtin_amdgcn_mfma_f32_16x16x32_bf16(Btf[n][k], At[m][k], acc[ai][bj][m][n], 0, 0, 0); \
;     __builtin_amdgcn_s_setprio(0); } while (0)
; #define WAIT_V(n) asm volatile("s_waitcnt vmcnt(" #n ")" ::: "memory")
; #define WAIT_L(n) asm volatile("s_waitcnt lgkmcnt(" #n ")" ::: "memory")
; #define BAR __builtin_amdgcn_s_barrier()
; template <bool OVL, bool PANEL = false, class Epi>
; __device__ __forceinline__ void gemm_phase(const bf16_t* __restrict__ A, long lda, const bf16_t* __restrict__ Bt, long ldb, int nM, int nN, int K,
;                                            const Epi& epi, bf16_t* shm, int w0) {
;     ...
;       LDA(At, 0, 1); WAIT_V(4); BAR; WAIT_L(0); MMA(1, 0, At, B0); MMA(1, 1, At, B1); BAR; }
	v_mfma_f32_16x16x32_bf16 v[126:129], v[2:5], v[46:49], 0
	v_mfma_f32_16x16x32_bf16 v[150:153], v[6:9], v[98:101], v[126:129]
	v_mfma_f32_16x16x32_bf16 v[126:129], v[10:13], v[46:49], 0
	v_mfma_f32_16x16x32_bf16 v[154:157], v[14:17], v[98:101], v[126:129]
	v_mfma_f32_16x16x32_bf16 v[126:129], v[2:5], v[102:105], 0
	v_mfma_f32_16x16x32_bf16 v[158:161], v[6:9], v[106:109], v[126:129]
	v_mfma_f32_16x16x32_bf16 v[126:129], v[10:13], v[102:105], 0
	v_mfma_f32_16x16x32_bf16 v[162:165], v[14:17], v[106:109], v[126:129]
	v_mfma_f32_16x16x32_bf16 v[126:129], v[2:5], v[110:113], 0
	v_mfma_f32_16x16x32_bf16 v[2:5], v[2:5], v[118:121], 0
	v_mfma_f32_16x16x32_bf16 v[166:169], v[6:9], v[114:117], v[126:129]
	v_mfma_f32_16x16x32_bf16 v[2:5], v[6:9], v[122:125], v[2:5]
	v_mfma_f32_16x16x32_bf16 v[6:9], v[10:13], v[118:121], 0
	v_mfma_f32_16x16x32_bf16 v[126:129], v[10:13], v[110:113], 0
	v_mfma_f32_16x16x32_bf16 v[6:9], v[14:17], v[122:125], v[6:9]
	v_mfma_f32_16x16x32_bf16 v[170:173], v[14:17], v[114:117], v[126:129]


; #define LDA(dst, b, h) for (int m = 0; m < 4; ++m) for (int k = 0; k < 2; ++k) \
;     dst[m][k] = *reinterpret_cast<const bf16x8*>((char*)SA(b, h) + a_thr + (m * 2 + k) * 1024)
; #define MMA(ai, bj, At, Btf) do { __builtin_amdgcn_s_setprio(1); \
;     for (int m = 0; m < 4; ++m) for (int n = 0; n < 2; ++n) for (int k = 0; k < 2; ++k) \
;       acc[ai][bj][m][n] = __builtin_amdgcn_mfma_f32_16x16x32_bf16(Btf[n][k], At[m][k], acc[ai][bj][m][n], 0, 0, 0); \
;     __builtin_amdgcn_s_setprio(0); } while (0)
; #define WAIT_V(n) asm volatile("s_waitcnt vmcnt(" #n ")" ::: "memory")
; #define WAIT_L(n) asm volatile("s_waitcnt lgkmcnt(" #n ")" ::: "memory")
; #define BAR __builtin_amdgcn_s_barrier()
; template <bool OVL, bool PANEL = false, class Epi>
; __device__ __forceinline__ void gemm_phase(const bf16_t* __restrict__ A, long lda, const bf16_t* __restrict__ Bt, long ldb, int nM, int nN, int K,
;                                            const Epi& epi, bf16_t* shm, int w0) {
;     ...
;       LDA(At, 0, 1); WAIT_V(4); BAR; WAIT_L(0); MMA(1, 0, At, B0); MMA(1, 1, At, B1); BAR; }
	v_mfma_f32_16x16x32_bf16 v[10:13], v[82:85], v[46:49], 0
	v_mfma_f32_16x16x32_bf16 v[14:17], v[90:93], v[46:49], 0
	v_mfma_f32_16x16x32_bf16 v[46:49], v[82:85], v[102:105], 0
	v_mfma_f32_16x16x32_bf16 v[174:177], v[86:89], v[106:109], v[46:49]
	v_mfma_f32_16x16x32_bf16 v[46:49], v[90:93], v[102:105], 0
	v_mfma_f32_16x16x32_bf16 v[178:181], v[94:97], v[106:109], v[46:49]
	v_mfma_f32_16x16x32_bf16 v[46:49], v[82:85], v[110:113], 0
	v_mfma_f32_16x16x32_bf16 v[182:185], v[86:89], v[114:117], v[46:49]
	v_mfma_f32_16x16x32_bf16 v[46:49], v[90:93], v[110:113], 0
	v_mfma_f32_16x16x32_bf16 v[186:189], v[94:97], v[114:117], v[46:49]
	v_mfma_f32_16x16x32_bf16 v[46:49], v[82:85], v[118:121], 0
	v_mfma_f32_16x16x32_bf16 v[10:13], v[86:89], v[98:101], v[10:13]
	v_mfma_f32_16x16x32_bf16 v[14:17], v[94:97], v[98:101], v[14:17]
	v_mfma_f32_16x16x32_bf16 v[190:193], v[86:89], v[122:125], v[46:49]
	v_mfma_f32_16x16x32_bf16 v[46:49], v[90:93], v[118:121], 0
	v_mfma_f32_16x16x32_bf16 v[194:197], v[94:97], v[122:125], v[46:49]

; #define LDA(dst, b, h) for (int m = 0; m < 4; ++m) for (int k = 0; k < 2; ++k) \
;     dst[m][k] = *reinterpret_cast<const bf16x8*>((char*)SA(b, h) + a_thr + (m * 2 + k) * 1024)
; #define LDB(dst, b, h) for (int n = 0; n < 2; ++n) for (int k = 0; k < 2; ++k) \
;     dst[n][k] = *reinterpret_cast<const bf16x8*>((char*)SB(b, h) + b_thr + (n * 2 + k) * 1024)
; #define MMA(ai, bj, At, Btf) do { __builtin_amdgcn_s_setprio(1); \
;     for (int m = 0; m < 4; ++m) for (int n = 0; n < 2; ++n) for (int k = 0; k < 2; ++k) \
;       acc[ai][bj][m][n] = __builtin_amdgcn_mfma_f32_16x16x32_bf16(Btf[n][k], At[m][k], acc[ai][bj][m][n], 0, 0, 0); \
;     __builtin_amdgcn_s_setprio(0); } while (0)
; #define WAIT_V(n) asm volatile("s_waitcnt vmcnt(" #n ")" ::: "memory")
; #define WAIT_L(n) asm volatile("s_waitcnt lgkmcnt(" #n ")" ::: "memory")
; #define BAR __builtin_amdgcn_s_barrier()
; template <bool OVL, bool PANEL = false, class Epi>
; __device__ __forceinline__ void gemm_phase(const bf16_t* __restrict__ A, long lda, const bf16_t* __restrict__ Bt, long ldb, int nM, int nN, int K,
;                                            const Epi& epi, bf16_t* shm, int w0) {
;     ...
;     { LDB(B0, 1, 0); LDA(At, 1, 0); WAIT_V(2); BAR; WAIT_L(0); MMA(0, 0, At, B0); BAR;
	v_add_u32_e32 v0, s96, v143
	s_barrier
	ds_read_b128 v[198:201], v0
	ds_read_b128 v[202:205], v0 offset:1024
	ds_read_b128 v[206:209], v0 offset:2048
	ds_read_b128 v[210:213], v0 offset:3072
	ds_read_b128 v[46:49], v144 offset:32768
	ds_read_b128 v[82:85], v144 offset:33792
	ds_read_b128 v[214:217], v144 offset:34816
	ds_read_b128 v[218:221], v144 offset:35840
	ds_read_b128 v[222:225], v144 offset:36864
	ds_read_b128 v[228:231], v144 offset:37888
	ds_read_b128 v[232:235], v144 offset:38912
	ds_read_b128 v[236:239], v144 offset:39936
	s_waitcnt vmcnt(2)
	s_barrier
	s_waitcnt lgkmcnt(0)

; #define LDA(dst, b, h) for (int m = 0; m < 4; ++m) for (int k = 0; k < 2; ++k) \
;     dst[m][k] = *reinterpret_cast<const bf16x8*>((char*)SA(b, h) + a_thr + (m * 2 + k) * 1024)
; #define LDB(dst, b, h) for (int n = 0; n < 2; ++n) for (int k = 0; k < 2; ++k) \
;     dst[n][k] = *reinterpret_cast<const bf16x8*>((char*)SB(b, h) + b_thr + (n * 2 + k) * 1024)
; #define MMA(ai, bj, At, Btf) do { __builtin_amdgcn_s_setprio(1); \
;     for (int m = 0; m < 4; ++m) for (int n = 0; n < 2; ++n) for (int k = 0; k < 2; ++k) \
;       acc[ai][bj][m][n] = __builtin_amdgcn_mfma_f32_16x16x32_bf16(Btf[n][k], At[m][k], acc[ai][bj][m][n], 0, 0, 0); \
;     __builtin_amdgcn_s_setprio(0); } while (0)
; #define WAIT_V(n) asm volatile("s_waitcnt vmcnt(" #n ")" ::: "memory")
; #define WAIT_L(n) asm volatile("s_waitcnt lgkmcnt(" #n ")" ::: "memory")
; #define BAR __builtin_amdgcn_s_barrier()
; template <bool OVL, bool PANEL = false, class Epi>
; __device__ __forceinline__ void gemm_phase(const bf16_t* __restrict__ A, long lda, const bf16_t* __restrict__ Bt, long ldb, int nM, int nN, int K,
;                                            const Epi& epi, bf16_t* shm, int w0) {
;     ...
;     { LDB(B0, 1, 0); LDA(At, 1, 0); WAIT_V(2); BAR; WAIT_L(0); MMA(0, 0, At, B0); BAR;
	v_mfma_f32_16x16x32_bf16 v[50:53], v[198:201], v[46:49], v[50:53]
	v_mfma_f32_16x16x32_bf16 v[126:129], v[202:205], v[82:85], v[50:53]
	v_mfma_f32_16x16x32_bf16 v[50:53], v[206:209], v[46:49], v[54:57]
	v_mfma_f32_16x16x32_bf16 v[122:125], v[210:213], v[82:85], v[50:53]
	v_mfma_f32_16x16x32_bf16 v[50:53], v[198:201], v[214:217], v[58:61]
	v_mfma_f32_16x16x32_bf16 v[118:121], v[202:205], v[218:221], v[50:53]
	v_mfma_f32_16x16x32_bf16 v[50:53], v[206:209], v[214:217], v[62:65]
	v_mfma_f32_16x16x32_bf16 v[114:117], v[210:213], v[218:221], v[50:53]
	v_mfma_f32_16x16x32_bf16 v[50:53], v[198:201], v[222:225], v[66:69]
	v_mfma_f32_16x16x32_bf16 v[110:113], v[202:205], v[228:231], v[50:53]
	v_mfma_f32_16x16x32_bf16 v[50:53], v[206:209], v[222:225], v[70:73]
	v_mfma_f32_16x16x32_bf16 v[106:109], v[210:213], v[228:231], v[50:53]
	v_mfma_f32_16x16x32_bf16 v[50:53], v[198:201], v[232:235], v[74:77]
	v_mfma_f32_16x16x32_bf16 v[102:105], v[202:205], v[236:239], v[50:53]
	v_mfma_f32_16x16x32_bf16 v[50:53], v[206:209], v[232:235], v[78:81]
	v_mfma_f32_16x16x32_bf16 v[98:101], v[210:213], v[236:239], v[50:53]

; #define LDB(dst, b, h) for (int n = 0; n < 2; ++n) for (int k = 0; k < 2; ++k) \
;     dst[n][k] = *reinterpret_cast<const bf16x8*>((char*)SB(b, h) + b_thr + (n * 2 + k) * 1024)
; #define MMA(ai, bj, At, Btf) do { __builtin_amdgcn_s_setprio(1); \
;     for (int m = 0; m < 4; ++m) for (int n = 0; n < 2; ++n) for (int k = 0; k < 2; ++k) \
;       acc[ai][bj][m][n] = __builtin_amdgcn_mfma_f32_16x16x32_bf16(Btf[n][k], At[m][k], acc[ai][bj][m][n], 0, 0, 0); \
;     __builtin_amdgcn_s_setprio(0); } while (0)
; #define WAIT_V(n) asm volatile("s_waitcnt vmcnt(" #n ")" ::: "memory")
; #define WAIT_L(n) asm volatile("s_waitcnt lgkmcnt(" #n ")" ::: "memory")
; #define BAR __builtin_amdgcn_s_barrier()
; template <bool OVL, bool PANEL = false, class Epi>
; __device__ __forceinline__ void gemm_phase(const bf16_t* __restrict__ A, long lda, const bf16_t* __restrict__ Bt, long ldb, int nM, int nN, int K,
;                                            const Epi& epi, bf16_t* shm, int w0) {
;     ...
;       LDB(B1, 1, 1); WAIT_V(0); BAR; WAIT_L(0); MMA(0, 1, At, B1); BAR;
	v_add_u32_e32 v0, s75, v143
	s_barrier
	ds_read_b128 v[240:243], v0
	ds_read_b128 v[244:247], v0 offset:1024
	ds_read_b128 v[138:141], v0 offset:2048
	ds_read_b128 v[130:133], v0 offset:3072
	s_waitcnt vmcnt(0)
	s_barrier
	s_waitcnt lgkmcnt(0)

; #define LDB(dst, b, h) for (int n = 0; n < 2; ++n) for (int k = 0; k < 2; ++k) \
;     dst[n][k] = *reinterpret_cast<const bf16x8*>((char*)SB(b, h) + b_thr + (n * 2 + k) * 1024)
; #define MMA(ai, bj, At, Btf) do { __builtin_amdgcn_s_setprio(1); \
;     for (int m = 0; m < 4; ++m) for (int n = 0; n < 2; ++n) for (int k = 0; k < 2; ++k) \
;       acc[ai][bj][m][n] = __builtin_amdgcn_mfma_f32_16x16x32_bf16(Btf[n][k], At[m][k], acc[ai][bj][m][n], 0, 0, 0); \
;     __builtin_amdgcn_s_setprio(0); } while (0)
; #define WAIT_V(n) asm volatile("s_waitcnt vmcnt(" #n ")" ::: "memory")
; #define WAIT_L(n) asm volatile("s_waitcnt lgkmcnt(" #n ")" ::: "memory")
; #define BAR __builtin_amdgcn_s_barrier()
; template <bool OVL, bool PANEL = false, class Epi>
; __device__ __forceinline__ void gemm_phase(const bf16_t* __restrict__ A, long lda, const bf16_t* __restrict__ Bt, long ldb, int nM, int nN, int K,
;                                            const Epi& epi, bf16_t* shm, int w0) {
;     ...
;       LDB(B1, 1, 1); WAIT_V(0); BAR; WAIT_L(0); MMA(0, 1, At, B1); BAR;
	v_mfma_f32_16x16x32_bf16 v[18:21], v[138:141], v[46:49], v[18:21]
	v_mfma_f32_16x16x32_bf16 v[90:93], v[130:133], v[82:85], v[18:21]
	v_mfma_f32_16x16x32_bf16 v[18:21], v[240:243], v[214:217], v[22:25]
	v_mfma_f32_16x16x32_bf16 v[50:53], v[240:243], v[46:49], v[146:149]
	v_mfma_f32_16x16x32_bf16 v[86:89], v[244:247], v[218:221], v[18:21]
	v_mfma_f32_16x16x32_bf16 v[18:21], v[138:141], v[214:217], v[26:29]
	v_mfma_f32_16x16x32_bf16 v[94:97], v[244:247], v[82:85], v[50:53]
	v_mfma_f32_16x16x32_bf16 v[82:85], v[130:133], v[218:221], v[18:21]
	v_mfma_f32_16x16x32_bf16 v[18:21], v[240:243], v[222:225], v[30:33]
	v_mfma_f32_16x16x32_bf16 v[78:81], v[244:247], v[228:231], v[18:21]
	v_mfma_f32_16x16x32_bf16 v[18:21], v[138:141], v[222:225], v[34:37]
	v_mfma_f32_16x16x32_bf16 v[74:77], v[130:133], v[228:231], v[18:21]
	v_mfma_f32_16x16x32_bf16 v[18:21], v[240:243], v[232:235], v[38:41]
	v_mfma_f32_16x16x32_bf16 v[70:73], v[244:247], v[236:239], v[18:21]
	v_mfma_f32_16x16x32_bf16 v[18:21], v[138:141], v[232:235], v[42:45]
	v_mfma_f32_16x16x32_bf16 v[66:69], v[130:133], v[236:239], v[18:21]

; #define LDA(dst, b, h) for (int m = 0; m < 4; ++m) for (int k = 0; k < 2; ++k) \
;     dst[m][k] = *reinterpret_cast<const bf16x8*>((char*)SA(b, h) + a_thr + (m * 2 + k) * 1024)
; #define MMA(ai, bj, At, Btf) do { __builtin_amdgcn_s_setprio(1); \
;     for (int m = 0; m < 4; ++m) for (int n = 0; n < 2; ++n) for (int k = 0; k < 2; ++k) \
;       acc[ai][bj][m][n] = __builtin_amdgcn_mfma_f32_16x16x32_bf16(Btf[n][k], At[m][k], acc[ai][bj][m][n], 0, 0, 0); \
;     __builtin_amdgcn_s_setprio(0); } while (0)
; #define WAIT_L(n) asm volatile("s_waitcnt lgkmcnt(" #n ")" ::: "memory")
; #define BAR __builtin_amdgcn_s_barrier()
; template <bool OVL, bool PANEL = false, class Epi>
; __device__ __forceinline__ void gemm_phase(const bf16_t* __restrict__ A, long lda, const bf16_t* __restrict__ Bt, long ldb, int nM, int nN, int K,
;                                            const Epi& epi, bf16_t* shm, int w0) {
;     ...
;       LDA(At, 1, 1); BAR; WAIT_L(0); MMA(1, 0, At, B0); MMA(1, 1, At, B1); BAR; }
	s_barrier
	s_nop 4
	ds_read_b128 v[18:21], v144 offset:49152
	ds_read_b128 v[22:25], v144 offset:50176
	ds_read_b128 v[146:149], v144 offset:51200
	ds_read_b128 v[214:217], v144 offset:52224
	ds_read_b128 v[218:221], v144 offset:53248
	ds_read_b128 v[222:225], v144 offset:54272
	ds_read_b128 v[228:231], v144 offset:55296
	ds_read_b128 v[232:235], v144 offset:56320
	s_barrier
	s_waitcnt lgkmcnt(0)

; #define LDA(dst, b, h) for (int m = 0; m < 4; ++m) for (int k = 0; k < 2; ++k) \
;     dst[m][k] = *reinterpret_cast<const bf16x8*>((char*)SA(b, h) + a_thr + (m * 2 + k) * 1024)
; #define MMA(ai, bj, At, Btf) do { __builtin_amdgcn_s_setprio(1); \
;     for (int m = 0; m < 4; ++m) for (int n = 0; n < 2; ++n) for (int k = 0; k < 2; ++k) \
;       acc[ai][bj][m][n] = __builtin_amdgcn_mfma_f32_16x16x32_bf16(Btf[n][k], At[m][k], acc[ai][bj][m][n], 0, 0, 0); \
;     __builtin_amdgcn_s_setprio(0); } while (0)
; #define WAIT_L(n) asm volatile("s_waitcnt lgkmcnt(" #n ")" ::: "memory")
; #define BAR __builtin_amdgcn_s_barrier()
; template <bool OVL, bool PANEL = false, class Epi>
; __device__ __forceinline__ void gemm_phase(const bf16_t* __restrict__ A, long lda, const bf16_t* __restrict__ Bt, long ldb, int nM, int nN, int K,
;                                            const Epi& epi, bf16_t* shm, int w0) {
;     ...
;       LDA(At, 1, 1); BAR; WAIT_L(0); MMA(1, 0, At, B0); MMA(1, 1, At, B1); BAR; }
	v_mfma_f32_16x16x32_bf16 v[26:29], v[198:201], v[18:21], v[150:153]
	v_mfma_f32_16x16x32_bf16 v[62:65], v[202:205], v[22:25], v[26:29]
	v_mfma_f32_16x16x32_bf16 v[26:29], v[206:209], v[18:21], v[154:157]
	v_mfma_f32_16x16x32_bf16 v[58:61], v[210:213], v[22:25], v[26:29]
	v_mfma_f32_16x16x32_bf16 v[26:29], v[198:201], v[146:149], v[158:161]
	v_mfma_f32_16x16x32_bf16 v[54:57], v[202:205], v[214:217], v[26:29]
	v_mfma_f32_16x16x32_bf16 v[26:29], v[206:209], v[146:149], v[162:165]
	v_mfma_f32_16x16x32_bf16 v[50:53], v[210:213], v[214:217], v[26:29]
	v_mfma_f32_16x16x32_bf16 v[26:29], v[198:201], v[218:221], v[166:169]
	v_mfma_f32_16x16x32_bf16 v[2:5], v[198:201], v[228:231], v[2:5]
	v_mfma_f32_16x16x32_bf16 v[46:49], v[202:205], v[222:225], v[26:29]
	v_mfma_f32_16x16x32_bf16 v[26:29], v[206:209], v[218:221], v[170:173]
	v_mfma_f32_16x16x32_bf16 v[38:41], v[202:205], v[232:235], v[2:5]
	v_mfma_f32_16x16x32_bf16 v[2:5], v[206:209], v[228:231], v[6:9]
	v_mfma_f32_16x16x32_bf16 v[42:45], v[210:213], v[222:225], v[26:29]
	v_mfma_f32_16x16x32_bf16 v[34:37], v[210:213], v[232:235], v[2:5]


; #define LDA(dst, b, h) for (int m = 0; m < 4; ++m) for (int k = 0; k < 2; ++k) \
;     dst[m][k] = *reinterpret_cast<const bf16x8*>((char*)SA(b, h) + a_thr + (m * 2 + k) * 1024)
; #define MMA(ai, bj, At, Btf) do { __builtin_amdgcn_s_setprio(1); \
;     for (int m = 0; m < 4; ++m) for (int n = 0; n < 2; ++n) for (int k = 0; k < 2; ++k) \
;       acc[ai][bj][m][n] = __builtin_amdgcn_mfma_f32_16x16x32_bf16(Btf[n][k], At[m][k], acc[ai][bj][m][n], 0, 0, 0); \
;     __builtin_amdgcn_s_setprio(0); } while (0)
; #define WAIT_L(n) asm volatile("s_waitcnt lgkmcnt(" #n ")" ::: "memory")
; #define BAR __builtin_amdgcn_s_barrier()
; template <bool OVL, bool PANEL = false, class Epi>
; __device__ __forceinline__ void gemm_phase(const bf16_t* __restrict__ A, long lda, const bf16_t* __restrict__ Bt, long ldb, int nM, int nN, int K,
;                                            const Epi& epi, bf16_t* shm, int w0) {
;     ...
;       LDA(At, 1, 1); BAR; WAIT_L(0); MMA(1, 0, At, B0); MMA(1, 1, At, B1); BAR; }
	v_mfma_f32_16x16x32_bf16 v[2:5], v[240:243], v[18:21], v[10:13]
	v_mfma_f32_16x16x32_bf16 v[30:33], v[244:247], v[22:25], v[2:5]
	v_mfma_f32_16x16x32_bf16 v[2:5], v[138:141], v[18:21], v[14:17]
	v_mfma_f32_16x16x32_bf16 v[26:29], v[130:133], v[22:25], v[2:5]
	v_mfma_f32_16x16x32_bf16 v[2:5], v[240:243], v[146:149], v[174:177]
	v_mfma_f32_16x16x32_bf16 v[22:25], v[244:247], v[214:217], v[2:5]
	v_mfma_f32_16x16x32_bf16 v[2:5], v[138:141], v[146:149], v[178:181]
	v_mfma_f32_16x16x32_bf16 v[18:21], v[130:133], v[214:217], v[2:5]
	v_mfma_f32_16x16x32_bf16 v[2:5], v[240:243], v[218:221], v[182:185]
	v_mfma_f32_16x16x32_bf16 v[14:17], v[244:247], v[222:225], v[2:5]
	v_mfma_f32_16x16x32_bf16 v[2:5], v[138:141], v[218:221], v[186:189]
	v_mfma_f32_16x16x32_bf16 v[10:13], v[130:133], v[222:225], v[2:5]
	v_mfma_f32_16x16x32_bf16 v[2:5], v[240:243], v[228:231], v[190:193]
	v_mfma_f32_16x16x32_bf16 v[6:9], v[244:247], v[232:235], v[2:5]
	v_mfma_f32_16x16x32_bf16 v[2:5], v[138:141], v[228:231], v[194:197]
	v_mfma_f32_16x16x32_bf16 v[2:5], v[130:133], v[232:235], v[2:5]

; #define LDA(dst, b, h) for (int m = 0; m < 4; ++m) for (int k = 0; k < 2; ++k) \
;     dst[m][k] = *reinterpret_cast<const bf16x8*>((char*)SA(b, h) + a_thr + (m * 2 + k) * 1024)
; #define MMA(ai, bj, At, Btf) do { __builtin_amdgcn_s_setprio(1); \
;     for (int m = 0; m < 4; ++m) for (int n = 0; n < 2; ++n) for (int k = 0; k < 2; ++k) \
;       acc[ai][bj][m][n] = __builtin_amdgcn_mfma_f32_16x16x32_bf16(Btf[n][k], At[m][k], acc[ai][bj][m][n], 0, 0, 0); \
;     __builtin_amdgcn_s_setprio(0); } while (0)
; #define WAIT_L(n) asm volatile("s_waitcnt lgkmcnt(" #n ")" ::: "memory")
; #define BAR __builtin_amdgcn_s_barrier()
; template <bool OVL, bool PANEL = false, class Epi>
; __device__ __forceinline__ void gemm_phase(const bf16_t* __restrict__ A, long lda, const bf16_t* __restrict__ Bt, long ldb, int nM, int nN, int K,
;                                            const Epi& epi, bf16_t* shm, int w0) {
;     ...
;       LDA(At, 1, 1); BAR; WAIT_L(0); MMA(1, 0, At, B0); MMA(1, 1, At, B1); BAR; }
;     if (wr == 0) BAR;
	s_barrier
	s_and_saveexec_b64 s[8:9], s[6:7]
	s_cbranch_execz .LBB0_698
	s_barrier

; #define LDA(dst, b, h) for (int m = 0; m < 4; ++m) for (int k = 0; k < 2; ++k) \
;     dst[m][k] = *reinterpret_cast<const bf16x8*>((char*)SA(b, h) + a_thr + (m * 2 + k) * 1024)
; #define LDB(dst, b, h) for (int n = 0; n < 2; ++n) for (int k = 0; k < 2; ++k) \
;     dst[n][k] = *reinterpret_cast<const bf16x8*>((char*)SB(b, h) + b_thr + (n * 2 + k) * 1024)
; #define MMA(ai, bj, At, Btf) do { __builtin_amdgcn_s_setprio(1); \
;     for (int m = 0; m < 4; ++m) for (int n = 0; n < 2; ++n) for (int k = 0; k < 2; ++k) \
;       acc[ai][bj][m][n] = __builtin_amdgcn_mfma_f32_16x16x32_bf16(Btf[n][k], At[m][k], acc[ai][bj][m][n], 0, 0, 0); \
;     __builtin_amdgcn_s_setprio(0); } while (0)
; #define WAIT_V(n) asm volatile("s_waitcnt vmcnt(" #n ")" ::: "memory")
; #define WAIT_L(n) asm volatile("s_waitcnt lgkmcnt(" #n ")" ::: "memory")
; #define BAR __builtin_amdgcn_s_barrier()
; template <bool OVL, bool PANEL = false, class Epi>
; __device__ __forceinline__ void gemm_phase(const bf16_t* __restrict__ A, long lda, const bf16_t* __restrict__ Bt, long ldb, int nM, int nN, int K,
;                                            const Epi& epi, bf16_t* shm, int w0) {
;     ...
;     if (wr == 1) BAR;
;     WAIT_V(4); BAR;
;     STAGE(SB(1, 0), Bt, ldb, boff, bcol, 1); STAGE(SA(1, 0), A, lda, aoff, brow, 1); STAGE(SB(1, 1), Bt, ldb, boff, bcol + HALF, 1);
;     WAIT_V(6); BAR;
;     ...
;     { LDB(B0, 0, 0); LDA(At, 0, 0); STAGE(SA(1, 1), A, lda, aoff, brow + HALF, nt - 1);
;       BAR; WAIT_L(0); MMA(0, 0, At, B0); BAR;
.LBB0_828:
	s_or_b64 exec, exec, s[8:9]
	v_readlane_b32 s16, v252, 20
	s_lshl_b32 s14, s13, 8
	s_mul_i32 s2, s13, 0xf8000
	v_readlane_b32 s24, v252, 28
	s_mul_hi_u32 s9, s14, 0xf80
	v_readlane_b32 s25, v252, 29
	s_add_u32 s8, s24, s2
	v_mov_b32_e32 v0, v140
	s_waitcnt vmcnt(4)
	s_barrier
	s_addc_u32 s9, s25, s9
	v_readlane_b32 s17, v252, 21
	v_lshl_add_u64 v[2:3], s[8:9], 0, v[0:1]
	v_add_u32_e32 v0, s96, v138
	s_mov_b64 s[16:17], 0xec0
	v_readfirstlane_b32 s2, v0
	v_add_u32_e32 v0, 0x2000, v0
	v_readlane_b32 s18, v252, 22
	v_readlane_b32 s19, v252, 23
	v_lshl_add_u64 v[4:5], v[2:3], 0, s[16:17]
	s_mov_b32 m0, s2
	v_readfirstlane_b32 s2, v0
	v_readlane_b32 s40, v252, 3
	global_load_lds_dwordx4 v[4:5], off
	s_mov_b64 s[18:19], 0x3eec0
	s_mov_b32 m0, s2
	s_lshl_b32 s2, s15, 17
	v_readlane_b32 s52, v252, 15
	v_lshl_add_u64 v[2:3], v[2:3], 0, s[18:19]
	v_readlane_b32 s53, v252, 16
	s_add_u32 s8, s52, s2
	v_mov_b32_e32 v0, v139
	global_load_lds_dwordx4 v[2:3], off
	s_addc_u32 s9, s53, 0
	s_mov_b64 s[10:11], 0x80
	v_lshl_add_u64 v[2:3], s[8:9], 0, v[0:1]
	v_add_u32_e32 v0, 0x8000, v143
	v_lshl_add_u64 v[4:5], v[2:3], 0, s[10:11]
	v_readfirstlane_b32 s2, v0
	v_add_u32_e32 v0, 0xa000, v143
	s_mov_b32 m0, s2
	v_readfirstlane_b32 s2, v0
	global_load_lds_dwordx4 v[4:5], off
	s_mov_b64 s[10:11], 0x8080
	s_mov_b32 m0, s2
	s_or_b32 s2, s14, 0x80
	v_lshl_add_u64 v[2:3], v[2:3], 0, s[10:11]
	s_mul_hi_u32 s11, s2, 0xf80
	s_mulk_i32 s2, 0xf80
	s_add_u32 s10, s24, s2
	v_mov_b32_e32 v0, v140
	global_load_lds_dwordx4 v[2:3], off
	s_addc_u32 s11, s25, s11
	v_add_u32_e32 v82, 16, v149
	v_lshl_add_u64 v[2:3], s[10:11], 0, v[0:1]
	v_add_u32_e32 v0, s75, v138
	v_lshl_add_u64 v[4:5], v[2:3], 0, s[16:17]
	v_readfirstlane_b32 s2, v0
	v_add_u32_e32 v0, 0x2000, v0
	s_mov_b32 m0, s2
	v_readfirstlane_b32 s2, v0
	global_load_lds_dwordx4 v[4:5], off
	v_lshl_add_u64 v[2:3], v[2:3], 0, s[18:19]
	s_mov_b32 m0, s2
	v_add_u32_e32 v0, 0x10000, v82
	global_load_lds_dwordx4 v[2:3], off
	s_waitcnt vmcnt(6)
	s_barrier
	ds_read_b128 v[2:5], v0
	ds_read_b128 v[6:9], v0 offset:1024
	s_waitcnt vmcnt(0)
	ds_read_b128 v[10:13], v0 offset:2048
	ds_read_b128 v[14:17], v0 offset:3072
	ds_read_b128 v[18:21], v153
	ds_read_b128 v[22:25], v153 offset:1024
	ds_read_b128 v[26:29], v153 offset:2048
	ds_read_b128 v[30:33], v153 offset:3072
	ds_read_b128 v[34:37], v153 offset:4096
	ds_read_b128 v[38:41], v153 offset:5120
	ds_read_b128 v[42:45], v153 offset:6144
	ds_read_b128 v[46:49], v153 offset:7168
	v_mov_b32_e32 v0, v139
	v_readlane_b32 s20, v252, 24
	v_lshl_add_u64 v[50:51], s[8:9], 0, v[0:1]
	v_add_u32_e32 v0, 0xc000, v143
	s_mov_b64 s[8:9], 0x10080
	v_readfirstlane_b32 s2, v0
	v_add_u32_e32 v0, 0xe000, v143
	v_lshl_add_u64 v[52:53], v[50:51], 0, s[8:9]
	s_mov_b32 m0, s2
	s_mov_b64 s[8:9], 0x18080
	v_readfirstlane_b32 s2, v0
	global_load_lds_dwordx4 v[52:53], off
	v_lshl_add_u64 v[50:51], v[50:51], 0, s[8:9]
	s_mov_b32 m0, s2
	v_readlane_b32 s21, v252, 25
	global_load_lds_dwordx4 v[50:51], off
	s_barrier
	s_waitcnt lgkmcnt(0)
	v_readlane_b32 s22, v252, 26
	v_readlane_b32 s23, v252, 27
	v_readlane_b32 s26, v252, 30
	v_readlane_b32 s27, v252, 31
	v_readlane_b32 s28, v252, 32
	v_readlane_b32 s29, v252, 33
	v_readlane_b32 s30, v252, 34
	v_readlane_b32 s31, v252, 35
	v_readlane_b32 s41, v252, 4
	v_readlane_b32 s42, v252, 5
	v_readlane_b32 s43, v252, 6
	v_readlane_b32 s44, v252, 7
	v_readlane_b32 s45, v252, 8
	v_readlane_b32 s46, v252, 9
	v_readlane_b32 s47, v252, 10
	v_readlane_b32 s48, v252, 11
	v_readlane_b32 s49, v252, 12
	v_readlane_b32 s50, v252, 13
	v_readlane_b32 s51, v252, 14
	v_readlane_b32 s54, v252, 17
	v_readlane_b32 s55, v252, 18

; #define MMA(ai, bj, At, Btf) do { __builtin_amdgcn_s_setprio(1); \
;     for (int m = 0; m < 4; ++m) for (int n = 0; n < 2; ++n) for (int k = 0; k < 2; ++k) \
;       acc[ai][bj][m][n] = __builtin_amdgcn_mfma_f32_16x16x32_bf16(Btf[n][k], At[m][k], acc[ai][bj][m][n], 0, 0, 0); \
;     __builtin_amdgcn_s_setprio(0); } while (0)
; #define WAIT_L(n) asm volatile("s_waitcnt lgkmcnt(" #n ")" ::: "memory")
; #define BAR __builtin_amdgcn_s_barrier()
; template <bool OVL, bool PANEL = false, class Epi>
; __device__ __forceinline__ void gemm_phase(const bf16_t* __restrict__ A, long lda, const bf16_t* __restrict__ Bt, long ldb, int nM, int nN, int K,
;                                            const Epi& epi, bf16_t* shm, int w0) {
;     ...
;       BAR; WAIT_L(0); MMA(0, 0, At, B0); BAR;
	s_waitcnt lgkmcnt(0)
	v_mfma_f32_16x16x32_bf16 v[50:53], v[2:5], v[18:21], 0
	v_mfma_f32_16x16x32_bf16 v[54:57], v[10:13], v[18:21], 0
	v_mfma_f32_16x16x32_bf16 v[58:61], v[2:5], v[26:29], 0
	v_mfma_f32_16x16x32_bf16 v[62:65], v[10:13], v[26:29], 0
	v_mfma_f32_16x16x32_bf16 v[66:69], v[2:5], v[34:37], 0
	v_mfma_f32_16x16x32_bf16 v[70:73], v[10:13], v[34:37], 0
	v_mfma_f32_16x16x32_bf16 v[74:77], v[2:5], v[42:45], 0
	v_mfma_f32_16x16x32_bf16 v[78:81], v[10:13], v[42:45], 0
	v_mfma_f32_16x16x32_bf16 v[50:53], v[6:9], v[22:25], v[50:53]
	v_mfma_f32_16x16x32_bf16 v[54:57], v[14:17], v[22:25], v[54:57]
	v_mfma_f32_16x16x32_bf16 v[58:61], v[6:9], v[30:33], v[58:61]
	v_mfma_f32_16x16x32_bf16 v[62:65], v[14:17], v[30:33], v[62:65]
	v_mfma_f32_16x16x32_bf16 v[66:69], v[6:9], v[38:41], v[66:69]
	v_mfma_f32_16x16x32_bf16 v[70:73], v[14:17], v[38:41], v[70:73]
	v_mfma_f32_16x16x32_bf16 v[74:77], v[6:9], v[46:49], v[74:77]
	v_mfma_f32_16x16x32_bf16 v[78:81], v[14:17], v[46:49], v[78:81]

; #define LDB(dst, b, h) for (int n = 0; n < 2; ++n) for (int k = 0; k < 2; ++k) \
;     dst[n][k] = *reinterpret_cast<const bf16x8*>((char*)SB(b, h) + b_thr + (n * 2 + k) * 1024)
; #define MMA(ai, bj, At, Btf) do { __builtin_amdgcn_s_setprio(1); \
;     for (int m = 0; m < 4; ++m) for (int n = 0; n < 2; ++n) for (int k = 0; k < 2; ++k) \
;       acc[ai][bj][m][n] = __builtin_amdgcn_mfma_f32_16x16x32_bf16(Btf[n][k], At[m][k], acc[ai][bj][m][n], 0, 0, 0); \
;     __builtin_amdgcn_s_setprio(0); } while (0)
; #define WAIT_L(n) asm volatile("s_waitcnt lgkmcnt(" #n ")" ::: "memory")
; #define BAR __builtin_amdgcn_s_barrier()
; template <bool OVL, bool PANEL = false, class Epi>
; __device__ __forceinline__ void gemm_phase(const bf16_t* __restrict__ A, long lda, const bf16_t* __restrict__ Bt, long ldb, int nM, int nN, int K,
;                                            const Epi& epi, bf16_t* shm, int w0) {
;     ...
;       LDB(B1, 0, 1); BAR; WAIT_L(0); MMA(0, 1, At, B1); BAR;
	v_add_u32_e32 v0, 0x14000, v82
	s_barrier
	ds_read_b128 v[82:85], v0
	ds_read_b128 v[86:89], v0 offset:1024
	ds_read_b128 v[90:93], v0 offset:2048
	ds_read_b128 v[94:97], v0 offset:3072
	s_barrier
	s_waitcnt lgkmcnt(0)

; #define LDB(dst, b, h) for (int n = 0; n < 2; ++n) for (int k = 0; k < 2; ++k) \
;     dst[n][k] = *reinterpret_cast<const bf16x8*>((char*)SB(b, h) + b_thr + (n * 2 + k) * 1024)
; #define MMA(ai, bj, At, Btf) do { __builtin_amdgcn_s_setprio(1); \
;     for (int m = 0; m < 4; ++m) for (int n = 0; n < 2; ++n) for (int k = 0; k < 2; ++k) \
;       acc[ai][bj][m][n] = __builtin_amdgcn_mfma_f32_16x16x32_bf16(Btf[n][k], At[m][k], acc[ai][bj][m][n], 0, 0, 0); \
;     __builtin_amdgcn_s_setprio(0); } while (0)
; #define WAIT_L(n) asm volatile("s_waitcnt lgkmcnt(" #n ")" ::: "memory")
; #define BAR __builtin_amdgcn_s_barrier()
; template <bool OVL, bool PANEL = false, class Epi>
; __device__ __forceinline__ void gemm_phase(const bf16_t* __restrict__ A, long lda, const bf16_t* __restrict__ Bt, long ldb, int nM, int nN, int K,
;                                            const Epi& epi, bf16_t* shm, int w0) {
;     ...
;       LDB(B1, 0, 1); BAR; WAIT_L(0); MMA(0, 1, At, B1); BAR;
	v_mfma_f32_16x16x32_bf16 v[98:101], v[82:85], v[18:21], 0
	v_mfma_f32_16x16x32_bf16 v[18:21], v[90:93], v[18:21], 0
	v_mfma_f32_16x16x32_bf16 v[98:101], v[86:89], v[22:25], v[98:101]
	v_mfma_f32_16x16x32_bf16 v[18:21], v[94:97], v[22:25], v[18:21]
	v_mfma_f32_16x16x32_bf16 v[22:25], v[82:85], v[26:29], 0
	v_mfma_f32_16x16x32_bf16 v[26:29], v[90:93], v[26:29], 0
	v_mfma_f32_16x16x32_bf16 v[22:25], v[86:89], v[30:33], v[22:25]
	v_mfma_f32_16x16x32_bf16 v[26:29], v[94:97], v[30:33], v[26:29]
	v_mfma_f32_16x16x32_bf16 v[30:33], v[82:85], v[34:37], 0
	v_mfma_f32_16x16x32_bf16 v[102:105], v[86:89], v[38:41], v[30:33]
	v_mfma_f32_16x16x32_bf16 v[30:33], v[90:93], v[34:37], 0
	v_mfma_f32_16x16x32_bf16 v[34:37], v[94:97], v[38:41], v[30:33]
	v_mfma_f32_16x16x32_bf16 v[30:33], v[82:85], v[42:45], 0
	v_mfma_f32_16x16x32_bf16 v[38:41], v[86:89], v[46:49], v[30:33]
	v_mfma_f32_16x16x32_bf16 v[30:33], v[90:93], v[42:45], 0
	v_mfma_f32_16x16x32_bf16 v[42:45], v[94:97], v[46:49], v[30:33]

; #define LDA(dst, b, h) for (int m = 0; m < 4; ++m) for (int k = 0; k < 2; ++k) \
;     dst[m][k] = *reinterpret_cast<const bf16x8*>((char*)SA(b, h) + a_thr + (m * 2 + k) * 1024)
; #define MMA(ai, bj, At, Btf) do { __builtin_amdgcn_s_setprio(1); \
;     for (int m = 0; m < 4; ++m) for (int n = 0; n < 2; ++n) for (int k = 0; k < 2; ++k) \
;       acc[ai][bj][m][n] = __builtin_amdgcn_mfma_f32_16x16x32_bf16(Btf[n][k], At[m][k], acc[ai][bj][m][n], 0, 0, 0); \
;     __builtin_amdgcn_s_setprio(0); } while (0)
; #define WAIT_V(n) asm volatile("s_waitcnt vmcnt(" #n ")" ::: "memory")
; #define WAIT_L(n) asm volatile("s_waitcnt lgkmcnt(" #n ")" ::: "memory")
; #define BAR __builtin_amdgcn_s_barrier()
; template <bool OVL, bool PANEL = false, class Epi>
; __device__ __forceinline__ void gemm_phase(const bf16_t* __restrict__ A, long lda, const bf16_t* __restrict__ Bt, long ldb, int nM, int nN, int K,
;                                            const Epi& epi, bf16_t* shm, int w0) {
;     ...
;       LDA(At, 0, 1); WAIT_V(4); BAR; WAIT_L(0); MMA(1, 0, At, B0); MMA(1, 1, At, B1); BAR; }
	s_barrier
	s_nop 4
	ds_read_b128 v[30:33], v153 offset:16384
	ds_read_b128 v[46:49], v153 offset:17408
	ds_read_b128 v[106:109], v153 offset:18432
	ds_read_b128 v[110:113], v153 offset:19456
	ds_read_b128 v[114:117], v153 offset:20480
	ds_read_b128 v[118:121], v153 offset:21504
	ds_read_b128 v[122:125], v153 offset:22528
	ds_read_b128 v[126:129], v153 offset:23552
	s_waitcnt vmcnt(4)
	s_barrier
	s_waitcnt lgkmcnt(0)

; #define LDA(dst, b, h) for (int m = 0; m < 4; ++m) for (int k = 0; k < 2; ++k) \
;     dst[m][k] = *reinterpret_cast<const bf16x8*>((char*)SA(b, h) + a_thr + (m * 2 + k) * 1024)
; #define MMA(ai, bj, At, Btf) do { __builtin_amdgcn_s_setprio(1); \
;     for (int m = 0; m < 4; ++m) for (int n = 0; n < 2; ++n) for (int k = 0; k < 2; ++k) \
;       acc[ai][bj][m][n] = __builtin_amdgcn_mfma_f32_16x16x32_bf16(Btf[n][k], At[m][k], acc[ai][bj][m][n], 0, 0, 0); \
;     __builtin_amdgcn_s_setprio(0); } while (0)
; #define WAIT_V(n) asm volatile("s_waitcnt vmcnt(" #n ")" ::: "memory")
; #define WAIT_L(n) asm volatile("s_waitcnt lgkmcnt(" #n ")" ::: "memory")
; #define BAR __builtin_amdgcn_s_barrier()
; template <bool OVL, bool PANEL = false, class Epi>
; __device__ __forceinline__ void gemm_phase(const bf16_t* __restrict__ A, long lda, const bf16_t* __restrict__ Bt, long ldb, int nM, int nN, int K,
;                                            const Epi& epi, bf16_t* shm, int w0) {
;     ...
;       LDA(At, 0, 1); WAIT_V(4); BAR; WAIT_L(0); MMA(1, 0, At, B0); MMA(1, 1, At, B1); BAR; }
	v_mfma_f32_16x16x32_bf16 v[130:133], v[2:5], v[30:33], 0
	v_mfma_f32_16x16x32_bf16 v[154:157], v[2:5], v[106:109], 0
	v_mfma_f32_16x16x32_bf16 v[162:165], v[2:5], v[114:117], 0
	v_mfma_f32_16x16x32_bf16 v[2:5], v[2:5], v[122:125], 0
	v_mfma_f32_16x16x32_bf16 v[130:133], v[6:9], v[46:49], v[130:133]
	v_mfma_f32_16x16x32_bf16 v[154:157], v[6:9], v[110:113], v[154:157]
	v_mfma_f32_16x16x32_bf16 v[162:165], v[6:9], v[118:121], v[162:165]
	v_mfma_f32_16x16x32_bf16 v[2:5], v[6:9], v[126:129], v[2:5]
	v_mfma_f32_16x16x32_bf16 v[6:9], v[10:13], v[122:125], 0
	v_mfma_f32_16x16x32_bf16 v[134:137], v[10:13], v[30:33], 0
	v_mfma_f32_16x16x32_bf16 v[158:161], v[10:13], v[106:109], 0
	v_mfma_f32_16x16x32_bf16 v[166:169], v[10:13], v[114:117], 0
	v_mfma_f32_16x16x32_bf16 v[6:9], v[14:17], v[126:129], v[6:9]
	v_mfma_f32_16x16x32_bf16 v[134:137], v[14:17], v[46:49], v[134:137]
	v_mfma_f32_16x16x32_bf16 v[158:161], v[14:17], v[110:113], v[158:161]
	v_mfma_f32_16x16x32_bf16 v[166:169], v[14:17], v[118:121], v[166:169]


; #define LDA(dst, b, h) for (int m = 0; m < 4; ++m) for (int k = 0; k < 2; ++k) \
;     dst[m][k] = *reinterpret_cast<const bf16x8*>((char*)SA(b, h) + a_thr + (m * 2 + k) * 1024)
; #define MMA(ai, bj, At, Btf) do { __builtin_amdgcn_s_setprio(1); \
;     for (int m = 0; m < 4; ++m) for (int n = 0; n < 2; ++n) for (int k = 0; k < 2; ++k) \
;       acc[ai][bj][m][n] = __builtin_amdgcn_mfma_f32_16x16x32_bf16(Btf[n][k], At[m][k], acc[ai][bj][m][n], 0, 0, 0); \
;     __builtin_amdgcn_s_setprio(0); } while (0)
; #define WAIT_V(n) asm volatile("s_waitcnt vmcnt(" #n ")" ::: "memory")
; #define WAIT_L(n) asm volatile("s_waitcnt lgkmcnt(" #n ")" ::: "memory")
; #define BAR __builtin_amdgcn_s_barrier()
; template <bool OVL, bool PANEL = false, class Epi>
; __device__ __forceinline__ void gemm_phase(const bf16_t* __restrict__ A, long lda, const bf16_t* __restrict__ Bt, long ldb, int nM, int nN, int K,
;                                            const Epi& epi, bf16_t* shm, int w0) {
;     ...
;       LDA(At, 0, 1); WAIT_V(4); BAR; WAIT_L(0); MMA(1, 0, At, B0); MMA(1, 1, At, B1); BAR; }
	v_mfma_f32_16x16x32_bf16 v[14:17], v[90:93], v[30:33], 0
	v_mfma_f32_16x16x32_bf16 v[170:173], v[94:97], v[46:49], v[14:17]
	v_mfma_f32_16x16x32_bf16 v[14:17], v[82:85], v[106:109], 0
	v_mfma_f32_16x16x32_bf16 v[174:177], v[86:89], v[110:113], v[14:17]
	v_mfma_f32_16x16x32_bf16 v[14:17], v[90:93], v[106:109], 0
	v_mfma_f32_16x16x32_bf16 v[194:197], v[94:97], v[110:113], v[14:17]
	v_mfma_f32_16x16x32_bf16 v[14:17], v[82:85], v[114:117], 0
	v_mfma_f32_16x16x32_bf16 v[198:201], v[86:89], v[118:121], v[14:17]
	v_mfma_f32_16x16x32_bf16 v[14:17], v[90:93], v[114:117], 0
	v_mfma_f32_16x16x32_bf16 v[10:13], v[82:85], v[30:33], 0
	v_mfma_f32_16x16x32_bf16 v[202:205], v[94:97], v[118:121], v[14:17]
	v_mfma_f32_16x16x32_bf16 v[14:17], v[82:85], v[122:125], 0
	v_mfma_f32_16x16x32_bf16 v[10:13], v[86:89], v[46:49], v[10:13]
	v_mfma_f32_16x16x32_bf16 v[206:209], v[86:89], v[126:129], v[14:17]
	v_mfma_f32_16x16x32_bf16 v[14:17], v[90:93], v[122:125], 0
	v_mfma_f32_16x16x32_bf16 v[210:213], v[94:97], v[126:129], v[14:17]

; #define LDA(dst, b, h) for (int m = 0; m < 4; ++m) for (int k = 0; k < 2; ++k) \
;     dst[m][k] = *reinterpret_cast<const bf16x8*>((char*)SA(b, h) + a_thr + (m * 2 + k) * 1024)
; #define LDB(dst, b, h) for (int n = 0; n < 2; ++n) for (int k = 0; k < 2; ++k) \
;     dst[n][k] = *reinterpret_cast<const bf16x8*>((char*)SB(b, h) + b_thr + (n * 2 + k) * 1024)
; #define MMA(ai, bj, At, Btf) do { __builtin_amdgcn_s_setprio(1); \
;     for (int m = 0; m < 4; ++m) for (int n = 0; n < 2; ++n) for (int k = 0; k < 2; ++k) \
;       acc[ai][bj][m][n] = __builtin_amdgcn_mfma_f32_16x16x32_bf16(Btf[n][k], At[m][k], acc[ai][bj][m][n], 0, 0, 0); \
;     __builtin_amdgcn_s_setprio(0); } while (0)
; #define WAIT_V(n) asm volatile("s_waitcnt vmcnt(" #n ")" ::: "memory")
; #define WAIT_L(n) asm volatile("s_waitcnt lgkmcnt(" #n ")" ::: "memory")
; #define BAR __builtin_amdgcn_s_barrier()
; template <bool OVL, bool PANEL = false, class Epi>
; __device__ __forceinline__ void gemm_phase(const bf16_t* __restrict__ A, long lda, const bf16_t* __restrict__ Bt, long ldb, int nM, int nN, int K,
;                                            const Epi& epi, bf16_t* shm, int w0) {
;     ...
;     { LDB(B0, 1, 0); LDA(At, 1, 0); WAIT_V(2); BAR; WAIT_L(0); MMA(0, 0, At, B0); BAR;
	v_add_u32_e32 v0, s96, v149
	s_barrier
	ds_read_b128 v[214:217], v0
	ds_read_b128 v[218:221], v0 offset:1024
	ds_read_b128 v[234:237], v0 offset:2048
	ds_read_b128 v[238:241], v0 offset:3072
	ds_read_b128 v[14:17], v153 offset:32768
	ds_read_b128 v[30:33], v153 offset:33792
	ds_read_b128 v[46:49], v153 offset:34816
	ds_read_b128 v[82:85], v153 offset:35840
	ds_read_b128 v[106:109], v153 offset:36864
	ds_read_b128 v[114:117], v153 offset:37888
	ds_read_b128 v[242:245], v153 offset:38912
	ds_read_b128 v[246:249], v153 offset:39936
	s_waitcnt vmcnt(2)
	s_barrier
	s_waitcnt lgkmcnt(0)

; #define LDA(dst, b, h) for (int m = 0; m < 4; ++m) for (int k = 0; k < 2; ++k) \
;     dst[m][k] = *reinterpret_cast<const bf16x8*>((char*)SA(b, h) + a_thr + (m * 2 + k) * 1024)
; #define LDB(dst, b, h) for (int n = 0; n < 2; ++n) for (int k = 0; k < 2; ++k) \
;     dst[n][k] = *reinterpret_cast<const bf16x8*>((char*)SB(b, h) + b_thr + (n * 2 + k) * 1024)
; #define MMA(ai, bj, At, Btf) do { __builtin_amdgcn_s_setprio(1); \
;     for (int m = 0; m < 4; ++m) for (int n = 0; n < 2; ++n) for (int k = 0; k < 2; ++k) \
;       acc[ai][bj][m][n] = __builtin_amdgcn_mfma_f32_16x16x32_bf16(Btf[n][k], At[m][k], acc[ai][bj][m][n], 0, 0, 0); \
;     __builtin_amdgcn_s_setprio(0); } while (0)
; #define WAIT_V(n) asm volatile("s_waitcnt vmcnt(" #n ")" ::: "memory")
; #define WAIT_L(n) asm volatile("s_waitcnt lgkmcnt(" #n ")" ::: "memory")
; #define BAR __builtin_amdgcn_s_barrier()
; template <bool OVL, bool PANEL = false, class Epi>
; __device__ __forceinline__ void gemm_phase(const bf16_t* __restrict__ A, long lda, const bf16_t* __restrict__ Bt, long ldb, int nM, int nN, int K,
;                                            const Epi& epi, bf16_t* shm, int w0) {
;     ...
;     { LDB(B0, 1, 0); LDA(At, 1, 0); WAIT_V(2); BAR; WAIT_L(0); MMA(0, 0, At, B0); BAR;
	v_mfma_f32_16x16x32_bf16 v[50:53], v[214:217], v[14:17], v[50:53]
	v_mfma_f32_16x16x32_bf16 v[126:129], v[218:221], v[30:33], v[50:53]
	v_mfma_f32_16x16x32_bf16 v[50:53], v[234:237], v[14:17], v[54:57]
	v_mfma_f32_16x16x32_bf16 v[94:97], v[238:241], v[30:33], v[50:53]
	v_mfma_f32_16x16x32_bf16 v[50:53], v[214:217], v[46:49], v[58:61]
	v_mfma_f32_16x16x32_bf16 v[122:125], v[218:221], v[82:85], v[50:53]
	v_mfma_f32_16x16x32_bf16 v[50:53], v[234:237], v[46:49], v[62:65]
	v_mfma_f32_16x16x32_bf16 v[90:93], v[238:241], v[82:85], v[50:53]
	v_mfma_f32_16x16x32_bf16 v[50:53], v[214:217], v[106:109], v[66:69]
	v_mfma_f32_16x16x32_bf16 v[118:121], v[218:221], v[114:117], v[50:53]
	v_mfma_f32_16x16x32_bf16 v[50:53], v[234:237], v[106:109], v[70:73]
	v_mfma_f32_16x16x32_bf16 v[86:89], v[238:241], v[114:117], v[50:53]
	v_mfma_f32_16x16x32_bf16 v[50:53], v[214:217], v[242:245], v[74:77]
	v_mfma_f32_16x16x32_bf16 v[110:113], v[218:221], v[246:249], v[50:53]
	v_mfma_f32_16x16x32_bf16 v[50:53], v[234:237], v[242:245], v[78:81]
	v_mfma_f32_16x16x32_bf16 v[78:81], v[238:241], v[246:249], v[50:53]

; #define LDA(dst, b, h) for (int m = 0; m < 4; ++m) for (int k = 0; k < 2; ++k) \
;     dst[m][k] = *reinterpret_cast<const bf16x8*>((char*)SA(b, h) + a_thr + (m * 2 + k) * 1024)
; #define LDB(dst, b, h) for (int n = 0; n < 2; ++n) for (int k = 0; k < 2; ++k) \
;     dst[n][k] = *reinterpret_cast<const bf16x8*>((char*)SB(b, h) + b_thr + (n * 2 + k) * 1024)
; #define MMA(ai, bj, At, Btf) do { __builtin_amdgcn_s_setprio(1); \
;     for (int m = 0; m < 4; ++m) for (int n = 0; n < 2; ++n) for (int k = 0; k < 2; ++k) \
;       acc[ai][bj][m][n] = __builtin_amdgcn_mfma_f32_16x16x32_bf16(Btf[n][k], At[m][k], acc[ai][bj][m][n], 0, 0, 0); \
;     __builtin_amdgcn_s_setprio(0); } while (0)
; #define WAIT_V(n) asm volatile("s_waitcnt vmcnt(" #n ")" ::: "memory")
; #define WAIT_L(n) asm volatile("s_waitcnt lgkmcnt(" #n ")" ::: "memory")
; #define BAR __builtin_amdgcn_s_barrier()
; template <bool OVL, bool PANEL = false, class Epi>
; __device__ __forceinline__ void gemm_phase(const bf16_t* __restrict__ A, long lda, const bf16_t* __restrict__ Bt, long ldb, int nM, int nN, int K,
;                                            const Epi& epi, bf16_t* shm, int w0) {
;     ...
;     { LDB(B0, 1, 0); LDA(At, 1, 0); WAIT_V(2); BAR; WAIT_L(0); MMA(0, 0, At, B0); BAR;
;       LDB(B1, 1, 1); WAIT_V(0); BAR; WAIT_L(0); MMA(0, 1, At, B1); BAR;
	v_add_u32_e32 v0, s75, v149
	s_barrier
	ds_read_b128 v[222:225], v0
	ds_read_b128 v[190:193], v0 offset:1024
	ds_read_b128 v[178:181], v0 offset:2048
	ds_read_b128 v[182:185], v0 offset:3072
	s_waitcnt vmcnt(0)
	s_barrier
	s_waitcnt lgkmcnt(0)

; #define LDB(dst, b, h) for (int n = 0; n < 2; ++n) for (int k = 0; k < 2; ++k) \
;     dst[n][k] = *reinterpret_cast<const bf16x8*>((char*)SB(b, h) + b_thr + (n * 2 + k) * 1024)
; #define MMA(ai, bj, At, Btf) do { __builtin_amdgcn_s_setprio(1); \
;     for (int m = 0; m < 4; ++m) for (int n = 0; n < 2; ++n) for (int k = 0; k < 2; ++k) \
;       acc[ai][bj][m][n] = __builtin_amdgcn_mfma_f32_16x16x32_bf16(Btf[n][k], At[m][k], acc[ai][bj][m][n], 0, 0, 0); \
;     __builtin_amdgcn_s_setprio(0); } while (0)
; #define WAIT_V(n) asm volatile("s_waitcnt vmcnt(" #n ")" ::: "memory")
; #define WAIT_L(n) asm volatile("s_waitcnt lgkmcnt(" #n ")" ::: "memory")
; #define BAR __builtin_amdgcn_s_barrier()
; template <bool OVL, bool PANEL = false, class Epi>
; __device__ __forceinline__ void gemm_phase(const bf16_t* __restrict__ A, long lda, const bf16_t* __restrict__ Bt, long ldb, int nM, int nN, int K,
;                                            const Epi& epi, bf16_t* shm, int w0) {
;     ...
;       LDB(B1, 1, 1); WAIT_V(0); BAR; WAIT_L(0); MMA(0, 1, At, B1); BAR;
	v_mfma_f32_16x16x32_bf16 v[50:53], v[222:225], v[14:17], v[98:101]
	v_mfma_f32_16x16x32_bf16 v[14:17], v[178:181], v[14:17], v[18:21]
	v_mfma_f32_16x16x32_bf16 v[62:65], v[190:193], v[30:33], v[50:53]
	v_mfma_f32_16x16x32_bf16 v[30:33], v[182:185], v[30:33], v[14:17]
	v_mfma_f32_16x16x32_bf16 v[14:17], v[222:225], v[46:49], v[22:25]
	v_mfma_f32_16x16x32_bf16 v[58:61], v[190:193], v[82:85], v[14:17]
	v_mfma_f32_16x16x32_bf16 v[14:17], v[178:181], v[46:49], v[26:29]
	v_mfma_f32_16x16x32_bf16 v[26:29], v[182:185], v[82:85], v[14:17]
	v_mfma_f32_16x16x32_bf16 v[14:17], v[222:225], v[106:109], v[102:105]
	v_mfma_f32_16x16x32_bf16 v[54:57], v[190:193], v[114:117], v[14:17]
	v_mfma_f32_16x16x32_bf16 v[14:17], v[178:181], v[106:109], v[34:37]
	v_mfma_f32_16x16x32_bf16 v[22:25], v[182:185], v[114:117], v[14:17]
	v_mfma_f32_16x16x32_bf16 v[14:17], v[222:225], v[242:245], v[38:41]
	v_mfma_f32_16x16x32_bf16 v[46:49], v[190:193], v[246:249], v[14:17]
	v_mfma_f32_16x16x32_bf16 v[14:17], v[178:181], v[242:245], v[42:45]
	v_mfma_f32_16x16x32_bf16 v[14:17], v[182:185], v[246:249], v[14:17]

; #define LDA(dst, b, h) for (int m = 0; m < 4; ++m) for (int k = 0; k < 2; ++k) \
;     dst[m][k] = *reinterpret_cast<const bf16x8*>((char*)SA(b, h) + a_thr + (m * 2 + k) * 1024)
; #define MMA(ai, bj, At, Btf) do { __builtin_amdgcn_s_setprio(1); \
;     for (int m = 0; m < 4; ++m) for (int n = 0; n < 2; ++n) for (int k = 0; k < 2; ++k) \
;       acc[ai][bj][m][n] = __builtin_amdgcn_mfma_f32_16x16x32_bf16(Btf[n][k], At[m][k], acc[ai][bj][m][n], 0, 0, 0); \
;     __builtin_amdgcn_s_setprio(0); } while (0)
; #define WAIT_L(n) asm volatile("s_waitcnt lgkmcnt(" #n ")" ::: "memory")
; #define BAR __builtin_amdgcn_s_barrier()
; template <bool OVL, bool PANEL = false, class Epi>
; __device__ __forceinline__ void gemm_phase(const bf16_t* __restrict__ A, long lda, const bf16_t* __restrict__ Bt, long ldb, int nM, int nN, int K,
;                                            const Epi& epi, bf16_t* shm, int w0) {
;     ...
;       LDA(At, 1, 1); BAR; WAIT_L(0); MMA(1, 0, At, B0); MMA(1, 1, At, B1); BAR; }
	s_barrier
	ds_read_b128 v[18:21], v153 offset:49152
	ds_read_b128 v[34:37], v153 offset:50176
	ds_read_b128 v[38:41], v153 offset:51200
	ds_read_b128 v[242:245], v153 offset:52224
	ds_read_b128 v[246:249], v153 offset:53248
	ds_read_b128 v[186:189], v153 offset:54272
	ds_read_b128 v[230:233], v153 offset:55296
	ds_read_b128 v[144:147], v153 offset:56320
	s_barrier
	s_waitcnt lgkmcnt(0)

; #define LDA(dst, b, h) for (int m = 0; m < 4; ++m) for (int k = 0; k < 2; ++k) \
;     dst[m][k] = *reinterpret_cast<const bf16x8*>((char*)SA(b, h) + a_thr + (m * 2 + k) * 1024)
; #define MMA(ai, bj, At, Btf) do { __builtin_amdgcn_s_setprio(1); \
;     for (int m = 0; m < 4; ++m) for (int n = 0; n < 2; ++n) for (int k = 0; k < 2; ++k) \
;       acc[ai][bj][m][n] = __builtin_amdgcn_mfma_f32_16x16x32_bf16(Btf[n][k], At[m][k], acc[ai][bj][m][n], 0, 0, 0); \
;     __builtin_amdgcn_s_setprio(0); } while (0)
; #define WAIT_L(n) asm volatile("s_waitcnt lgkmcnt(" #n ")" ::: "memory")
; #define BAR __builtin_amdgcn_s_barrier()
; template <bool OVL, bool PANEL = false, class Epi>
; __device__ __forceinline__ void gemm_phase(const bf16_t* __restrict__ A, long lda, const bf16_t* __restrict__ Bt, long ldb, int nM, int nN, int K,
;                                            const Epi& epi, bf16_t* shm, int w0) {
;     ...
;       LDA(At, 1, 1); BAR; WAIT_L(0); MMA(1, 0, At, B0); MMA(1, 1, At, B1); BAR; }
	v_mfma_f32_16x16x32_bf16 v[42:45], v[214:217], v[18:21], v[130:133]
	v_mfma_f32_16x16x32_bf16 v[114:117], v[218:221], v[34:37], v[42:45]
	v_mfma_f32_16x16x32_bf16 v[42:45], v[234:237], v[18:21], v[134:137]
	v_mfma_f32_16x16x32_bf16 v[82:85], v[238:241], v[34:37], v[42:45]
	v_mfma_f32_16x16x32_bf16 v[42:45], v[214:217], v[38:41], v[154:157]
	v_mfma_f32_16x16x32_bf16 v[106:109], v[218:221], v[242:245], v[42:45]
	v_mfma_f32_16x16x32_bf16 v[42:45], v[234:237], v[38:41], v[158:161]
	v_mfma_f32_16x16x32_bf16 v[74:77], v[238:241], v[242:245], v[42:45]
	v_mfma_f32_16x16x32_bf16 v[42:45], v[214:217], v[246:249], v[162:165]
	v_mfma_f32_16x16x32_bf16 v[2:5], v[214:217], v[230:233], v[2:5]
	v_mfma_f32_16x16x32_bf16 v[102:105], v[218:221], v[186:189], v[42:45]
	v_mfma_f32_16x16x32_bf16 v[42:45], v[234:237], v[246:249], v[166:169]
	v_mfma_f32_16x16x32_bf16 v[98:101], v[218:221], v[144:147], v[2:5]
	v_mfma_f32_16x16x32_bf16 v[2:5], v[234:237], v[230:233], v[6:9]
	v_mfma_f32_16x16x32_bf16 v[70:73], v[238:241], v[186:189], v[42:45]
	v_mfma_f32_16x16x32_bf16 v[66:69], v[238:241], v[144:147], v[2:5]


; #define LDA(dst, b, h) for (int m = 0; m < 4; ++m) for (int k = 0; k < 2; ++k) \
;     dst[m][k] = *reinterpret_cast<const bf16x8*>((char*)SA(b, h) + a_thr + (m * 2 + k) * 1024)
; #define MMA(ai, bj, At, Btf) do { __builtin_amdgcn_s_setprio(1); \
;     for (int m = 0; m < 4; ++m) for (int n = 0; n < 2; ++n) for (int k = 0; k < 2; ++k) \
;       acc[ai][bj][m][n] = __builtin_amdgcn_mfma_f32_16x16x32_bf16(Btf[n][k], At[m][k], acc[ai][bj][m][n], 0, 0, 0); \
;     __builtin_amdgcn_s_setprio(0); } while (0)
; #define WAIT_L(n) asm volatile("s_waitcnt lgkmcnt(" #n ")" ::: "memory")
; #define BAR __builtin_amdgcn_s_barrier()
; template <bool OVL, bool PANEL = false, class Epi>
; __device__ __forceinline__ void gemm_phase(const bf16_t* __restrict__ A, long lda, const bf16_t* __restrict__ Bt, long ldb, int nM, int nN, int K,
;                                            const Epi& epi, bf16_t* shm, int w0) {
;     ...
;       LDA(At, 1, 1); BAR; WAIT_L(0); MMA(1, 0, At, B0); MMA(1, 1, At, B1); BAR; }
	v_mfma_f32_16x16x32_bf16 v[2:5], v[222:225], v[18:21], v[10:13]
	v_mfma_f32_16x16x32_bf16 v[50:53], v[190:193], v[34:37], v[2:5]
	v_mfma_f32_16x16x32_bf16 v[2:5], v[178:181], v[18:21], v[170:173]
	v_mfma_f32_16x16x32_bf16 v[18:21], v[182:185], v[34:37], v[2:5]
	v_mfma_f32_16x16x32_bf16 v[2:5], v[222:225], v[38:41], v[174:177]
	v_mfma_f32_16x16x32_bf16 v[42:45], v[190:193], v[242:245], v[2:5]
	v_mfma_f32_16x16x32_bf16 v[2:5], v[178:181], v[38:41], v[194:197]
	v_mfma_f32_16x16x32_bf16 v[10:13], v[182:185], v[242:245], v[2:5]
	v_mfma_f32_16x16x32_bf16 v[2:5], v[222:225], v[246:249], v[198:201]
	v_mfma_f32_16x16x32_bf16 v[38:41], v[190:193], v[186:189], v[2:5]
	v_mfma_f32_16x16x32_bf16 v[2:5], v[178:181], v[246:249], v[202:205]
	v_mfma_f32_16x16x32_bf16 v[6:9], v[182:185], v[186:189], v[2:5]
	v_mfma_f32_16x16x32_bf16 v[2:5], v[222:225], v[230:233], v[206:209]
	v_mfma_f32_16x16x32_bf16 v[34:37], v[190:193], v[144:147], v[2:5]
	v_mfma_f32_16x16x32_bf16 v[2:5], v[178:181], v[230:233], v[210:213]
	v_mfma_f32_16x16x32_bf16 v[2:5], v[182:185], v[144:147], v[2:5]

; #define LDA(dst, b, h) for (int m = 0; m < 4; ++m) for (int k = 0; k < 2; ++k) \
;     dst[m][k] = *reinterpret_cast<const bf16x8*>((char*)SA(b, h) + a_thr + (m * 2 + k) * 1024)
; #define MMA(ai, bj, At, Btf) do { __builtin_amdgcn_s_setprio(1); \
;     for (int m = 0; m < 4; ++m) for (int n = 0; n < 2; ++n) for (int k = 0; k < 2; ++k) \
;       acc[ai][bj][m][n] = __builtin_amdgcn_mfma_f32_16x16x32_bf16(Btf[n][k], At[m][k], acc[ai][bj][m][n], 0, 0, 0); \
;     __builtin_amdgcn_s_setprio(0); } while (0)
; #define WAIT_L(n) asm volatile("s_waitcnt lgkmcnt(" #n ")" ::: "memory")
; #define BAR __builtin_amdgcn_s_barrier()
; template <bool OVL, bool PANEL = false, class Epi>
; __device__ __forceinline__ void gemm_phase(const bf16_t* __restrict__ A, long lda, const bf16_t* __restrict__ Bt, long ldb, int nM, int nN, int K,
;                                            const Epi& epi, bf16_t* shm, int w0) {
;     ...
;       LDA(At, 1, 1); BAR; WAIT_L(0); MMA(1, 0, At, B0); MMA(1, 1, At, B1); BAR; }
;     if (wr == 0) BAR;
	s_barrier
	s_and_saveexec_b64 s[8:9], s[6:7]
	s_cbranch_execz .LBB0_830
	s_barrier

; #define LDA(dst, b, h) for (int m = 0; m < 4; ++m) for (int k = 0; k < 2; ++k) \
;     dst[m][k] = *reinterpret_cast<const bf16x8*>((char*)SA(b, h) + a_thr + (m * 2 + k) * 1024)
; #define LDB(dst, b, h) for (int n = 0; n < 2; ++n) for (int k = 0; k < 2; ++k) \
;     dst[n][k] = *reinterpret_cast<const bf16x8*>((char*)SB(b, h) + b_thr + (n * 2 + k) * 1024)
; #define MMA(ai, bj, At, Btf) do { __builtin_amdgcn_s_setprio(1); \
;     for (int m = 0; m < 4; ++m) for (int n = 0; n < 2; ++n) for (int k = 0; k < 2; ++k) \
;       acc[ai][bj][m][n] = __builtin_amdgcn_mfma_f32_16x16x32_bf16(Btf[n][k], At[m][k], acc[ai][bj][m][n], 0, 0, 0); \
;     __builtin_amdgcn_s_setprio(0); } while (0)
; #define WAIT_V(n) asm volatile("s_waitcnt vmcnt(" #n ")" ::: "memory")
; #define WAIT_L(n) asm volatile("s_waitcnt lgkmcnt(" #n ")" ::: "memory")
; #define BAR __builtin_amdgcn_s_barrier()
; #define SCHED __builtin_amdgcn_sched_barrier(0)
; template <bool OVL, bool PANEL = false, class Epi>
; __device__ __forceinline__ void gemm_phase(const bf16_t* __restrict__ A, long lda, const bf16_t* __restrict__ Bt, long ldb, int nM, int nN, int K,
;                                            const Epi& epi, bf16_t* shm, int w0) {
;     ...
;     for (int t = 0; t < nt - 2; t += 2) {
;       LDB(B0, 0, 0); SCHED; LDA(At, 0, 0); STAGE(SA(1, 1), A, lda, aoff, brow + HALF, t + 1);
;       WAIT_L(8); BAR; WAIT_L(0); MMA(0, 0, At, B0); BAR; SCHED;
;       LDB(B1, 0, 1); STAGE(SB(0, 0), Bt, ldb, boff, bcol, t + 2);
;       BAR; WAIT_L(0); MMA(0, 1, At, B1); BAR;
;       LDA(At, 0, 1); STAGE(SA(0, 0), A, lda, aoff, brow, t + 2);
;       BAR; WAIT_L(0); MMA(1, 0, At, B0); BAR; SCHED;
;       STAGE(SB(0, 1), Bt, ldb, boff, bcol + HALF, t + 2);
;       WAIT_V(6); BAR; MMA(1, 1, At, B1); BAR;
;       LDB(B0, 1, 0); SCHED; LDA(At, 1, 0); STAGE(SA(0, 1), A, lda, aoff, brow + HALF, t + 2);
;       WAIT_L(8); BAR; WAIT_L(0); MMA(0, 0, At, B0); BAR; SCHED;
;       LDB(B1, 1, 1); STAGE(SB(1, 0), Bt, ldb, boff, bcol, t + 3);
;       BAR; WAIT_L(0); MMA(0, 1, At, B1); BAR;
;       LDA(At, 1, 1); STAGE(SA(1, 0), A, lda, aoff, brow, t + 3);
;       BAR; WAIT_L(0); MMA(1, 0, At, B0); BAR; SCHED;
;       STAGE(SB(1, 1), Bt, ldb, boff, bcol + HALF, t + 3);
;       WAIT_V(6); BAR; MMA(1, 1, At, B1); BAR;
;     }
.LBB0_1053:
	ds_read_b128 v[152:155], v184
	ds_read_b128 v[156:159], v184 offset:1024
	ds_read_b128 v[160:163], v184 offset:2048
	ds_read_b128 v[164:167], v184 offset:3072
	s_add_u32 s40, s10, s14
	s_addc_u32 s41, s11, s15
	ds_read_b128 v[168:171], v147
	ds_read_b128 v[172:175], v147 offset:1024
	ds_read_b128 v[176:179], v147 offset:2048
	ds_read_b128 v[194:197], v147 offset:3072
	ds_read_b128 v[198:201], v147 offset:4096
	ds_read_b128 v[202:205], v147 offset:5120
	ds_read_b128 v[206:209], v147 offset:6144
	ds_read_b128 v[210:213], v147 offset:7168
	s_mov_b32 m0, s22
	s_add_u32 s98, s40, s16
	s_addc_u32 s99, s41, s17
	global_load_lds_dwordx4 v135, s[98:99]
	s_mov_b32 m0, s23
	s_add_u32 s98, s40, s36
	s_addc_u32 s99, s41, s37
	global_load_lds_dwordx4 v135, s[98:99]
	s_waitcnt lgkmcnt(8)
	s_waitcnt vmcnt(10)
	s_barrier
	s_waitcnt lgkmcnt(0)
	v_mfma_f32_16x16x32_bf16 v[126:129], v[152:155], v[168:171], v[126:129]
	v_mfma_f32_16x16x32_bf16 v[122:125], v[160:163], v[168:171], v[122:125]
	v_mfma_f32_16x16x32_bf16 v[118:121], v[152:155], v[176:179], v[118:121]
	v_mfma_f32_16x16x32_bf16 v[114:117], v[160:163], v[176:179], v[114:117]
	v_mfma_f32_16x16x32_bf16 v[110:113], v[152:155], v[198:201], v[110:113]
	v_mfma_f32_16x16x32_bf16 v[106:109], v[160:163], v[198:201], v[106:109]
	v_mfma_f32_16x16x32_bf16 v[102:105], v[152:155], v[206:209], v[102:105]
	v_mfma_f32_16x16x32_bf16 v[98:101], v[160:163], v[206:209], v[98:101]
	v_mfma_f32_16x16x32_bf16 v[126:129], v[156:159], v[172:175], v[126:129]
	v_mfma_f32_16x16x32_bf16 v[122:125], v[164:167], v[172:175], v[122:125]
	v_mfma_f32_16x16x32_bf16 v[118:121], v[156:159], v[194:197], v[118:121]
	v_mfma_f32_16x16x32_bf16 v[114:117], v[164:167], v[194:197], v[114:117]
	v_mfma_f32_16x16x32_bf16 v[110:113], v[156:159], v[202:205], v[110:113]
	v_mfma_f32_16x16x32_bf16 v[106:109], v[164:167], v[202:205], v[106:109]
	v_mfma_f32_16x16x32_bf16 v[102:105], v[156:159], v[210:213], v[102:105]
	v_mfma_f32_16x16x32_bf16 v[98:101], v[164:167], v[210:213], v[98:101]
	s_barrier
	s_add_u32 s42, s8, s14
	ds_read_b128 v[214:217], v185
	ds_read_b128 v[218:221], v185 offset:1024
	ds_read_b128 v[234:237], v185 offset:2048
	ds_read_b128 v[238:241], v185 offset:3072
	s_addc_u32 s43, s9, s15
	s_mov_b32 m0, s24
	s_add_u32 s98, s42, s34
	s_addc_u32 s99, s43, s35
	global_load_lds_dwordx4 v135, s[98:99]
	s_mov_b32 m0, s25
	s_add_u32 s98, s42, s64
	s_addc_u32 s99, s43, s65
	global_load_lds_dwordx4 v135, s[98:99]
	s_waitcnt vmcnt(10)
	s_barrier
	s_waitcnt lgkmcnt(0)
	v_mfma_f32_16x16x32_bf16 v[94:97], v[214:217], v[168:171], v[94:97]
	v_mfma_f32_16x16x32_bf16 v[90:93], v[234:237], v[168:171], v[90:93]
	v_mfma_f32_16x16x32_bf16 v[86:89], v[214:217], v[176:179], v[86:89]
	v_mfma_f32_16x16x32_bf16 v[82:85], v[234:237], v[176:179], v[82:85]
	v_mfma_f32_16x16x32_bf16 v[78:81], v[214:217], v[198:201], v[78:81]
	v_mfma_f32_16x16x32_bf16 v[74:77], v[234:237], v[198:201], v[74:77]
	v_mfma_f32_16x16x32_bf16 v[70:73], v[214:217], v[206:209], v[70:73]
	v_mfma_f32_16x16x32_bf16 v[66:69], v[234:237], v[206:209], v[66:69]
	v_mfma_f32_16x16x32_bf16 v[94:97], v[218:221], v[172:175], v[94:97]
	v_mfma_f32_16x16x32_bf16 v[90:93], v[238:241], v[172:175], v[90:93]
	v_mfma_f32_16x16x32_bf16 v[86:89], v[218:221], v[194:197], v[86:89]
	v_mfma_f32_16x16x32_bf16 v[82:85], v[238:241], v[194:197], v[82:85]
	v_mfma_f32_16x16x32_bf16 v[78:81], v[218:221], v[202:205], v[78:81]
	v_mfma_f32_16x16x32_bf16 v[74:77], v[238:241], v[202:205], v[74:77]
	v_mfma_f32_16x16x32_bf16 v[70:73], v[218:221], v[210:213], v[70:73]
	v_mfma_f32_16x16x32_bf16 v[66:69], v[238:241], v[210:213], v[66:69]
	s_barrier
	ds_read_b128 v[168:171], v147 offset:16384
	ds_read_b128 v[172:175], v147 offset:17408
	ds_read_b128 v[176:179], v147 offset:18432
	ds_read_b128 v[194:197], v147 offset:19456
	ds_read_b128 v[198:201], v147 offset:20480
	ds_read_b128 v[202:205], v147 offset:21504
	ds_read_b128 v[206:209], v147 offset:22528
	ds_read_b128 v[210:213], v147 offset:23552
	s_mov_b32 m0, s26
	s_add_u32 s98, s40, s34
	s_addc_u32 s99, s41, s35
	global_load_lds_dwordx4 v135, s[98:99]
	s_mov_b32 m0, s27
	s_add_u32 s98, s40, s64
	s_addc_u32 s99, s41, s65
	global_load_lds_dwordx4 v135, s[98:99]
	s_barrier
	s_waitcnt lgkmcnt(0)
	v_mfma_f32_16x16x32_bf16 v[62:65], v[152:155], v[168:171], v[62:65]
	v_mfma_f32_16x16x32_bf16 v[58:61], v[160:163], v[168:171], v[58:61]
	v_mfma_f32_16x16x32_bf16 v[54:57], v[152:155], v[176:179], v[54:57]
	v_mfma_f32_16x16x32_bf16 v[50:53], v[160:163], v[176:179], v[50:53]
	v_mfma_f32_16x16x32_bf16 v[46:49], v[152:155], v[198:201], v[46:49]
	v_mfma_f32_16x16x32_bf16 v[42:45], v[160:163], v[198:201], v[42:45]
	v_mfma_f32_16x16x32_bf16 v[38:41], v[152:155], v[206:209], v[38:41]
	v_mfma_f32_16x16x32_bf16 v[34:37], v[160:163], v[206:209], v[34:37]
	v_mfma_f32_16x16x32_bf16 v[62:65], v[156:159], v[172:175], v[62:65]
	v_mfma_f32_16x16x32_bf16 v[58:61], v[164:167], v[172:175], v[58:61]
	v_mfma_f32_16x16x32_bf16 v[54:57], v[156:159], v[194:197], v[54:57]
	v_mfma_f32_16x16x32_bf16 v[50:53], v[164:167], v[194:197], v[50:53]
	v_mfma_f32_16x16x32_bf16 v[46:49], v[156:159], v[202:205], v[46:49]
	v_mfma_f32_16x16x32_bf16 v[42:45], v[164:167], v[202:205], v[42:45]
	v_mfma_f32_16x16x32_bf16 v[38:41], v[156:159], v[210:213], v[38:41]
	v_mfma_f32_16x16x32_bf16 v[34:37], v[164:167], v[210:213], v[34:37]
	s_barrier
	s_mov_b32 m0, s28
	s_add_u32 s98, s42, s68
	s_addc_u32 s99, s43, s69
	global_load_lds_dwordx4 v135, s[98:99]
	s_mov_b32 m0, s29
	s_add_u32 s98, s42, s70
	s_addc_u32 s99, s43, s71
	global_load_lds_dwordx4 v135, s[98:99]
	s_waitcnt vmcnt(10)
	s_barrier
; #define LDA(dst, b, h) for (int m = 0; m < 4; ++m) for (int k = 0; k < 2; ++k) \
;     dst[m][k] = *reinterpret_cast<const bf16x8*>((char*)SA(b, h) + a_thr + (m * 2 + k) * 1024)
; #define LDB(dst, b, h) for (int n = 0; n < 2; ++n) for (int k = 0; k < 2; ++k) \
;     dst[n][k] = *reinterpret_cast<const bf16x8*>((char*)SB(b, h) + b_thr + (n * 2 + k) * 1024)
; #define MMA(ai, bj, At, Btf) do { __builtin_amdgcn_s_setprio(1); \
;     for (int m = 0; m < 4; ++m) for (int n = 0; n < 2; ++n) for (int k = 0; k < 2; ++k) \
;       acc[ai][bj][m][n] = __builtin_amdgcn_mfma_f32_16x16x32_bf16(Btf[n][k], At[m][k], acc[ai][bj][m][n], 0, 0, 0); \
;     __builtin_amdgcn_s_setprio(0); } while (0)
; #define WAIT_V(n) asm volatile("s_waitcnt vmcnt(" #n ")" ::: "memory")
; #define WAIT_L(n) asm volatile("s_waitcnt lgkmcnt(" #n ")" ::: "memory")
; #define BAR __builtin_amdgcn_s_barrier()
; #define SCHED __builtin_amdgcn_sched_barrier(0)
; template <bool OVL, bool PANEL = false, class Epi>
; __device__ __forceinline__ void gemm_phase(const bf16_t* __restrict__ A, long lda, const bf16_t* __restrict__ Bt, long ldb, int nM, int nN, int K,
;                                            const Epi& epi, bf16_t* shm, int w0) {
;     ...
;     for (int t = 0; t < nt - 2; t += 2) {
;       LDB(B0, 0, 0); SCHED; LDA(At, 0, 0); STAGE(SA(1, 1), A, lda, aoff, brow + HALF, t + 1);
;       WAIT_L(8); BAR; WAIT_L(0); MMA(0, 0, At, B0); BAR; SCHED;
;       LDB(B1, 0, 1); STAGE(SB(0, 0), Bt, ldb, boff, bcol, t + 2);
;       BAR; WAIT_L(0); MMA(0, 1, At, B1); BAR;
;       LDA(At, 0, 1); STAGE(SA(0, 0), A, lda, aoff, brow, t + 2);
;       BAR; WAIT_L(0); MMA(1, 0, At, B0); BAR; SCHED;
;       STAGE(SB(0, 1), Bt, ldb, boff, bcol + HALF, t + 2);
;       WAIT_V(6); BAR; MMA(1, 1, At, B1); BAR;
;       LDB(B0, 1, 0); SCHED; LDA(At, 1, 0); STAGE(SA(0, 1), A, lda, aoff, brow + HALF, t + 2);
;       WAIT_L(8); BAR; WAIT_L(0); MMA(0, 0, At, B0); BAR; SCHED;
;       LDB(B1, 1, 1); STAGE(SB(1, 0), Bt, ldb, boff, bcol, t + 3);
;       BAR; WAIT_L(0); MMA(0, 1, At, B1); BAR;
;       LDA(At, 1, 1); STAGE(SA(1, 0), A, lda, aoff, brow, t + 3);
;       BAR; WAIT_L(0); MMA(1, 0, At, B0); BAR; SCHED;
;       STAGE(SB(1, 1), Bt, ldb, boff, bcol + HALF, t + 3);
;       WAIT_V(6); BAR; MMA(1, 1, At, B1); BAR;
;     }
	v_mfma_f32_16x16x32_bf16 v[30:33], v[214:217], v[168:171], v[30:33]
	v_mfma_f32_16x16x32_bf16 v[26:29], v[234:237], v[168:171], v[26:29]
	v_mfma_f32_16x16x32_bf16 v[22:25], v[214:217], v[176:179], v[22:25]
	v_mfma_f32_16x16x32_bf16 v[18:21], v[234:237], v[176:179], v[18:21]
	v_mfma_f32_16x16x32_bf16 v[14:17], v[214:217], v[198:201], v[14:17]
	v_mfma_f32_16x16x32_bf16 v[10:13], v[234:237], v[198:201], v[10:13]
	v_mfma_f32_16x16x32_bf16 v[6:9], v[214:217], v[206:209], v[6:9]
	v_mfma_f32_16x16x32_bf16 v[2:5], v[234:237], v[206:209], v[2:5]
	v_mfma_f32_16x16x32_bf16 v[30:33], v[218:221], v[172:175], v[30:33]
	v_mfma_f32_16x16x32_bf16 v[26:29], v[238:241], v[172:175], v[26:29]
	v_mfma_f32_16x16x32_bf16 v[22:25], v[218:221], v[194:197], v[22:25]
	v_mfma_f32_16x16x32_bf16 v[18:21], v[238:241], v[194:197], v[18:21]
	v_mfma_f32_16x16x32_bf16 v[14:17], v[218:221], v[202:205], v[14:17]
	v_mfma_f32_16x16x32_bf16 v[10:13], v[238:241], v[202:205], v[10:13]
	v_mfma_f32_16x16x32_bf16 v[6:9], v[218:221], v[210:213], v[6:9]
	v_mfma_f32_16x16x32_bf16 v[2:5], v[238:241], v[210:213], v[2:5]
	s_barrier
	ds_read_b128 v[152:155], v186
	ds_read_b128 v[156:159], v186 offset:1024
	ds_read_b128 v[160:163], v186 offset:2048
	ds_read_b128 v[164:167], v186 offset:3072
	ds_read_b128 v[168:171], v147 offset:32768
	ds_read_b128 v[172:175], v147 offset:33792
	ds_read_b128 v[176:179], v147 offset:34816
	ds_read_b128 v[194:197], v147 offset:35840
	ds_read_b128 v[198:201], v147 offset:36864
	ds_read_b128 v[202:205], v147 offset:37888
	ds_read_b128 v[206:209], v147 offset:38912
	ds_read_b128 v[210:213], v147 offset:39936
	s_mov_b32 m0, s30
	s_add_u32 s98, s40, s68
	s_addc_u32 s99, s41, s69
	global_load_lds_dwordx4 v135, s[98:99]
	s_mov_b32 m0, s31
	s_add_u32 s98, s40, s70
	s_addc_u32 s99, s41, s71
	global_load_lds_dwordx4 v135, s[98:99]
	s_waitcnt lgkmcnt(8)
	s_waitcnt vmcnt(10)
	s_barrier
	s_waitcnt lgkmcnt(0)
	v_mfma_f32_16x16x32_bf16 v[126:129], v[152:155], v[168:171], v[126:129]
	v_mfma_f32_16x16x32_bf16 v[122:125], v[160:163], v[168:171], v[122:125]
	v_mfma_f32_16x16x32_bf16 v[118:121], v[152:155], v[176:179], v[118:121]
	v_mfma_f32_16x16x32_bf16 v[114:117], v[160:163], v[176:179], v[114:117]
	v_mfma_f32_16x16x32_bf16 v[110:113], v[152:155], v[198:201], v[110:113]
	v_mfma_f32_16x16x32_bf16 v[106:109], v[160:163], v[198:201], v[106:109]
	v_mfma_f32_16x16x32_bf16 v[102:105], v[152:155], v[206:209], v[102:105]
	v_mfma_f32_16x16x32_bf16 v[98:101], v[160:163], v[206:209], v[98:101]
	v_mfma_f32_16x16x32_bf16 v[126:129], v[156:159], v[172:175], v[126:129]
	v_mfma_f32_16x16x32_bf16 v[122:125], v[164:167], v[172:175], v[122:125]
	v_mfma_f32_16x16x32_bf16 v[118:121], v[156:159], v[194:197], v[118:121]
	v_mfma_f32_16x16x32_bf16 v[114:117], v[164:167], v[194:197], v[114:117]
	v_mfma_f32_16x16x32_bf16 v[110:113], v[156:159], v[202:205], v[110:113]
	v_mfma_f32_16x16x32_bf16 v[106:109], v[164:167], v[202:205], v[106:109]
	v_mfma_f32_16x16x32_bf16 v[102:105], v[156:159], v[210:213], v[102:105]
	v_mfma_f32_16x16x32_bf16 v[98:101], v[164:167], v[210:213], v[98:101]
	s_barrier
	ds_read_b128 v[214:217], v187
	ds_read_b128 v[218:221], v187 offset:1024
	ds_read_b128 v[234:237], v187 offset:2048
	ds_read_b128 v[238:241], v187 offset:3072
	s_mov_b32 m0, s32
	s_add_u32 s98, s42, s94
	s_addc_u32 s99, s43, s95
	global_load_lds_dwordx4 v135, s[98:99]
	s_mov_b32 m0, s44
	s_add_u32 s98, s42, s72
	s_addc_u32 s99, s43, s73
	global_load_lds_dwordx4 v135, s[98:99]
	s_waitcnt vmcnt(10)
	s_barrier
	s_waitcnt lgkmcnt(0)
	v_mfma_f32_16x16x32_bf16 v[94:97], v[214:217], v[168:171], v[94:97]
	v_mfma_f32_16x16x32_bf16 v[90:93], v[234:237], v[168:171], v[90:93]
	v_mfma_f32_16x16x32_bf16 v[86:89], v[214:217], v[176:179], v[86:89]
	v_mfma_f32_16x16x32_bf16 v[82:85], v[234:237], v[176:179], v[82:85]
	v_mfma_f32_16x16x32_bf16 v[78:81], v[214:217], v[198:201], v[78:81]
	v_mfma_f32_16x16x32_bf16 v[74:77], v[234:237], v[198:201], v[74:77]
	v_mfma_f32_16x16x32_bf16 v[70:73], v[214:217], v[206:209], v[70:73]
	v_mfma_f32_16x16x32_bf16 v[66:69], v[234:237], v[206:209], v[66:69]
	v_mfma_f32_16x16x32_bf16 v[94:97], v[218:221], v[172:175], v[94:97]
	v_mfma_f32_16x16x32_bf16 v[90:93], v[238:241], v[172:175], v[90:93]
	v_mfma_f32_16x16x32_bf16 v[86:89], v[218:221], v[194:197], v[86:89]
	v_mfma_f32_16x16x32_bf16 v[82:85], v[238:241], v[194:197], v[82:85]
	v_mfma_f32_16x16x32_bf16 v[78:81], v[218:221], v[202:205], v[78:81]
	v_mfma_f32_16x16x32_bf16 v[74:77], v[238:241], v[202:205], v[74:77]
	v_mfma_f32_16x16x32_bf16 v[70:73], v[218:221], v[210:213], v[70:73]
	v_mfma_f32_16x16x32_bf16 v[66:69], v[238:241], v[210:213], v[66:69]
	s_barrier
; #define LDA(dst, b, h) for (int m = 0; m < 4; ++m) for (int k = 0; k < 2; ++k) \
;     dst[m][k] = *reinterpret_cast<const bf16x8*>((char*)SA(b, h) + a_thr + (m * 2 + k) * 1024)
; #define LDB(dst, b, h) for (int n = 0; n < 2; ++n) for (int k = 0; k < 2; ++k) \
;     dst[n][k] = *reinterpret_cast<const bf16x8*>((char*)SB(b, h) + b_thr + (n * 2 + k) * 1024)
; #define MMA(ai, bj, At, Btf) do { __builtin_amdgcn_s_setprio(1); \
;     for (int m = 0; m < 4; ++m) for (int n = 0; n < 2; ++n) for (int k = 0; k < 2; ++k) \
;       acc[ai][bj][m][n] = __builtin_amdgcn_mfma_f32_16x16x32_bf16(Btf[n][k], At[m][k], acc[ai][bj][m][n], 0, 0, 0); \
;     __builtin_amdgcn_s_setprio(0); } while (0)
; #define WAIT_V(n) asm volatile("s_waitcnt vmcnt(" #n ")" ::: "memory")
; #define WAIT_L(n) asm volatile("s_waitcnt lgkmcnt(" #n ")" ::: "memory")
; #define BAR __builtin_amdgcn_s_barrier()
; #define SCHED __builtin_amdgcn_sched_barrier(0)
; template <bool OVL, bool PANEL = false, class Epi>
; __device__ __forceinline__ void gemm_phase(const bf16_t* __restrict__ A, long lda, const bf16_t* __restrict__ Bt, long ldb, int nM, int nN, int K,
;                                            const Epi& epi, bf16_t* shm, int w0) {
;     ...
;       WAIT_V(6); BAR; MMA(1, 1, At, B1); BAR;
;       LDB(B0, 1, 0); SCHED; LDA(At, 1, 0); STAGE(SA(0, 1), A, lda, aoff, brow + HALF, t + 2);
;       WAIT_L(8); BAR; WAIT_L(0); MMA(0, 0, At, B0); BAR; SCHED;
;       LDB(B1, 1, 1); STAGE(SB(1, 0), Bt, ldb, boff, bcol, t + 3);
;       BAR; WAIT_L(0); MMA(0, 1, At, B1); BAR;
;       LDA(At, 1, 1); STAGE(SA(1, 0), A, lda, aoff, brow, t + 3);
;       BAR; WAIT_L(0); MMA(1, 0, At, B0); BAR; SCHED;
;       STAGE(SB(1, 1), Bt, ldb, boff, bcol + HALF, t + 3);
;       WAIT_V(6); BAR; MMA(1, 1, At, B1); BAR;
;     }
;     { LDB(B0, 0, 0); LDA(At, 0, 0); STAGE(SA(1, 1), A, lda, aoff, brow + HALF, nt - 1);
;       BAR; WAIT_L(0); MMA(0, 0, At, B0); BAR;
	ds_read_b128 v[168:171], v147 offset:49152
	ds_read_b128 v[172:175], v147 offset:50176
	ds_read_b128 v[176:179], v147 offset:51200
	ds_read_b128 v[194:197], v147 offset:52224
	ds_read_b128 v[198:201], v147 offset:53248
	ds_read_b128 v[202:205], v147 offset:54272
	ds_read_b128 v[206:209], v147 offset:55296
	ds_read_b128 v[210:213], v147 offset:56320
	s_mov_b32 m0, s45
	s_add_u32 s98, s40, s94
	s_addc_u32 s99, s41, s95
	global_load_lds_dwordx4 v135, s[98:99]
	s_mov_b32 m0, s46
	s_add_u32 s98, s40, s72
	s_addc_u32 s99, s41, s73
	global_load_lds_dwordx4 v135, s[98:99]
	s_barrier
	s_waitcnt lgkmcnt(0)
	v_mfma_f32_16x16x32_bf16 v[62:65], v[152:155], v[168:171], v[62:65]
	v_mfma_f32_16x16x32_bf16 v[58:61], v[160:163], v[168:171], v[58:61]
	v_mfma_f32_16x16x32_bf16 v[54:57], v[152:155], v[176:179], v[54:57]
	v_mfma_f32_16x16x32_bf16 v[50:53], v[160:163], v[176:179], v[50:53]
	v_mfma_f32_16x16x32_bf16 v[46:49], v[152:155], v[198:201], v[46:49]
	v_mfma_f32_16x16x32_bf16 v[42:45], v[160:163], v[198:201], v[42:45]
	v_mfma_f32_16x16x32_bf16 v[38:41], v[152:155], v[206:209], v[38:41]
	v_mfma_f32_16x16x32_bf16 v[34:37], v[160:163], v[206:209], v[34:37]
	v_mfma_f32_16x16x32_bf16 v[62:65], v[156:159], v[172:175], v[62:65]
	v_mfma_f32_16x16x32_bf16 v[58:61], v[164:167], v[172:175], v[58:61]
	v_mfma_f32_16x16x32_bf16 v[54:57], v[156:159], v[194:197], v[54:57]
	v_mfma_f32_16x16x32_bf16 v[50:53], v[164:167], v[194:197], v[50:53]
	v_mfma_f32_16x16x32_bf16 v[46:49], v[156:159], v[202:205], v[46:49]
	v_mfma_f32_16x16x32_bf16 v[42:45], v[164:167], v[202:205], v[42:45]
	v_mfma_f32_16x16x32_bf16 v[38:41], v[156:159], v[210:213], v[38:41]
	v_mfma_f32_16x16x32_bf16 v[34:37], v[164:167], v[210:213], v[34:37]
	s_barrier
	s_mov_b32 m0, s47
	s_add_u32 s98, s42, s18
	s_addc_u32 s99, s43, s19
	global_load_lds_dwordx4 v135, s[98:99]
	s_mov_b32 m0, s48
	s_add_u32 s98, s42, s20
	s_addc_u32 s99, s43, s21
	global_load_lds_dwordx4 v135, s[98:99]
	s_add_i32 s1, s1, 2
	s_add_u32 s14, s14, 0x100
	s_addc_u32 s15, s15, 0
	s_cmp_lt_u32 s1, 12
	s_waitcnt vmcnt(10)
	s_barrier
	v_mfma_f32_16x16x32_bf16 v[30:33], v[214:217], v[168:171], v[30:33]
	v_mfma_f32_16x16x32_bf16 v[26:29], v[234:237], v[168:171], v[26:29]
	v_mfma_f32_16x16x32_bf16 v[22:25], v[214:217], v[176:179], v[22:25]
	v_mfma_f32_16x16x32_bf16 v[18:21], v[234:237], v[176:179], v[18:21]
	v_mfma_f32_16x16x32_bf16 v[14:17], v[214:217], v[198:201], v[14:17]
	v_mfma_f32_16x16x32_bf16 v[10:13], v[234:237], v[198:201], v[10:13]
	v_mfma_f32_16x16x32_bf16 v[6:9], v[214:217], v[206:209], v[6:9]
	v_mfma_f32_16x16x32_bf16 v[2:5], v[234:237], v[206:209], v[2:5]
	v_mfma_f32_16x16x32_bf16 v[30:33], v[218:221], v[172:175], v[30:33]
	v_mfma_f32_16x16x32_bf16 v[26:29], v[238:241], v[172:175], v[26:29]
	v_mfma_f32_16x16x32_bf16 v[22:25], v[218:221], v[194:197], v[22:25]
	v_mfma_f32_16x16x32_bf16 v[18:21], v[238:241], v[194:197], v[18:21]
	v_mfma_f32_16x16x32_bf16 v[14:17], v[218:221], v[202:205], v[14:17]
	v_mfma_f32_16x16x32_bf16 v[10:13], v[238:241], v[202:205], v[10:13]
	v_mfma_f32_16x16x32_bf16 v[6:9], v[218:221], v[210:213], v[6:9]
	v_mfma_f32_16x16x32_bf16 v[2:5], v[238:241], v[210:213], v[2:5]
	s_barrier
	s_cbranch_scc1 .LBB0_1053
	s_waitcnt vmcnt(6)
	s_or_b32 s8, s0, 0x80
	s_ashr_i32 s9, s8, 31
	v_readlane_b32 s40, v252, 20
	s_lshl_b64 s[8:9], s[8:9], 11
	v_readlane_b32 s46, v252, 26
	v_add_u32_e32 v182, 16, v144
	v_readlane_b32 s47, v252, 27
	s_add_u32 s8, s46, s8
	v_add_u32_e32 v0, 0x10000, v182
	s_addc_u32 s9, s47, s9
	ds_read_b128 v[130:133], v0
	ds_read_b128 v[152:155], v0 offset:1024
	ds_read_b128 v[156:159], v0 offset:2048
	ds_read_b128 v[160:163], v0 offset:3072
	ds_read_b128 v[164:167], v147
	ds_read_b128 v[168:171], v147 offset:1024
	ds_read_b128 v[172:175], v147 offset:2048
	ds_read_b128 v[176:179], v147 offset:3072
	ds_read_b128 v[194:197], v147 offset:4096
	ds_read_b128 v[198:201], v147 offset:5120
	ds_read_b128 v[202:205], v147 offset:6144
	ds_read_b128 v[206:209], v147 offset:7168
	v_mov_b32_e32 v0, v135
	v_readfirstlane_b32 s1, v150
	v_lshl_add_u64 v[148:149], s[8:9], 0, v[0:1]
	s_mov_b64 s[8:9], 0x780
	v_lshl_add_u64 v[180:181], v[148:149], 0, s[8:9]
	s_mov_b32 m0, s1
	s_mov_b64 s[8:9], 0x20780
	v_readfirstlane_b32 s1, v151
	global_load_lds_dwordx4 v[180:181], off
	v_lshl_add_u64 v[148:149], v[148:149], 0, s[8:9]
	s_mov_b32 m0, s1
	v_readlane_b32 s41, v252, 21
	global_load_lds_dwordx4 v[148:149], off
	s_barrier
	s_waitcnt lgkmcnt(0)
	v_readlane_b32 s42, v252, 22
	v_readlane_b32 s43, v252, 23
	v_readlane_b32 s44, v252, 24
	v_readlane_b32 s45, v252, 25
	v_readlane_b32 s48, v252, 28
	v_readlane_b32 s49, v252, 29
	v_readlane_b32 s50, v252, 30
	v_readlane_b32 s51, v252, 31
	v_readlane_b32 s52, v252, 32
	v_readlane_b32 s53, v252, 33
	v_readlane_b32 s54, v252, 34
	v_readlane_b32 s55, v252, 35

; #define MMA(ai, bj, At, Btf) do { __builtin_amdgcn_s_setprio(1); \
;     for (int m = 0; m < 4; ++m) for (int n = 0; n < 2; ++n) for (int k = 0; k < 2; ++k) \
;       acc[ai][bj][m][n] = __builtin_amdgcn_mfma_f32_16x16x32_bf16(Btf[n][k], At[m][k], acc[ai][bj][m][n], 0, 0, 0); \
;     __builtin_amdgcn_s_setprio(0); } while (0)
; #define WAIT_L(n) asm volatile("s_waitcnt lgkmcnt(" #n ")" ::: "memory")
; #define BAR __builtin_amdgcn_s_barrier()
; template <bool OVL, bool PANEL = false, class Epi>
; __device__ __forceinline__ void gemm_phase(const bf16_t* __restrict__ A, long lda, const bf16_t* __restrict__ Bt, long ldb, int nM, int nN, int K,
;                                            const Epi& epi, bf16_t* shm, int w0) {
;     ...
;       BAR; WAIT_L(0); MMA(0, 0, At, B0); BAR;
	s_waitcnt lgkmcnt(0)
	v_mfma_f32_16x16x32_bf16 v[126:129], v[130:133], v[164:167], v[126:129]
	v_mfma_f32_16x16x32_bf16 v[122:125], v[156:159], v[164:167], v[122:125]
	v_mfma_f32_16x16x32_bf16 v[118:121], v[130:133], v[172:175], v[118:121]
	v_mfma_f32_16x16x32_bf16 v[114:117], v[156:159], v[172:175], v[114:117]
	v_mfma_f32_16x16x32_bf16 v[110:113], v[130:133], v[194:197], v[110:113]
	v_mfma_f32_16x16x32_bf16 v[106:109], v[156:159], v[194:197], v[106:109]
	v_mfma_f32_16x16x32_bf16 v[102:105], v[130:133], v[202:205], v[102:105]
	v_mfma_f32_16x16x32_bf16 v[98:101], v[156:159], v[202:205], v[98:101]
	v_mfma_f32_16x16x32_bf16 v[126:129], v[152:155], v[168:171], v[126:129]
	v_mfma_f32_16x16x32_bf16 v[122:125], v[160:163], v[168:171], v[122:125]
	v_mfma_f32_16x16x32_bf16 v[118:121], v[152:155], v[176:179], v[118:121]
	v_mfma_f32_16x16x32_bf16 v[114:117], v[160:163], v[176:179], v[114:117]
	v_mfma_f32_16x16x32_bf16 v[110:113], v[152:155], v[198:201], v[110:113]
	v_mfma_f32_16x16x32_bf16 v[106:109], v[160:163], v[198:201], v[106:109]
	v_mfma_f32_16x16x32_bf16 v[102:105], v[152:155], v[206:209], v[102:105]
	v_mfma_f32_16x16x32_bf16 v[98:101], v[160:163], v[206:209], v[98:101]

; #define LDB(dst, b, h) for (int n = 0; n < 2; ++n) for (int k = 0; k < 2; ++k) \
;     dst[n][k] = *reinterpret_cast<const bf16x8*>((char*)SB(b, h) + b_thr + (n * 2 + k) * 1024)
; #define MMA(ai, bj, At, Btf) do { __builtin_amdgcn_s_setprio(1); \
;     for (int m = 0; m < 4; ++m) for (int n = 0; n < 2; ++n) for (int k = 0; k < 2; ++k) \
;       acc[ai][bj][m][n] = __builtin_amdgcn_mfma_f32_16x16x32_bf16(Btf[n][k], At[m][k], acc[ai][bj][m][n], 0, 0, 0); \
;     __builtin_amdgcn_s_setprio(0); } while (0)
; #define WAIT_L(n) asm volatile("s_waitcnt lgkmcnt(" #n ")" ::: "memory")
; #define BAR __builtin_amdgcn_s_barrier()
; template <bool OVL, bool PANEL = false, class Epi>
; __device__ __forceinline__ void gemm_phase(const bf16_t* __restrict__ A, long lda, const bf16_t* __restrict__ Bt, long ldb, int nM, int nN, int K,
;                                            const Epi& epi, bf16_t* shm, int w0) {
;     ...
;       BAR; WAIT_L(0); MMA(0, 0, At, B0); BAR;
;       LDB(B1, 0, 1); BAR; WAIT_L(0); MMA(0, 1, At, B1); BAR;
	v_add_u32_e32 v0, 0x14000, v182
	s_barrier
	ds_read_b128 v[148:151], v0
	ds_read_b128 v[210:213], v0 offset:1024
	ds_read_b128 v[214:217], v0 offset:2048
	ds_read_b128 v[218:221], v0 offset:3072
	s_barrier
	s_waitcnt lgkmcnt(0)

; #define LDB(dst, b, h) for (int n = 0; n < 2; ++n) for (int k = 0; k < 2; ++k) \
;     dst[n][k] = *reinterpret_cast<const bf16x8*>((char*)SB(b, h) + b_thr + (n * 2 + k) * 1024)
; #define MMA(ai, bj, At, Btf) do { __builtin_amdgcn_s_setprio(1); \
;     for (int m = 0; m < 4; ++m) for (int n = 0; n < 2; ++n) for (int k = 0; k < 2; ++k) \
;       acc[ai][bj][m][n] = __builtin_amdgcn_mfma_f32_16x16x32_bf16(Btf[n][k], At[m][k], acc[ai][bj][m][n], 0, 0, 0); \
;     __builtin_amdgcn_s_setprio(0); } while (0)
; #define WAIT_L(n) asm volatile("s_waitcnt lgkmcnt(" #n ")" ::: "memory")
; #define BAR __builtin_amdgcn_s_barrier()
; template <bool OVL, bool PANEL = false, class Epi>
; __device__ __forceinline__ void gemm_phase(const bf16_t* __restrict__ A, long lda, const bf16_t* __restrict__ Bt, long ldb, int nM, int nN, int K,
;                                            const Epi& epi, bf16_t* shm, int w0) {
;     ...
;       LDB(B1, 0, 1); BAR; WAIT_L(0); MMA(0, 1, At, B1); BAR;
	v_mfma_f32_16x16x32_bf16 v[94:97], v[148:151], v[164:167], v[94:97]
	v_mfma_f32_16x16x32_bf16 v[90:93], v[214:217], v[164:167], v[90:93]
	v_mfma_f32_16x16x32_bf16 v[86:89], v[148:151], v[172:175], v[86:89]
	v_mfma_f32_16x16x32_bf16 v[82:85], v[214:217], v[172:175], v[82:85]
	v_mfma_f32_16x16x32_bf16 v[78:81], v[148:151], v[194:197], v[78:81]
	v_mfma_f32_16x16x32_bf16 v[74:77], v[214:217], v[194:197], v[74:77]
	v_mfma_f32_16x16x32_bf16 v[70:73], v[148:151], v[202:205], v[70:73]
	v_mfma_f32_16x16x32_bf16 v[66:69], v[214:217], v[202:205], v[66:69]
	v_mfma_f32_16x16x32_bf16 v[94:97], v[210:213], v[168:171], v[94:97]
	v_mfma_f32_16x16x32_bf16 v[90:93], v[218:221], v[168:171], v[90:93]
	v_mfma_f32_16x16x32_bf16 v[86:89], v[210:213], v[176:179], v[86:89]
	v_mfma_f32_16x16x32_bf16 v[82:85], v[218:221], v[176:179], v[82:85]
	v_mfma_f32_16x16x32_bf16 v[78:81], v[210:213], v[198:201], v[78:81]
	v_mfma_f32_16x16x32_bf16 v[74:77], v[218:221], v[198:201], v[74:77]
	v_mfma_f32_16x16x32_bf16 v[70:73], v[210:213], v[206:209], v[70:73]
	v_mfma_f32_16x16x32_bf16 v[66:69], v[218:221], v[206:209], v[66:69]

; #define LDA(dst, b, h) for (int m = 0; m < 4; ++m) for (int k = 0; k < 2; ++k) \
;     dst[m][k] = *reinterpret_cast<const bf16x8*>((char*)SA(b, h) + a_thr + (m * 2 + k) * 1024)
; #define MMA(ai, bj, At, Btf) do { __builtin_amdgcn_s_setprio(1); \
;     for (int m = 0; m < 4; ++m) for (int n = 0; n < 2; ++n) for (int k = 0; k < 2; ++k) \
;       acc[ai][bj][m][n] = __builtin_amdgcn_mfma_f32_16x16x32_bf16(Btf[n][k], At[m][k], acc[ai][bj][m][n], 0, 0, 0); \
;     __builtin_amdgcn_s_setprio(0); } while (0)
; #define WAIT_V(n) asm volatile("s_waitcnt vmcnt(" #n ")" ::: "memory")
; #define WAIT_L(n) asm volatile("s_waitcnt lgkmcnt(" #n ")" ::: "memory")
; #define BAR __builtin_amdgcn_s_barrier()
; template <bool OVL, bool PANEL = false, class Epi>
; __device__ __forceinline__ void gemm_phase(const bf16_t* __restrict__ A, long lda, const bf16_t* __restrict__ Bt, long ldb, int nM, int nN, int K,
;                                            const Epi& epi, bf16_t* shm, int w0) {
;     ...
;       LDA(At, 0, 1); WAIT_V(4); BAR; WAIT_L(0); MMA(1, 0, At, B0); MMA(1, 1, At, B1); BAR; }
	s_barrier
	ds_read_b128 v[164:167], v147 offset:16384
	ds_read_b128 v[168:171], v147 offset:17408
	ds_read_b128 v[172:175], v147 offset:18432
	ds_read_b128 v[176:179], v147 offset:19456
	ds_read_b128 v[194:197], v147 offset:20480
	ds_read_b128 v[198:201], v147 offset:21504
	ds_read_b128 v[202:205], v147 offset:22528
	ds_read_b128 v[206:209], v147 offset:23552
	s_waitcnt vmcnt(4)
	s_barrier
	s_waitcnt lgkmcnt(0)

; #define LDA(dst, b, h) for (int m = 0; m < 4; ++m) for (int k = 0; k < 2; ++k) \
;     dst[m][k] = *reinterpret_cast<const bf16x8*>((char*)SA(b, h) + a_thr + (m * 2 + k) * 1024)
; #define MMA(ai, bj, At, Btf) do { __builtin_amdgcn_s_setprio(1); \
;     for (int m = 0; m < 4; ++m) for (int n = 0; n < 2; ++n) for (int k = 0; k < 2; ++k) \
;       acc[ai][bj][m][n] = __builtin_amdgcn_mfma_f32_16x16x32_bf16(Btf[n][k], At[m][k], acc[ai][bj][m][n], 0, 0, 0); \
;     __builtin_amdgcn_s_setprio(0); } while (0)
; #define WAIT_V(n) asm volatile("s_waitcnt vmcnt(" #n ")" ::: "memory")
; #define WAIT_L(n) asm volatile("s_waitcnt lgkmcnt(" #n ")" ::: "memory")
; #define BAR __builtin_amdgcn_s_barrier()
; template <bool OVL, bool PANEL = false, class Epi>
; __device__ __forceinline__ void gemm_phase(const bf16_t* __restrict__ A, long lda, const bf16_t* __restrict__ Bt, long ldb, int nM, int nN, int K,
;                                            const Epi& epi, bf16_t* shm, int w0) {
;     ...
;       LDA(At, 0, 1); WAIT_V(4); BAR; WAIT_L(0); MMA(1, 0, At, B0); MMA(1, 1, At, B1); BAR; }
	v_mfma_f32_16x16x32_bf16 v[62:65], v[130:133], v[164:167], v[62:65]
	v_mfma_f32_16x16x32_bf16 v[58:61], v[156:159], v[164:167], v[58:61]
	v_mfma_f32_16x16x32_bf16 v[54:57], v[130:133], v[172:175], v[54:57]
	v_mfma_f32_16x16x32_bf16 v[50:53], v[156:159], v[172:175], v[50:53]
	v_mfma_f32_16x16x32_bf16 v[46:49], v[130:133], v[194:197], v[46:49]
	v_mfma_f32_16x16x32_bf16 v[42:45], v[156:159], v[194:197], v[42:45]
	v_mfma_f32_16x16x32_bf16 v[38:41], v[130:133], v[202:205], v[38:41]
	v_mfma_f32_16x16x32_bf16 v[34:37], v[156:159], v[202:205], v[34:37]
	v_mfma_f32_16x16x32_bf16 v[62:65], v[152:155], v[168:171], v[62:65]
	v_mfma_f32_16x16x32_bf16 v[58:61], v[160:163], v[168:171], v[58:61]
	v_mfma_f32_16x16x32_bf16 v[54:57], v[152:155], v[176:179], v[54:57]
	v_mfma_f32_16x16x32_bf16 v[50:53], v[160:163], v[176:179], v[50:53]
	v_mfma_f32_16x16x32_bf16 v[46:49], v[152:155], v[198:201], v[46:49]
	v_mfma_f32_16x16x32_bf16 v[42:45], v[160:163], v[198:201], v[42:45]
	v_mfma_f32_16x16x32_bf16 v[38:41], v[152:155], v[206:209], v[38:41]
	v_mfma_f32_16x16x32_bf16 v[34:37], v[160:163], v[206:209], v[34:37]


; #define LDA(dst, b, h) for (int m = 0; m < 4; ++m) for (int k = 0; k < 2; ++k) \
;     dst[m][k] = *reinterpret_cast<const bf16x8*>((char*)SA(b, h) + a_thr + (m * 2 + k) * 1024)
; #define MMA(ai, bj, At, Btf) do { __builtin_amdgcn_s_setprio(1); \
;     for (int m = 0; m < 4; ++m) for (int n = 0; n < 2; ++n) for (int k = 0; k < 2; ++k) \
;       acc[ai][bj][m][n] = __builtin_amdgcn_mfma_f32_16x16x32_bf16(Btf[n][k], At[m][k], acc[ai][bj][m][n], 0, 0, 0); \
;     __builtin_amdgcn_s_setprio(0); } while (0)
; #define WAIT_V(n) asm volatile("s_waitcnt vmcnt(" #n ")" ::: "memory")
; #define WAIT_L(n) asm volatile("s_waitcnt lgkmcnt(" #n ")" ::: "memory")
; #define BAR __builtin_amdgcn_s_barrier()
; template <bool OVL, bool PANEL = false, class Epi>
; __device__ __forceinline__ void gemm_phase(const bf16_t* __restrict__ A, long lda, const bf16_t* __restrict__ Bt, long ldb, int nM, int nN, int K,
;                                            const Epi& epi, bf16_t* shm, int w0) {
;     ...
;       LDA(At, 0, 1); WAIT_V(4); BAR; WAIT_L(0); MMA(1, 0, At, B0); MMA(1, 1, At, B1); BAR; }
	v_mfma_f32_16x16x32_bf16 v[30:33], v[148:151], v[164:167], v[30:33]
	v_mfma_f32_16x16x32_bf16 v[26:29], v[214:217], v[164:167], v[26:29]
	v_mfma_f32_16x16x32_bf16 v[22:25], v[148:151], v[172:175], v[22:25]
	v_mfma_f32_16x16x32_bf16 v[18:21], v[214:217], v[172:175], v[18:21]
	v_mfma_f32_16x16x32_bf16 v[14:17], v[148:151], v[194:197], v[14:17]
	v_mfma_f32_16x16x32_bf16 v[10:13], v[214:217], v[194:197], v[10:13]
	v_mfma_f32_16x16x32_bf16 v[6:9], v[148:151], v[202:205], v[6:9]
	v_mfma_f32_16x16x32_bf16 v[2:5], v[214:217], v[202:205], v[2:5]
	v_mfma_f32_16x16x32_bf16 v[30:33], v[210:213], v[168:171], v[30:33]
	v_mfma_f32_16x16x32_bf16 v[26:29], v[218:221], v[168:171], v[26:29]
	v_mfma_f32_16x16x32_bf16 v[22:25], v[210:213], v[176:179], v[22:25]
	v_mfma_f32_16x16x32_bf16 v[18:21], v[218:221], v[176:179], v[18:21]
	v_mfma_f32_16x16x32_bf16 v[14:17], v[210:213], v[198:201], v[14:17]
	v_mfma_f32_16x16x32_bf16 v[10:13], v[218:221], v[198:201], v[10:13]
	v_mfma_f32_16x16x32_bf16 v[6:9], v[210:213], v[206:209], v[6:9]
	v_mfma_f32_16x16x32_bf16 v[2:5], v[218:221], v[206:209], v[2:5]

; #define LDA(dst, b, h) for (int m = 0; m < 4; ++m) for (int k = 0; k < 2; ++k) \
;     dst[m][k] = *reinterpret_cast<const bf16x8*>((char*)SA(b, h) + a_thr + (m * 2 + k) * 1024)
; #define LDB(dst, b, h) for (int n = 0; n < 2; ++n) for (int k = 0; k < 2; ++k) \
;     dst[n][k] = *reinterpret_cast<const bf16x8*>((char*)SB(b, h) + b_thr + (n * 2 + k) * 1024)
; #define MMA(ai, bj, At, Btf) do { __builtin_amdgcn_s_setprio(1); \
;     for (int m = 0; m < 4; ++m) for (int n = 0; n < 2; ++n) for (int k = 0; k < 2; ++k) \
;       acc[ai][bj][m][n] = __builtin_amdgcn_mfma_f32_16x16x32_bf16(Btf[n][k], At[m][k], acc[ai][bj][m][n], 0, 0, 0); \
;     __builtin_amdgcn_s_setprio(0); } while (0)
; #define WAIT_V(n) asm volatile("s_waitcnt vmcnt(" #n ")" ::: "memory")
; #define WAIT_L(n) asm volatile("s_waitcnt lgkmcnt(" #n ")" ::: "memory")
; #define BAR __builtin_amdgcn_s_barrier()
; template <bool OVL, bool PANEL = false, class Epi>
; __device__ __forceinline__ void gemm_phase(const bf16_t* __restrict__ A, long lda, const bf16_t* __restrict__ Bt, long ldb, int nM, int nN, int K,
;                                            const Epi& epi, bf16_t* shm, int w0) {
;     ...
;       LDA(At, 0, 1); WAIT_V(4); BAR; WAIT_L(0); MMA(1, 0, At, B0); MMA(1, 1, At, B1); BAR; }
;     { LDB(B0, 1, 0); LDA(At, 1, 0); WAIT_V(2); BAR; WAIT_L(0); MMA(0, 0, At, B0); BAR;
	v_add_u32_e32 v0, 0x18000, v182
	s_barrier
	ds_read_b128 v[130:133], v0
	ds_read_b128 v[148:151], v0 offset:1024
	ds_read_b128 v[152:155], v0 offset:2048
	ds_read_b128 v[156:159], v0 offset:3072
	ds_read_b128 v[160:163], v147 offset:32768
	ds_read_b128 v[164:167], v147 offset:33792
	ds_read_b128 v[168:171], v147 offset:34816
	ds_read_b128 v[172:175], v147 offset:35840
	ds_read_b128 v[176:179], v147 offset:36864
	ds_read_b128 v[194:197], v147 offset:37888
	ds_read_b128 v[198:201], v147 offset:38912
	ds_read_b128 v[202:205], v147 offset:39936
	s_waitcnt vmcnt(2)
	s_barrier
	s_waitcnt lgkmcnt(0)

; #define LDA(dst, b, h) for (int m = 0; m < 4; ++m) for (int k = 0; k < 2; ++k) \
;     dst[m][k] = *reinterpret_cast<const bf16x8*>((char*)SA(b, h) + a_thr + (m * 2 + k) * 1024)
; #define LDB(dst, b, h) for (int n = 0; n < 2; ++n) for (int k = 0; k < 2; ++k) \
;     dst[n][k] = *reinterpret_cast<const bf16x8*>((char*)SB(b, h) + b_thr + (n * 2 + k) * 1024)
; #define MMA(ai, bj, At, Btf) do { __builtin_amdgcn_s_setprio(1); \
;     for (int m = 0; m < 4; ++m) for (int n = 0; n < 2; ++n) for (int k = 0; k < 2; ++k) \
;       acc[ai][bj][m][n] = __builtin_amdgcn_mfma_f32_16x16x32_bf16(Btf[n][k], At[m][k], acc[ai][bj][m][n], 0, 0, 0); \
;     __builtin_amdgcn_s_setprio(0); } while (0)
; #define WAIT_V(n) asm volatile("s_waitcnt vmcnt(" #n ")" ::: "memory")
; #define WAIT_L(n) asm volatile("s_waitcnt lgkmcnt(" #n ")" ::: "memory")
; #define BAR __builtin_amdgcn_s_barrier()
; template <bool OVL, bool PANEL = false, class Epi>
; __device__ __forceinline__ void gemm_phase(const bf16_t* __restrict__ A, long lda, const bf16_t* __restrict__ Bt, long ldb, int nM, int nN, int K,
;                                            const Epi& epi, bf16_t* shm, int w0) {
;     ...
;     { LDB(B0, 1, 0); LDA(At, 1, 0); WAIT_V(2); BAR; WAIT_L(0); MMA(0, 0, At, B0); BAR;
	v_mfma_f32_16x16x32_bf16 v[126:129], v[130:133], v[160:163], v[126:129]
	v_mfma_f32_16x16x32_bf16 v[122:125], v[152:155], v[160:163], v[122:125]
	v_mfma_f32_16x16x32_bf16 v[118:121], v[130:133], v[168:171], v[118:121]
	v_mfma_f32_16x16x32_bf16 v[114:117], v[152:155], v[168:171], v[114:117]
	v_mfma_f32_16x16x32_bf16 v[110:113], v[130:133], v[176:179], v[110:113]
	v_mfma_f32_16x16x32_bf16 v[106:109], v[152:155], v[176:179], v[106:109]
	v_mfma_f32_16x16x32_bf16 v[102:105], v[130:133], v[198:201], v[102:105]
	v_mfma_f32_16x16x32_bf16 v[98:101], v[152:155], v[198:201], v[98:101]
	v_mfma_f32_16x16x32_bf16 v[126:129], v[148:151], v[164:167], v[126:129]
	v_mfma_f32_16x16x32_bf16 v[122:125], v[156:159], v[164:167], v[122:125]
	v_mfma_f32_16x16x32_bf16 v[118:121], v[148:151], v[172:175], v[118:121]
	v_mfma_f32_16x16x32_bf16 v[114:117], v[156:159], v[172:175], v[114:117]
	v_mfma_f32_16x16x32_bf16 v[110:113], v[148:151], v[194:197], v[110:113]
	v_mfma_f32_16x16x32_bf16 v[106:109], v[156:159], v[194:197], v[106:109]
	v_mfma_f32_16x16x32_bf16 v[102:105], v[148:151], v[202:205], v[102:105]
	v_mfma_f32_16x16x32_bf16 v[98:101], v[156:159], v[202:205], v[98:101]

; #define LDA(dst, b, h) for (int m = 0; m < 4; ++m) for (int k = 0; k < 2; ++k) \
;     dst[m][k] = *reinterpret_cast<const bf16x8*>((char*)SA(b, h) + a_thr + (m * 2 + k) * 1024)
; #define LDB(dst, b, h) for (int n = 0; n < 2; ++n) for (int k = 0; k < 2; ++k) \
;     dst[n][k] = *reinterpret_cast<const bf16x8*>((char*)SB(b, h) + b_thr + (n * 2 + k) * 1024)
; #define MMA(ai, bj, At, Btf) do { __builtin_amdgcn_s_setprio(1); \
;     for (int m = 0; m < 4; ++m) for (int n = 0; n < 2; ++n) for (int k = 0; k < 2; ++k) \
;       acc[ai][bj][m][n] = __builtin_amdgcn_mfma_f32_16x16x32_bf16(Btf[n][k], At[m][k], acc[ai][bj][m][n], 0, 0, 0); \
;     __builtin_amdgcn_s_setprio(0); } while (0)
; #define WAIT_V(n) asm volatile("s_waitcnt vmcnt(" #n ")" ::: "memory")
; #define WAIT_L(n) asm volatile("s_waitcnt lgkmcnt(" #n ")" ::: "memory")
; #define BAR __builtin_amdgcn_s_barrier()
; template <bool OVL, bool PANEL = false, class Epi>
; __device__ __forceinline__ void gemm_phase(const bf16_t* __restrict__ A, long lda, const bf16_t* __restrict__ Bt, long ldb, int nM, int nN, int K,
;                                            const Epi& epi, bf16_t* shm, int w0) {
;     ...
;     { LDB(B0, 1, 0); LDA(At, 1, 0); WAIT_V(2); BAR; WAIT_L(0); MMA(0, 0, At, B0); BAR;
;       LDB(B1, 1, 1); WAIT_V(0); BAR; WAIT_L(0); MMA(0, 1, At, B1); BAR;
	v_add_u32_e32 v0, 0x1c000, v182
	s_barrier
	ds_read_b128 v[206:209], v0
	ds_read_b128 v[210:213], v0 offset:1024
	ds_read_b128 v[214:217], v0 offset:2048
	ds_read_b128 v[218:221], v0 offset:3072
	s_waitcnt vmcnt(0)
	s_barrier
	s_waitcnt lgkmcnt(0)

; #define LDB(dst, b, h) for (int n = 0; n < 2; ++n) for (int k = 0; k < 2; ++k) \
;     dst[n][k] = *reinterpret_cast<const bf16x8*>((char*)SB(b, h) + b_thr + (n * 2 + k) * 1024)
; #define MMA(ai, bj, At, Btf) do { __builtin_amdgcn_s_setprio(1); \
;     for (int m = 0; m < 4; ++m) for (int n = 0; n < 2; ++n) for (int k = 0; k < 2; ++k) \
;       acc[ai][bj][m][n] = __builtin_amdgcn_mfma_f32_16x16x32_bf16(Btf[n][k], At[m][k], acc[ai][bj][m][n], 0, 0, 0); \
;     __builtin_amdgcn_s_setprio(0); } while (0)
; #define WAIT_V(n) asm volatile("s_waitcnt vmcnt(" #n ")" ::: "memory")
; #define WAIT_L(n) asm volatile("s_waitcnt lgkmcnt(" #n ")" ::: "memory")
; #define BAR __builtin_amdgcn_s_barrier()
; template <bool OVL, bool PANEL = false, class Epi>
; __device__ __forceinline__ void gemm_phase(const bf16_t* __restrict__ A, long lda, const bf16_t* __restrict__ Bt, long ldb, int nM, int nN, int K,
;                                            const Epi& epi, bf16_t* shm, int w0) {
;     ...
;       LDB(B1, 1, 1); WAIT_V(0); BAR; WAIT_L(0); MMA(0, 1, At, B1); BAR;
	v_mfma_f32_16x16x32_bf16 v[94:97], v[206:209], v[160:163], v[94:97]
	v_mfma_f32_16x16x32_bf16 v[90:93], v[214:217], v[160:163], v[90:93]
	v_mfma_f32_16x16x32_bf16 v[86:89], v[206:209], v[168:171], v[86:89]
	v_mfma_f32_16x16x32_bf16 v[82:85], v[214:217], v[168:171], v[82:85]
	v_mfma_f32_16x16x32_bf16 v[78:81], v[206:209], v[176:179], v[78:81]
	v_mfma_f32_16x16x32_bf16 v[74:77], v[214:217], v[176:179], v[74:77]
	v_mfma_f32_16x16x32_bf16 v[70:73], v[206:209], v[198:201], v[70:73]
	v_mfma_f32_16x16x32_bf16 v[66:69], v[214:217], v[198:201], v[66:69]
	v_mfma_f32_16x16x32_bf16 v[94:97], v[210:213], v[164:167], v[94:97]
	v_mfma_f32_16x16x32_bf16 v[90:93], v[218:221], v[164:167], v[90:93]
	v_mfma_f32_16x16x32_bf16 v[86:89], v[210:213], v[172:175], v[86:89]
	v_mfma_f32_16x16x32_bf16 v[82:85], v[218:221], v[172:175], v[82:85]
	v_mfma_f32_16x16x32_bf16 v[78:81], v[210:213], v[194:197], v[78:81]
	v_mfma_f32_16x16x32_bf16 v[74:77], v[218:221], v[194:197], v[74:77]
	v_mfma_f32_16x16x32_bf16 v[70:73], v[210:213], v[202:205], v[70:73]
	v_mfma_f32_16x16x32_bf16 v[66:69], v[218:221], v[202:205], v[66:69]

; #define LDA(dst, b, h) for (int m = 0; m < 4; ++m) for (int k = 0; k < 2; ++k) \
;     dst[m][k] = *reinterpret_cast<const bf16x8*>((char*)SA(b, h) + a_thr + (m * 2 + k) * 1024)
; #define LDB(dst, b, h) for (int n = 0; n < 2; ++n) for (int k = 0; k < 2; ++k) \
;     dst[n][k] = *reinterpret_cast<const bf16x8*>((char*)SB(b, h) + b_thr + (n * 2 + k) * 1024)
; #define MMA(ai, bj, At, Btf) do { __builtin_amdgcn_s_setprio(1); \
;     for (int m = 0; m < 4; ++m) for (int n = 0; n < 2; ++n) for (int k = 0; k < 2; ++k) \
;       acc[ai][bj][m][n] = __builtin_amdgcn_mfma_f32_16x16x32_bf16(Btf[n][k], At[m][k], acc[ai][bj][m][n], 0, 0, 0); \
;     __builtin_amdgcn_s_setprio(0); } while (0)
; #define WAIT_V(n) asm volatile("s_waitcnt vmcnt(" #n ")" ::: "memory")
; #define WAIT_L(n) asm volatile("s_waitcnt lgkmcnt(" #n ")" ::: "memory")
; #define BAR __builtin_amdgcn_s_barrier()
; template <bool OVL, bool PANEL = false, class Epi>
; __device__ __forceinline__ void gemm_phase(const bf16_t* __restrict__ A, long lda, const bf16_t* __restrict__ Bt, long ldb, int nM, int nN, int K,
;                                            const Epi& epi, bf16_t* shm, int w0) {
;     ...
;       LDB(B1, 1, 1); WAIT_V(0); BAR; WAIT_L(0); MMA(0, 1, At, B1); BAR;
;       LDA(At, 1, 1); BAR; WAIT_L(0); MMA(1, 0, At, B0); MMA(1, 1, At, B1); BAR; }
	s_barrier
	ds_read_b128 v[160:163], v147 offset:49152
	ds_read_b128 v[164:167], v147 offset:50176
	ds_read_b128 v[168:171], v147 offset:51200
	ds_read_b128 v[172:175], v147 offset:52224
	ds_read_b128 v[176:179], v147 offset:53248
	ds_read_b128 v[194:197], v147 offset:54272
	ds_read_b128 v[198:201], v147 offset:55296
	ds_read_b128 v[202:205], v147 offset:56320
	s_barrier
	s_waitcnt lgkmcnt(0)

; #define LDA(dst, b, h) for (int m = 0; m < 4; ++m) for (int k = 0; k < 2; ++k) \
;     dst[m][k] = *reinterpret_cast<const bf16x8*>((char*)SA(b, h) + a_thr + (m * 2 + k) * 1024)
; #define MMA(ai, bj, At, Btf) do { __builtin_amdgcn_s_setprio(1); \
;     for (int m = 0; m < 4; ++m) for (int n = 0; n < 2; ++n) for (int k = 0; k < 2; ++k) \
;       acc[ai][bj][m][n] = __builtin_amdgcn_mfma_f32_16x16x32_bf16(Btf[n][k], At[m][k], acc[ai][bj][m][n], 0, 0, 0); \
;     __builtin_amdgcn_s_setprio(0); } while (0)
; #define WAIT_L(n) asm volatile("s_waitcnt lgkmcnt(" #n ")" ::: "memory")
; #define BAR __builtin_amdgcn_s_barrier()
; template <bool OVL, bool PANEL = false, class Epi>
; __device__ __forceinline__ void gemm_phase(const bf16_t* __restrict__ A, long lda, const bf16_t* __restrict__ Bt, long ldb, int nM, int nN, int K,
;                                            const Epi& epi, bf16_t* shm, int w0) {
;     ...
;       LDA(At, 1, 1); BAR; WAIT_L(0); MMA(1, 0, At, B0); MMA(1, 1, At, B1); BAR; }
	v_mfma_f32_16x16x32_bf16 v[62:65], v[130:133], v[160:163], v[62:65]
	v_mfma_f32_16x16x32_bf16 v[58:61], v[152:155], v[160:163], v[58:61]
	v_mfma_f32_16x16x32_bf16 v[54:57], v[130:133], v[168:171], v[54:57]
	v_mfma_f32_16x16x32_bf16 v[50:53], v[152:155], v[168:171], v[50:53]
	v_mfma_f32_16x16x32_bf16 v[46:49], v[130:133], v[176:179], v[46:49]
	v_mfma_f32_16x16x32_bf16 v[42:45], v[152:155], v[176:179], v[42:45]
	v_mfma_f32_16x16x32_bf16 v[38:41], v[130:133], v[198:201], v[38:41]
	v_mfma_f32_16x16x32_bf16 v[34:37], v[152:155], v[198:201], v[34:37]
	v_mfma_f32_16x16x32_bf16 v[62:65], v[148:151], v[164:167], v[62:65]
	v_mfma_f32_16x16x32_bf16 v[58:61], v[156:159], v[164:167], v[58:61]
	v_mfma_f32_16x16x32_bf16 v[54:57], v[148:151], v[172:175], v[54:57]
	v_mfma_f32_16x16x32_bf16 v[50:53], v[156:159], v[172:175], v[50:53]
	v_mfma_f32_16x16x32_bf16 v[46:49], v[148:151], v[194:197], v[46:49]
	v_mfma_f32_16x16x32_bf16 v[42:45], v[156:159], v[194:197], v[42:45]
	v_mfma_f32_16x16x32_bf16 v[38:41], v[148:151], v[202:205], v[38:41]
	v_mfma_f32_16x16x32_bf16 v[34:37], v[156:159], v[202:205], v[34:37]


; #define LDA(dst, b, h) for (int m = 0; m < 4; ++m) for (int k = 0; k < 2; ++k) \
;     dst[m][k] = *reinterpret_cast<const bf16x8*>((char*)SA(b, h) + a_thr + (m * 2 + k) * 1024)
; #define MMA(ai, bj, At, Btf) do { __builtin_amdgcn_s_setprio(1); \
;     for (int m = 0; m < 4; ++m) for (int n = 0; n < 2; ++n) for (int k = 0; k < 2; ++k) \
;       acc[ai][bj][m][n] = __builtin_amdgcn_mfma_f32_16x16x32_bf16(Btf[n][k], At[m][k], acc[ai][bj][m][n], 0, 0, 0); \
;     __builtin_amdgcn_s_setprio(0); } while (0)
; #define WAIT_L(n) asm volatile("s_waitcnt lgkmcnt(" #n ")" ::: "memory")
; #define BAR __builtin_amdgcn_s_barrier()
; template <bool OVL, bool PANEL = false, class Epi>
; __device__ __forceinline__ void gemm_phase(const bf16_t* __restrict__ A, long lda, const bf16_t* __restrict__ Bt, long ldb, int nM, int nN, int K,
;                                            const Epi& epi, bf16_t* shm, int w0) {
;     ...
;       LDA(At, 1, 1); BAR; WAIT_L(0); MMA(1, 0, At, B0); MMA(1, 1, At, B1); BAR; }
	v_mfma_f32_16x16x32_bf16 v[30:33], v[206:209], v[160:163], v[30:33]
	v_mfma_f32_16x16x32_bf16 v[26:29], v[214:217], v[160:163], v[26:29]
	v_mfma_f32_16x16x32_bf16 v[22:25], v[206:209], v[168:171], v[22:25]
	v_mfma_f32_16x16x32_bf16 v[18:21], v[214:217], v[168:171], v[18:21]
	v_mfma_f32_16x16x32_bf16 v[14:17], v[206:209], v[176:179], v[14:17]
	v_mfma_f32_16x16x32_bf16 v[10:13], v[214:217], v[176:179], v[10:13]
	v_mfma_f32_16x16x32_bf16 v[6:9], v[206:209], v[198:201], v[6:9]
	v_mfma_f32_16x16x32_bf16 v[2:5], v[214:217], v[198:201], v[2:5]
	v_mfma_f32_16x16x32_bf16 v[30:33], v[210:213], v[164:167], v[30:33]
	v_mfma_f32_16x16x32_bf16 v[26:29], v[218:221], v[164:167], v[26:29]
	v_mfma_f32_16x16x32_bf16 v[22:25], v[210:213], v[172:175], v[22:25]
	v_mfma_f32_16x16x32_bf16 v[18:21], v[218:221], v[172:175], v[18:21]
	v_mfma_f32_16x16x32_bf16 v[14:17], v[210:213], v[194:197], v[14:17]
	v_mfma_f32_16x16x32_bf16 v[10:13], v[218:221], v[194:197], v[10:13]
	v_mfma_f32_16x16x32_bf16 v[6:9], v[210:213], v[202:205], v[6:9]
	v_mfma_f32_16x16x32_bf16 v[2:5], v[218:221], v[202:205], v[2:5]

; #define LDA(dst, b, h) for (int m = 0; m < 4; ++m) for (int k = 0; k < 2; ++k) \
;     dst[m][k] = *reinterpret_cast<const bf16x8*>((char*)SA(b, h) + a_thr + (m * 2 + k) * 1024)
; #define MMA(ai, bj, At, Btf) do { __builtin_amdgcn_s_setprio(1); \
;     for (int m = 0; m < 4; ++m) for (int n = 0; n < 2; ++n) for (int k = 0; k < 2; ++k) \
;       acc[ai][bj][m][n] = __builtin_amdgcn_mfma_f32_16x16x32_bf16(Btf[n][k], At[m][k], acc[ai][bj][m][n], 0, 0, 0); \
;     __builtin_amdgcn_s_setprio(0); } while (0)
; #define WAIT_L(n) asm volatile("s_waitcnt lgkmcnt(" #n ")" ::: "memory")
; #define BAR __builtin_amdgcn_s_barrier()
; template <bool OVL, bool PANEL = false, class Epi>
; __device__ __forceinline__ void gemm_phase(const bf16_t* __restrict__ A, long lda, const bf16_t* __restrict__ Bt, long ldb, int nM, int nN, int K,
;                                            const Epi& epi, bf16_t* shm, int w0) {
;     ...
;       LDA(At, 1, 1); BAR; WAIT_L(0); MMA(1, 0, At, B0); MMA(1, 1, At, B1); BAR; }
;     if (wr == 0) BAR;
	s_barrier
	s_and_saveexec_b64 s[8:9], s[6:7]
	s_cbranch_execz .LBB0_1056
	s_barrier
